# row-pair-interleaved layout extended to B operands (w1, w2, w_in) and A operands of w_o and merge gate GEMMs; w2 transpose loads 16-deep
# speedup vs baseline: 1.0888x; 1.0308x over previous
; DI void do_transpose(const float* __restrict__ src, int K, int N, u16* __restrict__ dst, const float* __restrict__ ksc, int perm, int tile, float* tl) {
;     ...
;   __syncthreads();
; #pragma unroll 4
;   for (int i = 0; i < 16; ++i) {
;     const int kk = i * 4 + (tid >> 6), nn = tid & 63;
;     float v = 0.f;
;     if (n0 + nn < N) v = src[(size_t)(k0 + kk) * N + n0 + nn];
;     if (ksc) v *= ksc[k0 + kk];
;     tl[kk * 65 + nn] = v;
;   }
;   __syncthreads();
.LBB0_101:
	v_mov_b32_e32 v16, 0
	v_mov_b32_e32 v17, 0
	v_mov_b32_e32 v18, 0
	v_mov_b32_e32 v19, 0
	v_mov_b32_e32 v20, 0
	v_mov_b32_e32 v21, 0
	v_mov_b32_e32 v22, 0
	v_mov_b32_e32 v23, 0
	v_mov_b32_e32 v24, 0
	v_mov_b32_e32 v25, 0
	v_mov_b32_e32 v26, 0
	v_mov_b32_e32 v27, 0
	v_mov_b32_e32 v28, 0
	v_mov_b32_e32 v29, 0
	v_mov_b32_e32 v30, 0
	v_mov_b32_e32 v31, 0
	s_and_saveexec_b64 s[4:5], vcc
	s_cbranch_execz .Lw2_ld_done
	v_mov_b32_e32 v10, v1
	v_ashrrev_i32_e32 v11, 31, v10
	v_lshlrev_b64 v[10:11], 12, v[10:11]
	v_lshl_add_u64 v[10:11], v[4:5], 0, v[10:11]
	global_load_dword v16, v[10:11], off
	v_add_u32_e32 v10, 4, v1
	v_ashrrev_i32_e32 v11, 31, v10
	v_lshlrev_b64 v[10:11], 12, v[10:11]
	v_lshl_add_u64 v[10:11], v[4:5], 0, v[10:11]
	global_load_dword v17, v[10:11], off
	v_add_u32_e32 v10, 8, v1
	v_ashrrev_i32_e32 v11, 31, v10
	v_lshlrev_b64 v[10:11], 12, v[10:11]
	v_lshl_add_u64 v[10:11], v[4:5], 0, v[10:11]
	global_load_dword v18, v[10:11], off
	v_add_u32_e32 v10, 12, v1
	v_ashrrev_i32_e32 v11, 31, v10
	v_lshlrev_b64 v[10:11], 12, v[10:11]
	v_lshl_add_u64 v[10:11], v[4:5], 0, v[10:11]
	global_load_dword v19, v[10:11], off
	v_add_u32_e32 v10, 16, v1
	v_ashrrev_i32_e32 v11, 31, v10
	v_lshlrev_b64 v[10:11], 12, v[10:11]
	v_lshl_add_u64 v[10:11], v[4:5], 0, v[10:11]
	global_load_dword v20, v[10:11], off
	v_add_u32_e32 v10, 20, v1
	v_ashrrev_i32_e32 v11, 31, v10
	v_lshlrev_b64 v[10:11], 12, v[10:11]
	v_lshl_add_u64 v[10:11], v[4:5], 0, v[10:11]
	global_load_dword v21, v[10:11], off
	v_add_u32_e32 v10, 24, v1
	v_ashrrev_i32_e32 v11, 31, v10
	v_lshlrev_b64 v[10:11], 12, v[10:11]
	v_lshl_add_u64 v[10:11], v[4:5], 0, v[10:11]
	global_load_dword v22, v[10:11], off
	v_add_u32_e32 v10, 28, v1
	v_ashrrev_i32_e32 v11, 31, v10
	v_lshlrev_b64 v[10:11], 12, v[10:11]
	v_lshl_add_u64 v[10:11], v[4:5], 0, v[10:11]
	global_load_dword v23, v[10:11], off
	v_add_u32_e32 v10, 32, v1
	v_ashrrev_i32_e32 v11, 31, v10
	v_lshlrev_b64 v[10:11], 12, v[10:11]
	v_lshl_add_u64 v[10:11], v[4:5], 0, v[10:11]
	global_load_dword v24, v[10:11], off
	v_add_u32_e32 v10, 36, v1
	v_ashrrev_i32_e32 v11, 31, v10
	v_lshlrev_b64 v[10:11], 12, v[10:11]
	v_lshl_add_u64 v[10:11], v[4:5], 0, v[10:11]
	global_load_dword v25, v[10:11], off
	v_add_u32_e32 v10, 40, v1
	v_ashrrev_i32_e32 v11, 31, v10
	v_lshlrev_b64 v[10:11], 12, v[10:11]
	v_lshl_add_u64 v[10:11], v[4:5], 0, v[10:11]
	global_load_dword v26, v[10:11], off
	v_add_u32_e32 v10, 44, v1
	v_ashrrev_i32_e32 v11, 31, v10
	v_lshlrev_b64 v[10:11], 12, v[10:11]
	v_lshl_add_u64 v[10:11], v[4:5], 0, v[10:11]
	global_load_dword v27, v[10:11], off
	v_add_u32_e32 v10, 48, v1
	v_ashrrev_i32_e32 v11, 31, v10
	v_lshlrev_b64 v[10:11], 12, v[10:11]
	v_lshl_add_u64 v[10:11], v[4:5], 0, v[10:11]
	global_load_dword v28, v[10:11], off
	v_add_u32_e32 v10, 52, v1
	v_ashrrev_i32_e32 v11, 31, v10
	v_lshlrev_b64 v[10:11], 12, v[10:11]
	v_lshl_add_u64 v[10:11], v[4:5], 0, v[10:11]
	global_load_dword v29, v[10:11], off
	v_add_u32_e32 v10, 56, v1
	v_ashrrev_i32_e32 v11, 31, v10
	v_lshlrev_b64 v[10:11], 12, v[10:11]
	v_lshl_add_u64 v[10:11], v[4:5], 0, v[10:11]
	global_load_dword v30, v[10:11], off
	v_add_u32_e32 v10, 60, v1
	v_ashrrev_i32_e32 v11, 31, v10
	v_lshlrev_b64 v[10:11], 12, v[10:11]
	v_lshl_add_u64 v[10:11], v[4:5], 0, v[10:11]
	global_load_dword v31, v[10:11], off
.Lw2_ld_done:
	s_or_b64 exec, exec, s[4:5]
	s_waitcnt vmcnt(0)
	ds_write_b32 v8, v16
	ds_write_b32 v8, v17 offset:1040
	ds_write_b32 v8, v18 offset:2080
	ds_write_b32 v8, v19 offset:3120
	ds_write_b32 v8, v20 offset:4160
	ds_write_b32 v8, v21 offset:5200
	ds_write_b32 v8, v22 offset:6240
	ds_write_b32 v8, v23 offset:7280
	ds_write_b32 v8, v24 offset:8320
	ds_write_b32 v8, v25 offset:9360
	ds_write_b32 v8, v26 offset:10400
	ds_write_b32 v8, v27 offset:11440
	ds_write_b32 v8, v28 offset:12480
	ds_write_b32 v8, v29 offset:13520
	ds_write_b32 v8, v30 offset:14560
	ds_write_b32 v8, v31 offset:15600
.LBB0_109:
	s_lshl_b32 s4, s6, 8
	s_add_u32 s4, s56, s4
	s_addc_u32 s5, s57, 0
	v_and_b32_e32 v2, 31, v6
	v_lshlrev_b32_e32 v2, 1, v2
	v_lshrrev_b32_e32 v10, 5, v6
	v_lshl_or_b32 v2, v10, 7, v2
	v_lshl_add_u64 v[4:5], s[4:5], 0, v[2:3]
	s_mov_b64 s[4:5], 0x1720000
	v_lshl_add_u64 v[4:5], v[4:5], 0, s[4:5]
	v_add_u32_e32 v1, s66, v7
	s_lshl_b32 s4, s7, 10
	v_subrev_u32_e32 v1, s4, v1
	s_mul_i32 s4, s54, 0x3dc00
	v_lshlrev_b32_e32 v2, 2, v7
	v_subrev_u32_e32 v1, s4, v1
	v_mad_u32_u24 v2, v6, s82, v2
	s_mov_b32 s6, 0
	s_waitcnt lgkmcnt(0)
	s_barrier
	s_branch .LBB0_111

; DI u16 f2bf(float a) { return (u16)(pack2(a, 0.f) & 0xffffu); }
; DI void do_transpose(const float* __restrict__ src, int K, int N, u16* __restrict__ dst, const float* __restrict__ ksc, int perm, int tile, float* tl) {
;     ...
; #pragma unroll 4
;   for (int i = 0; i < 16; ++i) {
;     const int nn = i * 4 + (tid >> 6), kk = tid & 63;
;     int n = n0 + nn;
;     if (n < N) {
;       if (perm) { const int h = n / 96, d = n - h * 96; n = d < 64 ? h * 64 + d : 512 + h * 32 + (d - 64); }
;       dst[(size_t)n * K + k0 + kk] = f2bf(tl[kk * 65 + nn]);
;     }
;   }
.LBB0_111:
	v_add_u32_e32 v8, s6, v1
	v_add_u32_e32 v6, 0xfffd2a00, v8
	v_cmp_gt_i32_e32 vcc, s83, v6
	s_and_saveexec_b64 s[4:5], vcc
	s_cbranch_execz .LBB0_113
	ds_read_b32 v9, v2
	v_ashrrev_i32_e32 v7, 31, v6
	v_and_b32_e32 v10, 1, v6
	v_lshrrev_b32_e32 v6, 1, v6
	v_mov_b32_e32 v7, 0
	v_lshlrev_b64 v[6:7], 14, v[6:7]
	v_lshl_or_b32 v6, v10, 6, v6
	v_lshl_add_u64 v[6:7], v[4:5], 0, v[6:7]
	s_waitcnt lgkmcnt(0)
	v_cvt_pk_bf16_f32 v9, v9, s0
	global_store_short v[6:7], v9, off
.LBB0_113:
	s_or_b64 exec, exec, s[4:5]
	v_add_u32_e32 v6, 0xfffd2a04, v8
	v_cmp_gt_i32_e32 vcc, s83, v6
	s_and_saveexec_b64 s[4:5], vcc
	s_cbranch_execz .LBB0_115
	ds_read_b32 v9, v2 offset:16
	v_ashrrev_i32_e32 v7, 31, v6
	v_and_b32_e32 v10, 1, v6
	v_lshrrev_b32_e32 v6, 1, v6
	v_mov_b32_e32 v7, 0
	v_lshlrev_b64 v[6:7], 14, v[6:7]
	v_lshl_or_b32 v6, v10, 6, v6
	v_lshl_add_u64 v[6:7], v[4:5], 0, v[6:7]
	s_waitcnt lgkmcnt(0)
	v_cvt_pk_bf16_f32 v9, v9, s0
	global_store_short v[6:7], v9, off
.LBB0_115:
	s_or_b64 exec, exec, s[4:5]
	v_add_u32_e32 v6, 0xfffd2a08, v8
	v_cmp_gt_i32_e32 vcc, s83, v6
	s_and_saveexec_b64 s[4:5], vcc
	s_cbranch_execz .LBB0_117
	ds_read_b32 v9, v2 offset:32
	v_ashrrev_i32_e32 v7, 31, v6
	v_and_b32_e32 v10, 1, v6
	v_lshrrev_b32_e32 v6, 1, v6
	v_mov_b32_e32 v7, 0
	v_lshlrev_b64 v[6:7], 14, v[6:7]
	v_lshl_or_b32 v6, v10, 6, v6
	v_lshl_add_u64 v[6:7], v[4:5], 0, v[6:7]
	s_waitcnt lgkmcnt(0)
	v_cvt_pk_bf16_f32 v9, v9, s0
	global_store_short v[6:7], v9, off
.LBB0_117:
	s_or_b64 exec, exec, s[4:5]
	v_add_u32_e32 v6, 0xfffd2a0c, v8
	v_cmp_gt_i32_e32 vcc, s83, v6
	s_and_saveexec_b64 s[4:5], vcc
	s_cbranch_execz .LBB0_110
	ds_read_b32 v8, v2 offset:48
	v_ashrrev_i32_e32 v7, 31, v6
	v_and_b32_e32 v10, 1, v6
	v_lshrrev_b32_e32 v6, 1, v6
	v_mov_b32_e32 v7, 0
	v_lshlrev_b64 v[6:7], 14, v[6:7]
	v_lshl_or_b32 v6, v10, 6, v6
	v_lshl_add_u64 v[6:7], v[4:5], 0, v[6:7]
	s_waitcnt lgkmcnt(0)
	v_cvt_pk_bf16_f32 v8, v8, s0
	global_store_short v[6:7], v8, off
	s_branch .LBB0_110

; DI u16 f2bf(float a) { return (u16)(pack2(a, 0.f) & 0xffffu); }
; DI void do_transpose(const float* __restrict__ src, int K, int N, u16* __restrict__ dst, const float* __restrict__ ksc, int perm, int tile, float* tl) {
;     ...
; #pragma unroll 4
;   for (int i = 0; i < 16; ++i) {
;     const int kk = i * 4 + (tid >> 6), nn = tid & 63;
;     float v = 0.f;
;     if (n0 + nn < N) v = src[(size_t)(k0 + kk) * N + n0 + nn];
;     if (ksc) v *= ksc[k0 + kk];
;     tl[kk * 65 + nn] = v;
;   }
;   __syncthreads();
; #pragma unroll 4
;   for (int i = 0; i < 16; ++i) {
;     const int nn = i * 4 + (tid >> 6), kk = tid & 63;
;     int n = n0 + nn;
;     if (n < N) {
;       if (perm) { const int h = n / 96, d = n - h * 96; n = d < 64 ? h * 64 + d : 512 + h * 32 + (d - 64); }
;       dst[(size_t)n * K + k0 + kk] = f2bf(tl[kk * 65 + nn]);
.LBB0_122:
	s_lshl_b32 s7, s6, 2
	s_lshl_b32 s48, s5, 2
	v_add_u32_e32 v28, s7, v10
	v_add_u32_e32 v26, s48, v5
	v_add_u32_e32 v30, s48, v11
	v_add_u32_e32 v32, s7, v16
	v_add_u32_e32 v34, s48, v15
	v_add_u32_e32 v36, s7, v20
	v_add_u32_e32 v38, s48, v19
	v_add_u32_e32 v40, s7, v24
	v_ashrrev_i32_e32 v29, 31, v28
	v_ashrrev_i32_e32 v27, 31, v26
	v_ashrrev_i32_e32 v33, 31, v32
	v_ashrrev_i32_e32 v31, 31, v30
	v_ashrrev_i32_e32 v37, 31, v36
	v_ashrrev_i32_e32 v35, 31, v34
	v_ashrrev_i32_e32 v41, 31, v40
	v_ashrrev_i32_e32 v39, 31, v38
	v_lshlrev_b64 v[28:29], 14, v[28:29]
	v_lshlrev_b64 v[26:27], 14, v[26:27]
	v_lshlrev_b64 v[30:31], 14, v[30:31]
	v_lshlrev_b64 v[32:33], 14, v[32:33]
	v_lshlrev_b64 v[34:35], 14, v[34:35]
	v_lshlrev_b64 v[36:37], 14, v[36:37]
	v_lshlrev_b64 v[38:39], 14, v[38:39]
	v_lshlrev_b64 v[40:41], 14, v[40:41]
	v_lshl_add_u64 v[28:29], v[8:9], 0, v[28:29]
	v_lshl_add_u64 v[26:27], v[8:9], 0, v[26:27]
	v_lshl_add_u64 v[32:33], v[8:9], 0, v[32:33]
	v_lshl_add_u64 v[30:31], v[8:9], 0, v[30:31]
	v_lshl_add_u64 v[36:37], v[8:9], 0, v[36:37]
	v_lshl_add_u64 v[34:35], v[8:9], 0, v[34:35]
	v_lshl_add_u64 v[40:41], v[8:9], 0, v[40:41]
	v_lshl_add_u64 v[38:39], v[8:9], 0, v[38:39]
	global_load_dword v21, v[28:29], off
	global_load_dword v23, v[26:27], off
	global_load_dword v25, v[32:33], off
	global_load_dword v42, v[30:31], off
	global_load_dword v43, v[36:37], off
	global_load_dword v44, v[34:35], off
	global_load_dword v45, v[40:41], off
	global_load_dword v46, v[38:39], off
	s_add_i32 s6, s6, 8
	s_add_i32 s5, s5, 8
	s_add_i32 s4, s4, -8
	v_add_u32_e32 v26, s7, v4
	v_add_u32_e32 v28, s48, v1
	v_add_u32_e32 v32, s48, v7
	v_add_u32_e32 v30, s7, v12
	v_add_u32_e32 v36, s48, v13
	v_add_u32_e32 v34, s7, v18
	v_add_u32_e32 v40, s48, v17
	v_add_u32_e32 v38, s7, v22
	s_cmp_lg_u32 s4, 0
	v_mad_u64_u32 v[26:27], s[58:59], v26, s82, v[2:3]
	v_mad_u64_u32 v[28:29], s[58:59], v28, s82, v[2:3]
	v_mad_u64_u32 v[30:31], s[58:59], v30, s82, v[2:3]
	v_mad_u64_u32 v[32:33], s[58:59], v32, s82, v[2:3]
	v_mad_u64_u32 v[34:35], s[58:59], v34, s82, v[2:3]
	v_mad_u64_u32 v[36:37], s[58:59], v36, s82, v[2:3]
	v_mad_u64_u32 v[38:39], s[58:59], v38, s82, v[2:3]
	v_mad_u64_u32 v[40:41], s[58:59], v40, s82, v[2:3]
	s_waitcnt vmcnt(7)
	ds_write_b32 v26, v21
	s_waitcnt vmcnt(6)
	ds_write_b32 v28, v23
	s_waitcnt vmcnt(5)
	ds_write_b32 v30, v25
	s_waitcnt vmcnt(4)
	ds_write_b32 v32, v42
	s_waitcnt vmcnt(3)
	ds_write_b32 v34, v43
	s_waitcnt vmcnt(2)
	ds_write_b32 v36, v44
	s_waitcnt vmcnt(1)
	ds_write_b32 v38, v45
	s_waitcnt vmcnt(0)
	ds_write_b32 v40, v46
	s_cbranch_scc1 .LBB0_122
	s_lshl_b32 s4, s54, 10
	s_add_i32 s4, s69, s4
	s_and_b32 s4, s4, 0xfc0
	v_add_u32_e32 v8, s4, v4
	s_mul_i32 s4, s54, 0xf70
	s_sub_i32 s4, s72, s4
	s_lshl_b64 s[4:5], s[4:5], 1
	s_and_b32 s5, s5, 1
	s_and_b32 s4, s4, 0xffffff80
	s_lshl_b32 s4, s4, 1
	s_add_u32 s4, s70, s4
	v_add_u32_e32 v10, 12, v8
	s_addc_u32 s5, s71, s5
	v_add_u32_e32 v12, 8, v8
	v_add_u32_e32 v16, 4, v8
	v_ashrrev_i32_e32 v11, 31, v10
	s_add_u32 s4, s4, s96
	v_ashrrev_i32_e32 v13, 31, v12
	v_ashrrev_i32_e32 v17, 31, v16
	v_ashrrev_i32_e32 v9, 31, v8
	v_and_b32_e32 v19, 1, v10
	v_lshrrev_b32_e32 v10, 1, v10
	v_mov_b32_e32 v11, 0
	v_lshlrev_b64 v[10:11], 12, v[10:11]
	v_lshl_or_b32 v10, v19, 6, v10
	s_addc_u32 s5, s5, s95
	v_and_b32_e32 v19, 1, v12
	v_lshrrev_b32_e32 v12, 1, v12
	v_mov_b32_e32 v13, 0
	v_lshlrev_b64 v[12:13], 12, v[12:13]
	v_lshl_or_b32 v12, v19, 6, v12
	v_and_b32_e32 v19, 1, v16
	v_lshrrev_b32_e32 v16, 1, v16
	v_mov_b32_e32 v17, 0
	v_lshlrev_b64 v[16:17], 12, v[16:17]
	v_lshl_or_b32 v16, v19, 6, v16
	v_lshlrev_b32_e32 v1, 2, v4
	v_and_b32_e32 v19, 1, v8
	v_lshrrev_b32_e32 v4, 1, v8
	v_mov_b32_e32 v5, 0
	v_lshlrev_b64 v[4:5], 12, v[4:5]
	v_lshl_or_b32 v4, v19, 6, v4
	v_and_b32_e32 v2, 31, v6
	v_lshlrev_b32_e32 v2, 1, v2
	v_lshrrev_b32_e32 v18, 5, v6
	v_lshl_or_b32 v2, v18, 7, v2
	v_lshl_add_u64 v[10:11], s[4:5], 0, v[10:11]
	v_lshl_add_u64 v[12:13], s[4:5], 0, v[12:13]
	v_lshl_add_u64 v[16:17], s[4:5], 0, v[16:17]
	v_mad_u32_u24 v1, v6, s82, v1
	v_lshl_add_u64 v[4:5], s[4:5], 0, v[4:5]
	s_mov_b32 s6, 0
	s_waitcnt lgkmcnt(0)
	s_barrier
	s_branch .LBB0_125

; DI u16 f2bf(float a) { return (u16)(pack2(a, 0.f) & 0xffffu); }
; DI void do_transpose(const float* __restrict__ src, int K, int N, u16* __restrict__ dst, const float* __restrict__ ksc, int perm, int tile, float* tl) {
;     ...
;   __syncthreads();
; #pragma unroll 4
;   for (int i = 0; i < 16; ++i) {
;     const int nn = i * 4 + (tid >> 6), kk = tid & 63;
;     int n = n0 + nn;
;     if (n < N) {
;       if (perm) { const int h = n / 96, d = n - h * 96; n = d < 64 ? h * 64 + d : 512 + h * 32 + (d - 64); }
;       dst[(size_t)n * K + k0 + kk] = f2bf(tl[kk * 65 + nn]);
.LBB0_287:
	s_ashr_i32 s5, s4, 31
	s_lshl_b64 s[4:5], s[4:5], 2
	s_add_u32 s6, s56, s4
	s_addc_u32 s7, s57, s5
	v_and_b32_e32 v2, 31, v8
	v_lshlrev_b32_e32 v2, 1, v2
	v_lshrrev_b32_e32 v10, 5, v8
	v_lshl_or_b32 v2, v10, 7, v2
	v_lshl_add_u64 v[4:5], s[6:7], 0, v[2:3]
	v_add_u32_e32 v1, s66, v9
	s_mul_i32 s6, s48, 0x1440
	v_subrev_u32_e32 v1, s6, v1
	s_mul_i32 s6, s54, 0x3dc00
	s_mulk_i32 s48, 0x51
	v_subrev_u32_e32 v1, s6, v1
	s_sub_i32 s6, s94, s48
	s_mul_i32 s7, s54, 0xf70
	s_sub_i32 s6, s6, s7
	v_lshl_add_u32 v6, s6, 6, v9
	v_lshlrev_b32_e32 v7, 2, v9
	v_mad_u32_u24 v12, v8, s82, v7
	v_ashrrev_i32_e32 v7, 31, v6
	s_add_u32 s4, s4, s96
	v_and_b32_e32 v13, 1, v6
	v_lshrrev_b32_e32 v8, 1, v6
	v_mov_b32_e32 v9, 0
	v_lshlrev_b64 v[8:9], 12, v[8:9]
	v_lshl_or_b32 v8, v13, 6, v8
	s_addc_u32 s5, s5, s95
	v_lshl_add_u64 v[8:9], s[4:5], 0, v[8:9]
	v_lshl_add_u64 v[8:9], v[8:9], 0, v[2:3]
	v_lshl_add_u64 v[8:9], s[26:27], 0, v[8:9]
	s_mov_b32 s6, 0
	s_waitcnt lgkmcnt(0)
	s_barrier
	s_branch .LBB0_289

; DI u16 f2bf(float a) { return (u16)(pack2(a, 0.f) & 0xffffu); }
; DI void do_transpose(const float* __restrict__ src, int K, int N, u16* __restrict__ dst, const float* __restrict__ ksc, int perm, int tile, float* tl) {
;     ...
; #pragma unroll 4
;   for (int i = 0; i < 16; ++i) {
;     const int nn = i * 4 + (tid >> 6), kk = tid & 63;
;     int n = n0 + nn;
;     if (n < N) {
;       if (perm) { const int h = n / 96, d = n - h * 96; n = d < 64 ? h * 64 + d : 512 + h * 32 + (d - 64); }
;       dst[(size_t)n * K + k0 + kk] = f2bf(tl[kk * 65 + nn]);
;     }
;   }
.LBB0_291:
	s_or_b64 exec, exec, s[4:5]
	v_add3_u32 v10, v6, s6, 4
	v_cmp_gt_i32_e32 vcc, s92, v10
	s_and_saveexec_b64 s[4:5], vcc
	s_cbranch_execz .LBB0_293
	ds_read_b32 v7, v12 offset:16
	v_ashrrev_i32_e32 v11, 31, v10
	v_and_b32_e32 v13, 1, v10
	v_lshrrev_b32_e32 v10, 1, v10
	v_mov_b32_e32 v11, 0
	v_lshlrev_b64 v[10:11], 12, v[10:11]
	v_lshl_or_b32 v10, v13, 6, v10
	v_lshl_add_u64 v[10:11], v[4:5], 0, v[10:11]
	s_waitcnt lgkmcnt(0)
	v_cvt_pk_bf16_f32 v7, v7, s0
	global_store_short v[10:11], v7, off
.LBB0_293:
	s_or_b64 exec, exec, s[4:5]
	v_add_u32_e32 v10, 8, v2
	v_cmp_gt_i32_e32 vcc, s92, v10
	s_and_saveexec_b64 s[4:5], vcc
	s_cbranch_execz .LBB0_295
	ds_read_b32 v7, v12 offset:32
	v_ashrrev_i32_e32 v11, 31, v10
	v_and_b32_e32 v13, 1, v10
	v_lshrrev_b32_e32 v10, 1, v10
	v_mov_b32_e32 v11, 0
	v_lshlrev_b64 v[10:11], 12, v[10:11]
	v_lshl_or_b32 v10, v13, 6, v10
	v_lshl_add_u64 v[10:11], v[4:5], 0, v[10:11]
	s_waitcnt lgkmcnt(0)
	v_cvt_pk_bf16_f32 v7, v7, s0
	global_store_short v[10:11], v7, off
.LBB0_295:
	s_or_b64 exec, exec, s[4:5]
	v_add_u32_e32 v10, 12, v2
	v_cmp_gt_i32_e32 vcc, s92, v10
	s_and_saveexec_b64 s[4:5], vcc
	s_cbranch_execz .LBB0_288
	ds_read_b32 v2, v12 offset:48
	v_ashrrev_i32_e32 v11, 31, v10
	v_and_b32_e32 v13, 1, v10
	v_lshrrev_b32_e32 v10, 1, v10
	v_mov_b32_e32 v11, 0
	v_lshlrev_b64 v[10:11], 12, v[10:11]
	v_lshl_or_b32 v10, v13, 6, v10
	v_lshl_add_u64 v[10:11], v[4:5], 0, v[10:11]
	s_waitcnt lgkmcnt(0)
	v_cvt_pk_bf16_f32 v2, v2, s0
	global_store_short v[10:11], v2, off
	s_branch .LBB0_288

; DI bool tile_map(int it, int NTM, int NTN, int blk, int nblk, int& tm, int& tn) {
;   const int xcd = blk & 7, local = blk >> 3, LB = nblk >> 3;
;   const int R = NTM >> 3;
;   const int s = it * LB + local;
;   if (s >= R * NTN) return false;
;   const int F = R >> 3, per_full = 8 * NTN;
;   int mg, r, gm;
;   if (s < F * per_full) { mg = s / per_full; r = s - mg * per_full; gm = 8; }
;   else { mg = F; r = s - F * per_full; gm = R - F * 8; }
;   const int ng = r / (gm * 8);
;   const int r2 = r - ng * gm * 8;
;   const int mi = r2 % gm, ni = r2 / gm;
;   tm = xcd * R + mg * 8 + mi; tn = ng * 8 + ni;
;   return true;
; template <int MI, int NI>
; DI void gemm256(f32x4 (&acc)[MI][NI], const u16* __restrict__ A, int lda, const u16* __restrict__ Bt, int ldb, int K, int m0, int n0, char* smem) {
;     ...
;   const int srow = lane >> 2, scol = ((lane & 3) ^ ((lane >> 5) << 1)) * 8;
;   const u16* Ag = A + (size_t)(m0 + wave * NAW * 16 + srow) * lda + scol;
;   const u16* Bg = Bt + (size_t)(n0 + wave * NBW * 16 + srow) * ldb + scol;
;   char* la = smem + (wave * NAW) * 1024 + lane * 16;
;   char* lb = smem + ABYTES + (wave * NBW) * 1024 + lane * 16;
;     ...
;   const int nk = K >> 5;
;   G256_ISSUE(0, 0);
;   if (nk > 1) G256_ISSUE(1, 32);
.LBB0_444:
	s_lshl_b32 s12, s4, 3
	v_cvt_f32_u32_e32 v0, s12
	s_sub_i32 s11, 0, s12
	s_sub_i32 s9, s9, s10
	s_abs_i32 s10, s9
	v_rcp_iflag_f32_e32 v0, v0
	s_ashr_i32 s13, s9, 31
	s_waitcnt vmcnt(0)
	v_mov_b32_e32 v8, v163
	v_mul_f32_e32 v0, 0x4f7ffffe, v0
	v_cvt_u32_f32_e32 v0, v0
	v_lshrrev_b32_e32 v2, 4, v8
	v_and_b32_e32 v10, 0xffffffc0, v8
	v_ashrrev_i32_e32 v7, 6, v8
	v_readfirstlane_b32 s14, v0
	s_mul_i32 s11, s11, s14
	s_mul_hi_u32 s11, s14, s11
	s_add_i32 s14, s14, s11
	s_mul_hi_u32 s11, s10, s14
	s_mul_i32 s14, s11, s12
	s_sub_i32 s10, s10, s14
	s_add_i32 s15, s11, 1
	s_sub_i32 s14, s10, s12
	s_cmp_ge_u32 s10, s12
	s_cselect_b32 s11, s15, s11
	s_cselect_b32 s10, s14, s10
	s_add_i32 s14, s11, 1
	s_cmp_ge_u32 s10, s12
	s_cselect_b32 s10, s14, s11
	s_abs_i32 s14, s4
	v_cvt_f32_u32_e32 v0, s14
	s_xor_b32 s15, s10, s13
	s_sub_i32 s10, 0, s14
	s_sub_i32 s16, s15, s13
	v_rcp_iflag_f32_e32 v0, v0
	s_mul_i32 s12, s16, s12
	s_sub_i32 s9, s9, s12
	s_abs_i32 s17, s9
	v_mul_f32_e32 v0, 0x4f7ffffe, v0
	v_cvt_u32_f32_e32 v0, v0
	s_xor_b32 s12, s9, s4
	s_ashr_i32 s12, s12, 31
	v_bfe_u32 v9, v8, 2, 4
	v_readfirstlane_b32 s18, v0
	s_mul_i32 s10, s10, s18
	s_mul_hi_u32 s10, s18, s10
	s_add_i32 s18, s18, s10
	s_mul_hi_u32 s10, s17, s18
	s_mul_i32 s18, s10, s14
	s_sub_i32 s17, s17, s18
	s_add_i32 s19, s10, 1
	s_sub_i32 s18, s17, s14
	s_cmp_ge_u32 s17, s14
	s_cselect_b32 s10, s19, s10
	s_cselect_b32 s17, s18, s17
	s_add_i32 s18, s10, 1
	s_cmp_ge_u32 s17, s14
	s_cselect_b32 s10, s18, s10
	s_xor_b32 s14, s10, s12
	s_sub_i32 s17, s14, s12
	s_mul_i32 s4, s17, s4
	s_add_i32 s5, s5, s7
	s_sub_i32 s4, s9, s4
	s_add_i32 s5, s5, s4
	s_lshl_b32 s10, s5, 8
	s_lshl_b32 s4, s16, 10
	s_lshl_b32 s9, s17, 7
	v_and_b32_e32 v0, 3, v8
	s_add_i32 s9, s9, s4
	s_mov_b32 s4, s2
	v_bitop3_b32 v0, v2, v0, 2 bitop3:0x6c
	v_add_u32_e32 v2, s10, v10
	v_or_b32_e32 v2, v2, v9
	v_lshlrev_b32_e32 v11, 5, v7
	v_ashrrev_i32_e32 v3, 31, v2
	v_readlane_b32 s4, v253, 39
	v_add_u32_e32 v4, s9, v11
	v_and_b32_e32 v6, 63, v8
	v_lshlrev_b64 v[2:3], 11, v[2:3]
	v_readlane_b32 s5, v253, 40
	v_or_b32_e32 v4, v4, v9
	v_ashrrev_i32_e32 v5, 31, v4
	v_lshl_add_u64 v[2:3], s[4:5], 0, v[2:3]
	v_readlane_b32 s4, v253, 44
	v_lshlrev_b32_e32 v12, 12, v7
	v_lshlrev_b32_e32 v6, 4, v6
	v_lshlrev_b64 v[4:5], 11, v[4:5]
	v_readlane_b32 s5, v253, 45
	v_or_b32_e32 v138, v12, v6
	v_lshlrev_b32_e32 v0, 4, v0
	v_lshl_add_u64 v[4:5], s[4:5], 0, v[4:5]
	v_readfirstlane_b32 s4, v138
	v_or_b32_e32 v14, 0x400, v138
	v_lshl_add_u64 v[2:3], v[2:3], 0, v[0:1]
	v_bfe_i32 v199, v163, 2, 1
	v_and_b32_e32 v198, 0xfffff840, v199
	v_lshl_add_u64 v[2:3], v[2:3], 0, v[198:199]
	s_mov_b32 m0, s4
	v_readfirstlane_b32 s4, v14
	v_lshl_or_b32 v139, v7, 11, v6
	global_load_lds_dwordx4 v[2:3], off
	v_lshl_add_u64 v[6:7], v[2:3], 0, s[68:69]
	s_mov_b32 m0, s4
	s_mov_b64 s[4:5], 0x10000
	v_or_b32_e32 v14, 0x800, v138
	global_load_lds_dwordx4 v[6:7], off
	v_lshl_add_u64 v[6:7], v[2:3], 0, s[4:5]
	v_readfirstlane_b32 s4, v14
	s_mov_b32 m0, s4
	s_mov_b64 s[4:5], 0x18000
	v_or_b32_e32 v14, 0xc00, v138
	v_add_u32_e32 v13, 0x4000, v139
	global_load_lds_dwordx4 v[6:7], off
	v_lshl_add_u64 v[6:7], v[2:3], 0, s[4:5]
	v_readfirstlane_b32 s4, v14
	s_mov_b32 m0, s4
	v_readfirstlane_b32 s4, v13
	v_add_u32_e32 v13, 0x4400, v139
	global_load_lds_dwordx4 v[6:7], off
	v_lshl_add_u64 v[4:5], v[4:5], 0, v[0:1]
	v_bfe_i32 v199, v163, 2, 1
	v_and_b32_e32 v198, 0xfffff840, v199
	v_lshl_add_u64 v[4:5], v[4:5], 0, v[198:199]
	s_mov_b32 m0, s4
	v_readfirstlane_b32 s4, v13
	v_add_u32_e32 v13, 0x6000, v138
	global_load_lds_dwordx4 v[4:5], off
	v_lshl_add_u64 v[6:7], v[4:5], 0, s[68:69]
	s_mov_b32 m0, s4
	v_readfirstlane_b32 s4, v13
	v_add_u32_e32 v13, 0x6400, v138
	global_load_lds_dwordx4 v[6:7], off
	s_mov_b64 s[98:99], 0x80
	v_lshl_add_u64 v[6:7], v[2:3], 0, s[98:99]
	s_mov_b32 m0, s4
	v_readfirstlane_b32 s4, v13
	global_load_lds_dwordx4 v[6:7], off
	s_mov_b64 s[98:99], 0x8080
	v_lshl_add_u64 v[6:7], v[2:3], 0, s[98:99]
	s_mov_b32 m0, s4
	s_mov_b64 s[4:5], 0x10080
	v_add_u32_e32 v13, 0x6800, v138
	global_load_lds_dwordx4 v[6:7], off
	v_lshl_add_u64 v[6:7], v[2:3], 0, s[4:5]
	v_readfirstlane_b32 s4, v13
	s_mov_b32 m0, s4
	s_mov_b64 s[4:5], 0x18080
	global_load_lds_dwordx4 v[6:7], off
	v_add_u32_e32 v6, 0x6c00, v138
	v_lshl_add_u64 v[2:3], v[2:3], 0, s[4:5]
	v_readfirstlane_b32 s4, v6
	v_add_u32_e32 v6, 0xa000, v139
	s_mov_b32 m0, s4
	v_readfirstlane_b32 s4, v6
	global_load_lds_dwordx4 v[2:3], off
	s_mov_b64 s[98:99], 0x80
	v_lshl_add_u64 v[2:3], v[4:5], 0, s[98:99]
	s_mov_b32 m0, s4
	s_lshl_b32 s5, s14, 7
	global_load_lds_dwordx4 v[2:3], off
	s_mov_b64 s[98:99], 0x8080
	v_lshl_add_u64 v[2:3], v[4:5], 0, s[98:99]
	v_add_u32_e32 v4, 0xa400, v139
	s_mov_b32 s11, 0
	v_readfirstlane_b32 s4, v4
	s_mov_b32 m0, s4
	v_and_b32_e32 v4, 48, v8
	global_load_lds_dwordx4 v[2:3], off
	v_lshlrev_b32_e32 v3, 2, v8
	s_lshl_b32 s4, s15, 10
	v_lshlrev_b32_e32 v2, 6, v8
	v_bitop3_b32 v3, v3, v4, 32 bitop3:0x6c
	s_add_i32 s5, s5, s4
	v_and_or_b32 v140, v2, s59, v3
	v_and_b32_e32 v142, 0xffffe000, v2
	v_or_b32_e32 v2, s5, v9
	v_add_u32_e32 v2, v2, v11
	s_lshl_b32 s4, s12, 7
	v_subrev_u32_e32 v2, s4, v2
	s_lshl_b32 s4, s13, 10
	v_subrev_u32_e32 v2, s4, v2
	v_ashrrev_i32_e32 v3, 31, v2
	v_lshlrev_b64 v[2:3], 11, v[2:3]
	v_readlane_b32 s4, v254, 52
	v_or_b32_e32 v2, v2, v0
	v_readlane_b32 s5, v254, 53
	v_and_b32_e32 v141, 0x1000, v12
	s_nop 0
	v_lshl_add_u64 v[130:131], s[4:5], 0, v[2:3]
	v_or_b32_e32 v2, s10, v9
	v_add_u32_e32 v2, v2, v10
	v_ashrrev_i32_e32 v3, 31, v2
	v_lshlrev_b64 v[2:3], 11, v[2:3]
	v_or_b32_e32 v2, v2, v0
	v_lshl_add_u64 v[132:133], s[62:63], 0, v[2:3]
	v_mov_b32_e32 v2, 0
	s_mov_b64 s[4:5], 0
	v_mov_b32_e32 v3, v2
	v_mov_b32_e32 v4, v2
	v_mov_b32_e32 v5, v2
	v_mov_b32_e32 v6, v2
	v_mov_b32_e32 v7, v2
	v_mov_b32_e32 v8, v2
	v_mov_b32_e32 v9, v2
	v_mov_b32_e32 v10, v2
	v_mov_b32_e32 v11, v2
	v_mov_b32_e32 v12, v2
	v_mov_b32_e32 v13, v2
	v_mov_b32_e32 v14, v2
	v_mov_b32_e32 v15, v2
	v_mov_b32_e32 v16, v2
	v_mov_b32_e32 v17, v2
	v_mov_b32_e32 v18, v2
	v_mov_b32_e32 v19, v2
	v_mov_b32_e32 v20, v2
	v_mov_b32_e32 v21, v2
	v_mov_b32_e32 v22, v2
	v_mov_b32_e32 v23, v2
	v_mov_b32_e32 v24, v2
	v_mov_b32_e32 v25, v2
	s_waitcnt lgkmcnt(0)
; template <int MI, int NI>
; DI void gemm256(f32x4 (&acc)[MI][NI], const u16* __restrict__ A, int lda, const u16* __restrict__ Bt, int ldb, int K, int m0, int n0, char* smem) {
;     ...
;   const int srow = lane >> 2, scol = ((lane & 3) ^ ((lane >> 5) << 1)) * 8;
;   const u16* Ag = A + (size_t)(m0 + wave * NAW * 16 + srow) * lda + scol;
;   const u16* Bg = Bt + (size_t)(n0 + wave * NBW * 16 + srow) * ldb + scol;
;   char* la = smem + (wave * NAW) * 1024 + lane * 16;
;   char* lb = smem + ABYTES + (wave * NBW) * 1024 + lane * 16;
;     ...
;   const int nk = K >> 5;
;   G256_ISSUE(0, 0);
;   if (nk > 1) G256_ISSUE(1, 32);
;   const int foff = lr * 64 + ((lq ^ ((lr >> 3) << 1)) * 16);
;   int st = 0;
;   for (int kt = 0; kt < nk; ++kt) {
;     if (kt + 1 < nk) asm volatile("s_waitcnt vmcnt(%0) lgkmcnt(0)" :: "n"(LPS) : "memory");
;     else asm volatile("s_waitcnt vmcnt(0) lgkmcnt(0)" ::: "memory");
;     __builtin_amdgcn_s_barrier();
;     __builtin_amdgcn_s_setprio(1);
;     const char* sb = smem + st * STAGE + foff;
;     bf16x8 af[MI], bfr[NI];
; #pragma unroll
;     for (int mi = 0; mi < MI; ++mi) af[mi] = *(const bf16x8*)(sb + (wr * MI + mi) * 1024);
; #pragma unroll
;     for (int ni = 0; ni < NI; ++ni) bfr[ni] = *(const bf16x8*)(sb + ABYTES + (wc * NI + ni) * 1024);
;     __builtin_amdgcn_sched_barrier(0x0);
;     if (kt + 2 < nk) { const int s2 = st >= 1 ? st - 1 : 2; G256_ISSUE(s2, (kt + 2) * 32); }
;     __builtin_amdgcn_s_setprio(0);
; #pragma unroll
;     for (int mi = 0; mi < MI; ++mi)
; #pragma unroll
;       for (int ni = 0; ni < NI; ++ni)
;         acc[mi][ni] = __builtin_amdgcn_mfma_f32_16x16x32_bf16(bfr[ni], af[mi], acc[mi][ni], 0, 0, 0);
;     st = st == 2 ? 0 : st + 1;
;   }
	v_mov_b32_e32 v26, v2
	v_mov_b32_e32 v27, v2
	v_mov_b32_e32 v28, v2
	v_mov_b32_e32 v29, v2
	v_mov_b32_e32 v30, v2
	v_mov_b32_e32 v31, v2
	v_mov_b32_e32 v32, v2
	v_mov_b32_e32 v33, v2
	v_mov_b32_e32 v34, v2
	v_mov_b32_e32 v35, v2
	v_mov_b32_e32 v36, v2
	v_mov_b32_e32 v37, v2
	v_mov_b32_e32 v38, v2
	v_mov_b32_e32 v39, v2
	v_mov_b32_e32 v40, v2
	v_mov_b32_e32 v41, v2
	v_mov_b32_e32 v42, v2
	v_mov_b32_e32 v43, v2
	v_mov_b32_e32 v44, v2
	v_mov_b32_e32 v45, v2
	v_mov_b32_e32 v46, v2
	v_mov_b32_e32 v47, v2
	v_mov_b32_e32 v48, v2
	v_mov_b32_e32 v49, v2
	v_mov_b32_e32 v50, v2
	v_mov_b32_e32 v51, v2
	v_mov_b32_e32 v52, v2
	v_mov_b32_e32 v53, v2
	v_mov_b32_e32 v54, v2
	v_mov_b32_e32 v55, v2
	v_mov_b32_e32 v56, v2
	v_mov_b32_e32 v57, v2
	v_mov_b32_e32 v58, v2
	v_mov_b32_e32 v59, v2
	v_mov_b32_e32 v60, v2
	v_mov_b32_e32 v61, v2
	v_mov_b32_e32 v62, v2
	v_mov_b32_e32 v63, v2
	v_mov_b32_e32 v64, v2
	v_mov_b32_e32 v65, v2
	v_mov_b32_e32 v66, v2
	v_mov_b32_e32 v67, v2
	v_mov_b32_e32 v68, v2
	v_mov_b32_e32 v69, v2
	v_mov_b32_e32 v70, v2
	v_mov_b32_e32 v71, v2
	v_mov_b32_e32 v72, v2
	v_mov_b32_e32 v73, v2
	v_mov_b32_e32 v74, v2
	v_mov_b32_e32 v75, v2
	v_mov_b32_e32 v76, v2
	v_mov_b32_e32 v77, v2
	v_mov_b32_e32 v78, v2
	v_mov_b32_e32 v79, v2
	v_mov_b32_e32 v80, v2
	v_mov_b32_e32 v81, v2
	v_mov_b32_e32 v82, v2
	v_mov_b32_e32 v83, v2
	v_mov_b32_e32 v84, v2
	v_mov_b32_e32 v85, v2
	v_mov_b32_e32 v86, v2
	v_mov_b32_e32 v87, v2
	v_mov_b32_e32 v88, v2
	v_mov_b32_e32 v89, v2
	v_mov_b32_e32 v90, v2
	v_mov_b32_e32 v91, v2
	v_mov_b32_e32 v92, v2
	v_mov_b32_e32 v93, v2
	v_mov_b32_e32 v94, v2
	v_mov_b32_e32 v95, v2
	v_mov_b32_e32 v96, v2
	v_mov_b32_e32 v97, v2
	v_mov_b32_e32 v98, v2
	v_mov_b32_e32 v99, v2
	v_mov_b32_e32 v100, v2
	v_mov_b32_e32 v101, v2
	v_mov_b32_e32 v102, v2
	v_mov_b32_e32 v103, v2
	v_mov_b32_e32 v104, v2
	v_mov_b32_e32 v105, v2
	v_mov_b32_e32 v106, v2
	v_mov_b32_e32 v107, v2
	v_mov_b32_e32 v108, v2
	v_mov_b32_e32 v109, v2
	v_mov_b32_e32 v110, v2
	v_mov_b32_e32 v111, v2
	v_mov_b32_e32 v112, v2
	v_mov_b32_e32 v113, v2
	v_mov_b32_e32 v114, v2
	v_mov_b32_e32 v115, v2
	v_mov_b32_e32 v116, v2
	v_mov_b32_e32 v117, v2
	v_mov_b32_e32 v118, v2
	v_mov_b32_e32 v119, v2
	v_mov_b32_e32 v120, v2
	v_mov_b32_e32 v121, v2
	v_mov_b32_e32 v122, v2
	v_mov_b32_e32 v123, v2
	v_mov_b32_e32 v124, v2
	v_mov_b32_e32 v125, v2
	v_mov_b32_e32 v126, v2
	v_mov_b32_e32 v127, v2
	v_mov_b32_e32 v128, v2
	v_mov_b32_e32 v129, v2
	s_mov_b64 s[12:13], 0x16281100
	v_lshl_add_u64 v[198:199], v[132:133], 0, s[12:13]
	s_mov_b64 s[12:13], 0x16289100
	v_lshl_add_u64 v[200:201], v[132:133], 0, s[12:13]
	s_mov_b64 s[12:13], 0x16291100
	v_lshl_add_u64 v[202:203], v[132:133], 0, s[12:13]
	s_mov_b64 s[12:13], 0x16299100
	v_lshl_add_u64 v[204:205], v[132:133], 0, s[12:13]
	s_mov_b64 s[12:13], 0x1861100
	v_lshl_add_u64 v[206:207], v[130:131], 0, s[12:13]
	s_mov_b64 s[12:13], 0x1869100
	v_lshl_add_u64 v[208:209], v[130:131], 0, s[12:13]
	v_bfe_i32 v197, v163, 2, 1
	v_and_b32_e32 v196, 0xfffff840, v197
	v_lshl_add_u64 v[198:199], v[198:199], 0, v[196:197]
	v_lshl_add_u64 v[200:201], v[200:201], 0, v[196:197]
	v_lshl_add_u64 v[202:203], v[202:203], 0, v[196:197]
	v_lshl_add_u64 v[204:205], v[204:205], 0, v[196:197]
	v_and_b32_e32 v196, 0xfffff840, v197
	v_lshl_add_u64 v[206:207], v[206:207], 0, v[196:197]
	v_lshl_add_u64 v[208:209], v[208:209], 0, v[196:197]
	s_mov_b64 s[98:99], 0x80
	v_add_u32_e32 v143, v140, v142
	v_add_u32_e32 v0, v140, v141
	v_readfirstlane_b32 s14, v138
	v_readfirstlane_b32 s4, v139
	s_mov_b32 s11, 0
	s_movk_i32 s5, 29
	s_add_i32 s4, s4, 0x4000
	s_waitcnt vmcnt(6) lgkmcnt(0)
	s_barrier
	ds_read_b128 v[144:147], v143
	ds_read_b128 v[148:151], v143 offset:1024
	ds_read_b128 v[152:155], v143 offset:2048
	ds_read_b128 v[156:159], v143 offset:3072
	ds_read_b128 v[180:183], v0 offset:16384
	ds_read_b128 v[184:187], v0 offset:17408
	ds_read_b128 v[188:191], v0 offset:18432
	ds_read_b128 v[192:195], v0 offset:19456
.Lpipe_mlp1:
	v_add_u32_e32 v160, s11, v143
	ds_read_b128 v[164:167], v160 offset:4096
	ds_read_b128 v[168:171], v160 offset:5120
	ds_read_b128 v[172:175], v160 offset:6144
	ds_read_b128 v[176:179], v160 offset:7168
	s_add_i32 s12, s11, 0xffffa000
	s_cmp_eq_u32 s11, 0
	s_cselect_b32 s12, 0xc000, s12
	s_add_i32 s13, s12, s14
	s_add_i32 s12, s12, s4
	s_mov_b32 m0, s13
	s_waitcnt lgkmcnt(7)
	v_mfma_f32_16x16x32_bf16 v[126:129], v[180:183], v[144:147], v[126:129]
	global_load_lds_dwordx4 v[198:199], off
	v_mfma_f32_16x16x32_bf16 v[110:113], v[180:183], v[148:151], v[110:113]
	v_lshl_add_u64 v[198:199], v[198:199], 0, s[98:99]
	s_add_i32 m0, s13, 0x400
	v_mfma_f32_16x16x32_bf16 v[94:97], v[180:183], v[152:155], v[94:97]
	global_load_lds_dwordx4 v[200:201], off
	v_mfma_f32_16x16x32_bf16 v[78:81], v[180:183], v[156:159], v[78:81]
	v_lshl_add_u64 v[200:201], v[200:201], 0, s[98:99]
	s_add_i32 m0, s13, 0x800
	s_waitcnt lgkmcnt(6)
	v_mfma_f32_16x16x32_bf16 v[122:125], v[184:187], v[144:147], v[122:125]
	global_load_lds_dwordx4 v[202:203], off
	v_mfma_f32_16x16x32_bf16 v[106:109], v[184:187], v[148:151], v[106:109]
	v_lshl_add_u64 v[202:203], v[202:203], 0, s[98:99]
	s_add_i32 m0, s13, 0xc00
	v_mfma_f32_16x16x32_bf16 v[90:93], v[184:187], v[152:155], v[90:93]
	global_load_lds_dwordx4 v[204:205], off
	v_mfma_f32_16x16x32_bf16 v[74:77], v[184:187], v[156:159], v[74:77]
	v_lshl_add_u64 v[204:205], v[204:205], 0, s[98:99]
	s_mov_b32 m0, s12
	s_waitcnt lgkmcnt(5)
	v_mfma_f32_16x16x32_bf16 v[118:121], v[188:191], v[144:147], v[118:121]
	global_load_lds_dwordx4 v[206:207], off
	v_mfma_f32_16x16x32_bf16 v[102:105], v[188:191], v[148:151], v[102:105]
	v_lshl_add_u64 v[206:207], v[206:207], 0, s[98:99]
	s_add_i32 m0, s12, 0x400
	v_mfma_f32_16x16x32_bf16 v[86:89], v[188:191], v[152:155], v[86:89]
	global_load_lds_dwordx4 v[208:209], off
	v_mfma_f32_16x16x32_bf16 v[70:73], v[188:191], v[156:159], v[70:73]
	v_lshl_add_u64 v[208:209], v[208:209], 0, s[98:99]
	s_waitcnt lgkmcnt(4)
	v_mfma_f32_16x16x32_bf16 v[114:117], v[192:195], v[144:147], v[114:117]
	v_mfma_f32_16x16x32_bf16 v[98:101], v[192:195], v[148:151], v[98:101]
	v_mfma_f32_16x16x32_bf16 v[82:85], v[192:195], v[152:155], v[82:85]
	v_mfma_f32_16x16x32_bf16 v[66:69], v[192:195], v[156:159], v[66:69]
	s_waitcnt vmcnt(6) lgkmcnt(0)
	s_barrier
; template <int MI, int NI>
; DI void gemm256(f32x4 (&acc)[MI][NI], const u16* __restrict__ A, int lda, const u16* __restrict__ Bt, int ldb, int K, int m0, int n0, char* smem) {
;     ...
;   for (int kt = 0; kt < nk; ++kt) {
;     if (kt + 1 < nk) asm volatile("s_waitcnt vmcnt(%0) lgkmcnt(0)" :: "n"(LPS) : "memory");
;     else asm volatile("s_waitcnt vmcnt(0) lgkmcnt(0)" ::: "memory");
;     __builtin_amdgcn_s_barrier();
;     __builtin_amdgcn_s_setprio(1);
;     const char* sb = smem + st * STAGE + foff;
;     bf16x8 af[MI], bfr[NI];
; #pragma unroll
;     for (int mi = 0; mi < MI; ++mi) af[mi] = *(const bf16x8*)(sb + (wr * MI + mi) * 1024);
; #pragma unroll
;     for (int ni = 0; ni < NI; ++ni) bfr[ni] = *(const bf16x8*)(sb + ABYTES + (wc * NI + ni) * 1024);
;     __builtin_amdgcn_sched_barrier(0x0);
;     if (kt + 2 < nk) { const int s2 = st >= 1 ? st - 1 : 2; G256_ISSUE(s2, (kt + 2) * 32); }
;     __builtin_amdgcn_s_setprio(0);
; #pragma unroll
;     for (int mi = 0; mi < MI; ++mi)
; #pragma unroll
;       for (int ni = 0; ni < NI; ++ni)
;         acc[mi][ni] = __builtin_amdgcn_mfma_f32_16x16x32_bf16(bfr[ni], af[mi], acc[mi][ni], 0, 0, 0);
;     st = st == 2 ? 0 : st + 1;
;   }
	s_add_i32 s13, s11, 0x6000
	s_cmp_eq_u32 s11, 0xc000
	s_cselect_b32 s11, 0, s13
	v_add_u32_e32 v196, s11, v143
	v_add_u32_e32 v197, s11, v0
	v_mfma_f32_16x16x32_bf16 v[62:65], v[180:183], v[164:167], v[62:65]
	ds_read_b128 v[144:147], v196
	v_mfma_f32_16x16x32_bf16 v[46:49], v[180:183], v[168:171], v[46:49]
	ds_read_b128 v[148:151], v196 offset:1024
	v_mfma_f32_16x16x32_bf16 v[30:33], v[180:183], v[172:175], v[30:33]
	ds_read_b128 v[152:155], v196 offset:2048
	v_mfma_f32_16x16x32_bf16 v[14:17], v[180:183], v[176:179], v[14:17]
	ds_read_b128 v[156:159], v196 offset:3072
	ds_read_b128 v[180:183], v197 offset:16384
	v_mfma_f32_16x16x32_bf16 v[58:61], v[184:187], v[164:167], v[58:61]
	v_mfma_f32_16x16x32_bf16 v[42:45], v[184:187], v[168:171], v[42:45]
	v_mfma_f32_16x16x32_bf16 v[26:29], v[184:187], v[172:175], v[26:29]
	v_mfma_f32_16x16x32_bf16 v[10:13], v[184:187], v[176:179], v[10:13]
	ds_read_b128 v[184:187], v197 offset:17408
	v_mfma_f32_16x16x32_bf16 v[54:57], v[188:191], v[164:167], v[54:57]
	v_mfma_f32_16x16x32_bf16 v[38:41], v[188:191], v[168:171], v[38:41]
	v_mfma_f32_16x16x32_bf16 v[22:25], v[188:191], v[172:175], v[22:25]
	v_mfma_f32_16x16x32_bf16 v[6:9], v[188:191], v[176:179], v[6:9]
	ds_read_b128 v[188:191], v197 offset:18432
	v_mfma_f32_16x16x32_bf16 v[50:53], v[192:195], v[164:167], v[50:53]
	v_mfma_f32_16x16x32_bf16 v[34:37], v[192:195], v[168:171], v[34:37]
	v_mfma_f32_16x16x32_bf16 v[18:21], v[192:195], v[172:175], v[18:21]
	v_mfma_f32_16x16x32_bf16 v[2:5], v[192:195], v[176:179], v[2:5]
	ds_read_b128 v[192:195], v197 offset:19456
	s_sub_i32 s5, s5, 1
	s_cmp_lg_u32 s5, 0
	s_cbranch_scc1 .Lpipe_mlp1
	v_add_u32_e32 v160, s11, v143
	ds_read_b128 v[164:167], v160 offset:4096
	ds_read_b128 v[168:171], v160 offset:5120
	ds_read_b128 v[172:175], v160 offset:6144
	ds_read_b128 v[176:179], v160 offset:7168
	s_add_i32 s12, s11, 0xffffa000
	s_cmp_eq_u32 s11, 0
	s_cselect_b32 s12, 0xc000, s12
	s_add_i32 s13, s12, s14
	s_add_i32 s12, s12, s4
	s_mov_b32 m0, s13
	s_waitcnt lgkmcnt(7)
	v_mfma_f32_16x16x32_bf16 v[126:129], v[180:183], v[144:147], v[126:129]
	global_load_lds_dwordx4 v[198:199], off
	v_mfma_f32_16x16x32_bf16 v[110:113], v[180:183], v[148:151], v[110:113]
	v_lshl_add_u64 v[198:199], v[198:199], 0, s[98:99]
	s_add_i32 m0, s13, 0x400
	v_mfma_f32_16x16x32_bf16 v[94:97], v[180:183], v[152:155], v[94:97]
	global_load_lds_dwordx4 v[200:201], off
	v_mfma_f32_16x16x32_bf16 v[78:81], v[180:183], v[156:159], v[78:81]
	v_lshl_add_u64 v[200:201], v[200:201], 0, s[98:99]
	s_add_i32 m0, s13, 0x800
	s_waitcnt lgkmcnt(6)
	v_mfma_f32_16x16x32_bf16 v[122:125], v[184:187], v[144:147], v[122:125]
	global_load_lds_dwordx4 v[202:203], off
	v_mfma_f32_16x16x32_bf16 v[106:109], v[184:187], v[148:151], v[106:109]
	v_lshl_add_u64 v[202:203], v[202:203], 0, s[98:99]
	s_add_i32 m0, s13, 0xc00
	v_mfma_f32_16x16x32_bf16 v[90:93], v[184:187], v[152:155], v[90:93]
	global_load_lds_dwordx4 v[204:205], off
	v_mfma_f32_16x16x32_bf16 v[74:77], v[184:187], v[156:159], v[74:77]
	v_lshl_add_u64 v[204:205], v[204:205], 0, s[98:99]
	s_mov_b32 m0, s12
	s_waitcnt lgkmcnt(5)
	v_mfma_f32_16x16x32_bf16 v[118:121], v[188:191], v[144:147], v[118:121]
	global_load_lds_dwordx4 v[206:207], off
	v_mfma_f32_16x16x32_bf16 v[102:105], v[188:191], v[148:151], v[102:105]
	v_lshl_add_u64 v[206:207], v[206:207], 0, s[98:99]
	s_add_i32 m0, s12, 0x400
	v_mfma_f32_16x16x32_bf16 v[86:89], v[188:191], v[152:155], v[86:89]
	global_load_lds_dwordx4 v[208:209], off
	v_mfma_f32_16x16x32_bf16 v[70:73], v[188:191], v[156:159], v[70:73]
	v_lshl_add_u64 v[208:209], v[208:209], 0, s[98:99]
	s_waitcnt lgkmcnt(4)
	v_mfma_f32_16x16x32_bf16 v[114:117], v[192:195], v[144:147], v[114:117]
	v_mfma_f32_16x16x32_bf16 v[98:101], v[192:195], v[148:151], v[98:101]
	v_mfma_f32_16x16x32_bf16 v[82:85], v[192:195], v[152:155], v[82:85]
	v_mfma_f32_16x16x32_bf16 v[66:69], v[192:195], v[156:159], v[66:69]
	s_waitcnt lgkmcnt(0)
	v_mfma_f32_16x16x32_bf16 v[62:65], v[180:183], v[164:167], v[62:65]
	v_mfma_f32_16x16x32_bf16 v[46:49], v[180:183], v[168:171], v[46:49]
	v_mfma_f32_16x16x32_bf16 v[30:33], v[180:183], v[172:175], v[30:33]
	v_mfma_f32_16x16x32_bf16 v[14:17], v[180:183], v[176:179], v[14:17]
	v_mfma_f32_16x16x32_bf16 v[58:61], v[184:187], v[164:167], v[58:61]
	v_mfma_f32_16x16x32_bf16 v[42:45], v[184:187], v[168:171], v[42:45]
	v_mfma_f32_16x16x32_bf16 v[26:29], v[184:187], v[172:175], v[26:29]
	v_mfma_f32_16x16x32_bf16 v[10:13], v[184:187], v[176:179], v[10:13]
	v_mfma_f32_16x16x32_bf16 v[54:57], v[188:191], v[164:167], v[54:57]
	v_mfma_f32_16x16x32_bf16 v[38:41], v[188:191], v[168:171], v[38:41]
	v_mfma_f32_16x16x32_bf16 v[22:25], v[188:191], v[172:175], v[22:25]
	v_mfma_f32_16x16x32_bf16 v[6:9], v[188:191], v[176:179], v[6:9]
	v_mfma_f32_16x16x32_bf16 v[50:53], v[192:195], v[164:167], v[50:53]
	v_mfma_f32_16x16x32_bf16 v[34:37], v[192:195], v[168:171], v[34:37]
	v_mfma_f32_16x16x32_bf16 v[18:21], v[192:195], v[172:175], v[18:21]
	v_mfma_f32_16x16x32_bf16 v[2:5], v[192:195], v[176:179], v[2:5]
	s_waitcnt vmcnt(6) lgkmcnt(0)
	s_barrier
	s_setprio 1
	v_add_u32_e32 v0, v140, v142
	s_waitcnt vmcnt(0)
	ds_read_b128 v[130:133], v0
	ds_read_b128 v[142:145], v0 offset:1024
	ds_read_b128 v[146:149], v0 offset:2048
	ds_read_b128 v[150:153], v0 offset:3072
	ds_read_b128 v[154:157], v0 offset:4096
	ds_read_b128 v[158:161], v0 offset:5120
	ds_read_b128 v[164:167], v0 offset:6144
	ds_read_b128 v[168:171], v0 offset:7168
	v_add_u32_e32 v212, v140, v141
	ds_read_b128 v[138:141], v212 offset:16384
	ds_read_b128 v[172:175], v212 offset:17408
	ds_read_b128 v[176:179], v212 offset:18432
	ds_read_b128 v[180:183], v212 offset:19456
	s_setprio 0
	s_waitcnt vmcnt(0) lgkmcnt(0)
	s_waitcnt lgkmcnt(3)
	v_mfma_f32_16x16x32_bf16 v[126:129], v[138:141], v[130:133], v[126:129]
	s_barrier
; DI unsigned pack2(float a, float b) { float2_t v = {a, b}; bf16x2_t r = __builtin_convertvector(v, bf16x2_t); return __builtin_bit_cast(unsigned, r); }
; template <int MI, int NI>
; DI void gemm256(f32x4 (&acc)[MI][NI], const u16* __restrict__ A, int lda, const u16* __restrict__ Bt, int ldb, int K, int m0, int n0, char* smem) {
;     ...
; #pragma unroll
;     for (int mi = 0; mi < MI; ++mi)
; #pragma unroll
;       for (int ni = 0; ni < NI; ++ni)
;         acc[mi][ni] = __builtin_amdgcn_mfma_f32_16x16x32_bf16(bfr[ni], af[mi], acc[mi][ni], 0, 0, 0);
;     st = st == 2 ? 0 : st + 1;
;   }
; DI void phase_mlp1(const Params& p, int l, int Mout, char* smem) {
;     ...
;     for (int mi = 0; mi < 8; mi += 2) {
;       const int m = m0 + wr * 128 + (mi + (lq & 1)) * 16 + lr;
; #pragma unroll
;       for (int ni = 0; ni < 4; ++ni) {
;         const int n = n0 + wc * 64 + ni * 16 + (lq >> 1) * 8;
;         float va[4], vb[4];
; #pragma unroll
;         for (int j = 0; j < 4; ++j) { const float a = fmaxf(acc[mi][ni][j], 0.f); va[j] = a * a; const float b = fmaxf(acc[mi + 1][ni][j], 0.f); vb[j] = b * b; }
;         *(uint4*)(U + (size_t)m * DFF + n) = widen16(make_uint2(pack2(va[0], va[1]), pack2(va[2], va[3])), make_uint2(pack2(vb[0], vb[1]), pack2(vb[2], vb[3])));
;       }
;       __builtin_amdgcn_sched_barrier(0);
;     }
	s_waitcnt lgkmcnt(2)
	v_mfma_f32_16x16x32_bf16 v[122:125], v[172:175], v[130:133], v[122:125]
	s_waitcnt lgkmcnt(1)
	v_mfma_f32_16x16x32_bf16 v[184:187], v[176:179], v[130:133], v[118:121]
	s_waitcnt lgkmcnt(0)
	v_mfma_f32_16x16x32_bf16 v[114:117], v[180:183], v[130:133], v[114:117]
	v_mfma_f32_16x16x32_bf16 v[130:133], v[138:141], v[142:145], v[110:113]
	v_mfma_f32_16x16x32_bf16 v[106:109], v[172:175], v[142:145], v[106:109]
	v_mfma_f32_16x16x32_bf16 v[188:191], v[176:179], v[142:145], v[102:105]
	v_mfma_f32_16x16x32_bf16 v[98:101], v[180:183], v[142:145], v[98:101]
	v_mfma_f32_16x16x32_bf16 v[94:97], v[138:141], v[146:149], v[94:97]
	v_mfma_f32_16x16x32_bf16 v[90:93], v[172:175], v[146:149], v[90:93]
	v_mfma_f32_16x16x32_bf16 v[142:145], v[176:179], v[146:149], v[86:89]
	v_mfma_f32_16x16x32_bf16 v[82:85], v[180:183], v[146:149], v[82:85]
	v_mfma_f32_16x16x32_bf16 v[146:149], v[138:141], v[150:153], v[78:81]
	v_mfma_f32_16x16x32_bf16 v[74:77], v[172:175], v[150:153], v[74:77]
	v_mfma_f32_16x16x32_bf16 v[192:195], v[176:179], v[150:153], v[70:73]
	v_mfma_f32_16x16x32_bf16 v[66:69], v[180:183], v[150:153], v[66:69]
	v_mfma_f32_16x16x32_bf16 v[62:65], v[138:141], v[154:157], v[62:65]
	v_mfma_f32_16x16x32_bf16 v[58:61], v[172:175], v[154:157], v[58:61]
	v_mfma_f32_16x16x32_bf16 v[150:153], v[176:179], v[154:157], v[54:57]
	v_mfma_f32_16x16x32_bf16 v[50:53], v[180:183], v[154:157], v[50:53]
	v_mfma_f32_16x16x32_bf16 v[154:157], v[138:141], v[158:161], v[46:49]
	v_mfma_f32_16x16x32_bf16 v[42:45], v[172:175], v[158:161], v[42:45]
	v_mfma_f32_16x16x32_bf16 v[196:199], v[176:179], v[158:161], v[38:41]
	v_mfma_f32_16x16x32_bf16 v[34:37], v[180:183], v[158:161], v[34:37]
	v_mfma_f32_16x16x32_bf16 v[30:33], v[138:141], v[164:167], v[30:33]
	v_mfma_f32_16x16x32_bf16 v[26:29], v[172:175], v[164:167], v[26:29]
	v_mfma_f32_16x16x32_bf16 v[158:161], v[176:179], v[164:167], v[22:25]
	v_mfma_f32_16x16x32_bf16 v[18:21], v[180:183], v[164:167], v[18:21]
	v_mfma_f32_16x16x32_bf16 v[138:141], v[138:141], v[168:171], v[14:17]
	v_mfma_f32_16x16x32_bf16 v[10:13], v[172:175], v[168:171], v[10:13]
	v_mfma_f32_16x16x32_bf16 v[164:167], v[176:179], v[168:171], v[6:9]
	v_mfma_f32_16x16x32_bf16 v[2:5], v[180:183], v[168:171], v[2:5]
	s_setprio 1
	s_nop 0
	ds_read_b128 v[6:9], v0 offset:24576
	ds_read_b128 v[14:17], v0 offset:25600
	ds_read_b128 v[22:25], v0 offset:26624
	ds_read_b128 v[38:41], v0 offset:27648
	ds_read_b128 v[168:171], v0 offset:28672
	ds_read_b128 v[172:175], v0 offset:29696
	ds_read_b128 v[176:179], v0 offset:30720
	ds_read_b128 v[180:183], v0 offset:31744
	ds_read_b128 v[200:203], v212 offset:40960
	ds_read_b128 v[204:207], v212 offset:41984
	ds_read_b128 v[208:211], v212 offset:43008
	ds_read_b128 v[212:215], v212 offset:44032
	s_setprio 0
	s_waitcnt lgkmcnt(3)
	v_mfma_f32_16x16x32_bf16 v[216:219], v[200:203], v[6:9], v[126:129]
	v_mov_b32_e32 v0, v136
	s_waitcnt lgkmcnt(0)
	s_barrier
	s_waitcnt lgkmcnt(2)
	v_mfma_f32_16x16x32_bf16 v[118:121], v[204:207], v[6:9], v[122:125]
	v_mov_b32_e32 v126, v137
	v_mov_b32_e32 v127, v134
	v_lshlrev_b32_e32 v129, 2, v126
	v_lshlrev_b32_e32 v126, 4, v126
	v_mfma_f32_16x16x32_bf16 v[122:125], v[200:203], v[14:17], v[130:133]
	v_mov_b32_e32 v128, v135
	v_lshlrev_b32_e32 v127, 7, v127
	v_add_u32_e32 v0, s10, v0
	v_and_b32_e32 v126, 16, v126
	v_add3_u32 v126, v0, v127, v126
	v_lshlrev_b32_e32 v128, 6, v128
	v_and_b32_e32 v129, -8, v129
	v_ashrrev_i32_e32 v127, 31, v126
	v_add3_u32 v132, v129, s9, v128
	v_and_b32_e32 v220, 1, v126
	v_lshrrev_b32_e32 v128, 1, v126
	v_mov_b32_e32 v129, 0
	v_lshlrev_b64 v[128:129], 14, v[128:129]
	v_lshl_or_b32 v128, v220, 6, v128
	v_max_f32_e32 v0, v216, v216
	v_mfma_f32_16x16x32_bf16 v[94:97], v[200:203], v[22:25], v[94:97]
	v_ashrrev_i32_e32 v133, 31, v132
	v_mfma_f32_16x16x32_bf16 v[86:89], v[204:207], v[22:25], v[90:93]
	s_waitcnt lgkmcnt(1)
	v_mfma_f32_16x16x32_bf16 v[78:81], v[208:211], v[22:25], v[142:145]
	s_waitcnt lgkmcnt(0)
	v_mfma_f32_16x16x32_bf16 v[70:73], v[212:215], v[22:25], v[82:85]
	v_mfma_f32_16x16x32_bf16 v[22:25], v[204:207], v[176:179], v[26:29]
	v_mfma_f32_16x16x32_bf16 v[26:29], v[200:203], v[180:183], v[138:141]
	s_nop 2
	v_lshl_add_u64 v[138:139], s[60:61], 0, v[128:129]
	v_max_f32_e32 v128, 0, v0
	v_max_f32_e32 v0, v122, v122
	v_max_f32_e32 v122, 0, v0
	v_max_f32_e32 v0, v217, v217
	v_max_f32_e32 v129, 0, v0
	v_max_f32_e32 v0, v123, v123
	v_max_f32_e32 v123, 0, v0
	v_max_f32_e32 v0, v218, v218
	v_mfma_f32_16x16x32_bf16 v[102:105], v[212:215], v[6:9], v[114:117]
	v_max_f32_e32 v130, 0, v0
	v_max_f32_e32 v0, v124, v124
	v_max_f32_e32 v124, 0, v0
	v_mfma_f32_16x16x32_bf16 v[114:117], v[204:207], v[14:17], v[106:109]
	v_max_f32_e32 v0, v219, v219
	v_max_f32_e32 v131, 0, v0
	v_max_f32_e32 v0, v125, v125
	v_max_f32_e32 v125, 0, v0
	v_max_f32_e32 v0, v118, v118
	v_max_f32_e32 v118, 0, v0
	s_nop 1
	v_max_f32_e32 v0, v114, v114
	v_pk_mul_f32 v[128:129], v[128:129], v[128:129]
	v_pk_mul_f32 v[122:123], v[122:123], v[122:123]
	v_pk_mul_f32 v[130:131], v[130:131], v[130:131]
	v_pk_mul_f32 v[124:125], v[124:125], v[124:125]
	v_max_f32_e32 v114, 0, v0
	v_max_f32_e32 v0, v119, v119
	v_cvt_pk_bf16_f32 v128, v128, v129
	v_cvt_pk_bf16_f32 v129, v130, v131
	v_cvt_pk_bf16_f32 v130, v122, v123
	v_cvt_pk_bf16_f32 v131, v124, v125
	v_and_b32_e32 v220, 31, v132
	v_lshrrev_b32_e32 v122, 5, v132
	v_lshlrev_b32_e32 v122, 7, v122
	v_lshl_or_b32 v122, v220, 1, v122
	v_mov_b32_e32 v123, 0
	v_max_f32_e32 v119, 0, v0
	v_max_f32_e32 v0, v115, v115
	v_mfma_f32_16x16x32_bf16 v[110:113], v[208:211], v[6:9], v[184:187]
	v_permlane16_swap_b32_e32 v128, v130
	v_permlane16_swap_b32_e32 v129, v131
; DI unsigned pack2(float a, float b) { float2_t v = {a, b}; bf16x2_t r = __builtin_convertvector(v, bf16x2_t); return __builtin_bit_cast(unsigned, r); }
; DI void phase_mlp1(const Params& p, int l, int Mout, char* smem) {
;     ...
;     for (int mi = 0; mi < 8; mi += 2) {
;       const int m = m0 + wr * 128 + (mi + (lq & 1)) * 16 + lr;
; #pragma unroll
;       for (int ni = 0; ni < 4; ++ni) {
;         const int n = n0 + wc * 64 + ni * 16 + (lq >> 1) * 8;
;         float va[4], vb[4];
; #pragma unroll
;         for (int j = 0; j < 4; ++j) { const float a = fmaxf(acc[mi][ni][j], 0.f); va[j] = a * a; const float b = fmaxf(acc[mi + 1][ni][j], 0.f); vb[j] = b * b; }
;         *(uint4*)(U + (size_t)m * DFF + n) = widen16(make_uint2(pack2(va[0], va[1]), pack2(va[2], va[3])), make_uint2(pack2(vb[0], vb[1]), pack2(vb[2], vb[3])));
;       }
;       __builtin_amdgcn_sched_barrier(0);
;     }
	v_lshl_add_u64 v[124:125], v[138:139], 0, v[122:123]
	v_max_f32_e32 v115, 0, v0
	v_max_f32_e32 v0, v120, v120
	v_mfma_f32_16x16x32_bf16 v[106:109], v[208:211], v[14:17], v[188:191]
	flat_store_dwordx4 v[124:125], v[128:131]
	v_pk_mul_f32 v[118:119], v[118:119], v[118:119]
	s_nop 0
	v_pk_mul_f32 v[128:129], v[114:115], v[114:115]
	v_max_f32_e32 v114, 0, v0
	v_max_f32_e32 v0, v116, v116
	v_max_f32_e32 v116, 0, v0
	v_max_f32_e32 v0, v121, v121
	v_max_f32_e32 v115, 0, v0
	v_max_f32_e32 v0, v117, v117
	v_max_f32_e32 v117, 0, v0
	v_max_f32_e32 v0, v110, v110
	v_max_f32_e32 v110, 0, v0
	v_max_f32_e32 v0, v106, v106
	v_pk_mul_f32 v[120:121], v[114:115], v[114:115]
	v_pk_mul_f32 v[130:131], v[116:117], v[116:117]
	v_max_f32_e32 v106, 0, v0
	v_max_f32_e32 v0, v111, v111
	v_cvt_pk_bf16_f32 v114, v118, v119
	v_cvt_pk_bf16_f32 v115, v120, v121
	v_cvt_pk_bf16_f32 v116, v128, v129
	v_cvt_pk_bf16_f32 v117, v130, v131
	v_max_f32_e32 v111, 0, v0
	v_max_f32_e32 v0, v107, v107
	v_permlane16_swap_b32_e32 v114, v116
	v_permlane16_swap_b32_e32 v115, v117
	v_max_f32_e32 v107, 0, v0
	v_max_f32_e32 v0, v112, v112
	v_mfma_f32_16x16x32_bf16 v[98:101], v[212:215], v[14:17], v[98:101]
	flat_store_dwordx4 v[124:125], v[114:117] offset:32
	v_pk_mul_f32 v[110:111], v[110:111], v[110:111]
	s_nop 0
	v_pk_mul_f32 v[114:115], v[106:107], v[106:107]
	v_max_f32_e32 v106, 0, v0
	v_max_f32_e32 v0, v108, v108
	v_max_f32_e32 v108, 0, v0
	v_max_f32_e32 v0, v113, v113
	v_max_f32_e32 v107, 0, v0
	v_max_f32_e32 v0, v109, v109
	v_max_f32_e32 v109, 0, v0
	v_max_f32_e32 v0, v102, v102
	v_max_f32_e32 v102, 0, v0
	v_max_f32_e32 v0, v98, v98
	v_pk_mul_f32 v[112:113], v[106:107], v[106:107]
	v_pk_mul_f32 v[116:117], v[108:109], v[108:109]
	v_max_f32_e32 v98, 0, v0
	v_max_f32_e32 v0, v103, v103
	v_cvt_pk_bf16_f32 v106, v110, v111
	v_cvt_pk_bf16_f32 v107, v112, v113
	v_cvt_pk_bf16_f32 v108, v114, v115
	v_cvt_pk_bf16_f32 v109, v116, v117
	v_max_f32_e32 v103, 0, v0
	v_max_f32_e32 v0, v99, v99
	v_permlane16_swap_b32_e32 v106, v108
	v_permlane16_swap_b32_e32 v107, v109
	v_max_f32_e32 v99, 0, v0
	v_max_f32_e32 v0, v104, v104
	flat_store_dwordx4 v[124:125], v[106:109] offset:128
	v_pk_mul_f32 v[102:103], v[102:103], v[102:103]
	v_mfma_f32_16x16x32_bf16 v[90:93], v[200:203], v[38:41], v[146:149]
	v_mul_f32_e64 v106, v98, v98
	v_mul_f32_e64 v107, v99, v99
	v_max_f32_e32 v98, 0, v0
	v_max_f32_e32 v0, v100, v100
	v_max_f32_e32 v100, 0, v0
	v_max_f32_e32 v0, v105, v105
	v_max_f32_e32 v99, 0, v0
	v_max_f32_e32 v0, v101, v101
	v_max_f32_e32 v101, 0, v0
	v_pk_mul_f32 v[104:105], v[98:99], v[98:99]
	v_pk_mul_f32 v[108:109], v[100:101], v[100:101]
	v_cvt_pk_bf16_f32 v98, v102, v103
	v_cvt_pk_bf16_f32 v99, v104, v105
	v_cvt_pk_bf16_f32 v100, v106, v107
	v_cvt_pk_bf16_f32 v101, v108, v109
	s_nop 0
	v_permlane16_swap_b32_e32 v98, v100
	v_permlane16_swap_b32_e32 v99, v101
	v_mfma_f32_16x16x32_bf16 v[82:85], v[204:207], v[38:41], v[74:77]
	flat_store_dwordx4 v[124:125], v[98:101] offset:160
	v_mfma_f32_16x16x32_bf16 v[74:77], v[208:211], v[38:41], v[192:195]
	v_mfma_f32_16x16x32_bf16 v[66:69], v[212:215], v[38:41], v[66:69]
	v_mfma_f32_16x16x32_bf16 v[62:65], v[200:203], v[168:171], v[62:65]
	v_mfma_f32_16x16x32_bf16 v[54:57], v[204:207], v[168:171], v[58:61]
	v_mfma_f32_16x16x32_bf16 v[46:49], v[208:211], v[168:171], v[150:153]
	v_mfma_f32_16x16x32_bf16 v[38:41], v[212:215], v[168:171], v[50:53]
	v_mfma_f32_16x16x32_bf16 v[58:61], v[200:203], v[172:175], v[154:157]
	v_mfma_f32_16x16x32_bf16 v[50:53], v[204:207], v[172:175], v[42:45]
	v_mfma_f32_16x16x32_bf16 v[42:45], v[208:211], v[172:175], v[196:199]
	v_mfma_f32_16x16x32_bf16 v[34:37], v[212:215], v[172:175], v[34:37]
	v_mfma_f32_16x16x32_bf16 v[30:33], v[200:203], v[176:179], v[30:33]
	v_mfma_f32_16x16x32_bf16 v[14:17], v[208:211], v[176:179], v[158:161]
	v_mfma_f32_16x16x32_bf16 v[6:9], v[212:215], v[176:179], v[18:21]
	v_mfma_f32_16x16x32_bf16 v[18:21], v[204:207], v[180:183], v[10:13]
	v_mfma_f32_16x16x32_bf16 v[10:13], v[208:211], v[180:183], v[164:167]
	v_mfma_f32_16x16x32_bf16 v[2:5], v[212:215], v[180:183], v[2:5]
	v_max_f32_e32 v0, v94, v94
	v_max_f32_e32 v94, 0, v0
	v_max_f32_e32 v0, v90, v90
	v_max_f32_e32 v90, 0, v0
	v_max_f32_e32 v0, v95, v95
	v_max_f32_e32 v95, 0, v0
	v_max_f32_e32 v0, v91, v91
	v_max_f32_e32 v91, 0, v0
	v_max_f32_e32 v0, v96, v96
	v_pk_mul_f32 v[100:101], v[90:91], v[90:91]
	v_max_f32_e32 v90, 0, v0
	v_max_f32_e32 v0, v92, v92
	v_max_f32_e32 v92, 0, v0
	v_max_f32_e32 v0, v97, v97
	v_max_f32_e32 v91, 0, v0
	v_max_f32_e32 v0, v93, v93
	v_add_u32_e32 v98, 32, v126
	v_max_f32_e32 v93, 0, v0
	v_max_f32_e32 v0, v86, v86
	v_ashrrev_i32_e32 v99, 31, v98
	v_max_f32_e32 v86, 0, v0
	v_max_f32_e32 v0, v82, v82
	v_and_b32_e32 v220, 1, v98
	v_lshrrev_b32_e32 v98, 1, v98
	v_mov_b32_e32 v99, 0
	v_lshlrev_b64 v[98:99], 14, v[98:99]
	v_lshl_or_b32 v98, v220, 6, v98
	v_pk_mul_f32 v[94:95], v[94:95], v[94:95]
	v_pk_mul_f32 v[96:97], v[90:91], v[90:91]
	v_pk_mul_f32 v[102:103], v[92:93], v[92:93]
	v_max_f32_e32 v82, 0, v0
	v_max_f32_e32 v0, v87, v87
	v_lshl_add_u64 v[98:99], s[60:61], 0, v[98:99]
	v_cvt_pk_bf16_f32 v90, v94, v95
	v_cvt_pk_bf16_f32 v91, v96, v97
	v_cvt_pk_bf16_f32 v92, v100, v101
	v_cvt_pk_bf16_f32 v93, v102, v103
	v_max_f32_e32 v87, 0, v0
	v_max_f32_e32 v0, v83, v83
	v_permlane16_swap_b32_e32 v90, v92
	v_permlane16_swap_b32_e32 v91, v93
	v_lshl_add_u64 v[94:95], v[98:99], 0, v[122:123]
	v_max_f32_e32 v83, 0, v0
	v_max_f32_e32 v0, v88, v88
	flat_store_dwordx4 v[94:95], v[90:93]
	v_pk_mul_f32 v[86:87], v[86:87], v[86:87]
	s_nop 0
	v_pk_mul_f32 v[90:91], v[82:83], v[82:83]
	v_max_f32_e32 v82, 0, v0
	v_max_f32_e32 v0, v84, v84
; DI unsigned pack2(float a, float b) { float2_t v = {a, b}; bf16x2_t r = __builtin_convertvector(v, bf16x2_t); return __builtin_bit_cast(unsigned, r); }
; DI void phase_mlp1(const Params& p, int l, int Mout, char* smem) {
;     ...
;     for (int mi = 0; mi < 8; mi += 2) {
;       const int m = m0 + wr * 128 + (mi + (lq & 1)) * 16 + lr;
; #pragma unroll
;       for (int ni = 0; ni < 4; ++ni) {
;         const int n = n0 + wc * 64 + ni * 16 + (lq >> 1) * 8;
;         float va[4], vb[4];
; #pragma unroll
;         for (int j = 0; j < 4; ++j) { const float a = fmaxf(acc[mi][ni][j], 0.f); va[j] = a * a; const float b = fmaxf(acc[mi + 1][ni][j], 0.f); vb[j] = b * b; }
;         *(uint4*)(U + (size_t)m * DFF + n) = widen16(make_uint2(pack2(va[0], va[1]), pack2(va[2], va[3])), make_uint2(pack2(vb[0], vb[1]), pack2(vb[2], vb[3])));
;       }
;       __builtin_amdgcn_sched_barrier(0);
;     }
	v_max_f32_e32 v84, 0, v0
	v_max_f32_e32 v0, v89, v89
	v_max_f32_e32 v83, 0, v0
	v_max_f32_e32 v0, v85, v85
	v_max_f32_e32 v85, 0, v0
	v_max_f32_e32 v0, v78, v78
	v_max_f32_e32 v78, 0, v0
	v_max_f32_e32 v0, v74, v74
	v_pk_mul_f32 v[88:89], v[82:83], v[82:83]
	v_pk_mul_f32 v[92:93], v[84:85], v[84:85]
	v_max_f32_e32 v74, 0, v0
	v_max_f32_e32 v0, v79, v79
	v_cvt_pk_bf16_f32 v82, v86, v87
	v_cvt_pk_bf16_f32 v83, v88, v89
	v_cvt_pk_bf16_f32 v84, v90, v91
	v_cvt_pk_bf16_f32 v85, v92, v93
	v_max_f32_e32 v79, 0, v0
	v_max_f32_e32 v0, v75, v75
	v_permlane16_swap_b32_e32 v82, v84
	v_permlane16_swap_b32_e32 v83, v85
	v_max_f32_e32 v75, 0, v0
	v_max_f32_e32 v0, v80, v80
	flat_store_dwordx4 v[94:95], v[82:85] offset:32
	v_pk_mul_f32 v[78:79], v[78:79], v[78:79]
	s_nop 0
	v_pk_mul_f32 v[82:83], v[74:75], v[74:75]
	v_max_f32_e32 v74, 0, v0
	v_max_f32_e32 v0, v76, v76
	v_max_f32_e32 v76, 0, v0
	v_max_f32_e32 v0, v81, v81
	v_max_f32_e32 v75, 0, v0
	v_max_f32_e32 v0, v77, v77
	v_max_f32_e32 v77, 0, v0
	v_max_f32_e32 v0, v70, v70
	v_max_f32_e32 v70, 0, v0
	v_max_f32_e32 v0, v66, v66
	v_pk_mul_f32 v[80:81], v[74:75], v[74:75]
	v_pk_mul_f32 v[84:85], v[76:77], v[76:77]
	v_max_f32_e32 v66, 0, v0
	v_max_f32_e32 v0, v71, v71
	v_cvt_pk_bf16_f32 v74, v78, v79
	v_cvt_pk_bf16_f32 v75, v80, v81
	v_cvt_pk_bf16_f32 v76, v82, v83
	v_cvt_pk_bf16_f32 v77, v84, v85
	v_max_f32_e32 v71, 0, v0
	v_max_f32_e32 v0, v67, v67
	v_permlane16_swap_b32_e32 v74, v76
	v_permlane16_swap_b32_e32 v75, v77
	v_max_f32_e32 v67, 0, v0
	v_max_f32_e32 v0, v72, v72
	flat_store_dwordx4 v[94:95], v[74:77] offset:128
	v_pk_mul_f32 v[70:71], v[70:71], v[70:71]
	s_nop 0
	v_pk_mul_f32 v[74:75], v[66:67], v[66:67]
	v_max_f32_e32 v66, 0, v0
	v_max_f32_e32 v0, v68, v68
	v_max_f32_e32 v68, 0, v0
	v_max_f32_e32 v0, v73, v73
	v_max_f32_e32 v67, 0, v0
	v_max_f32_e32 v0, v69, v69
	v_max_f32_e32 v69, 0, v0
	v_pk_mul_f32 v[72:73], v[66:67], v[66:67]
	v_pk_mul_f32 v[76:77], v[68:69], v[68:69]
	v_cvt_pk_bf16_f32 v66, v70, v71
	v_cvt_pk_bf16_f32 v67, v72, v73
	v_cvt_pk_bf16_f32 v68, v74, v75
	v_cvt_pk_bf16_f32 v69, v76, v77
	s_nop 0
	v_permlane16_swap_b32_e32 v66, v68
	v_permlane16_swap_b32_e32 v67, v69
	flat_store_dwordx4 v[94:95], v[66:69] offset:160
	v_max_f32_e32 v0, v62, v62
	v_max_f32_e32 v62, 0, v0
	v_max_f32_e32 v0, v58, v58
	v_max_f32_e32 v58, 0, v0
	v_max_f32_e32 v0, v63, v63
	v_max_f32_e32 v63, 0, v0
	v_max_f32_e32 v0, v59, v59
	v_max_f32_e32 v59, 0, v0
	v_max_f32_e32 v0, v64, v64
	v_pk_mul_f32 v[68:69], v[58:59], v[58:59]
	v_max_f32_e32 v58, 0, v0
	v_max_f32_e32 v0, v60, v60
	v_max_f32_e32 v60, 0, v0
	v_max_f32_e32 v0, v65, v65
	v_max_f32_e32 v59, 0, v0
	v_max_f32_e32 v0, v61, v61
	v_add_u32_e32 v66, 64, v126
	v_max_f32_e32 v61, 0, v0
	v_max_f32_e32 v0, v54, v54
	v_ashrrev_i32_e32 v67, 31, v66
	v_max_f32_e32 v54, 0, v0
	v_max_f32_e32 v0, v50, v50
	v_and_b32_e32 v220, 1, v66
	v_lshrrev_b32_e32 v66, 1, v66
	v_mov_b32_e32 v67, 0
	v_lshlrev_b64 v[66:67], 14, v[66:67]
	v_lshl_or_b32 v66, v220, 6, v66
	v_pk_mul_f32 v[62:63], v[62:63], v[62:63]
	v_pk_mul_f32 v[64:65], v[58:59], v[58:59]
	v_pk_mul_f32 v[70:71], v[60:61], v[60:61]
	v_max_f32_e32 v50, 0, v0
	v_max_f32_e32 v0, v55, v55
	v_lshl_add_u64 v[66:67], s[60:61], 0, v[66:67]
	v_cvt_pk_bf16_f32 v58, v62, v63
	v_cvt_pk_bf16_f32 v59, v64, v65
	v_cvt_pk_bf16_f32 v60, v68, v69
	v_cvt_pk_bf16_f32 v61, v70, v71
	v_max_f32_e32 v55, 0, v0
	v_max_f32_e32 v0, v51, v51
	v_permlane16_swap_b32_e32 v58, v60
	v_permlane16_swap_b32_e32 v59, v61
	v_lshl_add_u64 v[62:63], v[66:67], 0, v[122:123]
	v_max_f32_e32 v51, 0, v0
	v_max_f32_e32 v0, v56, v56
	flat_store_dwordx4 v[62:63], v[58:61]
	v_pk_mul_f32 v[54:55], v[54:55], v[54:55]
	s_nop 0
	v_pk_mul_f32 v[58:59], v[50:51], v[50:51]
	v_max_f32_e32 v50, 0, v0
	v_max_f32_e32 v0, v52, v52
	v_max_f32_e32 v52, 0, v0
	v_max_f32_e32 v0, v57, v57
	v_max_f32_e32 v51, 0, v0
	v_max_f32_e32 v0, v53, v53
	v_max_f32_e32 v53, 0, v0
	v_max_f32_e32 v0, v46, v46
	v_max_f32_e32 v46, 0, v0
	v_max_f32_e32 v0, v42, v42
	v_pk_mul_f32 v[56:57], v[50:51], v[50:51]
	v_pk_mul_f32 v[60:61], v[52:53], v[52:53]
	v_max_f32_e32 v42, 0, v0
	v_max_f32_e32 v0, v47, v47
	v_cvt_pk_bf16_f32 v50, v54, v55
	v_cvt_pk_bf16_f32 v51, v56, v57
	v_cvt_pk_bf16_f32 v52, v58, v59
	v_cvt_pk_bf16_f32 v53, v60, v61
	v_max_f32_e32 v47, 0, v0
	v_max_f32_e32 v0, v43, v43
	v_permlane16_swap_b32_e32 v50, v52
	v_permlane16_swap_b32_e32 v51, v53
	v_max_f32_e32 v43, 0, v0
	v_max_f32_e32 v0, v48, v48
	flat_store_dwordx4 v[62:63], v[50:53] offset:32
	v_pk_mul_f32 v[46:47], v[46:47], v[46:47]
	s_nop 0
	v_pk_mul_f32 v[50:51], v[42:43], v[42:43]
	v_max_f32_e32 v42, 0, v0
	v_max_f32_e32 v0, v44, v44
	v_max_f32_e32 v44, 0, v0
	v_max_f32_e32 v0, v49, v49
	v_max_f32_e32 v43, 0, v0
	v_max_f32_e32 v0, v45, v45
	v_max_f32_e32 v45, 0, v0
	v_max_f32_e32 v0, v38, v38
	v_max_f32_e32 v38, 0, v0
	v_max_f32_e32 v0, v34, v34
	v_pk_mul_f32 v[48:49], v[42:43], v[42:43]
	v_pk_mul_f32 v[52:53], v[44:45], v[44:45]
; DI unsigned pack2(float a, float b) { float2_t v = {a, b}; bf16x2_t r = __builtin_convertvector(v, bf16x2_t); return __builtin_bit_cast(unsigned, r); }
; #define EPI_BEGIN const int lr1_ = launder_v(lr), lq1_ = launder_v(lq), wr1_ = launder_v(wr), wc1_ = launder_v(wc); { const int lr = lr1_, lq = lq1_, wr = wr1_, wc = wc1_; (void)lr; (void)lq; (void)wr; (void)wc;
; DI void phase_mlp1(const Params& p, int l, int Mout, char* smem) {
;     ...
;   for (int it = 0;; ++it) {
;     int tm, tn;
;     if (!tile_map(it, ntm, 32, blk__, gridDim.x, tm, tn)) break;
;     const int m0 = tm * 256, n0 = tn * 128;
;     f32x4 acc[8][4]; zero_accm<8, 4>(acc);
;     gemm256<8, 4>(acc, hb, 1024, (const u16*)(wl + WO_W1), 1024, 1024, m0, n0, smem);
;     EPI_BEGIN
; #pragma unroll
;     for (int mi = 0; mi < 8; mi += 2) {
;       const int m = m0 + wr * 128 + (mi + (lq & 1)) * 16 + lr;
; #pragma unroll
;       for (int ni = 0; ni < 4; ++ni) {
;         const int n = n0 + wc * 64 + ni * 16 + (lq >> 1) * 8;
;         float va[4], vb[4];
; #pragma unroll
;         for (int j = 0; j < 4; ++j) { const float a = fmaxf(acc[mi][ni][j], 0.f); va[j] = a * a; const float b = fmaxf(acc[mi + 1][ni][j], 0.f); vb[j] = b * b; }
;         *(uint4*)(U + (size_t)m * DFF + n) = widen16(make_uint2(pack2(va[0], va[1]), pack2(va[2], va[3])), make_uint2(pack2(vb[0], vb[1]), pack2(vb[2], vb[3])));
;       }
;       __builtin_amdgcn_sched_barrier(0);
;     }
;     EPI_END
	v_max_f32_e32 v34, 0, v0
	v_max_f32_e32 v0, v39, v39
	v_cvt_pk_bf16_f32 v42, v46, v47
	v_cvt_pk_bf16_f32 v43, v48, v49
	v_cvt_pk_bf16_f32 v44, v50, v51
	v_cvt_pk_bf16_f32 v45, v52, v53
	v_max_f32_e32 v39, 0, v0
	v_max_f32_e32 v0, v35, v35
	v_permlane16_swap_b32_e32 v42, v44
	v_permlane16_swap_b32_e32 v43, v45
	v_max_f32_e32 v35, 0, v0
	v_max_f32_e32 v0, v40, v40
	flat_store_dwordx4 v[62:63], v[42:45] offset:128
	v_pk_mul_f32 v[38:39], v[38:39], v[38:39]
	s_nop 0
	v_pk_mul_f32 v[42:43], v[34:35], v[34:35]
	v_max_f32_e32 v34, 0, v0
	v_max_f32_e32 v0, v36, v36
	v_max_f32_e32 v36, 0, v0
	v_max_f32_e32 v0, v41, v41
	v_max_f32_e32 v35, 0, v0
	v_max_f32_e32 v0, v37, v37
	v_max_f32_e32 v37, 0, v0
	v_pk_mul_f32 v[40:41], v[34:35], v[34:35]
	v_pk_mul_f32 v[44:45], v[36:37], v[36:37]
	v_cvt_pk_bf16_f32 v34, v38, v39
	v_cvt_pk_bf16_f32 v35, v40, v41
	v_cvt_pk_bf16_f32 v36, v42, v43
	v_cvt_pk_bf16_f32 v37, v44, v45
	s_nop 0
	v_permlane16_swap_b32_e32 v34, v36
	v_permlane16_swap_b32_e32 v35, v37
	flat_store_dwordx4 v[62:63], v[34:37] offset:160
	v_max_f32_e32 v0, v30, v30
	v_max_f32_e32 v30, 0, v0
	v_max_f32_e32 v0, v26, v26
	v_max_f32_e32 v26, 0, v0
	v_max_f32_e32 v0, v31, v31
	v_max_f32_e32 v31, 0, v0
	v_max_f32_e32 v0, v27, v27
	v_max_f32_e32 v27, 0, v0
	v_max_f32_e32 v0, v32, v32
	v_pk_mul_f32 v[36:37], v[26:27], v[26:27]
	v_max_f32_e32 v26, 0, v0
	v_max_f32_e32 v0, v28, v28
	v_max_f32_e32 v28, 0, v0
	v_max_f32_e32 v0, v33, v33
	v_max_f32_e32 v27, 0, v0
	v_max_f32_e32 v0, v29, v29
	v_add_u32_e32 v34, 0x60, v126
	v_max_f32_e32 v29, 0, v0
	v_max_f32_e32 v0, v22, v22
	v_ashrrev_i32_e32 v35, 31, v34
	v_max_f32_e32 v22, 0, v0
	v_max_f32_e32 v0, v18, v18
	v_and_b32_e32 v220, 1, v34
	v_lshrrev_b32_e32 v34, 1, v34
	v_mov_b32_e32 v35, 0
	v_lshlrev_b64 v[34:35], 14, v[34:35]
	v_lshl_or_b32 v34, v220, 6, v34
	v_pk_mul_f32 v[30:31], v[30:31], v[30:31]
	v_pk_mul_f32 v[32:33], v[26:27], v[26:27]
	v_pk_mul_f32 v[38:39], v[28:29], v[28:29]
	v_max_f32_e32 v18, 0, v0
	v_max_f32_e32 v0, v23, v23
	v_lshl_add_u64 v[34:35], s[60:61], 0, v[34:35]
	v_cvt_pk_bf16_f32 v26, v30, v31
	v_cvt_pk_bf16_f32 v27, v32, v33
	v_cvt_pk_bf16_f32 v28, v36, v37
	v_cvt_pk_bf16_f32 v29, v38, v39
	v_max_f32_e32 v23, 0, v0
	v_max_f32_e32 v0, v19, v19
	v_permlane16_swap_b32_e32 v26, v28
	v_permlane16_swap_b32_e32 v27, v29
	v_lshl_add_u64 v[30:31], v[34:35], 0, v[122:123]
	v_max_f32_e32 v19, 0, v0
	v_max_f32_e32 v0, v24, v24
	flat_store_dwordx4 v[30:31], v[26:29]
	v_pk_mul_f32 v[22:23], v[22:23], v[22:23]
	s_nop 0
	v_pk_mul_f32 v[26:27], v[18:19], v[18:19]
	v_max_f32_e32 v18, 0, v0
	v_max_f32_e32 v0, v20, v20
	v_max_f32_e32 v20, 0, v0
	v_max_f32_e32 v0, v25, v25
	v_max_f32_e32 v19, 0, v0
	v_max_f32_e32 v0, v21, v21
	v_max_f32_e32 v21, 0, v0
	v_max_f32_e32 v0, v14, v14
	v_max_f32_e32 v14, 0, v0
	v_max_f32_e32 v0, v10, v10
	v_pk_mul_f32 v[24:25], v[18:19], v[18:19]
	v_pk_mul_f32 v[28:29], v[20:21], v[20:21]
	v_max_f32_e32 v10, 0, v0
	v_max_f32_e32 v0, v15, v15
	v_cvt_pk_bf16_f32 v18, v22, v23
	v_cvt_pk_bf16_f32 v19, v24, v25
	v_cvt_pk_bf16_f32 v20, v26, v27
	v_cvt_pk_bf16_f32 v21, v28, v29
	v_max_f32_e32 v15, 0, v0
	v_max_f32_e32 v0, v11, v11
	v_permlane16_swap_b32_e32 v18, v20
	v_permlane16_swap_b32_e32 v19, v21
	v_max_f32_e32 v11, 0, v0
	v_max_f32_e32 v0, v16, v16
	flat_store_dwordx4 v[30:31], v[18:21] offset:32
	v_pk_mul_f32 v[14:15], v[14:15], v[14:15]
	s_nop 0
	v_pk_mul_f32 v[18:19], v[10:11], v[10:11]
	v_max_f32_e32 v10, 0, v0
	v_max_f32_e32 v0, v12, v12
	v_max_f32_e32 v12, 0, v0
	v_max_f32_e32 v0, v17, v17
	v_max_f32_e32 v11, 0, v0
	v_max_f32_e32 v0, v13, v13
	v_max_f32_e32 v13, 0, v0
	v_max_f32_e32 v0, v6, v6
	v_max_f32_e32 v6, 0, v0
	v_max_f32_e32 v0, v2, v2
	v_pk_mul_f32 v[16:17], v[10:11], v[10:11]
	v_pk_mul_f32 v[20:21], v[12:13], v[12:13]
	v_max_f32_e32 v2, 0, v0
	v_max_f32_e32 v0, v7, v7
	v_cvt_pk_bf16_f32 v10, v14, v15
	v_cvt_pk_bf16_f32 v11, v16, v17
	v_cvt_pk_bf16_f32 v12, v18, v19
	v_cvt_pk_bf16_f32 v13, v20, v21
	v_max_f32_e32 v7, 0, v0
	v_max_f32_e32 v0, v3, v3
	v_permlane16_swap_b32_e32 v10, v12
	v_permlane16_swap_b32_e32 v11, v13
	v_max_f32_e32 v3, 0, v0
	v_max_f32_e32 v0, v8, v8
	flat_store_dwordx4 v[30:31], v[10:13] offset:128
	v_pk_mul_f32 v[6:7], v[6:7], v[6:7]
	s_nop 0
	v_pk_mul_f32 v[10:11], v[2:3], v[2:3]
	v_max_f32_e32 v2, 0, v0
	v_max_f32_e32 v0, v4, v4
	v_max_f32_e32 v4, 0, v0
	v_max_f32_e32 v0, v9, v9
	v_max_f32_e32 v3, 0, v0
	v_max_f32_e32 v0, v5, v5
	v_max_f32_e32 v5, 0, v0
	v_pk_mul_f32 v[8:9], v[2:3], v[2:3]
	v_pk_mul_f32 v[12:13], v[4:5], v[4:5]
	v_cvt_pk_bf16_f32 v2, v6, v7
	v_cvt_pk_bf16_f32 v3, v8, v9
	v_cvt_pk_bf16_f32 v4, v10, v11
	v_cvt_pk_bf16_f32 v5, v12, v13
	s_nop 0
	v_permlane16_swap_b32_e32 v2, v4
	v_permlane16_swap_b32_e32 v3, v5
	flat_store_dwordx4 v[30:31], v[2:5] offset:160
	s_add_i32 s8, s8, 1
	s_mul_i32 s4, s8, s39
	s_add_i32 s9, s4, s6
	v_readlane_b32 s4, v253, 41
	s_cmp_ge_i32 s9, s4
	s_cbranch_scc0 .LBB0_441

; DI bool tile_map(int it, int NTM, int NTN, int blk, int nblk, int& tm, int& tn) {
;   const int xcd = blk & 7, local = blk >> 3, LB = nblk >> 3;
;   const int R = NTM >> 3;
;   const int s = it * LB + local;
;   if (s >= R * NTN) return false;
;   const int F = R >> 3, per_full = 8 * NTN;
;   int mg, r, gm;
;   if (s < F * per_full) { mg = s / per_full; r = s - mg * per_full; gm = 8; }
;   else { mg = F; r = s - F * per_full; gm = R - F * 8; }
;   const int ng = r / (gm * 8);
;   const int r2 = r - ng * gm * 8;
;   const int mi = r2 % gm, ni = r2 / gm;
;   tm = xcd * R + mg * 8 + mi; tn = ng * 8 + ni;
;   return true;
; template <int MI, int NI>
; DI void gemm256(f32x4 (&acc)[MI][NI], const u16* __restrict__ A, int lda, const u16* __restrict__ Bt, int ldb, int K, int m0, int n0, char* smem) {
;     ...
;   const int srow = lane >> 2, scol = ((lane & 3) ^ ((lane >> 5) << 1)) * 8;
;   const u16* Ag = A + (size_t)(m0 + wave * NAW * 16 + srow) * lda + scol;
;   const u16* Bg = Bt + (size_t)(n0 + wave * NBW * 16 + srow) * ldb + scol;
;   char* la = smem + (wave * NAW) * 1024 + lane * 16;
;   char* lb = smem + ABYTES + (wave * NBW) * 1024 + lane * 16;
;     ...
;   const int nk = K >> 5;
;   G256_ISSUE(0, 0);
;   if (nk > 1) G256_ISSUE(1, 32);
.LBB0_461:
	s_ashr_i32 s5, s4, 31
	s_lshr_b32 s5, s5, 26
	s_add_i32 s5, s4, s5
	s_and_b32 s10, s5, 0xffffffc0
	s_sub_i32 s4, s4, s10
	s_ashr_i32 s10, s4, 31
	s_lshr_b32 s10, s10, 26
	s_add_i32 s11, s4, s10
	s_and_b32 s10, s11, 0xffffffc0
	s_sub_i32 s4, s4, s10
	s_ashr_i32 s10, s4, 31
	s_lshr_b32 s10, s10, 29
	s_lshr_b32 s5, s5, 3
	s_add_i32 s12, s4, s10
	s_and_b32 s5, s5, 0x1ffffff8
	s_and_b32 s10, s12, 0xfffff8
	s_sub_i32 s4, s4, s10
	s_add_i32 s5, s5, s8
	s_add_i32 s5, s5, s4
	s_lshl_b32 s10, s5, 8
	s_lshl_b32 s4, s11, 4
	s_lshl_b32 s5, s12, 4
	s_and_b32 s4, s4, 0xfffffc00
	s_and_b32 s11, s5, 0xffffff80
	s_add_i32 s11, s11, s4
	v_mov_b32_e32 v134, v163
	s_mov_b32 s4, s2
	s_waitcnt vmcnt(0)
	v_mov_b32_e32 v10, v163
	s_mov_b32 s4, s2
	v_ashrrev_i32_e32 v9, 6, v10
	v_and_b32_e32 v0, 3, v10
	v_lshrrev_b32_e32 v2, 4, v10
	v_bitop3_b32 v0, v2, v0, 2 bitop3:0x6c
	v_and_b32_e32 v2, 0xffffffc0, v10
	v_lshlrev_b32_e32 v12, 5, v9
	v_bfe_u32 v11, v10, 2, 4
	v_add_u32_e32 v2, s10, v2
	v_add_u32_e32 v6, s11, v12
	v_and_b32_e32 v8, 63, v10
	v_or_b32_e32 v2, v2, v11
	v_or_b32_e32 v6, v6, v11
	v_ashrrev_i32_e32 v3, 31, v2
	v_ashrrev_i32_e32 v7, 31, v6
	v_readlane_b32 s4, v253, 49
	v_lshlrev_b32_e32 v13, 12, v9
	v_lshlrev_b32_e32 v8, 4, v8
	v_lshlrev_b64 v[2:3], 11, v[2:3]
	v_lshlrev_b64 v[6:7], 11, v[6:7]
	v_readlane_b32 s5, v253, 50
	v_or_b32_e32 v135, v13, v8
	v_lshl_add_u64 v[4:5], s[60:61], 0, v[2:3]
	v_lshlrev_b32_e32 v0, 4, v0
	v_lshl_add_u64 v[6:7], s[4:5], 0, v[6:7]
	v_readfirstlane_b32 s4, v135
	v_or_b32_e32 v15, 0x400, v135
	v_lshl_add_u64 v[4:5], v[4:5], 0, v[0:1]
	v_bfe_i32 v199, v163, 2, 1
	v_and_b32_e32 v198, 0xfffff840, v199
	v_lshl_add_u64 v[4:5], v[4:5], 0, v[198:199]
	s_mov_b32 m0, s4
	v_readfirstlane_b32 s4, v15
	v_lshl_or_b32 v136, v9, 11, v8
	global_load_lds_dwordx4 v[4:5], off
	v_lshl_add_u64 v[8:9], v[4:5], 0, s[68:69]
	s_mov_b32 m0, s4
	s_mov_b64 s[4:5], 0x10000
	v_or_b32_e32 v15, 0x800, v135
	global_load_lds_dwordx4 v[8:9], off
	v_lshl_add_u64 v[8:9], v[4:5], 0, s[4:5]
	v_readfirstlane_b32 s4, v15
	s_mov_b32 m0, s4
	s_mov_b64 s[4:5], 0x18000
	v_or_b32_e32 v15, 0xc00, v135
	v_add_u32_e32 v14, 0x4000, v136
	global_load_lds_dwordx4 v[8:9], off
	v_lshl_add_u64 v[8:9], v[4:5], 0, s[4:5]
	v_readfirstlane_b32 s4, v15
	s_mov_b32 m0, s4
	v_readfirstlane_b32 s4, v14
	v_add_u32_e32 v14, 0x4400, v136
	global_load_lds_dwordx4 v[8:9], off
	v_lshl_add_u64 v[6:7], v[6:7], 0, v[0:1]
	s_mov_b32 m0, s4
	v_readfirstlane_b32 s4, v14
	v_add_u32_e32 v14, 0x6000, v135
	global_load_lds_dwordx4 v[6:7], off
	v_lshl_add_u64 v[8:9], v[6:7], 0, s[68:69]
	s_mov_b32 m0, s4
	v_readfirstlane_b32 s4, v14
	v_add_u32_e32 v14, 0x6400, v135
	global_load_lds_dwordx4 v[8:9], off
	s_mov_b64 s[98:99], 0x80
	v_lshl_add_u64 v[8:9], v[4:5], 0, s[98:99]
	s_mov_b32 m0, s4
	v_readfirstlane_b32 s4, v14
	global_load_lds_dwordx4 v[8:9], off
	s_mov_b64 s[98:99], 0x8080
	v_lshl_add_u64 v[8:9], v[4:5], 0, s[98:99]
	s_mov_b32 m0, s4
	s_mov_b64 s[4:5], 0x10080
	v_add_u32_e32 v14, 0x6800, v135
	global_load_lds_dwordx4 v[8:9], off
	v_lshl_add_u64 v[8:9], v[4:5], 0, s[4:5]
	v_readfirstlane_b32 s4, v14
	s_mov_b32 m0, s4
	s_mov_b64 s[4:5], 0x18080
	global_load_lds_dwordx4 v[8:9], off
	v_add_u32_e32 v8, 0x6c00, v135
	v_lshl_add_u64 v[4:5], v[4:5], 0, s[4:5]
	v_readfirstlane_b32 s4, v8
	v_add_u32_e32 v8, 0xa000, v136
	s_mov_b32 m0, s4
	v_readfirstlane_b32 s4, v8
	global_load_lds_dwordx4 v[4:5], off
	v_lshl_add_u64 v[4:5], v[6:7], 0, 64
	s_mov_b32 m0, s4
	v_or_b32_e32 v2, v2, v0
	global_load_lds_dwordx4 v[4:5], off
	v_lshl_add_u64 v[4:5], v[6:7], 0, s[74:75]
	v_add_u32_e32 v6, 0xa400, v136
	v_lshl_add_u64 v[132:133], s[62:63], 0, v[2:3]
	v_readfirstlane_b32 s4, v6
	s_mov_b32 m0, s4
	v_and_b32_e32 v6, 48, v10
	global_load_lds_dwordx4 v[4:5], off
	v_lshlrev_b32_e32 v5, 2, v10
	v_lshlrev_b32_e32 v4, 6, v10
	v_bitop3_b32 v5, v5, v6, 32 bitop3:0x6c
	v_and_or_b32 v137, v4, s59, v5
	v_and_b32_e32 v139, 0xffffe000, v4
	v_or_b32_e32 v4, s11, v11
	v_add_u32_e32 v4, v4, v12
	v_ashrrev_i32_e32 v5, 31, v4
	v_lshlrev_b64 v[4:5], 11, v[4:5]
	v_readlane_b32 s4, v254, 52
	v_or_b32_e32 v4, v4, v0
	v_readlane_b32 s5, v254, 53
	v_mov_b32_e32 v2, 0
	v_and_b32_e32 v138, 0x1000, v13
	v_lshl_add_u64 v[130:131], s[4:5], 0, v[4:5]
	s_mov_b64 s[4:5], 0
	s_mov_b32 s12, 0
	v_mov_b32_e32 v3, v2
	v_mov_b32_e32 v4, v2
	v_mov_b32_e32 v5, v2
	v_mov_b32_e32 v6, v2
	v_mov_b32_e32 v7, v2
	v_mov_b32_e32 v8, v2
	v_mov_b32_e32 v9, v2
	v_mov_b32_e32 v10, v2
	v_mov_b32_e32 v11, v2
	v_mov_b32_e32 v12, v2
	v_mov_b32_e32 v13, v2
	v_mov_b32_e32 v14, v2
	v_mov_b32_e32 v15, v2
	v_mov_b32_e32 v16, v2
	v_mov_b32_e32 v17, v2
	v_mov_b32_e32 v18, v2
	v_mov_b32_e32 v19, v2
	v_mov_b32_e32 v20, v2
	v_mov_b32_e32 v21, v2
	v_mov_b32_e32 v22, v2
	v_mov_b32_e32 v23, v2
	v_mov_b32_e32 v24, v2
	v_mov_b32_e32 v25, v2
	s_waitcnt lgkmcnt(0)
; template <int MI, int NI>
; DI void gemm256(f32x4 (&acc)[MI][NI], const u16* __restrict__ A, int lda, const u16* __restrict__ Bt, int ldb, int K, int m0, int n0, char* smem) {
;     ...
;   const int srow = lane >> 2, scol = ((lane & 3) ^ ((lane >> 5) << 1)) * 8;
;   const u16* Ag = A + (size_t)(m0 + wave * NAW * 16 + srow) * lda + scol;
;   const u16* Bg = Bt + (size_t)(n0 + wave * NBW * 16 + srow) * ldb + scol;
;   char* la = smem + (wave * NAW) * 1024 + lane * 16;
;   char* lb = smem + ABYTES + (wave * NBW) * 1024 + lane * 16;
;     ...
;   const int nk = K >> 5;
;   G256_ISSUE(0, 0);
;   if (nk > 1) G256_ISSUE(1, 32);
;   const int foff = lr * 64 + ((lq ^ ((lr >> 3) << 1)) * 16);
;   int st = 0;
;   for (int kt = 0; kt < nk; ++kt) {
;     if (kt + 1 < nk) asm volatile("s_waitcnt vmcnt(%0) lgkmcnt(0)" :: "n"(LPS) : "memory");
;     else asm volatile("s_waitcnt vmcnt(0) lgkmcnt(0)" ::: "memory");
;     __builtin_amdgcn_s_barrier();
;     __builtin_amdgcn_s_setprio(1);
;     const char* sb = smem + st * STAGE + foff;
;     bf16x8 af[MI], bfr[NI];
; #pragma unroll
;     for (int mi = 0; mi < MI; ++mi) af[mi] = *(const bf16x8*)(sb + (wr * MI + mi) * 1024);
; #pragma unroll
;     for (int ni = 0; ni < NI; ++ni) bfr[ni] = *(const bf16x8*)(sb + ABYTES + (wc * NI + ni) * 1024);
;     __builtin_amdgcn_sched_barrier(0x0);
;     if (kt + 2 < nk) { const int s2 = st >= 1 ? st - 1 : 2; G256_ISSUE(s2, (kt + 2) * 32); }
;     __builtin_amdgcn_s_setprio(0);
; #pragma unroll
;     for (int mi = 0; mi < MI; ++mi)
; #pragma unroll
;       for (int ni = 0; ni < NI; ++ni)
;         acc[mi][ni] = __builtin_amdgcn_mfma_f32_16x16x32_bf16(bfr[ni], af[mi], acc[mi][ni], 0, 0, 0);
;     st = st == 2 ? 0 : st + 1;
;   }
	v_mov_b32_e32 v26, v2
	v_mov_b32_e32 v27, v2
	v_mov_b32_e32 v28, v2
	v_mov_b32_e32 v29, v2
	v_mov_b32_e32 v30, v2
	v_mov_b32_e32 v31, v2
	v_mov_b32_e32 v32, v2
	v_mov_b32_e32 v33, v2
	v_mov_b32_e32 v34, v2
	v_mov_b32_e32 v35, v2
	v_mov_b32_e32 v36, v2
	v_mov_b32_e32 v37, v2
	v_mov_b32_e32 v38, v2
	v_mov_b32_e32 v39, v2
	v_mov_b32_e32 v40, v2
	v_mov_b32_e32 v41, v2
	v_mov_b32_e32 v42, v2
	v_mov_b32_e32 v43, v2
	v_mov_b32_e32 v44, v2
	v_mov_b32_e32 v45, v2
	v_mov_b32_e32 v46, v2
	v_mov_b32_e32 v47, v2
	v_mov_b32_e32 v48, v2
	v_mov_b32_e32 v49, v2
	v_mov_b32_e32 v50, v2
	v_mov_b32_e32 v51, v2
	v_mov_b32_e32 v52, v2
	v_mov_b32_e32 v53, v2
	v_mov_b32_e32 v54, v2
	v_mov_b32_e32 v55, v2
	v_mov_b32_e32 v56, v2
	v_mov_b32_e32 v57, v2
	v_mov_b32_e32 v58, v2
	v_mov_b32_e32 v59, v2
	v_mov_b32_e32 v60, v2
	v_mov_b32_e32 v61, v2
	v_mov_b32_e32 v62, v2
	v_mov_b32_e32 v63, v2
	v_mov_b32_e32 v64, v2
	v_mov_b32_e32 v65, v2
	v_mov_b32_e32 v66, v2
	v_mov_b32_e32 v67, v2
	v_mov_b32_e32 v68, v2
	v_mov_b32_e32 v69, v2
	v_mov_b32_e32 v70, v2
	v_mov_b32_e32 v71, v2
	v_mov_b32_e32 v72, v2
	v_mov_b32_e32 v73, v2
	v_mov_b32_e32 v74, v2
	v_mov_b32_e32 v75, v2
	v_mov_b32_e32 v76, v2
	v_mov_b32_e32 v77, v2
	v_mov_b32_e32 v78, v2
	v_mov_b32_e32 v79, v2
	v_mov_b32_e32 v80, v2
	v_mov_b32_e32 v81, v2
	v_mov_b32_e32 v82, v2
	v_mov_b32_e32 v83, v2
	v_mov_b32_e32 v84, v2
	v_mov_b32_e32 v85, v2
	v_mov_b32_e32 v86, v2
	v_mov_b32_e32 v87, v2
	v_mov_b32_e32 v88, v2
	v_mov_b32_e32 v89, v2
	v_mov_b32_e32 v90, v2
	v_mov_b32_e32 v91, v2
	v_mov_b32_e32 v92, v2
	v_mov_b32_e32 v93, v2
	v_mov_b32_e32 v94, v2
	v_mov_b32_e32 v95, v2
	v_mov_b32_e32 v96, v2
	v_mov_b32_e32 v97, v2
	v_mov_b32_e32 v98, v2
	v_mov_b32_e32 v99, v2
	v_mov_b32_e32 v100, v2
	v_mov_b32_e32 v101, v2
	v_mov_b32_e32 v102, v2
	v_mov_b32_e32 v103, v2
	v_mov_b32_e32 v104, v2
	v_mov_b32_e32 v105, v2
	v_mov_b32_e32 v106, v2
	v_mov_b32_e32 v107, v2
	v_mov_b32_e32 v108, v2
	v_mov_b32_e32 v109, v2
	v_mov_b32_e32 v110, v2
	v_mov_b32_e32 v111, v2
	v_mov_b32_e32 v112, v2
	v_mov_b32_e32 v113, v2
	v_mov_b32_e32 v114, v2
	v_mov_b32_e32 v115, v2
	v_mov_b32_e32 v116, v2
	v_mov_b32_e32 v117, v2
	v_mov_b32_e32 v118, v2
	v_mov_b32_e32 v119, v2
	v_mov_b32_e32 v120, v2
	v_mov_b32_e32 v121, v2
	v_mov_b32_e32 v122, v2
	v_mov_b32_e32 v123, v2
	v_mov_b32_e32 v124, v2
	v_mov_b32_e32 v125, v2
	v_mov_b32_e32 v126, v2
	v_mov_b32_e32 v127, v2
	v_mov_b32_e32 v128, v2
	v_mov_b32_e32 v129, v2
	s_mov_b64 s[14:15], 0x47e1100
	v_lshl_add_u64 v[196:197], v[132:133], 0, s[14:15]
	s_mov_b64 s[14:15], 0x47e9100
	v_lshl_add_u64 v[198:199], v[132:133], 0, s[14:15]
	s_mov_b64 s[14:15], 0x47f1100
	v_lshl_add_u64 v[200:201], v[132:133], 0, s[14:15]
	s_mov_b64 s[14:15], 0x47f9100
	v_lshl_add_u64 v[202:203], v[132:133], 0, s[14:15]
	s_mov_b64 s[14:15], 0x1661080
	v_lshl_add_u64 v[204:205], v[130:131], 0, s[14:15]
	s_mov_b64 s[14:15], 0x1669080
	v_lshl_add_u64 v[206:207], v[130:131], 0, s[14:15]
	v_bfe_i32 v193, v163, 2, 1
	v_and_b32_e32 v192, 0xfffff840, v193
	v_lshl_add_u64 v[196:197], v[196:197], 0, v[192:193]
	v_lshl_add_u64 v[198:199], v[198:199], 0, v[192:193]
	v_lshl_add_u64 v[200:201], v[200:201], 0, v[192:193]
	v_lshl_add_u64 v[202:203], v[202:203], 0, v[192:193]
	s_mov_b64 s[98:99], 0x80
	v_add_u32_e32 v160, v137, v139
	v_add_u32_e32 v0, v137, v138
	v_readfirstlane_b32 s13, v135
	v_readfirstlane_b32 s4, v136
	s_mov_b32 s12, 0
	s_movk_i32 s5, 29
	s_add_i32 s4, s4, 0x4000
	s_waitcnt vmcnt(6) lgkmcnt(0)
	s_barrier
	ds_read_b128 v[140:143], v160
	ds_read_b128 v[144:147], v160 offset:1024
	ds_read_b128 v[148:151], v160 offset:2048
	ds_read_b128 v[152:155], v160 offset:3072
	ds_read_b128 v[176:179], v0 offset:16384
	ds_read_b128 v[180:183], v0 offset:17408
	ds_read_b128 v[184:187], v0 offset:18432
	ds_read_b128 v[188:191], v0 offset:19456
.Lpipe_wo:
	v_add_u32_e32 v161, s12, v160
	ds_read_b128 v[156:159], v161 offset:4096
	ds_read_b128 v[164:167], v161 offset:5120
	ds_read_b128 v[168:171], v161 offset:6144
	ds_read_b128 v[172:175], v161 offset:7168
	s_add_i32 s14, s12, 0xffffa000
	s_cmp_eq_u32 s12, 0
	s_cselect_b32 s14, 0xc000, s14
	s_add_i32 s15, s14, s13
	s_add_i32 s14, s14, s4
	s_mov_b32 m0, s15
	s_waitcnt lgkmcnt(7)
	v_mfma_f32_16x16x32_bf16 v[126:129], v[176:179], v[140:143], v[126:129]
	global_load_lds_dwordx4 v[196:197], off
	v_mfma_f32_16x16x32_bf16 v[110:113], v[176:179], v[144:147], v[110:113]
	v_lshl_add_u64 v[196:197], v[196:197], 0, s[98:99]
	s_add_i32 m0, s15, 0x400
	v_mfma_f32_16x16x32_bf16 v[94:97], v[176:179], v[148:151], v[94:97]
	global_load_lds_dwordx4 v[198:199], off
	v_mfma_f32_16x16x32_bf16 v[78:81], v[176:179], v[152:155], v[78:81]
	v_lshl_add_u64 v[198:199], v[198:199], 0, s[98:99]
	s_add_i32 m0, s15, 0x800
	s_waitcnt lgkmcnt(6)
	v_mfma_f32_16x16x32_bf16 v[122:125], v[180:183], v[140:143], v[122:125]
	global_load_lds_dwordx4 v[200:201], off
	v_mfma_f32_16x16x32_bf16 v[106:109], v[180:183], v[144:147], v[106:109]
	v_lshl_add_u64 v[200:201], v[200:201], 0, s[98:99]
	s_add_i32 m0, s15, 0xc00
	v_mfma_f32_16x16x32_bf16 v[90:93], v[180:183], v[148:151], v[90:93]
	global_load_lds_dwordx4 v[202:203], off
	v_mfma_f32_16x16x32_bf16 v[74:77], v[180:183], v[152:155], v[74:77]
	v_lshl_add_u64 v[202:203], v[202:203], 0, s[98:99]
	s_mov_b32 m0, s14
	s_waitcnt lgkmcnt(5)
	v_mfma_f32_16x16x32_bf16 v[118:121], v[184:187], v[140:143], v[118:121]
	global_load_lds_dwordx4 v[204:205], off
	v_mfma_f32_16x16x32_bf16 v[102:105], v[184:187], v[144:147], v[102:105]
	v_lshl_add_u64 v[204:205], v[204:205], 0, 64
	s_add_i32 m0, s14, 0x400
	v_mfma_f32_16x16x32_bf16 v[86:89], v[184:187], v[148:151], v[86:89]
	global_load_lds_dwordx4 v[206:207], off
	v_mfma_f32_16x16x32_bf16 v[70:73], v[184:187], v[152:155], v[70:73]
	v_lshl_add_u64 v[206:207], v[206:207], 0, 64
	s_waitcnt lgkmcnt(4)
	v_mfma_f32_16x16x32_bf16 v[114:117], v[188:191], v[140:143], v[114:117]
	v_mfma_f32_16x16x32_bf16 v[98:101], v[188:191], v[144:147], v[98:101]
	v_mfma_f32_16x16x32_bf16 v[82:85], v[188:191], v[148:151], v[82:85]
	v_mfma_f32_16x16x32_bf16 v[66:69], v[188:191], v[152:155], v[66:69]
	s_waitcnt vmcnt(6) lgkmcnt(0)
	s_barrier
; template <int MI, int NI>
; DI void gemm256(f32x4 (&acc)[MI][NI], const u16* __restrict__ A, int lda, const u16* __restrict__ Bt, int ldb, int K, int m0, int n0, char* smem) {
;     ...
;   for (int kt = 0; kt < nk; ++kt) {
;     if (kt + 1 < nk) asm volatile("s_waitcnt vmcnt(%0) lgkmcnt(0)" :: "n"(LPS) : "memory");
;     else asm volatile("s_waitcnt vmcnt(0) lgkmcnt(0)" ::: "memory");
;     __builtin_amdgcn_s_barrier();
;     __builtin_amdgcn_s_setprio(1);
;     const char* sb = smem + st * STAGE + foff;
;     bf16x8 af[MI], bfr[NI];
; #pragma unroll
;     for (int mi = 0; mi < MI; ++mi) af[mi] = *(const bf16x8*)(sb + (wr * MI + mi) * 1024);
; #pragma unroll
;     for (int ni = 0; ni < NI; ++ni) bfr[ni] = *(const bf16x8*)(sb + ABYTES + (wc * NI + ni) * 1024);
;     __builtin_amdgcn_sched_barrier(0x0);
;     if (kt + 2 < nk) { const int s2 = st >= 1 ? st - 1 : 2; G256_ISSUE(s2, (kt + 2) * 32); }
;     __builtin_amdgcn_s_setprio(0);
; #pragma unroll
;     for (int mi = 0; mi < MI; ++mi)
; #pragma unroll
;       for (int ni = 0; ni < NI; ++ni)
;         acc[mi][ni] = __builtin_amdgcn_mfma_f32_16x16x32_bf16(bfr[ni], af[mi], acc[mi][ni], 0, 0, 0);
;     st = st == 2 ? 0 : st + 1;
;   }
	s_add_i32 s15, s12, 0x6000
	s_cmp_eq_u32 s12, 0xc000
	s_cselect_b32 s12, 0, s15
	v_add_u32_e32 v192, s12, v160
	v_add_u32_e32 v193, s12, v0
	v_mfma_f32_16x16x32_bf16 v[62:65], v[176:179], v[156:159], v[62:65]
	ds_read_b128 v[140:143], v192
	v_mfma_f32_16x16x32_bf16 v[46:49], v[176:179], v[164:167], v[46:49]
	ds_read_b128 v[144:147], v192 offset:1024
	v_mfma_f32_16x16x32_bf16 v[30:33], v[176:179], v[168:171], v[30:33]
	ds_read_b128 v[148:151], v192 offset:2048
	v_mfma_f32_16x16x32_bf16 v[14:17], v[176:179], v[172:175], v[14:17]
	ds_read_b128 v[152:155], v192 offset:3072
	ds_read_b128 v[176:179], v193 offset:16384
	v_mfma_f32_16x16x32_bf16 v[58:61], v[180:183], v[156:159], v[58:61]
	v_mfma_f32_16x16x32_bf16 v[42:45], v[180:183], v[164:167], v[42:45]
	v_mfma_f32_16x16x32_bf16 v[26:29], v[180:183], v[168:171], v[26:29]
	v_mfma_f32_16x16x32_bf16 v[10:13], v[180:183], v[172:175], v[10:13]
	ds_read_b128 v[180:183], v193 offset:17408
	v_mfma_f32_16x16x32_bf16 v[54:57], v[184:187], v[156:159], v[54:57]
	v_mfma_f32_16x16x32_bf16 v[38:41], v[184:187], v[164:167], v[38:41]
	v_mfma_f32_16x16x32_bf16 v[22:25], v[184:187], v[168:171], v[22:25]
	v_mfma_f32_16x16x32_bf16 v[6:9], v[184:187], v[172:175], v[6:9]
	ds_read_b128 v[184:187], v193 offset:18432
	v_mfma_f32_16x16x32_bf16 v[50:53], v[188:191], v[156:159], v[50:53]
	v_mfma_f32_16x16x32_bf16 v[34:37], v[188:191], v[164:167], v[34:37]
	v_mfma_f32_16x16x32_bf16 v[18:21], v[188:191], v[168:171], v[18:21]
	v_mfma_f32_16x16x32_bf16 v[2:5], v[188:191], v[172:175], v[2:5]
	ds_read_b128 v[188:191], v193 offset:19456
	s_sub_i32 s5, s5, 1
	s_cmp_lg_u32 s5, 0
	s_cbranch_scc1 .Lpipe_wo
	v_add_u32_e32 v161, s12, v160
	ds_read_b128 v[156:159], v161 offset:4096
	ds_read_b128 v[164:167], v161 offset:5120
	ds_read_b128 v[168:171], v161 offset:6144
	ds_read_b128 v[172:175], v161 offset:7168
	s_add_i32 s14, s12, 0xffffa000
	s_cmp_eq_u32 s12, 0
	s_cselect_b32 s14, 0xc000, s14
	s_add_i32 s15, s14, s13
	s_add_i32 s14, s14, s4
	s_mov_b32 m0, s15
	s_waitcnt lgkmcnt(7)
	v_mfma_f32_16x16x32_bf16 v[126:129], v[176:179], v[140:143], v[126:129]
	global_load_lds_dwordx4 v[196:197], off
	v_mfma_f32_16x16x32_bf16 v[110:113], v[176:179], v[144:147], v[110:113]
	v_lshl_add_u64 v[196:197], v[196:197], 0, s[98:99]
	s_add_i32 m0, s15, 0x400
	v_mfma_f32_16x16x32_bf16 v[94:97], v[176:179], v[148:151], v[94:97]
	global_load_lds_dwordx4 v[198:199], off
	v_mfma_f32_16x16x32_bf16 v[78:81], v[176:179], v[152:155], v[78:81]
	v_lshl_add_u64 v[198:199], v[198:199], 0, s[98:99]
	s_add_i32 m0, s15, 0x800
	s_waitcnt lgkmcnt(6)
	v_mfma_f32_16x16x32_bf16 v[122:125], v[180:183], v[140:143], v[122:125]
	global_load_lds_dwordx4 v[200:201], off
	v_mfma_f32_16x16x32_bf16 v[106:109], v[180:183], v[144:147], v[106:109]
	v_lshl_add_u64 v[200:201], v[200:201], 0, s[98:99]
	s_add_i32 m0, s15, 0xc00
	v_mfma_f32_16x16x32_bf16 v[90:93], v[180:183], v[148:151], v[90:93]
	global_load_lds_dwordx4 v[202:203], off
	v_mfma_f32_16x16x32_bf16 v[74:77], v[180:183], v[152:155], v[74:77]
	v_lshl_add_u64 v[202:203], v[202:203], 0, s[98:99]
	s_mov_b32 m0, s14
	s_waitcnt lgkmcnt(5)
	v_mfma_f32_16x16x32_bf16 v[118:121], v[184:187], v[140:143], v[118:121]
	global_load_lds_dwordx4 v[204:205], off
	v_mfma_f32_16x16x32_bf16 v[102:105], v[184:187], v[144:147], v[102:105]
	v_lshl_add_u64 v[204:205], v[204:205], 0, 64
	s_add_i32 m0, s14, 0x400
	v_mfma_f32_16x16x32_bf16 v[86:89], v[184:187], v[148:151], v[86:89]
	global_load_lds_dwordx4 v[206:207], off
	v_mfma_f32_16x16x32_bf16 v[70:73], v[184:187], v[152:155], v[70:73]
	v_lshl_add_u64 v[206:207], v[206:207], 0, 64
	s_waitcnt lgkmcnt(4)
	v_mfma_f32_16x16x32_bf16 v[114:117], v[188:191], v[140:143], v[114:117]
	v_mfma_f32_16x16x32_bf16 v[98:101], v[188:191], v[144:147], v[98:101]
	v_mfma_f32_16x16x32_bf16 v[82:85], v[188:191], v[148:151], v[82:85]
	v_mfma_f32_16x16x32_bf16 v[66:69], v[188:191], v[152:155], v[66:69]
	s_waitcnt lgkmcnt(0)
	v_mfma_f32_16x16x32_bf16 v[62:65], v[176:179], v[156:159], v[62:65]
	v_mfma_f32_16x16x32_bf16 v[46:49], v[176:179], v[164:167], v[46:49]
	v_mfma_f32_16x16x32_bf16 v[30:33], v[176:179], v[168:171], v[30:33]
	v_mfma_f32_16x16x32_bf16 v[14:17], v[176:179], v[172:175], v[14:17]
	v_mfma_f32_16x16x32_bf16 v[58:61], v[180:183], v[156:159], v[58:61]
	v_mfma_f32_16x16x32_bf16 v[42:45], v[180:183], v[164:167], v[42:45]
	v_mfma_f32_16x16x32_bf16 v[26:29], v[180:183], v[168:171], v[26:29]
	v_mfma_f32_16x16x32_bf16 v[10:13], v[180:183], v[172:175], v[10:13]
	v_mfma_f32_16x16x32_bf16 v[54:57], v[184:187], v[156:159], v[54:57]
	v_mfma_f32_16x16x32_bf16 v[38:41], v[184:187], v[164:167], v[38:41]
	v_mfma_f32_16x16x32_bf16 v[22:25], v[184:187], v[168:171], v[22:25]
	v_mfma_f32_16x16x32_bf16 v[6:9], v[184:187], v[172:175], v[6:9]
	v_mfma_f32_16x16x32_bf16 v[50:53], v[188:191], v[156:159], v[50:53]
	v_mfma_f32_16x16x32_bf16 v[34:37], v[188:191], v[164:167], v[34:37]
	v_mfma_f32_16x16x32_bf16 v[18:21], v[188:191], v[168:171], v[18:21]
	v_mfma_f32_16x16x32_bf16 v[2:5], v[188:191], v[172:175], v[2:5]
	s_waitcnt vmcnt(6) lgkmcnt(0)
	s_barrier
	s_setprio 1
	v_add_u32_e32 v0, v137, v139
	s_waitcnt vmcnt(0)
	ds_read_b128 v[130:133], v0
	ds_read_b128 v[140:143], v0 offset:1024
	ds_read_b128 v[144:147], v0 offset:2048
	ds_read_b128 v[148:151], v0 offset:3072
	ds_read_b128 v[152:155], v0 offset:4096
	ds_read_b128 v[156:159], v0 offset:5120
	ds_read_b128 v[164:167], v0 offset:6144
	ds_read_b128 v[168:171], v0 offset:7168
	v_add_u32_e32 v184, v137, v138
	ds_read_b128 v[136:139], v184 offset:16384
	ds_read_b128 v[172:175], v184 offset:17408
	ds_read_b128 v[176:179], v184 offset:18432
	ds_read_b128 v[180:183], v184 offset:19456
	v_bfe_u32 v188, v134, 6, 1
	s_setprio 0
	s_waitcnt vmcnt(0) lgkmcnt(0)
	s_waitcnt lgkmcnt(3)
	v_mfma_f32_16x16x32_bf16 v[126:129], v[136:139], v[130:133], v[126:129]
	v_ashrrev_i32_e32 v189, 7, v134
	v_and_b32_e32 v190, 15, v134
	v_bfe_u32 v191, v134, 4, 2
	s_waitcnt lgkmcnt(2)
	v_mfma_f32_16x16x32_bf16 v[122:125], v[172:175], v[130:133], v[122:125]
	s_barrier
; template <int MI, int NI>
; DI void gemm256(f32x4 (&acc)[MI][NI], const u16* __restrict__ A, int lda, const u16* __restrict__ Bt, int ldb, int K, int m0, int n0, char* smem) {
;     ...
; #pragma unroll
;     for (int mi = 0; mi < MI; ++mi)
; #pragma unroll
;       for (int ni = 0; ni < NI; ++ni)
;         acc[mi][ni] = __builtin_amdgcn_mfma_f32_16x16x32_bf16(bfr[ni], af[mi], acc[mi][ni], 0, 0, 0);
;     st = st == 2 ? 0 : st + 1;
;   }
; template <int MI, int NI>
; DI void resid_tile(const u16* A, int K, const u16* Bt, const float* gate, const float* xl_in, const float* xc_in, float* xl_out, float* xc_out,
;                    int m0, int n0, char* smem) {
;     ...
; #pragma unroll
;   for (int mi = 0; mi < MI; ++mi) {
;     const int m = m0 + wr * 16 * MI + mi * 16 + lr;
;     const int b9 = m < NTL ? m >> 12 : 8;
;     const float* xi = xrow(xl_in, xc_in, m);
;     float* xo = m < NTL ? xl_out + (size_t)m * D : xc_out + (size_t)(m - NTL) * D;
; #pragma unroll
;     for (int ni = 0; ni < NI; ++ni) {
;       const int n = n0 + wc * 16 * NI + ni * 16 + lq * 4;
;       const float4 g = *(const float4*)(gate + (size_t)b9 * 6144 + n);
;       const float4 xv = *(const float4*)(xi + n);
;       float4 ov;
;       ov.x = xv.x + g.x * acc[mi][ni][0]; ov.y = xv.y + g.y * acc[mi][ni][1]; ov.z = xv.z + g.z * acc[mi][ni][2]; ov.w = xv.w + g.w * acc[mi][ni][3];
;       *(float4*)(xo + n) = ov;
;     }
	s_waitcnt lgkmcnt(1)
	v_mfma_f32_16x16x32_bf16 v[118:121], v[176:179], v[130:133], v[118:121]
	s_waitcnt lgkmcnt(0)
	v_mfma_f32_16x16x32_bf16 v[114:117], v[180:183], v[130:133], v[114:117]
	v_mfma_f32_16x16x32_bf16 v[110:113], v[136:139], v[140:143], v[110:113]
	v_mfma_f32_16x16x32_bf16 v[106:109], v[172:175], v[140:143], v[106:109]
	v_mfma_f32_16x16x32_bf16 v[102:105], v[176:179], v[140:143], v[102:105]
	v_mfma_f32_16x16x32_bf16 v[98:101], v[180:183], v[140:143], v[98:101]
	v_mfma_f32_16x16x32_bf16 v[94:97], v[136:139], v[144:147], v[94:97]
	v_mfma_f32_16x16x32_bf16 v[90:93], v[172:175], v[144:147], v[90:93]
	v_mfma_f32_16x16x32_bf16 v[86:89], v[176:179], v[144:147], v[86:89]
	v_mfma_f32_16x16x32_bf16 v[82:85], v[180:183], v[144:147], v[82:85]
	v_mfma_f32_16x16x32_bf16 v[78:81], v[136:139], v[148:151], v[78:81]
	v_mfma_f32_16x16x32_bf16 v[130:133], v[172:175], v[148:151], v[74:77]
	v_mfma_f32_16x16x32_bf16 v[70:73], v[176:179], v[148:151], v[70:73]
	v_mfma_f32_16x16x32_bf16 v[66:69], v[180:183], v[148:151], v[66:69]
	v_mfma_f32_16x16x32_bf16 v[62:65], v[136:139], v[152:155], v[62:65]
	v_mfma_f32_16x16x32_bf16 v[58:61], v[172:175], v[152:155], v[58:61]
	v_mfma_f32_16x16x32_bf16 v[54:57], v[176:179], v[152:155], v[54:57]
	v_mfma_f32_16x16x32_bf16 v[50:53], v[180:183], v[152:155], v[50:53]
	v_mfma_f32_16x16x32_bf16 v[46:49], v[136:139], v[156:159], v[46:49]
	v_mfma_f32_16x16x32_bf16 v[42:45], v[172:175], v[156:159], v[42:45]
	v_mfma_f32_16x16x32_bf16 v[38:41], v[176:179], v[156:159], v[38:41]
	v_mfma_f32_16x16x32_bf16 v[34:37], v[180:183], v[156:159], v[34:37]
	v_mfma_f32_16x16x32_bf16 v[30:33], v[136:139], v[164:167], v[30:33]
	v_mfma_f32_16x16x32_bf16 v[26:29], v[172:175], v[164:167], v[26:29]
	v_mfma_f32_16x16x32_bf16 v[22:25], v[176:179], v[164:167], v[22:25]
	v_mfma_f32_16x16x32_bf16 v[18:21], v[180:183], v[164:167], v[18:21]
	v_mfma_f32_16x16x32_bf16 v[14:17], v[136:139], v[168:171], v[14:17]
	v_mfma_f32_16x16x32_bf16 v[10:13], v[172:175], v[168:171], v[10:13]
	v_mfma_f32_16x16x32_bf16 v[6:9], v[176:179], v[168:171], v[6:9]
	v_mfma_f32_16x16x32_bf16 v[134:137], v[180:183], v[168:171], v[2:5]
	s_setprio 1
	s_nop 1
	ds_read_b128 v[2:5], v0 offset:24576
	ds_read_b128 v[74:77], v0 offset:25600
	ds_read_b128 v[138:141], v0 offset:26624
	ds_read_b128 v[142:145], v0 offset:27648
	ds_read_b128 v[146:149], v0 offset:28672
	ds_read_b128 v[150:153], v0 offset:29696
	ds_read_b128 v[154:157], v0 offset:30720
	ds_read_b128 v[158:161], v0 offset:31744
	ds_read_b128 v[164:167], v184 offset:40960
	ds_read_b128 v[168:171], v184 offset:41984
	ds_read_b128 v[172:175], v184 offset:43008
	ds_read_b128 v[176:179], v184 offset:44032
	s_setprio 0
	s_waitcnt lgkmcnt(0)
	s_barrier
	v_readlane_b32 s4, v253, 55
	v_lshlrev_b32_e32 v0, 7, v189
	s_waitcnt lgkmcnt(3)
	v_mfma_f32_16x16x32_bf16 v[126:129], v[164:167], v[2:5], v[126:129]
	s_waitcnt lgkmcnt(2)
	v_mfma_f32_16x16x32_bf16 v[122:125], v[168:171], v[2:5], v[122:125]
	s_waitcnt lgkmcnt(1)
	v_mfma_f32_16x16x32_bf16 v[180:183], v[172:175], v[2:5], v[118:121]
	s_waitcnt lgkmcnt(0)
	v_mfma_f32_16x16x32_bf16 v[184:187], v[176:179], v[2:5], v[114:117]
	v_lshlrev_b32_e32 v2, 2, v191
	v_mov_b32_e32 v118, s4
	v_readlane_b32 s4, v253, 53
	v_add3_u32 v116, v190, s10, v0
	v_lshlrev_b32_e32 v0, 6, v188
	v_add3_u32 v2, v2, s11, v0
	v_min_i32_e32 v0, 0x8000, v116
	v_mov_b32_e32 v119, s4
	v_readlane_b32 s4, v253, 56
	v_mfma_f32_16x16x32_bf16 v[110:113], v[164:167], v[74:77], v[110:113]
	v_ashrrev_i32_e32 v117, 31, v116
	v_cmp_gt_i32_e32 vcc, s58, v116
	v_mov_b32_e32 v120, s4
	v_mfma_f32_16x16x32_bf16 v[106:109], v[168:171], v[74:77], v[106:109]
	v_readlane_b32 s4, v253, 54
	v_cndmask_b32_e32 v5, 0, v117, vcc
	v_cndmask_b32_e32 v115, v118, v119, vcc
	v_mfma_f32_16x16x32_bf16 v[102:105], v[172:175], v[74:77], v[102:105]
	v_mov_b32_e32 v121, s4
	v_cndmask_b32_e32 v114, v120, v121, vcc
	v_readlane_b32 s4, v253, 51
	v_mfma_f32_16x16x32_bf16 v[98:101], v[176:179], v[74:77], v[98:101]
	v_ashrrev_i32_e32 v3, 31, v2
	v_readlane_b32 s5, v253, 52
	v_mfma_f32_16x16x32_bf16 v[74:77], v[164:167], v[142:145], v[78:81]
	v_mfma_f32_16x16x32_bf16 v[78:81], v[168:171], v[142:145], v[130:133]
	s_nop 2
	v_ashrrev_i32_e32 v130, 12, v0
	v_add_u32_e32 v0, 0xffff8000, v116
	v_cndmask_b32_e32 v4, v0, v116, vcc
	v_lshlrev_b64 v[4:5], 12, v[4:5]
	v_lshl_add_u64 v[4:5], v[114:115], 0, v[4:5]
	v_mul_hi_i32_i24_e32 v115, 0x6000, v130
	v_mul_i32_i24_e32 v114, 0x6000, v130
	v_lshl_add_u64 v[130:131], s[4:5], 0, v[114:115]
	v_lshlrev_b64 v[114:115], 2, v[2:3]
	v_mfma_f32_16x16x32_bf16 v[94:97], v[164:167], v[138:141], v[94:97]
	v_mfma_f32_16x16x32_bf16 v[90:93], v[168:171], v[138:141], v[90:93]
	v_mfma_f32_16x16x32_bf16 v[86:89], v[172:175], v[138:141], v[86:89]
	v_mfma_f32_16x16x32_bf16 v[82:85], v[176:179], v[138:141], v[82:85]
	v_lshl_add_u64 v[138:139], v[130:131], 0, v[114:115]
	v_lshl_add_u64 v[140:141], v[4:5], 0, v[114:115]
	flat_load_dwordx4 v[2:5], v[138:139]
	flat_load_dwordx4 v[130:133], v[140:141]
	v_mfma_f32_16x16x32_bf16 v[70:73], v[172:175], v[142:145], v[70:73]
	s_waitcnt vmcnt(0) lgkmcnt(0)
	v_pk_fma_f32 v[2:3], v[126:127], v[2:3], v[130:131]
	v_mfma_f32_16x16x32_bf16 v[66:69], v[176:179], v[142:145], v[66:69]
	v_lshlrev_b64 v[142:143], 12, v[116:117]
	v_lshlrev_b64 v[144:145], 12, v[0:1]
	v_lshl_add_u64 v[142:143], s[48:49], 0, v[142:143]
	v_lshl_add_u64 v[144:145], s[94:95], 0, v[144:145]
	v_cndmask_b32_e32 v143, v145, v143, vcc
	v_cndmask_b32_e32 v142, v144, v142, vcc
	v_lshl_add_u64 v[142:143], v[142:143], 0, v[114:115]
	v_pk_fma_f32 v[4:5], v[128:129], v[4:5], v[132:133]
	flat_store_dwordx4 v[142:143], v[2:5]
	flat_load_dwordx4 v[126:129], v[138:139] offset:64
	flat_load_dwordx4 v[130:133], v[140:141] offset:64
	v_mfma_f32_16x16x32_bf16 v[2:5], v[168:171], v[158:161], v[10:13]
	v_mfma_f32_16x16x32_bf16 v[62:65], v[164:167], v[146:149], v[62:65]
	s_waitcnt vmcnt(0) lgkmcnt(0)
; template <int MI, int NI>
; DI void resid_tile(const u16* A, int K, const u16* Bt, const float* gate, const float* xl_in, const float* xc_in, float* xl_out, float* xc_out,
;                    int m0, int n0, char* smem) {
;     ...
; #pragma unroll
;   for (int mi = 0; mi < MI; ++mi) {
;     const int m = m0 + wr * 16 * MI + mi * 16 + lr;
;     const int b9 = m < NTL ? m >> 12 : 8;
;     const float* xi = xrow(xl_in, xc_in, m);
;     float* xo = m < NTL ? xl_out + (size_t)m * D : xc_out + (size_t)(m - NTL) * D;
; #pragma unroll
;     for (int ni = 0; ni < NI; ++ni) {
;       const int n = n0 + wc * 16 * NI + ni * 16 + lq * 4;
;       const float4 g = *(const float4*)(gate + (size_t)b9 * 6144 + n);
;       const float4 xv = *(const float4*)(xi + n);
;       float4 ov;
;       ov.x = xv.x + g.x * acc[mi][ni][0]; ov.y = xv.y + g.y * acc[mi][ni][1]; ov.z = xv.z + g.z * acc[mi][ni][2]; ov.w = xv.w + g.w * acc[mi][ni][3];
;       *(float4*)(xo + n) = ov;
;     }
;     __builtin_amdgcn_sched_barrier(0);
;   }
	s_nop 0
	v_pk_fma_f32 v[10:11], v[122:123], v[126:127], v[130:131]
	v_pk_fma_f32 v[12:13], v[124:125], v[128:129], v[132:133]
	flat_store_dwordx4 v[142:143], v[10:13] offset:64
	flat_load_dwordx4 v[10:13], v[138:139] offset:128
	s_nop 0
	flat_load_dwordx4 v[122:125], v[140:141] offset:128
	v_mfma_f32_16x16x32_bf16 v[58:61], v[168:171], v[146:149], v[58:61]
	s_waitcnt vmcnt(0) lgkmcnt(0)
	v_pk_fma_f32 v[10:11], v[180:181], v[10:11], v[122:123]
	v_pk_fma_f32 v[12:13], v[182:183], v[12:13], v[124:125]
	flat_store_dwordx4 v[142:143], v[10:13] offset:128
	flat_load_dwordx4 v[122:125], v[138:139] offset:192
	flat_load_dwordx4 v[126:129], v[140:141] offset:192
	v_mfma_f32_16x16x32_bf16 v[54:57], v[172:175], v[146:149], v[54:57]
	s_waitcnt vmcnt(0) lgkmcnt(0)
	v_pk_fma_f32 v[122:123], v[184:185], v[122:123], v[126:127]
	v_pk_fma_f32 v[124:125], v[186:187], v[124:125], v[128:129]
	v_mfma_f32_16x16x32_bf16 v[50:53], v[176:179], v[146:149], v[50:53]
	flat_store_dwordx4 v[142:143], v[122:125] offset:192
	v_mfma_f32_16x16x32_bf16 v[46:49], v[164:167], v[150:153], v[46:49]
	v_mfma_f32_16x16x32_bf16 v[42:45], v[168:171], v[150:153], v[42:45]
	v_mfma_f32_16x16x32_bf16 v[38:41], v[172:175], v[150:153], v[38:41]
	v_mfma_f32_16x16x32_bf16 v[34:37], v[176:179], v[150:153], v[34:37]
	v_mfma_f32_16x16x32_bf16 v[30:33], v[164:167], v[154:157], v[30:33]
	v_mfma_f32_16x16x32_bf16 v[26:29], v[168:171], v[154:157], v[26:29]
	v_mfma_f32_16x16x32_bf16 v[22:25], v[172:175], v[154:157], v[22:25]
	v_mfma_f32_16x16x32_bf16 v[18:21], v[176:179], v[154:157], v[18:21]
	v_mfma_f32_16x16x32_bf16 v[14:17], v[164:167], v[158:161], v[14:17]
	v_mfma_f32_16x16x32_bf16 v[6:9], v[172:175], v[158:161], v[6:9]
	v_mfma_f32_16x16x32_bf16 v[10:13], v[176:179], v[158:161], v[134:137]
	v_add_u32_e32 v122, 16, v116
	v_min_i32_e32 v0, 0x8000, v122
	v_cmp_gt_i32_e32 vcc, s58, v122
	v_ashrrev_i32_e32 v117, 12, v0
	v_add_u32_e32 v0, 0xffff8010, v116
	v_ashrrev_i32_e32 v123, 31, v122
	v_cndmask_b32_e32 v125, 0, v123, vcc
	v_cndmask_b32_e32 v124, v0, v122, vcc
	v_cndmask_b32_e32 v127, v118, v119, vcc
	v_cndmask_b32_e32 v126, v120, v121, vcc
	v_lshlrev_b64 v[124:125], 12, v[124:125]
	v_lshl_add_u64 v[124:125], v[126:127], 0, v[124:125]
	v_lshlrev_b64 v[122:123], 12, v[122:123]
	v_lshlrev_b64 v[126:127], 12, v[0:1]
	v_lshl_add_u64 v[122:123], s[48:49], 0, v[122:123]
	v_lshl_add_u64 v[126:127], s[94:95], 0, v[126:127]
	v_cndmask_b32_e32 v123, v127, v123, vcc
	v_cndmask_b32_e32 v122, v126, v122, vcc
	v_mul_hi_i32_i24_e32 v127, 0x6000, v117
	v_mul_i32_i24_e32 v126, 0x6000, v117
	v_lshl_add_u64 v[126:127], s[4:5], 0, v[126:127]
	v_lshl_add_u64 v[130:131], v[126:127], 0, v[114:115]
	v_lshl_add_u64 v[132:133], v[124:125], 0, v[114:115]
	v_lshl_add_u64 v[134:135], v[122:123], 0, v[114:115]
	flat_load_dwordx4 v[122:125], v[130:131]
	flat_load_dwordx4 v[126:129], v[132:133]
	s_waitcnt vmcnt(0) lgkmcnt(0)
	v_pk_fma_f32 v[110:111], v[110:111], v[122:123], v[126:127]
	v_pk_fma_f32 v[112:113], v[112:113], v[124:125], v[128:129]
	flat_store_dwordx4 v[134:135], v[110:113]
	flat_load_dwordx4 v[110:113], v[130:131] offset:64
	s_nop 0
	flat_load_dwordx4 v[122:125], v[132:133] offset:64
	s_waitcnt vmcnt(0) lgkmcnt(0)
	v_pk_fma_f32 v[106:107], v[106:107], v[110:111], v[122:123]
	v_pk_fma_f32 v[108:109], v[108:109], v[112:113], v[124:125]
	flat_store_dwordx4 v[134:135], v[106:109] offset:64
	flat_load_dwordx4 v[106:109], v[130:131] offset:128
	s_nop 0
	flat_load_dwordx4 v[110:113], v[132:133] offset:128
	s_waitcnt vmcnt(0) lgkmcnt(0)
	v_pk_fma_f32 v[102:103], v[102:103], v[106:107], v[110:111]
	v_pk_fma_f32 v[104:105], v[104:105], v[108:109], v[112:113]
	flat_store_dwordx4 v[134:135], v[102:105] offset:128
	flat_load_dwordx4 v[102:105], v[130:131] offset:192
	s_nop 0
	flat_load_dwordx4 v[106:109], v[132:133] offset:192
	s_waitcnt vmcnt(0) lgkmcnt(0)
	v_pk_fma_f32 v[98:99], v[98:99], v[102:103], v[106:107]
	v_pk_fma_f32 v[100:101], v[100:101], v[104:105], v[108:109]
	flat_store_dwordx4 v[134:135], v[98:101] offset:192
	s_nop 1
	v_add_u32_e32 v98, 32, v116
	v_min_i32_e32 v0, 0x8000, v98
	v_cmp_gt_i32_e32 vcc, s58, v98
	v_ashrrev_i32_e32 v104, 12, v0
	v_add_u32_e32 v0, 0xffff8020, v116
	v_ashrrev_i32_e32 v99, 31, v98
	v_cndmask_b32_e32 v101, 0, v99, vcc
	v_cndmask_b32_e32 v100, v0, v98, vcc
	v_cndmask_b32_e32 v103, v118, v119, vcc
	v_cndmask_b32_e32 v102, v120, v121, vcc
	v_lshlrev_b64 v[100:101], 12, v[100:101]
	v_lshl_add_u64 v[100:101], v[102:103], 0, v[100:101]
	v_lshlrev_b64 v[98:99], 12, v[98:99]
	v_lshlrev_b64 v[102:103], 12, v[0:1]
	v_lshl_add_u64 v[98:99], s[48:49], 0, v[98:99]
	v_lshl_add_u64 v[102:103], s[94:95], 0, v[102:103]
	v_cndmask_b32_e32 v99, v103, v99, vcc
	v_cndmask_b32_e32 v98, v102, v98, vcc
	v_mul_hi_i32_i24_e32 v103, 0x6000, v104
	v_mul_i32_i24_e32 v102, 0x6000, v104
	v_lshl_add_u64 v[102:103], s[4:5], 0, v[102:103]
	v_lshl_add_u64 v[106:107], v[102:103], 0, v[114:115]
	v_lshl_add_u64 v[108:109], v[100:101], 0, v[114:115]
	v_lshl_add_u64 v[110:111], v[98:99], 0, v[114:115]
	flat_load_dwordx4 v[98:101], v[106:107]
	flat_load_dwordx4 v[102:105], v[108:109]
	s_waitcnt vmcnt(0) lgkmcnt(0)
	v_pk_fma_f32 v[94:95], v[94:95], v[98:99], v[102:103]
	v_pk_fma_f32 v[96:97], v[96:97], v[100:101], v[104:105]
	flat_store_dwordx4 v[110:111], v[94:97]
	flat_load_dwordx4 v[94:97], v[106:107] offset:64
	s_nop 0
	flat_load_dwordx4 v[98:101], v[108:109] offset:64
	s_waitcnt vmcnt(0) lgkmcnt(0)
	v_pk_fma_f32 v[90:91], v[90:91], v[94:95], v[98:99]
	v_pk_fma_f32 v[92:93], v[92:93], v[96:97], v[100:101]
	flat_store_dwordx4 v[110:111], v[90:93] offset:64
	flat_load_dwordx4 v[90:93], v[106:107] offset:128
	s_nop 0
	flat_load_dwordx4 v[94:97], v[108:109] offset:128
	s_waitcnt vmcnt(0) lgkmcnt(0)
; template <int MI, int NI>
; DI void resid_tile(const u16* A, int K, const u16* Bt, const float* gate, const float* xl_in, const float* xc_in, float* xl_out, float* xc_out,
;                    int m0, int n0, char* smem) {
;     ...
; #pragma unroll
;   for (int mi = 0; mi < MI; ++mi) {
;     const int m = m0 + wr * 16 * MI + mi * 16 + lr;
;     const int b9 = m < NTL ? m >> 12 : 8;
;     const float* xi = xrow(xl_in, xc_in, m);
;     float* xo = m < NTL ? xl_out + (size_t)m * D : xc_out + (size_t)(m - NTL) * D;
; #pragma unroll
;     for (int ni = 0; ni < NI; ++ni) {
;       const int n = n0 + wc * 16 * NI + ni * 16 + lq * 4;
;       const float4 g = *(const float4*)(gate + (size_t)b9 * 6144 + n);
;       const float4 xv = *(const float4*)(xi + n);
;       float4 ov;
;       ov.x = xv.x + g.x * acc[mi][ni][0]; ov.y = xv.y + g.y * acc[mi][ni][1]; ov.z = xv.z + g.z * acc[mi][ni][2]; ov.w = xv.w + g.w * acc[mi][ni][3];
;       *(float4*)(xo + n) = ov;
;     }
;     __builtin_amdgcn_sched_barrier(0);
;   }
	v_pk_fma_f32 v[86:87], v[86:87], v[90:91], v[94:95]
	v_pk_fma_f32 v[88:89], v[88:89], v[92:93], v[96:97]
	flat_store_dwordx4 v[110:111], v[86:89] offset:128
	flat_load_dwordx4 v[86:89], v[106:107] offset:192
	s_nop 0
	flat_load_dwordx4 v[90:93], v[108:109] offset:192
	s_waitcnt vmcnt(0) lgkmcnt(0)
	v_pk_fma_f32 v[82:83], v[82:83], v[86:87], v[90:91]
	v_pk_fma_f32 v[84:85], v[84:85], v[88:89], v[92:93]
	flat_store_dwordx4 v[110:111], v[82:85] offset:192
	s_nop 1
	v_add_u32_e32 v82, 48, v116
	v_min_i32_e32 v0, 0x8000, v82
	v_cmp_gt_i32_e32 vcc, s58, v82
	v_ashrrev_i32_e32 v88, 12, v0
	v_add_u32_e32 v0, 0xffff8030, v116
	v_ashrrev_i32_e32 v83, 31, v82
	v_cndmask_b32_e32 v85, 0, v83, vcc
	v_cndmask_b32_e32 v84, v0, v82, vcc
	v_cndmask_b32_e32 v87, v118, v119, vcc
	v_cndmask_b32_e32 v86, v120, v121, vcc
	v_lshlrev_b64 v[84:85], 12, v[84:85]
	v_lshl_add_u64 v[84:85], v[86:87], 0, v[84:85]
	v_lshlrev_b64 v[82:83], 12, v[82:83]
	v_lshlrev_b64 v[86:87], 12, v[0:1]
	v_lshl_add_u64 v[82:83], s[48:49], 0, v[82:83]
	v_lshl_add_u64 v[86:87], s[94:95], 0, v[86:87]
	v_cndmask_b32_e32 v83, v87, v83, vcc
	v_cndmask_b32_e32 v82, v86, v82, vcc
	v_mul_hi_i32_i24_e32 v87, 0x6000, v88
	v_mul_i32_i24_e32 v86, 0x6000, v88
	v_lshl_add_u64 v[86:87], s[4:5], 0, v[86:87]
	v_lshl_add_u64 v[90:91], v[86:87], 0, v[114:115]
	v_lshl_add_u64 v[92:93], v[84:85], 0, v[114:115]
	v_lshl_add_u64 v[94:95], v[82:83], 0, v[114:115]
	flat_load_dwordx4 v[82:85], v[90:91]
	flat_load_dwordx4 v[86:89], v[92:93]
	s_waitcnt vmcnt(0) lgkmcnt(0)
	v_pk_fma_f32 v[74:75], v[74:75], v[82:83], v[86:87]
	v_pk_fma_f32 v[76:77], v[76:77], v[84:85], v[88:89]
	flat_store_dwordx4 v[94:95], v[74:77]
	flat_load_dwordx4 v[74:77], v[90:91] offset:64
	s_nop 0
	flat_load_dwordx4 v[82:85], v[92:93] offset:64
	s_waitcnt vmcnt(0) lgkmcnt(0)
	v_pk_fma_f32 v[74:75], v[78:79], v[74:75], v[82:83]
	v_pk_fma_f32 v[76:77], v[80:81], v[76:77], v[84:85]
	flat_store_dwordx4 v[94:95], v[74:77] offset:64
	flat_load_dwordx4 v[74:77], v[90:91] offset:128
	s_nop 0
	flat_load_dwordx4 v[78:81], v[92:93] offset:128
	s_waitcnt vmcnt(0) lgkmcnt(0)
	v_pk_fma_f32 v[70:71], v[70:71], v[74:75], v[78:79]
	v_pk_fma_f32 v[72:73], v[72:73], v[76:77], v[80:81]
	flat_store_dwordx4 v[94:95], v[70:73] offset:128
	flat_load_dwordx4 v[70:73], v[90:91] offset:192
	s_nop 0
	flat_load_dwordx4 v[74:77], v[92:93] offset:192
	s_waitcnt vmcnt(0) lgkmcnt(0)
	v_pk_fma_f32 v[66:67], v[66:67], v[70:71], v[74:75]
	v_pk_fma_f32 v[68:69], v[68:69], v[72:73], v[76:77]
	flat_store_dwordx4 v[94:95], v[66:69] offset:192
	s_nop 1
	v_add_u32_e32 v66, 64, v116
	v_min_i32_e32 v0, 0x8000, v66
	v_cmp_gt_i32_e32 vcc, s58, v66
	v_ashrrev_i32_e32 v72, 12, v0
	v_add_u32_e32 v0, 0xffff8040, v116
	v_ashrrev_i32_e32 v67, 31, v66
	v_cndmask_b32_e32 v69, 0, v67, vcc
	v_cndmask_b32_e32 v68, v0, v66, vcc
	v_cndmask_b32_e32 v71, v118, v119, vcc
	v_cndmask_b32_e32 v70, v120, v121, vcc
	v_lshlrev_b64 v[68:69], 12, v[68:69]
	v_lshl_add_u64 v[68:69], v[70:71], 0, v[68:69]
	v_lshlrev_b64 v[66:67], 12, v[66:67]
	v_lshlrev_b64 v[70:71], 12, v[0:1]
	v_lshl_add_u64 v[66:67], s[48:49], 0, v[66:67]
	v_lshl_add_u64 v[70:71], s[94:95], 0, v[70:71]
	v_cndmask_b32_e32 v67, v71, v67, vcc
	v_cndmask_b32_e32 v66, v70, v66, vcc
	v_mul_hi_i32_i24_e32 v71, 0x6000, v72
	v_mul_i32_i24_e32 v70, 0x6000, v72
	v_lshl_add_u64 v[70:71], s[4:5], 0, v[70:71]
	v_lshl_add_u64 v[74:75], v[70:71], 0, v[114:115]
	v_lshl_add_u64 v[76:77], v[68:69], 0, v[114:115]
	v_lshl_add_u64 v[78:79], v[66:67], 0, v[114:115]
	flat_load_dwordx4 v[66:69], v[74:75]
	flat_load_dwordx4 v[70:73], v[76:77]
	s_waitcnt vmcnt(0) lgkmcnt(0)
	v_pk_fma_f32 v[62:63], v[62:63], v[66:67], v[70:71]
	v_pk_fma_f32 v[64:65], v[64:65], v[68:69], v[72:73]
	flat_store_dwordx4 v[78:79], v[62:65]
	flat_load_dwordx4 v[62:65], v[74:75] offset:64
	s_nop 0
	flat_load_dwordx4 v[66:69], v[76:77] offset:64
	s_waitcnt vmcnt(0) lgkmcnt(0)
	v_pk_fma_f32 v[58:59], v[58:59], v[62:63], v[66:67]
	v_pk_fma_f32 v[60:61], v[60:61], v[64:65], v[68:69]
	flat_store_dwordx4 v[78:79], v[58:61] offset:64
	flat_load_dwordx4 v[58:61], v[74:75] offset:128
	s_nop 0
	flat_load_dwordx4 v[62:65], v[76:77] offset:128
	s_waitcnt vmcnt(0) lgkmcnt(0)
	v_pk_fma_f32 v[54:55], v[54:55], v[58:59], v[62:63]
	v_pk_fma_f32 v[56:57], v[56:57], v[60:61], v[64:65]
	flat_store_dwordx4 v[78:79], v[54:57] offset:128
	flat_load_dwordx4 v[54:57], v[74:75] offset:192
	s_nop 0
	flat_load_dwordx4 v[58:61], v[76:77] offset:192
	s_waitcnt vmcnt(0) lgkmcnt(0)
	v_pk_fma_f32 v[50:51], v[50:51], v[54:55], v[58:59]
	v_pk_fma_f32 v[52:53], v[52:53], v[56:57], v[60:61]
	flat_store_dwordx4 v[78:79], v[50:53] offset:192
	s_nop 1
	v_add_u32_e32 v50, 0x50, v116
	v_min_i32_e32 v0, 0x8000, v50
	v_cmp_gt_i32_e32 vcc, s58, v50
	v_ashrrev_i32_e32 v56, 12, v0
	v_add_u32_e32 v0, 0xffff8050, v116
	v_ashrrev_i32_e32 v51, 31, v50
	v_cndmask_b32_e32 v53, 0, v51, vcc
	v_cndmask_b32_e32 v52, v0, v50, vcc
	v_cndmask_b32_e32 v55, v118, v119, vcc
	v_cndmask_b32_e32 v54, v120, v121, vcc
	v_lshlrev_b64 v[52:53], 12, v[52:53]
	v_lshl_add_u64 v[52:53], v[54:55], 0, v[52:53]
	v_lshlrev_b64 v[50:51], 12, v[50:51]
	v_lshlrev_b64 v[54:55], 12, v[0:1]
	v_lshl_add_u64 v[50:51], s[48:49], 0, v[50:51]
	v_lshl_add_u64 v[54:55], s[94:95], 0, v[54:55]
	v_cndmask_b32_e32 v51, v55, v51, vcc
	v_cndmask_b32_e32 v50, v54, v50, vcc
	v_mul_hi_i32_i24_e32 v55, 0x6000, v56
	v_mul_i32_i24_e32 v54, 0x6000, v56
	v_lshl_add_u64 v[54:55], s[4:5], 0, v[54:55]
	v_lshl_add_u64 v[58:59], v[54:55], 0, v[114:115]
	v_lshl_add_u64 v[60:61], v[52:53], 0, v[114:115]
	v_lshl_add_u64 v[62:63], v[50:51], 0, v[114:115]
	flat_load_dwordx4 v[50:53], v[58:59]
	flat_load_dwordx4 v[54:57], v[60:61]
	s_waitcnt vmcnt(0) lgkmcnt(0)
; #define LAUNDER_IDS const int tid__ = launder_v((int)threadIdx.x); const int blk__ = launder_s((int)blockIdx.x); (void)tid__; (void)blk__;
; template <int MI, int NI>
; DI void resid_tile(const u16* A, int K, const u16* Bt, const float* gate, const float* xl_in, const float* xc_in, float* xl_out, float* xc_out,
;                    int m0, int n0, char* smem) {
;     ...
; #pragma unroll
;   for (int mi = 0; mi < MI; ++mi) {
;     const int m = m0 + wr * 16 * MI + mi * 16 + lr;
;     const int b9 = m < NTL ? m >> 12 : 8;
;     const float* xi = xrow(xl_in, xc_in, m);
;     float* xo = m < NTL ? xl_out + (size_t)m * D : xc_out + (size_t)(m - NTL) * D;
; #pragma unroll
;     for (int ni = 0; ni < NI; ++ni) {
;       const int n = n0 + wc * 16 * NI + ni * 16 + lq * 4;
;       const float4 g = *(const float4*)(gate + (size_t)b9 * 6144 + n);
;       const float4 xv = *(const float4*)(xi + n);
;       float4 ov;
;       ov.x = xv.x + g.x * acc[mi][ni][0]; ov.y = xv.y + g.y * acc[mi][ni][1]; ov.z = xv.z + g.z * acc[mi][ni][2]; ov.w = xv.w + g.w * acc[mi][ni][3];
;       *(float4*)(xo + n) = ov;
;     }
;     __builtin_amdgcn_sched_barrier(0);
;   }
;   EPI_END
; }
; DI void phase_resid(const Params& p, const u16* A, int K, const u16* Bt, const float* gate  ,
;                     const float* xl_in, const float* xc_in, float* xl_out, float* xc_out, int Mout, char* smem) {
;   LAUNDER_IDS
;   for (int it = 0;; ++it) {
;     int tm, tn;
;     if (!tile_map(it, NTL / 256, 8, blk__, gridDim.x, tm, tn)) break;
;     resid_tile<8, 4>(A, K, Bt, gate, xl_in, xc_in, xl_out, xc_out, tm * 256, tn * 128, smem);
;   }
	v_pk_fma_f32 v[46:47], v[46:47], v[50:51], v[54:55]
	v_pk_fma_f32 v[48:49], v[48:49], v[52:53], v[56:57]
	flat_store_dwordx4 v[62:63], v[46:49]
	flat_load_dwordx4 v[46:49], v[58:59] offset:64
	s_nop 0
	flat_load_dwordx4 v[50:53], v[60:61] offset:64
	s_waitcnt vmcnt(0) lgkmcnt(0)
	v_pk_fma_f32 v[42:43], v[42:43], v[46:47], v[50:51]
	v_pk_fma_f32 v[44:45], v[44:45], v[48:49], v[52:53]
	flat_store_dwordx4 v[62:63], v[42:45] offset:64
	flat_load_dwordx4 v[42:45], v[58:59] offset:128
	s_nop 0
	flat_load_dwordx4 v[46:49], v[60:61] offset:128
	s_waitcnt vmcnt(0) lgkmcnt(0)
	v_pk_fma_f32 v[38:39], v[38:39], v[42:43], v[46:47]
	v_pk_fma_f32 v[40:41], v[40:41], v[44:45], v[48:49]
	flat_store_dwordx4 v[62:63], v[38:41] offset:128
	flat_load_dwordx4 v[38:41], v[58:59] offset:192
	s_nop 0
	flat_load_dwordx4 v[42:45], v[60:61] offset:192
	s_waitcnt vmcnt(0) lgkmcnt(0)
	v_pk_fma_f32 v[34:35], v[34:35], v[38:39], v[42:43]
	v_pk_fma_f32 v[36:37], v[36:37], v[40:41], v[44:45]
	flat_store_dwordx4 v[62:63], v[34:37] offset:192
	s_nop 1
	v_add_u32_e32 v34, 0x60, v116
	v_min_i32_e32 v0, 0x8000, v34
	v_cmp_gt_i32_e32 vcc, s58, v34
	v_ashrrev_i32_e32 v40, 12, v0
	v_add_u32_e32 v0, 0xffff8060, v116
	v_ashrrev_i32_e32 v35, 31, v34
	v_cndmask_b32_e32 v37, 0, v35, vcc
	v_cndmask_b32_e32 v36, v0, v34, vcc
	v_cndmask_b32_e32 v39, v118, v119, vcc
	v_cndmask_b32_e32 v38, v120, v121, vcc
	v_lshlrev_b64 v[36:37], 12, v[36:37]
	v_lshl_add_u64 v[36:37], v[38:39], 0, v[36:37]
	v_lshlrev_b64 v[34:35], 12, v[34:35]
	v_lshlrev_b64 v[38:39], 12, v[0:1]
	v_lshl_add_u64 v[34:35], s[48:49], 0, v[34:35]
	v_lshl_add_u64 v[38:39], s[94:95], 0, v[38:39]
	v_cndmask_b32_e32 v35, v39, v35, vcc
	v_cndmask_b32_e32 v34, v38, v34, vcc
	v_mul_hi_i32_i24_e32 v39, 0x6000, v40
	v_mul_i32_i24_e32 v38, 0x6000, v40
	v_lshl_add_u64 v[38:39], s[4:5], 0, v[38:39]
	v_lshl_add_u64 v[42:43], v[38:39], 0, v[114:115]
	v_lshl_add_u64 v[44:45], v[36:37], 0, v[114:115]
	v_lshl_add_u64 v[46:47], v[34:35], 0, v[114:115]
	flat_load_dwordx4 v[34:37], v[42:43]
	flat_load_dwordx4 v[38:41], v[44:45]
	s_waitcnt vmcnt(0) lgkmcnt(0)
	v_pk_fma_f32 v[30:31], v[30:31], v[34:35], v[38:39]
	v_pk_fma_f32 v[32:33], v[32:33], v[36:37], v[40:41]
	flat_store_dwordx4 v[46:47], v[30:33]
	flat_load_dwordx4 v[30:33], v[42:43] offset:64
	s_nop 0
	flat_load_dwordx4 v[34:37], v[44:45] offset:64
	s_waitcnt vmcnt(0) lgkmcnt(0)
	v_pk_fma_f32 v[26:27], v[26:27], v[30:31], v[34:35]
	v_pk_fma_f32 v[28:29], v[28:29], v[32:33], v[36:37]
	flat_store_dwordx4 v[46:47], v[26:29] offset:64
	flat_load_dwordx4 v[26:29], v[42:43] offset:128
	s_nop 0
	flat_load_dwordx4 v[30:33], v[44:45] offset:128
	s_waitcnt vmcnt(0) lgkmcnt(0)
	v_pk_fma_f32 v[22:23], v[22:23], v[26:27], v[30:31]
	v_pk_fma_f32 v[24:25], v[24:25], v[28:29], v[32:33]
	flat_store_dwordx4 v[46:47], v[22:25] offset:128
	flat_load_dwordx4 v[22:25], v[42:43] offset:192
	s_nop 0
	flat_load_dwordx4 v[26:29], v[44:45] offset:192
	s_waitcnt vmcnt(0) lgkmcnt(0)
	v_pk_fma_f32 v[18:19], v[18:19], v[22:23], v[26:27]
	v_pk_fma_f32 v[20:21], v[20:21], v[24:25], v[28:29]
	flat_store_dwordx4 v[46:47], v[18:21] offset:192
	s_nop 1
	v_add_u32_e32 v18, 0x70, v116
	v_min_i32_e32 v0, 0x8000, v18
	v_cmp_gt_i32_e32 vcc, s58, v18
	v_ashrrev_i32_e32 v24, 12, v0
	v_add_u32_e32 v0, 0xffff8070, v116
	v_ashrrev_i32_e32 v19, 31, v18
	v_cndmask_b32_e32 v21, 0, v19, vcc
	v_cndmask_b32_e32 v20, v0, v18, vcc
	v_cndmask_b32_e32 v23, v118, v119, vcc
	v_cndmask_b32_e32 v22, v120, v121, vcc
	v_lshlrev_b64 v[20:21], 12, v[20:21]
	v_lshl_add_u64 v[20:21], v[22:23], 0, v[20:21]
	v_lshlrev_b64 v[18:19], 12, v[18:19]
	v_lshlrev_b64 v[22:23], 12, v[0:1]
	v_lshl_add_u64 v[18:19], s[48:49], 0, v[18:19]
	v_lshl_add_u64 v[22:23], s[94:95], 0, v[22:23]
	v_cndmask_b32_e32 v19, v23, v19, vcc
	v_cndmask_b32_e32 v18, v22, v18, vcc
	v_mul_hi_i32_i24_e32 v23, 0x6000, v24
	v_mul_i32_i24_e32 v22, 0x6000, v24
	v_lshl_add_u64 v[22:23], s[4:5], 0, v[22:23]
	v_lshl_add_u64 v[26:27], v[22:23], 0, v[114:115]
	v_lshl_add_u64 v[28:29], v[20:21], 0, v[114:115]
	v_lshl_add_u64 v[30:31], v[18:19], 0, v[114:115]
	flat_load_dwordx4 v[18:21], v[26:27]
	flat_load_dwordx4 v[22:25], v[28:29]
	s_waitcnt vmcnt(0) lgkmcnt(0)
	v_pk_fma_f32 v[14:15], v[14:15], v[18:19], v[22:23]
	v_pk_fma_f32 v[16:17], v[16:17], v[20:21], v[24:25]
	flat_store_dwordx4 v[30:31], v[14:17]
	flat_load_dwordx4 v[14:17], v[26:27] offset:64
	s_nop 0
	flat_load_dwordx4 v[18:21], v[28:29] offset:64
	s_waitcnt vmcnt(0) lgkmcnt(0)
	v_pk_fma_f32 v[2:3], v[2:3], v[14:15], v[18:19]
	v_pk_fma_f32 v[4:5], v[4:5], v[16:17], v[20:21]
	flat_store_dwordx4 v[30:31], v[2:5] offset:64
	flat_load_dwordx4 v[2:5], v[26:27] offset:128
	s_nop 0
	flat_load_dwordx4 v[14:17], v[28:29] offset:128
	s_waitcnt vmcnt(0) lgkmcnt(0)
	v_pk_fma_f32 v[2:3], v[6:7], v[2:3], v[14:15]
	v_pk_fma_f32 v[4:5], v[8:9], v[4:5], v[16:17]
	flat_store_dwordx4 v[30:31], v[2:5] offset:128
	flat_load_dwordx4 v[2:5], v[26:27] offset:192
	s_nop 0
	flat_load_dwordx4 v[6:9], v[28:29] offset:192
	s_waitcnt vmcnt(0) lgkmcnt(0)
	v_pk_fma_f32 v[2:3], v[10:11], v[2:3], v[6:7]
	v_pk_fma_f32 v[4:5], v[12:13], v[4:5], v[8:9]
	flat_store_dwordx4 v[30:31], v[2:5] offset:192
	s_add_i32 s9, s9, 1
	s_mul_i32 s4, s9, s39
	s_add_i32 s4, s4, s7
	s_cmpk_gt_i32 s4, 0x7f
	s_cbranch_scc0 .LBB0_461

; template <int MI, int NI>
; DI void gemm256(f32x4 (&acc)[MI][NI], const u16* __restrict__ A, int lda, const u16* __restrict__ Bt, int ldb, int K, int m0, int n0, char* smem) {
;     ...
;   const int srow = lane >> 2, scol = ((lane & 3) ^ ((lane >> 5) << 1)) * 8;
;   const u16* Ag = A + (size_t)(m0 + wave * NAW * 16 + srow) * lda + scol;
;   const u16* Bg = Bt + (size_t)(n0 + wave * NBW * 16 + srow) * ldb + scol;
;   char* la = smem + (wave * NAW) * 1024 + lane * 16;
;   char* lb = smem + ABYTES + (wave * NBW) * 1024 + lane * 16;
;     ...
;   const int nk = K >> 5;
;   G256_ISSUE(0, 0);
;   if (nk > 1) G256_ISSUE(1, 32);
;   const int foff = lr * 64 + ((lq ^ ((lr >> 3) << 1)) * 16);
;   int st = 0;
;   for (int kt = 0; kt < nk; ++kt) {
;     if (kt + 1 < nk) asm volatile("s_waitcnt vmcnt(%0) lgkmcnt(0)" :: "n"(LPS) : "memory");
;     else asm volatile("s_waitcnt vmcnt(0) lgkmcnt(0)" ::: "memory");
;     __builtin_amdgcn_s_barrier();
;     __builtin_amdgcn_s_setprio(1);
;     const char* sb = smem + st * STAGE + foff;
;     bf16x8 af[MI], bfr[NI];
; #pragma unroll
;     for (int mi = 0; mi < MI; ++mi) af[mi] = *(const bf16x8*)(sb + (wr * MI + mi) * 1024);
; #pragma unroll
;     for (int ni = 0; ni < NI; ++ni) bfr[ni] = *(const bf16x8*)(sb + ABYTES + (wc * NI + ni) * 1024);
;     __builtin_amdgcn_sched_barrier(0x0);
;     if (kt + 2 < nk) { const int s2 = st >= 1 ? st - 1 : 2; G256_ISSUE(s2, (kt + 2) * 32); }
;     __builtin_amdgcn_s_setprio(0);
; #pragma unroll
;     for (int mi = 0; mi < MI; ++mi)
; #pragma unroll
;       for (int ni = 0; ni < NI; ++ni)
;         acc[mi][ni] = __builtin_amdgcn_mfma_f32_16x16x32_bf16(bfr[ni], af[mi], acc[mi][ni], 0, 0, 0);
;     st = st == 2 ? 0 : st + 1;
;   }
; DI void phase_resid(const Params& p, const u16* A, int K, const u16* Bt, const float* gate  ,
;                     const float* xl_in, const float* xc_in, float* xl_out, float* xc_out, int Mout, char* smem) {
;     ...
;     for (int t = blk__; t < (NTC / 64) * 16; t += gridDim.x) {
;       const int tm = t >> 4, tn = t & 15;
;       resid_tile<2, 2>(A, K, Bt, gate, xl_in, xc_in, xl_out, xc_out, NTL + tm * 64, tn * 64, smem);
.LBB0_466:
	s_lshl_b32 s4, s6, 2
	s_and_b32 s10, s4, 0xffffffc0
	s_lshl_b32 s4, s6, 6
	s_and_b32 s9, s4, 0x3c0
	v_mov_b32_e32 v22, v163
	s_mov_b32 s4, s2
	s_waitcnt vmcnt(0)
	v_mov_b32_e32 v6, v163
	s_add_i32 s10, s10, 0x8000
	v_ashrrev_i32_e32 v8, 6, v6
	v_bfe_u32 v9, v6, 2, 4
	v_lshlrev_b32_e32 v10, 4, v8
	s_mov_b32 s4, s2
	v_and_b32_e32 v0, 3, v6
	v_lshrrev_b32_e32 v2, 4, v6
	v_or_b32_e32 v4, v9, v10
	v_bitop3_b32 v0, v2, v0, 2 bitop3:0x6c
	v_add_u32_e32 v2, s10, v4
	v_add_u32_e32 v4, s9, v4
	v_and_b32_e32 v7, 63, v6
	v_ashrrev_i32_e32 v3, 31, v2
	v_ashrrev_i32_e32 v5, 31, v4
	v_readlane_b32 s4, v253, 49
	v_lshlrev_b32_e32 v11, 10, v8
	v_lshlrev_b64 v[2:3], 11, v[2:3]
	v_lshlrev_b64 v[4:5], 11, v[4:5]
	v_readlane_b32 s5, v253, 50
	v_lshl_or_b32 v23, v7, 4, v11
	v_lshl_add_u64 v[2:3], s[60:61], 0, v[2:3]
	v_lshlrev_b32_e32 v0, 4, v0
	v_lshl_add_u64 v[4:5], s[4:5], 0, v[4:5]
	v_add_u32_e32 v7, 0x1000, v23
	v_readfirstlane_b32 s4, v23
	v_lshl_add_u64 v[2:3], v[2:3], 0, v[0:1]
	v_bfe_i32 v199, v163, 2, 1
	v_and_b32_e32 v198, 0xfffff840, v199
	v_lshl_add_u64 v[2:3], v[2:3], 0, v[198:199]
	s_mov_b32 m0, s4
	v_readfirstlane_b32 s4, v7
	v_add_u32_e32 v7, 0x2000, v23
	v_lshl_add_u64 v[4:5], v[4:5], 0, v[0:1]
	global_load_lds_dwordx4 v[2:3], off
	s_mov_b32 m0, s4
	v_readfirstlane_b32 s4, v7
	global_load_lds_dwordx4 v[4:5], off
	s_mov_b64 s[98:99], 0x80
	v_lshl_add_u64 v[2:3], v[2:3], 0, s[98:99]
	s_mov_b32 m0, s4
	s_and_b32 s5, s8, 0x3c0
	global_load_lds_dwordx4 v[2:3], off
	v_lshl_add_u64 v[2:3], v[4:5], 0, 64
	v_add_u32_e32 v4, 0x3000, v23
	v_and_b32_e32 v27, 0xfffff800, v11
	v_readfirstlane_b32 s4, v4
	s_mov_b32 m0, s4
	v_and_b32_e32 v4, 48, v6
	global_load_lds_dwordx4 v[2:3], off
	v_lshlrev_b32_e32 v3, 2, v6
	v_lshlrev_b32_e32 v2, 6, v6
	v_bitop3_b32 v3, v3, v4, 32 bitop3:0x6c
	s_and_b32 s4, s7, 0xffffffc0
	v_and_or_b32 v24, v2, s59, v3
	v_lshlrev_b32_e32 v2, 11, v8
	v_and_b32_e32 v25, 0x800, v2
	v_or_b32_e32 v2, s4, v9
	v_add3_u32 v2, v2, v10, s58
	v_ashrrev_i32_e32 v3, 31, v2
	v_lshlrev_b64 v[2:3], 11, v[2:3]
	v_or_b32_e32 v2, v2, v0
	v_lshl_add_u64 v[18:19], s[62:63], 0, v[2:3]
	v_bfe_i32 v199, v163, 2, 1
	v_and_b32_e32 v198, 0xfffff840, v199
	v_lshl_add_u64 v[18:19], v[18:19], 0, v[198:199]
	v_or_b32_e32 v2, s5, v9
	v_add_u32_e32 v2, v2, v10
	v_ashrrev_i32_e32 v3, 31, v2
	v_lshlrev_b64 v[2:3], 11, v[2:3]
	v_readlane_b32 s4, v254, 52
	v_or_b32_e32 v2, v2, v0
	v_readlane_b32 s5, v254, 53
	v_mov_b32_e32 v6, 0
	s_waitcnt lgkmcnt(0)
	v_or_b32_e32 v26, 0x400, v11
	v_lshl_add_u64 v[20:21], s[4:5], 0, v[2:3]
	s_mov_b32 s11, 0
	s_mov_b64 s[4:5], 0
	v_mov_b32_e32 v7, v6
	v_mov_b32_e32 v8, v6
	v_mov_b32_e32 v9, v6
	v_mov_b32_e32 v2, v6
	v_mov_b32_e32 v3, v6
	v_mov_b32_e32 v4, v6
	v_mov_b32_e32 v5, v6
	v_mov_b32_e32 v10, v6
	v_mov_b32_e32 v11, v6
	v_mov_b32_e32 v12, v6
	v_mov_b32_e32 v13, v6
	v_mov_b32_e32 v14, v6
	v_mov_b32_e32 v15, v6
	v_mov_b32_e32 v16, v6
	v_mov_b32_e32 v17, v6
.LBB0_467:
	s_waitcnt vmcnt(2) lgkmcnt(0)
	s_barrier
	s_setprio 1
	s_lshl_b32 s12, s11, 13
	v_or_b32_e32 v0, s12, v24
	v_add_u32_e32 v28, v0, v27
	v_add_u32_e32 v32, v0, v26
	v_add_u32_e32 v0, v0, v25
	s_waitcnt vmcnt(0)
	ds_read_b128 v[28:31], v28
	ds_read_b128 v[32:35], v32
	ds_read_b128 v[36:39], v0 offset:4096
	ds_read_b128 v[40:43], v0 offset:5120
	s_addk_i32 s12, 0xe000
	s_cmp_gt_i32 s11, 0
	s_cselect_b32 s12, s12, 0x4000
	v_add_u32_e32 v0, s12, v23
	v_add_u32_e32 v52, 0x1000, v0
	v_lshl_add_u64 v[48:49], v[18:19], 0, s[4:5]
	v_lshl_add_u64 v[48:49], v[48:49], 0, s[4:5]
	v_readfirstlane_b32 s12, v0
	v_lshl_add_u64 v[44:45], v[20:21], 0, s[4:5]
	s_mov_b64 s[98:99], 0x47e1100
	v_lshl_add_u64 v[50:51], v[48:49], 0, s[98:99]
	s_mov_b32 m0, s12
	v_readfirstlane_b32 s12, v52
	v_lshl_add_u64 v[46:47], v[44:45], 0, s[86:87]
	global_load_lds_dwordx4 v[50:51], off
	s_mov_b32 m0, s12
	s_nop 0
	global_load_lds_dwordx4 v[46:47], off
	s_setprio 0
	s_waitcnt lgkmcnt(0)
	v_mfma_f32_16x16x32_bf16 v[14:17], v[36:39], v[28:31], v[14:17]
	s_add_i32 s12, s11, 1
	s_waitcnt vmcnt(2) lgkmcnt(0)
	s_cmp_lg_u32 s11, 2
	v_mfma_f32_16x16x32_bf16 v[10:13], v[40:43], v[28:31], v[10:13]
	s_cselect_b32 s11, s12, 0
	s_barrier
	v_mfma_f32_16x16x32_bf16 v[2:5], v[36:39], v[32:35], v[2:5]
	v_mfma_f32_16x16x32_bf16 v[6:9], v[40:43], v[32:35], v[6:9]
	s_setprio 1
	s_lshl_b32 s12, s11, 13
	v_or_b32_e32 v0, s12, v24
	v_add_u32_e32 v28, v0, v27
	v_add_u32_e32 v32, v0, v26
	v_add_u32_e32 v0, v0, v25
	s_waitcnt vmcnt(0)
	ds_read_b128 v[28:31], v28
	ds_read_b128 v[32:35], v32
	ds_read_b128 v[36:39], v0 offset:4096
	ds_read_b128 v[40:43], v0 offset:5120
	s_addk_i32 s12, 0xe000
	s_cmp_gt_i32 s11, 0
	s_cselect_b32 s12, s12, 0x4000
	v_add_u32_e32 v0, s12, v23
	s_mov_b64 s[12:13], 0x16610c0
	v_add_u32_e32 v52, 0x1000, v0
	v_lshl_add_u64 v[46:47], v[44:45], 0, s[12:13]
	v_readfirstlane_b32 s12, v0
	s_mov_b64 s[98:99], 0x47e1180
	v_lshl_add_u64 v[50:51], v[48:49], 0, s[98:99]
	s_mov_b32 m0, s12
	v_readfirstlane_b32 s12, v52
	global_load_lds_dwordx4 v[50:51], off
	s_mov_b32 m0, s12
	s_nop 0
	global_load_lds_dwordx4 v[46:47], off
	s_setprio 0
	s_waitcnt lgkmcnt(0)
	v_mfma_f32_16x16x32_bf16 v[14:17], v[36:39], v[28:31], v[14:17]
	s_add_i32 s12, s11, 1
	s_waitcnt vmcnt(2) lgkmcnt(0)
	s_cmp_lg_u32 s11, 2
	v_mfma_f32_16x16x32_bf16 v[10:13], v[40:43], v[28:31], v[10:13]
	s_cselect_b32 s11, s12, 0
	s_barrier
; template <int MI, int NI>
; DI void gemm256(f32x4 (&acc)[MI][NI], const u16* __restrict__ A, int lda, const u16* __restrict__ Bt, int ldb, int K, int m0, int n0, char* smem) {
;     ...
;   for (int kt = 0; kt < nk; ++kt) {
;     if (kt + 1 < nk) asm volatile("s_waitcnt vmcnt(%0) lgkmcnt(0)" :: "n"(LPS) : "memory");
;     else asm volatile("s_waitcnt vmcnt(0) lgkmcnt(0)" ::: "memory");
;     __builtin_amdgcn_s_barrier();
;     __builtin_amdgcn_s_setprio(1);
;     const char* sb = smem + st * STAGE + foff;
;     bf16x8 af[MI], bfr[NI];
; #pragma unroll
;     for (int mi = 0; mi < MI; ++mi) af[mi] = *(const bf16x8*)(sb + (wr * MI + mi) * 1024);
; #pragma unroll
;     for (int ni = 0; ni < NI; ++ni) bfr[ni] = *(const bf16x8*)(sb + ABYTES + (wc * NI + ni) * 1024);
;     __builtin_amdgcn_sched_barrier(0x0);
;     if (kt + 2 < nk) { const int s2 = st >= 1 ? st - 1 : 2; G256_ISSUE(s2, (kt + 2) * 32); }
;     __builtin_amdgcn_s_setprio(0);
; #pragma unroll
;     for (int mi = 0; mi < MI; ++mi)
; #pragma unroll
;       for (int ni = 0; ni < NI; ++ni)
;         acc[mi][ni] = __builtin_amdgcn_mfma_f32_16x16x32_bf16(bfr[ni], af[mi], acc[mi][ni], 0, 0, 0);
;     st = st == 2 ? 0 : st + 1;
;   }
	v_mfma_f32_16x16x32_bf16 v[2:5], v[36:39], v[32:35], v[2:5]
	v_mfma_f32_16x16x32_bf16 v[6:9], v[40:43], v[32:35], v[6:9]
	s_setprio 1
	s_lshl_b32 s12, s11, 13
	v_or_b32_e32 v0, s12, v24
	v_add_u32_e32 v28, v0, v27
	v_add_u32_e32 v32, v0, v26
	v_add_u32_e32 v0, v0, v25
	s_waitcnt vmcnt(0)
	ds_read_b128 v[28:31], v28
	ds_read_b128 v[32:35], v32
	ds_read_b128 v[36:39], v0 offset:4096
	ds_read_b128 v[40:43], v0 offset:5120
	s_addk_i32 s12, 0xe000
	s_cmp_gt_i32 s11, 0
	s_cselect_b32 s12, s12, 0x4000
	v_add_u32_e32 v0, s12, v23
	s_mov_b64 s[12:13], 0x1661100
	v_add_u32_e32 v52, 0x1000, v0
	v_lshl_add_u64 v[46:47], v[44:45], 0, s[12:13]
	v_readfirstlane_b32 s12, v0
	s_mov_b64 s[98:99], 0x47e1200
	v_lshl_add_u64 v[50:51], v[48:49], 0, s[98:99]
	s_mov_b32 m0, s12
	v_readfirstlane_b32 s12, v52
	global_load_lds_dwordx4 v[50:51], off
	s_mov_b32 m0, s12
	s_nop 0
	global_load_lds_dwordx4 v[46:47], off
	s_setprio 0
	s_waitcnt lgkmcnt(0)
	v_mfma_f32_16x16x32_bf16 v[14:17], v[36:39], v[28:31], v[14:17]
	s_add_i32 s12, s11, 1
	s_waitcnt vmcnt(2) lgkmcnt(0)
	s_cmp_lg_u32 s11, 2
	v_mfma_f32_16x16x32_bf16 v[10:13], v[40:43], v[28:31], v[10:13]
	s_cselect_b32 s11, s12, 0
	s_barrier
	v_mfma_f32_16x16x32_bf16 v[2:5], v[36:39], v[32:35], v[2:5]
	v_mfma_f32_16x16x32_bf16 v[6:9], v[40:43], v[32:35], v[6:9]
	s_setprio 1
	s_lshl_b32 s12, s11, 13
	v_or_b32_e32 v0, s12, v24
	v_add_u32_e32 v28, v0, v27
	v_add_u32_e32 v32, v0, v26
	v_add_u32_e32 v0, v0, v25
	s_waitcnt vmcnt(0)
	ds_read_b128 v[28:31], v28
	ds_read_b128 v[32:35], v32
	ds_read_b128 v[36:39], v0 offset:4096
	ds_read_b128 v[40:43], v0 offset:5120
	s_addk_i32 s12, 0xe000
	s_cmp_gt_i32 s11, 0
	s_cselect_b32 s12, s12, 0x4000
	v_add_u32_e32 v0, s12, v23
	s_mov_b64 s[12:13], 0x1661140
	v_lshl_add_u64 v[46:47], v[44:45], 0, s[12:13]
	s_mov_b64 s[12:13], 0x47e1140
	v_add_u32_e32 v52, 0x1000, v0
	s_mov_b64 s[98:99], 0x47e1280
	v_lshl_add_u64 v[50:51], v[48:49], 0, s[98:99]
	v_readfirstlane_b32 s12, v0
	s_mov_b32 m0, s12
	v_readfirstlane_b32 s12, v52
	global_load_lds_dwordx4 v[50:51], off
	s_mov_b32 m0, s12
	s_nop 0
	global_load_lds_dwordx4 v[46:47], off
	s_setprio 0
	s_waitcnt lgkmcnt(0)
	v_mfma_f32_16x16x32_bf16 v[14:17], v[36:39], v[28:31], v[14:17]
	s_add_i32 s12, s11, 1
	s_waitcnt vmcnt(2) lgkmcnt(0)
	s_cmp_lg_u32 s11, 2
	v_mfma_f32_16x16x32_bf16 v[10:13], v[40:43], v[28:31], v[10:13]
	s_cselect_b32 s11, s12, 0
	s_barrier
	v_mfma_f32_16x16x32_bf16 v[2:5], v[36:39], v[32:35], v[2:5]
	v_mfma_f32_16x16x32_bf16 v[6:9], v[40:43], v[32:35], v[6:9]
	s_setprio 1
	s_lshl_b32 s12, s11, 13
	v_or_b32_e32 v0, s12, v24
	v_add_u32_e32 v28, v0, v27
	v_add_u32_e32 v32, v0, v26
	v_add_u32_e32 v0, v0, v25
	s_waitcnt vmcnt(0)
	ds_read_b128 v[28:31], v28
	ds_read_b128 v[32:35], v32
	ds_read_b128 v[36:39], v0 offset:4096
	ds_read_b128 v[40:43], v0 offset:5120
	s_addk_i32 s12, 0xe000
	s_cmp_gt_i32 s11, 0
	s_cselect_b32 s12, s12, 0x4000
	v_add_u32_e32 v0, s12, v23
	s_mov_b64 s[12:13], 0x1661180
	v_lshl_add_u64 v[44:45], v[44:45], 0, s[12:13]
	s_mov_b64 s[12:13], 0x47e1180
	v_add_u32_e32 v50, 0x1000, v0
	s_mov_b64 s[98:99], 0x47e1300
	v_lshl_add_u64 v[46:47], v[48:49], 0, s[98:99]
	v_readfirstlane_b32 s12, v0
	s_mov_b32 m0, s12
	v_readfirstlane_b32 s12, v50
	global_load_lds_dwordx4 v[46:47], off
	s_mov_b32 m0, s12
	s_nop 0
	global_load_lds_dwordx4 v[44:45], off
	s_setprio 0
	s_add_i32 s12, s11, 1
	s_waitcnt lgkmcnt(0)
	v_mfma_f32_16x16x32_bf16 v[14:17], v[36:39], v[28:31], v[14:17]
	s_cmp_lg_u32 s11, 2
	s_cselect_b32 s11, s12, 0
	s_add_u32 s4, s4, 0x140
	v_mfma_f32_16x16x32_bf16 v[10:13], v[40:43], v[28:31], v[10:13]
	s_addc_u32 s5, s5, 0
	s_cmpk_eq_i32 s4, 0x780
	v_mfma_f32_16x16x32_bf16 v[2:5], v[36:39], v[32:35], v[2:5]
	v_mfma_f32_16x16x32_bf16 v[6:9], v[40:43], v[32:35], v[6:9]
	s_cbranch_scc0 .LBB0_467
	s_waitcnt vmcnt(2) lgkmcnt(0)
	s_barrier
	s_setprio 1
	v_add_u32_e32 v0, v24, v27
	v_add_u32_e32 v38, v24, v25
	v_add_u32_e32 v23, v24, v26
	s_waitcnt vmcnt(0)
	ds_read_b128 v[18:21], v0
	ds_read_b128 v[26:29], v23
	ds_read_b128 v[30:33], v38 offset:4096
	ds_read_b128 v[34:37], v38 offset:5120
	v_bfe_u32 v39, v22, 6, 1
	s_setprio 0
	s_waitcnt vmcnt(0) lgkmcnt(0)
	s_waitcnt lgkmcnt(1)
	v_mfma_f32_16x16x32_bf16 v[14:17], v[30:33], v[18:21], v[14:17]
	v_ashrrev_i32_e32 v40, 7, v22
	v_and_b32_e32 v41, 15, v22
	v_bfe_u32 v42, v22, 4, 2
	s_waitcnt lgkmcnt(0)
	v_mfma_f32_16x16x32_bf16 v[10:13], v[34:37], v[18:21], v[10:13]
	s_barrier
; #define EPI_BEGIN const int lr1_ = launder_v(lr), lq1_ = launder_v(lq), wr1_ = launder_v(wr), wc1_ = launder_v(wc); { const int lr = lr1_, lq = lq1_, wr = wr1_, wc = wc1_; (void)lr; (void)lq; (void)wr; (void)wc;
; template <int MI, int NI>
; DI void gemm256(f32x4 (&acc)[MI][NI], const u16* __restrict__ A, int lda, const u16* __restrict__ Bt, int ldb, int K, int m0, int n0, char* smem) {
;     ...
; #pragma unroll
;     for (int mi = 0; mi < MI; ++mi)
; #pragma unroll
;       for (int ni = 0; ni < NI; ++ni)
;         acc[mi][ni] = __builtin_amdgcn_mfma_f32_16x16x32_bf16(bfr[ni], af[mi], acc[mi][ni], 0, 0, 0);
;     st = st == 2 ? 0 : st + 1;
;   }
;   asm volatile("s_waitcnt lgkmcnt(0)" ::: "memory");
;   __builtin_amdgcn_s_barrier();
; template <int MI, int NI>
; DI void resid_tile(const u16* A, int K, const u16* Bt, const float* gate, const float* xl_in, const float* xc_in, float* xl_out, float* xc_out,
;                    int m0, int n0, char* smem) {
;     ...
;   EPI_BEGIN
; #pragma unroll
;   for (int mi = 0; mi < MI; ++mi) {
;     const int m = m0 + wr * 16 * MI + mi * 16 + lr;
;     const int b9 = m < NTL ? m >> 12 : 8;
;     const float* xi = xrow(xl_in, xc_in, m);
;     float* xo = m < NTL ? xl_out + (size_t)m * D : xc_out + (size_t)(m - NTL) * D;
; #pragma unroll
;     for (int ni = 0; ni < NI; ++ni) {
;       const int n = n0 + wc * 16 * NI + ni * 16 + lq * 4;
;       const float4 g = *(const float4*)(gate + (size_t)b9 * 6144 + n);
;       const float4 xv = *(const float4*)(xi + n);
;       float4 ov;
;       ov.x = xv.x + g.x * acc[mi][ni][0]; ov.y = xv.y + g.y * acc[mi][ni][1]; ov.z = xv.z + g.z * acc[mi][ni][2]; ov.w = xv.w + g.w * acc[mi][ni][3];
;       *(float4*)(xo + n) = ov;
;     }
;     __builtin_amdgcn_sched_barrier(0);
;   }
;   EPI_END
	v_mfma_f32_16x16x32_bf16 v[2:5], v[30:33], v[26:29], v[2:5]
	v_mfma_f32_16x16x32_bf16 v[18:21], v[34:37], v[26:29], v[6:9]
	s_setprio 1
	s_nop 1
	ds_read_b128 v[6:9], v0 offset:8192
	ds_read_b128 v[22:25], v23 offset:8192
	ds_read_b128 v[26:29], v38 offset:12288
	ds_read_b128 v[30:33], v38 offset:13312
	s_setprio 0
	s_waitcnt lgkmcnt(0)
	s_barrier
	v_readlane_b32 s4, v253, 55
	v_lshlrev_b32_e32 v0, 5, v40
	s_waitcnt lgkmcnt(1)
	v_mfma_f32_16x16x32_bf16 v[14:17], v[26:29], v[6:9], v[14:17]
	v_mov_b32_e32 v36, s4
	v_readlane_b32 s4, v253, 53
	s_waitcnt lgkmcnt(0)
	v_mfma_f32_16x16x32_bf16 v[10:13], v[30:33], v[6:9], v[10:13]
	v_mov_b32_e32 v37, s4
	v_readlane_b32 s4, v253, 56
	v_mfma_f32_16x16x32_bf16 v[6:9], v[26:29], v[22:25], v[2:5]
	v_add3_u32 v26, v41, s10, v0
	v_lshlrev_b32_e32 v0, 5, v39
	v_cmp_gt_i32_e32 vcc, s58, v26
	v_mfma_f32_16x16x32_bf16 v[2:5], v[30:33], v[22:25], v[18:21]
	v_ashrrev_i32_e32 v27, 31, v26
	v_mov_b32_e32 v38, s4
	v_readlane_b32 s4, v253, 54
	v_lshlrev_b32_e32 v18, 2, v42
	v_add3_u32 v18, v18, s9, v0
	v_min_i32_e32 v0, 0x8000, v26
	v_ashrrev_i32_e32 v28, 12, v0
	v_add_u32_e32 v0, 0xffff8000, v26
	v_cndmask_b32_e32 v21, 0, v27, vcc
	v_cndmask_b32_e32 v20, v0, v26, vcc
	v_mov_b32_e32 v39, s4
	v_cndmask_b32_e32 v23, v36, v37, vcc
	v_cndmask_b32_e32 v22, v38, v39, vcc
	v_lshlrev_b64 v[20:21], 12, v[20:21]
	v_lshl_add_u64 v[20:21], v[22:23], 0, v[20:21]
	v_lshlrev_b64 v[22:23], 12, v[26:27]
	v_lshlrev_b64 v[24:25], 12, v[0:1]
	v_lshl_add_u64 v[22:23], s[48:49], 0, v[22:23]
	v_lshl_add_u64 v[24:25], s[94:95], 0, v[24:25]
	v_readlane_b32 s4, v253, 51
	v_ashrrev_i32_e32 v19, 31, v18
	v_cndmask_b32_e32 v23, v25, v23, vcc
	v_cndmask_b32_e32 v22, v24, v22, vcc
	v_mul_hi_i32_i24_e32 v25, 0x6000, v28
	v_mul_i32_i24_e32 v24, 0x6000, v28
	v_readlane_b32 s5, v253, 52
	v_lshlrev_b64 v[28:29], 2, v[18:19]
	v_lshl_add_u64 v[32:33], v[20:21], 0, v[28:29]
	v_lshl_add_u64 v[24:25], s[4:5], 0, v[24:25]
	v_lshl_add_u64 v[30:31], v[24:25], 0, v[28:29]
	v_lshl_add_u64 v[34:35], v[22:23], 0, v[28:29]
	flat_load_dwordx4 v[18:21], v[30:31]
	flat_load_dwordx4 v[22:25], v[32:33]
	s_waitcnt vmcnt(0) lgkmcnt(0)
	v_pk_fma_f32 v[14:15], v[14:15], v[18:19], v[22:23]
	v_pk_fma_f32 v[16:17], v[16:17], v[20:21], v[24:25]
	flat_store_dwordx4 v[34:35], v[14:17]
	flat_load_dwordx4 v[14:17], v[30:31] offset:64
	s_nop 0
	flat_load_dwordx4 v[18:21], v[32:33] offset:64
	s_waitcnt vmcnt(0) lgkmcnt(0)
	v_pk_fma_f32 v[10:11], v[10:11], v[14:15], v[18:19]
	v_pk_fma_f32 v[12:13], v[12:13], v[16:17], v[20:21]
	flat_store_dwordx4 v[34:35], v[10:13] offset:64
	s_nop 1
	v_add_u32_e32 v10, 16, v26
	v_min_i32_e32 v0, 0x8000, v10
	v_cmp_gt_i32_e32 vcc, s58, v10
	v_ashrrev_i32_e32 v16, 12, v0
	v_add_u32_e32 v0, 0xffff8010, v26
	v_ashrrev_i32_e32 v11, 31, v10
	v_cndmask_b32_e32 v13, 0, v11, vcc
	v_cndmask_b32_e32 v12, v0, v10, vcc
	v_cndmask_b32_e32 v15, v36, v37, vcc
	v_cndmask_b32_e32 v14, v38, v39, vcc
	v_lshlrev_b64 v[12:13], 12, v[12:13]
	v_lshl_add_u64 v[12:13], v[14:15], 0, v[12:13]
	v_lshlrev_b64 v[10:11], 12, v[10:11]
	v_lshlrev_b64 v[14:15], 12, v[0:1]
	v_lshl_add_u64 v[10:11], s[48:49], 0, v[10:11]
	v_lshl_add_u64 v[14:15], s[94:95], 0, v[14:15]
	v_cndmask_b32_e32 v11, v15, v11, vcc
	v_cndmask_b32_e32 v10, v14, v10, vcc
	v_mul_hi_i32_i24_e32 v15, 0x6000, v16
	v_mul_i32_i24_e32 v14, 0x6000, v16
	v_lshl_add_u64 v[14:15], s[4:5], 0, v[14:15]
	v_lshl_add_u64 v[18:19], v[14:15], 0, v[28:29]
	v_lshl_add_u64 v[20:21], v[12:13], 0, v[28:29]
	v_lshl_add_u64 v[22:23], v[10:11], 0, v[28:29]
	flat_load_dwordx4 v[10:13], v[18:19]
	flat_load_dwordx4 v[14:17], v[20:21]
	s_waitcnt vmcnt(0) lgkmcnt(0)
	v_pk_fma_f32 v[6:7], v[6:7], v[10:11], v[14:15]
	v_pk_fma_f32 v[8:9], v[8:9], v[12:13], v[16:17]
	flat_store_dwordx4 v[22:23], v[6:9]
	flat_load_dwordx4 v[6:9], v[18:19] offset:64
	s_nop 0
	flat_load_dwordx4 v[10:13], v[20:21] offset:64
	s_waitcnt vmcnt(0) lgkmcnt(0)
	v_pk_fma_f32 v[2:3], v[2:3], v[6:7], v[10:11]
	v_pk_fma_f32 v[4:5], v[4:5], v[8:9], v[12:13]
	flat_store_dwordx4 v[22:23], v[2:5] offset:64
	s_add_i32 s6, s6, s79
	s_add_i32 s7, s7, s40
	s_add_i32 s8, s8, s41
	s_cmpk_gt_i32 s6, 0x1ff
	s_cbranch_scc0 .LBB0_466

; DI unsigned pack2(float a, float b) { float2_t v = {a, b}; bf16x2_t r = __builtin_convertvector(v, bf16x2_t); return __builtin_bit_cast(unsigned, r); }
; #define EPI_BEGIN const int lr1_ = launder_v(lr), lq1_ = launder_v(lq), wr1_ = launder_v(wr), wc1_ = launder_v(wc); { const int lr = lr1_, lq = lq1_, wr = wr1_, wc = wc1_; (void)lr; (void)lq; (void)wr; (void)wc;
; DI void phase_merge(const Params& p, int l, int Mout, char* smem) {
;     ...
;     EPI_BEGIN
; #pragma unroll
;     for (int mi = 0; mi < 4; mi += 2) {
;       const int m = m0 + wr * 64 + (mi + (lq & 1)) * 16 + lr;
; #pragma unroll
;       for (int ni = 0; ni < 4; ++ni) {
;         const int n = n0 + wc * 64 + ni * 16 + (lq >> 1) * 8;
;         *(uint4*)(mo + (size_t)m * 1024 + n) = widen16(make_uint2(pack2(msum[mi][ni][0], msum[mi][ni][1]), pack2(msum[mi][ni][2], msum[mi][ni][3])),
;                                                        make_uint2(pack2(msum[mi + 1][ni][0], msum[mi + 1][ni][1]), pack2(msum[mi + 1][ni][2], msum[mi + 1][ni][3])));
;       }
;     }
;     EPI_END
.LBB0_473:
	v_mov_b32_e32 v0, v245
	v_mov_b32_e32 v2, v246
	v_mov_b32_e32 v3, v243
	v_mov_b32_e32 v4, v244
	v_lshlrev_b32_e32 v5, 2, v2
	v_lshlrev_b32_e32 v2, 4, v2
	v_lshlrev_b32_e32 v3, 6, v3
	v_add_u32_e32 v0, s13, v0
	v_and_b32_e32 v2, 16, v2
	v_lshlrev_b32_e32 v4, 6, v4
	v_and_b32_e32 v5, -8, v5
	v_add3_u32 v8, v0, v3, v2
	v_add3_u32 v6, v5, s12, v4
	v_ashrrev_i32_e32 v9, 31, v8
	v_and_b32_e32 v12, 1, v8
	v_lshrrev_b32_e32 v2, 1, v8
	v_mov_b32_e32 v3, 0
	v_lshlrev_b64 v[2:3], 12, v[2:3]
	v_lshl_or_b32 v2, v12, 6, v2
	v_ashrrev_i32_e32 v7, 31, v6
	v_lshl_add_u64 v[10:11], s[60:61], 0, v[2:3]
	v_cvt_pk_bf16_f32 v2, v220, v221
	v_cvt_pk_bf16_f32 v3, v222, v223
	v_cvt_pk_bf16_f32 v4, v224, v225
	v_cvt_pk_bf16_f32 v5, v226, v227
	v_and_b32_e32 v12, 31, v6
	v_lshrrev_b32_e32 v6, 5, v6
	v_lshlrev_b32_e32 v6, 7, v6
	v_lshl_or_b32 v6, v12, 1, v6
	v_mov_b32_e32 v7, 0
	v_permlane16_swap_b32_e32 v2, v4
	v_permlane16_swap_b32_e32 v3, v5
	v_lshl_add_u64 v[10:11], v[10:11], 0, v[6:7]
	flat_store_dwordx4 v[10:11], v[2:5]
	s_add_i32 s10, s10, 1
	s_mul_i32 s4, s10, s39
	v_cvt_pk_bf16_f32 v2, v208, v209
	v_cvt_pk_bf16_f32 v3, v210, v211
	v_cvt_pk_bf16_f32 v4, v216, v217
	v_cvt_pk_bf16_f32 v5, v218, v219
	s_nop 0
	v_permlane16_swap_b32_e32 v2, v4
	v_permlane16_swap_b32_e32 v3, v5
	flat_store_dwordx4 v[10:11], v[2:5] offset:32
	s_add_i32 s6, s4, s8
	v_readlane_b32 s4, v253, 57
	v_cvt_pk_bf16_f32 v2, v196, v197
	v_cvt_pk_bf16_f32 v3, v198, v199
	v_cvt_pk_bf16_f32 v4, v212, v213
	v_cvt_pk_bf16_f32 v5, v214, v215
	s_nop 0
	v_permlane16_swap_b32_e32 v2, v4
	v_permlane16_swap_b32_e32 v3, v5
	flat_store_dwordx4 v[10:11], v[2:5] offset:128
	s_cmp_ge_i32 s6, s4
	s_nop 0
	v_cvt_pk_bf16_f32 v2, v186, v187
	v_cvt_pk_bf16_f32 v3, v190, v191
	v_cvt_pk_bf16_f32 v4, v202, v203
	v_cvt_pk_bf16_f32 v5, v206, v207
	s_nop 0
	v_permlane16_swap_b32_e32 v2, v4
	v_permlane16_swap_b32_e32 v3, v5
	flat_store_dwordx4 v[10:11], v[2:5] offset:160
	s_nop 1
	v_add_u32_e32 v2, 32, v8
	v_ashrrev_i32_e32 v3, 31, v2
	v_and_b32_e32 v12, 1, v2
	v_lshrrev_b32_e32 v2, 1, v2
	v_mov_b32_e32 v3, 0
	v_lshlrev_b64 v[2:3], 12, v[2:3]
	v_lshl_or_b32 v2, v12, 6, v2
	v_lshl_add_u64 v[8:9], s[60:61], 0, v[2:3]
	v_cvt_pk_bf16_f32 v2, v184, v185
	v_cvt_pk_bf16_f32 v3, v188, v189
	v_cvt_pk_bf16_f32 v4, v200, v201
	v_cvt_pk_bf16_f32 v5, v204, v205
	s_nop 0
	v_permlane16_swap_b32_e32 v2, v4
	v_permlane16_swap_b32_e32 v3, v5
	v_lshl_add_u64 v[6:7], v[8:9], 0, v[6:7]
	flat_store_dwordx4 v[6:7], v[2:5]
	s_nop 1
	v_cvt_pk_bf16_f32 v2, v176, v177
	v_cvt_pk_bf16_f32 v3, v178, v179
	v_cvt_pk_bf16_f32 v4, v192, v193
	v_cvt_pk_bf16_f32 v5, v194, v195
	s_nop 0
	v_permlane16_swap_b32_e32 v2, v4
	v_permlane16_swap_b32_e32 v3, v5
	flat_store_dwordx4 v[6:7], v[2:5] offset:32
	s_nop 1
	v_cvt_pk_bf16_f32 v2, v168, v169
	v_cvt_pk_bf16_f32 v3, v170, v171
	v_cvt_pk_bf16_f32 v4, v180, v181
	v_cvt_pk_bf16_f32 v5, v182, v183
	s_nop 0
	v_permlane16_swap_b32_e32 v2, v4
	v_permlane16_swap_b32_e32 v3, v5
	flat_store_dwordx4 v[6:7], v[2:5] offset:128
	s_nop 1
	v_cvt_pk_bf16_f32 v2, v164, v165
	v_cvt_pk_bf16_f32 v3, v166, v167
	v_cvt_pk_bf16_f32 v4, v172, v173
	v_cvt_pk_bf16_f32 v5, v174, v175
	s_nop 0
	v_permlane16_swap_b32_e32 v2, v4
	v_permlane16_swap_b32_e32 v3, v5
	flat_store_dwordx4 v[6:7], v[2:5] offset:160
	s_cbranch_scc1 .LBB0_485

; template <int MI, int NI>
; DI void gemm256(f32x4 (&acc)[MI][NI], const u16* __restrict__ A, int lda, const u16* __restrict__ Bt, int ldb, int K, int m0, int n0, char* smem) {
;     ...
;   const int srow = lane >> 2, scol = ((lane & 3) ^ ((lane >> 5) << 1)) * 8;
;   const u16* Ag = A + (size_t)(m0 + wave * NAW * 16 + srow) * lda + scol;
;   const u16* Bg = Bt + (size_t)(n0 + wave * NBW * 16 + srow) * ldb + scol;
;   char* la = smem + (wave * NAW) * 1024 + lane * 16;
;   char* lb = smem + ABYTES + (wave * NBW) * 1024 + lane * 16;
;     ...
;   const int nk = K >> 5;
;   G256_ISSUE(0, 0);
;   if (nk > 1) G256_ISSUE(1, 32);
;   const int foff = lr * 64 + ((lq ^ ((lr >> 3) << 1)) * 16);
;   int st = 0;
; DI void phase_merge(const Params& p, int l, int Mout, char* smem) {
;     ...
;         f32x4 ag[4][4]; zero_accm<4, 4>(ag);
;         gemm256<4, 4>(ag, hg, 1024, (const u16*)(wl + WO_WIN) + (size_t)(2080 + br * 1024) * 1024, 1024, 1024, m0, n0, smem);
.LBB0_479:
	s_waitcnt vmcnt(0)
	v_mov_b32_e32 v8, v163
	s_lshl_b32 s6, s11, 21
	v_ashrrev_i32_e32 v9, 6, v8
	v_bfe_u32 v10, v8, 2, 4
	v_lshlrev_b32_e32 v11, 5, v9
	v_and_b32_e32 v0, 3, v8
	v_lshrrev_b32_e32 v2, 4, v8
	v_or_b32_e32 v4, v10, v11
	v_and_b32_e32 v6, 63, v8
	v_bitop3_b32 v0, v2, v0, 2 bitop3:0x6c
	v_add_u32_e32 v2, s13, v4
	v_add_u32_e32 v4, s12, v4
	s_add_u32 s6, s44, s6
	v_ashrrev_i32_e32 v3, 31, v2
	v_ashrrev_i32_e32 v5, 31, v4
	v_lshlrev_b32_e32 v6, 4, v6
	s_addc_u32 s7, s45, 0
	v_lshlrev_b64 v[2:3], 11, v[2:3]
	v_lshlrev_b64 v[4:5], 11, v[4:5]
	v_lshl_or_b32 v70, v9, 11, v6
	v_lshl_add_u64 v[2:3], s[52:53], 0, v[2:3]
	v_lshlrev_b32_e32 v0, 4, v0
	v_lshl_add_u64 v[4:5], s[6:7], 0, v[4:5]
	v_readfirstlane_b32 s6, v70
	v_or_b32_e32 v13, 0x400, v70
	s_mov_b32 s15, s2
	v_lshl_add_u64 v[2:3], v[2:3], 0, v[0:1]
	v_bfe_i32 v75, v163, 2, 1
	v_and_b32_e32 v74, 0xfffff840, v75
	v_lshl_add_u64 v[2:3], v[2:3], 0, v[74:75]
	s_mov_b32 m0, s6
	v_readfirstlane_b32 s6, v13
	v_add_u32_e32 v12, 0x2000, v70
	global_load_lds_dwordx4 v[2:3], off
	v_lshl_add_u64 v[6:7], v[2:3], 0, s[68:69]
	s_mov_b32 m0, s6
	v_lshl_add_u64 v[4:5], v[4:5], 0, v[0:1]
	v_bfe_i32 v75, v163, 2, 1
	v_and_b32_e32 v74, 0xfffff840, v75
	v_lshl_add_u64 v[4:5], v[4:5], 0, v[74:75]
	s_mov_b64 s[6:7], 0x410000
	global_load_lds_dwordx4 v[6:7], off
	v_lshl_add_u64 v[6:7], v[4:5], 0, s[6:7]
	v_readfirstlane_b32 s6, v12
	s_mov_b32 m0, s6
	s_mov_b64 s[6:7], 0x418000
	v_add_u32_e32 v12, 0x2400, v70
	global_load_lds_dwordx4 v[6:7], off
	v_lshl_add_u64 v[6:7], v[4:5], 0, s[6:7]
	v_readfirstlane_b32 s6, v12
	v_add_u32_e32 v12, 0x4000, v70
	s_mov_b32 m0, s6
	v_readfirstlane_b32 s6, v12
	global_load_lds_dwordx4 v[6:7], off
	s_mov_b64 s[98:99], 0x80
	v_lshl_add_u64 v[6:7], v[2:3], 0, s[98:99]
	s_mov_b32 m0, s6
	s_mov_b64 s[98:99], 0x8080
	v_lshl_add_u64 v[2:3], v[2:3], 0, s[98:99]
	global_load_lds_dwordx4 v[6:7], off
	v_add_u32_e32 v6, 0x4400, v70
	s_mov_b32 s15, 0
	v_readfirstlane_b32 s6, v6
	s_mov_b32 m0, s6
	v_add_u32_e32 v6, 0x6000, v70
	s_mov_b64 s[6:7], 0x410080
	global_load_lds_dwordx4 v[2:3], off
	v_lshl_add_u64 v[2:3], v[4:5], 0, s[6:7]
	v_readfirstlane_b32 s6, v6
	s_mov_b32 m0, s6
	s_mov_b64 s[6:7], 0x418080
	global_load_lds_dwordx4 v[2:3], off
	v_lshl_add_u64 v[2:3], v[4:5], 0, s[6:7]
	v_add_u32_e32 v4, 0x6400, v70
	v_mov_b32_e32 v50, 0
	v_readfirstlane_b32 s6, v4
	s_mov_b32 m0, s6
	v_and_b32_e32 v4, 48, v8
	global_load_lds_dwordx4 v[2:3], off
	v_lshlrev_b32_e32 v3, 2, v8
	v_lshlrev_b32_e32 v2, 6, v8
	v_bitop3_b32 v3, v3, v4, 32 bitop3:0x6c
	v_and_or_b32 v71, v2, s59, v3
	v_lshlrev_b32_e32 v2, 12, v9
	v_and_b32_e32 v72, 0x1000, v2
	v_lshlrev_b32_e32 v2, 5, v8
	v_and_b32_e32 v73, 0xfffff000, v2
	v_add3_u32 v2, s14, v10, v11
	v_ashrrev_i32_e32 v3, 31, v2
	v_lshlrev_b64 v[2:3], 11, v[2:3]
	v_or_b32_e32 v2, v2, v0
	v_lshl_add_u64 v[66:67], s[4:5], 0, v[2:3]
	v_bfe_i32 v75, v163, 2, 1
	v_and_b32_e32 v74, 0xfffff840, v75
	v_lshl_add_u64 v[66:67], v[66:67], 0, v[74:75]
	v_add3_u32 v2, s13, v10, v11
	v_ashrrev_i32_e32 v3, 31, v2
	v_lshlrev_b64 v[2:3], 11, v[2:3]
	v_or_b32_e32 v2, v2, v0
	v_lshl_add_u64 v[68:69], s[62:63], 0, v[2:3]
	v_bfe_i32 v75, v163, 2, 1
	v_and_b32_e32 v74, 0xfffff840, v75
	v_lshl_add_u64 v[68:69], v[68:69], 0, v[74:75]
	s_mov_b64 s[6:7], 0
	v_mov_b32_e32 v51, v247
	v_mov_b32_e32 v52, v247
	v_mov_b32_e32 v53, v247
	v_mov_b32_e32 v2, 0
	v_mov_b32_e32 v3, v247
	v_mov_b32_e32 v4, v247
	v_mov_b32_e32 v5, v247
	v_mov_b32_e32 v6, 0
	v_mov_b32_e32 v7, v247
	v_mov_b32_e32 v8, v247
	v_mov_b32_e32 v9, v247
	v_mov_b32_e32 v10, 0
	v_mov_b32_e32 v11, v247
	v_mov_b32_e32 v12, v247
	v_mov_b32_e32 v13, v247
	v_mov_b32_e32 v14, 0
	v_mov_b32_e32 v15, v247
	v_mov_b32_e32 v16, v247
	v_mov_b32_e32 v17, v247
	v_mov_b32_e32 v18, 0
	v_mov_b32_e32 v19, v247
	v_mov_b32_e32 v20, v247
	v_mov_b32_e32 v21, v247
	v_mov_b32_e32 v22, 0
	v_mov_b32_e32 v23, v247
	v_mov_b32_e32 v24, v247
	v_mov_b32_e32 v25, v247
	s_waitcnt lgkmcnt(0)
	v_mov_b32_e32 v26, 0
	v_mov_b32_e32 v27, v247
	v_mov_b32_e32 v28, v247
	v_mov_b32_e32 v29, v247
	v_mov_b32_e32 v30, 0
	v_mov_b32_e32 v31, v247
	v_mov_b32_e32 v32, v247
	v_mov_b32_e32 v33, v247
	v_mov_b32_e32 v34, 0
	v_mov_b32_e32 v35, v247
	v_mov_b32_e32 v36, v247
	v_mov_b32_e32 v37, v247
	v_mov_b32_e32 v38, 0
	v_mov_b32_e32 v39, v247
	v_mov_b32_e32 v40, v247
	v_mov_b32_e32 v41, v247
	v_mov_b32_e32 v42, 0
	v_mov_b32_e32 v43, v247
	v_mov_b32_e32 v44, v247
	v_mov_b32_e32 v45, v247
	v_mov_b32_e32 v46, 0
	v_mov_b32_e32 v47, v247
	v_mov_b32_e32 v48, v247
	v_mov_b32_e32 v49, v247
	v_mov_b32_e32 v54, 0
	v_mov_b32_e32 v55, v247
	v_mov_b32_e32 v56, v247
	v_mov_b32_e32 v57, v247
	v_mov_b32_e32 v58, 0
	v_mov_b32_e32 v59, v247
	v_mov_b32_e32 v60, v247
	v_mov_b32_e32 v61, v247
	v_mov_b32_e32 v62, 0
	v_mov_b32_e32 v63, v247
	v_mov_b32_e32 v64, v247
	v_mov_b32_e32 v65, v247
; template <int MI, int NI>
; DI void gemm256(f32x4 (&acc)[MI][NI], const u16* __restrict__ A, int lda, const u16* __restrict__ Bt, int ldb, int K, int m0, int n0, char* smem) {
;     ...
;   for (int kt = 0; kt < nk; ++kt) {
;     if (kt + 1 < nk) asm volatile("s_waitcnt vmcnt(%0) lgkmcnt(0)" :: "n"(LPS) : "memory");
;     else asm volatile("s_waitcnt vmcnt(0) lgkmcnt(0)" ::: "memory");
;     __builtin_amdgcn_s_barrier();
;     __builtin_amdgcn_s_setprio(1);
;     const char* sb = smem + st * STAGE + foff;
;     bf16x8 af[MI], bfr[NI];
; #pragma unroll
;     for (int mi = 0; mi < MI; ++mi) af[mi] = *(const bf16x8*)(sb + (wr * MI + mi) * 1024);
; #pragma unroll
;     for (int ni = 0; ni < NI; ++ni) bfr[ni] = *(const bf16x8*)(sb + ABYTES + (wc * NI + ni) * 1024);
;     __builtin_amdgcn_sched_barrier(0x0);
;     if (kt + 2 < nk) { const int s2 = st >= 1 ? st - 1 : 2; G256_ISSUE(s2, (kt + 2) * 32); }
;     __builtin_amdgcn_s_setprio(0);
; #pragma unroll
;     for (int mi = 0; mi < MI; ++mi)
; #pragma unroll
;       for (int ni = 0; ni < NI; ++ni)
;         acc[mi][ni] = __builtin_amdgcn_mfma_f32_16x16x32_bf16(bfr[ni], af[mi], acc[mi][ni], 0, 0, 0);
;     st = st == 2 ? 0 : st + 1;
;   }
.LBB0_480:
	s_waitcnt vmcnt(4) lgkmcnt(0)
	s_barrier
	s_setprio 1
	s_lshl_b32 s16, s15, 14
	v_or_b32_e32 v0, s16, v71
	v_add_u32_e32 v86, v0, v73
	v_add_u32_e32 v0, v0, v72
	s_waitcnt vmcnt(0)
	ds_read_b128 v[74:77], v86
	ds_read_b128 v[78:81], v86 offset:1024
	ds_read_b128 v[82:85], v86 offset:2048
	ds_read_b128 v[86:89], v86 offset:3072
	ds_read_b128 v[90:93], v0 offset:8192
	ds_read_b128 v[94:97], v0 offset:9216
	ds_read_b128 v[98:101], v0 offset:10240
	ds_read_b128 v[102:105], v0 offset:11264
	s_add_i32 s18, s16, 0xffffc000
	s_cmp_gt_i32 s15, 0
	v_lshl_add_u64 v[106:107], v[68:69], 0, s[6:7]
	v_lshl_add_u64 v[106:107], v[106:107], 0, s[6:7]
	s_mov_b64 s[16:17], 0x8be1100
	v_lshl_add_u64 v[108:109], v[106:107], 0, s[16:17]
	s_cselect_b32 s16, s18, 0x8000
	v_add_u32_e32 v0, s16, v70
	v_add_u32_e32 v110, 0x400, v0
	v_readfirstlane_b32 s16, v0
	s_mov_b32 m0, s16
	s_mov_b64 s[16:17], 0x8be9100
	global_load_lds_dwordx4 v[108:109], off
	v_lshl_add_u64 v[108:109], v[106:107], 0, s[16:17]
	v_readfirstlane_b32 s16, v110
	s_mov_b32 m0, s16
	s_mov_b64 s[16:17], 0xd51100
	global_load_lds_dwordx4 v[108:109], off
	v_lshl_add_u64 v[108:109], v[66:67], 0, s[6:7]
	v_lshl_add_u64 v[108:109], v[108:109], 0, s[6:7]
	v_add_u32_e32 v112, 0x2000, v0
	v_lshl_add_u64 v[110:111], v[108:109], 0, s[16:17]
	v_readfirstlane_b32 s16, v112
	s_mov_b32 m0, s16
	s_mov_b64 s[16:17], 0xd59100
	v_add_u32_e32 v0, 0x2400, v0
	global_load_lds_dwordx4 v[110:111], off
	v_lshl_add_u64 v[110:111], v[108:109], 0, s[16:17]
	v_readfirstlane_b32 s16, v0
	s_mov_b32 m0, s16
	s_nop 0
	global_load_lds_dwordx4 v[110:111], off
	s_setprio 0
	s_waitcnt lgkmcnt(0)
	v_mfma_f32_16x16x32_bf16 v[62:65], v[90:93], v[74:77], v[62:65]
	s_add_i32 s16, s15, 1
	s_waitcnt vmcnt(4) lgkmcnt(0)
	s_cmp_lg_u32 s15, 2
	v_mfma_f32_16x16x32_bf16 v[58:61], v[94:97], v[74:77], v[58:61]
	s_cselect_b32 s15, s16, 0
	s_barrier
	v_mfma_f32_16x16x32_bf16 v[54:57], v[98:101], v[74:77], v[54:57]
	v_mfma_f32_16x16x32_bf16 v[46:49], v[102:105], v[74:77], v[46:49]
	v_mfma_f32_16x16x32_bf16 v[42:45], v[90:93], v[78:81], v[42:45]
	v_mfma_f32_16x16x32_bf16 v[38:41], v[94:97], v[78:81], v[38:41]
	v_mfma_f32_16x16x32_bf16 v[34:37], v[98:101], v[78:81], v[34:37]
	v_mfma_f32_16x16x32_bf16 v[30:33], v[102:105], v[78:81], v[30:33]
	v_mfma_f32_16x16x32_bf16 v[26:29], v[90:93], v[82:85], v[26:29]
	v_mfma_f32_16x16x32_bf16 v[22:25], v[94:97], v[82:85], v[22:25]
	v_mfma_f32_16x16x32_bf16 v[18:21], v[98:101], v[82:85], v[18:21]
	v_mfma_f32_16x16x32_bf16 v[14:17], v[102:105], v[82:85], v[14:17]
	v_mfma_f32_16x16x32_bf16 v[10:13], v[90:93], v[86:89], v[10:13]
	v_mfma_f32_16x16x32_bf16 v[6:9], v[94:97], v[86:89], v[6:9]
	v_mfma_f32_16x16x32_bf16 v[2:5], v[98:101], v[86:89], v[2:5]
	v_mfma_f32_16x16x32_bf16 v[50:53], v[102:105], v[86:89], v[50:53]
	s_setprio 1
	s_lshl_b32 s16, s15, 14
	v_or_b32_e32 v0, s16, v71
	v_add_u32_e32 v86, v0, v73
	v_add_u32_e32 v0, v0, v72
	s_waitcnt vmcnt(0)
	ds_read_b128 v[74:77], v86
	ds_read_b128 v[78:81], v86 offset:1024
	ds_read_b128 v[82:85], v86 offset:2048
	ds_read_b128 v[86:89], v86 offset:3072
	ds_read_b128 v[90:93], v0 offset:8192
	ds_read_b128 v[94:97], v0 offset:9216
	ds_read_b128 v[98:101], v0 offset:10240
	ds_read_b128 v[102:105], v0 offset:11264
	s_add_i32 s18, s16, 0xffffc000
	s_cmp_gt_i32 s15, 0
	s_mov_b64 s[16:17], 0x8be1180
	v_lshl_add_u64 v[110:111], v[106:107], 0, s[16:17]
	s_cselect_b32 s16, s18, 0x8000
	v_add_u32_e32 v0, s16, v70
	s_nop 0
	v_readfirstlane_b32 s16, v0
	s_mov_b32 m0, s16
	s_mov_b64 s[16:17], 0x8be9180
	global_load_lds_dwordx4 v[110:111], off
	v_add_u32_e32 v110, 0x400, v0
	v_lshl_add_u64 v[106:107], v[106:107], 0, s[16:17]
	v_readfirstlane_b32 s16, v110
	s_mov_b32 m0, s16
	s_mov_b64 s[16:17], 0xd51180
	v_add_u32_e32 v110, 0x2000, v0
	global_load_lds_dwordx4 v[106:107], off
	v_lshl_add_u64 v[106:107], v[108:109], 0, s[16:17]
	v_readfirstlane_b32 s16, v110
	s_mov_b32 m0, s16
	s_mov_b64 s[16:17], 0xd59180
	v_add_u32_e32 v0, 0x2400, v0
	global_load_lds_dwordx4 v[106:107], off
	v_lshl_add_u64 v[106:107], v[108:109], 0, s[16:17]
	v_readfirstlane_b32 s16, v0
	s_mov_b32 m0, s16
	s_nop 0
	global_load_lds_dwordx4 v[106:107], off
	s_setprio 0
	s_add_i32 s16, s15, 1
	s_waitcnt lgkmcnt(0)
	v_mfma_f32_16x16x32_bf16 v[62:65], v[90:93], v[74:77], v[62:65]
	s_cmp_lg_u32 s15, 2
	s_cselect_b32 s15, s16, 0
	s_add_u32 s6, s6, 0x80
	v_mfma_f32_16x16x32_bf16 v[58:61], v[94:97], v[74:77], v[58:61]
	s_addc_u32 s7, s7, 0
	s_cmpk_eq_i32 s6, 0x780
	v_mfma_f32_16x16x32_bf16 v[54:57], v[98:101], v[74:77], v[54:57]
	v_mfma_f32_16x16x32_bf16 v[46:49], v[102:105], v[74:77], v[46:49]
	v_mfma_f32_16x16x32_bf16 v[42:45], v[90:93], v[78:81], v[42:45]
	v_mfma_f32_16x16x32_bf16 v[38:41], v[94:97], v[78:81], v[38:41]
	v_mfma_f32_16x16x32_bf16 v[34:37], v[98:101], v[78:81], v[34:37]
	v_mfma_f32_16x16x32_bf16 v[30:33], v[102:105], v[78:81], v[30:33]
	v_mfma_f32_16x16x32_bf16 v[26:29], v[90:93], v[82:85], v[26:29]
	v_mfma_f32_16x16x32_bf16 v[22:25], v[94:97], v[82:85], v[22:25]
	v_mfma_f32_16x16x32_bf16 v[18:21], v[98:101], v[82:85], v[18:21]
	v_mfma_f32_16x16x32_bf16 v[14:17], v[102:105], v[82:85], v[14:17]
	v_mfma_f32_16x16x32_bf16 v[10:13], v[90:93], v[86:89], v[10:13]
	v_mfma_f32_16x16x32_bf16 v[6:9], v[94:97], v[86:89], v[6:9]
	v_mfma_f32_16x16x32_bf16 v[2:5], v[98:101], v[86:89], v[2:5]
	v_mfma_f32_16x16x32_bf16 v[50:53], v[102:105], v[86:89], v[50:53]
	s_cbranch_scc0 .LBB0_480
	s_waitcnt vmcnt(4) lgkmcnt(0)
	s_barrier
; template <int MI, int NI>
; DI void gemm256(f32x4 (&acc)[MI][NI], const u16* __restrict__ A, int lda, const u16* __restrict__ Bt, int ldb, int K, int m0, int n0, char* smem) {
;     ...
;   for (int kt = 0; kt < nk; ++kt) {
;     if (kt + 1 < nk) asm volatile("s_waitcnt vmcnt(%0) lgkmcnt(0)" :: "n"(LPS) : "memory");
;     else asm volatile("s_waitcnt vmcnt(0) lgkmcnt(0)" ::: "memory");
;     __builtin_amdgcn_s_barrier();
;     __builtin_amdgcn_s_setprio(1);
;     const char* sb = smem + st * STAGE + foff;
;     bf16x8 af[MI], bfr[NI];
; #pragma unroll
;     for (int mi = 0; mi < MI; ++mi) af[mi] = *(const bf16x8*)(sb + (wr * MI + mi) * 1024);
; #pragma unroll
;     for (int ni = 0; ni < NI; ++ni) bfr[ni] = *(const bf16x8*)(sb + ABYTES + (wc * NI + ni) * 1024);
;     __builtin_amdgcn_sched_barrier(0x0);
;     if (kt + 2 < nk) { const int s2 = st >= 1 ? st - 1 : 2; G256_ISSUE(s2, (kt + 2) * 32); }
;     __builtin_amdgcn_s_setprio(0);
; #pragma unroll
;     for (int mi = 0; mi < MI; ++mi)
; #pragma unroll
;       for (int ni = 0; ni < NI; ++ni)
;         acc[mi][ni] = __builtin_amdgcn_mfma_f32_16x16x32_bf16(bfr[ni], af[mi], acc[mi][ni], 0, 0, 0);
;     st = st == 2 ? 0 : st + 1;
;   }
;   asm volatile("s_waitcnt lgkmcnt(0)" ::: "memory");
;   __builtin_amdgcn_s_barrier();
	s_setprio 1
	v_add_u32_e32 v0, v71, v73
	v_add_u32_e32 v98, v71, v72
	s_waitcnt vmcnt(0)
	ds_read_b128 v[66:69], v0
	ds_read_b128 v[74:77], v0 offset:1024
	ds_read_b128 v[78:81], v0 offset:2048
	ds_read_b128 v[82:85], v0 offset:3072
	ds_read_b128 v[70:73], v98 offset:8192
	ds_read_b128 v[86:89], v98 offset:9216
	ds_read_b128 v[90:93], v98 offset:10240
	ds_read_b128 v[94:97], v98 offset:11264
	s_setprio 0
	s_waitcnt lgkmcnt(3)
	v_mfma_f32_16x16x32_bf16 v[62:65], v[70:73], v[66:69], v[62:65]
	s_waitcnt vmcnt(0) lgkmcnt(0)
	s_barrier
	s_waitcnt lgkmcnt(2)
	v_mfma_f32_16x16x32_bf16 v[58:61], v[86:89], v[66:69], v[58:61]
	s_waitcnt lgkmcnt(1)
	v_mfma_f32_16x16x32_bf16 v[54:57], v[90:93], v[66:69], v[54:57]
	s_waitcnt lgkmcnt(0)
	v_mfma_f32_16x16x32_bf16 v[46:49], v[94:97], v[66:69], v[46:49]
	v_mfma_f32_16x16x32_bf16 v[42:45], v[70:73], v[74:77], v[42:45]
	v_mfma_f32_16x16x32_bf16 v[38:41], v[86:89], v[74:77], v[38:41]
	v_mfma_f32_16x16x32_bf16 v[34:37], v[90:93], v[74:77], v[34:37]
	v_mfma_f32_16x16x32_bf16 v[30:33], v[94:97], v[74:77], v[30:33]
	v_mfma_f32_16x16x32_bf16 v[26:29], v[70:73], v[78:81], v[26:29]
	v_mfma_f32_16x16x32_bf16 v[22:25], v[86:89], v[78:81], v[22:25]
	v_mfma_f32_16x16x32_bf16 v[18:21], v[90:93], v[78:81], v[18:21]
	v_mfma_f32_16x16x32_bf16 v[14:17], v[94:97], v[78:81], v[14:17]
	v_mfma_f32_16x16x32_bf16 v[10:13], v[70:73], v[82:85], v[10:13]
	v_mfma_f32_16x16x32_bf16 v[6:9], v[86:89], v[82:85], v[6:9]
	v_mfma_f32_16x16x32_bf16 v[2:5], v[90:93], v[82:85], v[2:5]
	v_mfma_f32_16x16x32_bf16 v[50:53], v[94:97], v[82:85], v[50:53]
	s_setprio 1
	ds_read_b128 v[66:69], v0 offset:16384
	ds_read_b128 v[70:73], v0 offset:17408
	ds_read_b128 v[74:77], v0 offset:18432
	ds_read_b128 v[130:133], v0 offset:19456
	ds_read_b128 v[78:81], v98 offset:24576
	ds_read_b128 v[134:137], v98 offset:25600
	ds_read_b128 v[138:141], v98 offset:26624
	ds_read_b128 v[142:145], v98 offset:27648
	s_setprio 0
	s_waitcnt lgkmcnt(3)
	v_mfma_f32_16x16x32_bf16 v[126:129], v[78:81], v[66:69], v[62:65]
	s_waitcnt lgkmcnt(0)
	s_barrier
; template <int MI, int NI>
; DI void gemm256(f32x4 (&acc)[MI][NI], const u16* __restrict__ A, int lda, const u16* __restrict__ Bt, int ldb, int K, int m0, int n0, char* smem) {
;     ...
;   const int srow = lane >> 2, scol = ((lane & 3) ^ ((lane >> 5) << 1)) * 8;
;   const u16* Ag = A + (size_t)(m0 + wave * NAW * 16 + srow) * lda + scol;
;   const u16* Bg = Bt + (size_t)(n0 + wave * NBW * 16 + srow) * ldb + scol;
;   char* la = smem + (wave * NAW) * 1024 + lane * 16;
;   char* lb = smem + ABYTES + (wave * NBW) * 1024 + lane * 16;
;     ...
;   const int nk = K >> 5;
;   G256_ISSUE(0, 0);
;   if (nk > 1) G256_ISSUE(1, 32);
;   const int foff = lr * 64 + ((lq ^ ((lr >> 3) << 1)) * 16);
;   int st = 0;
; DI void phase_merge(const Params& p, int l, int Mout, char* smem) {
;     ...
;       f32x4 ab[4][4]; zero_accm<4, 4>(ab);
;       {
;         const int Kb = br == 1 ? 512 : 256;
;         const u16* Ab = br == 0 ? opool : br == 1 ? omla : orw;
;         const u16* Wb = (const u16*)(wl + (br == 0 ? WO_BRP : br == 1 ? WO_BRM : WO_BRR));
;         gemm256<4, 4>(ab, Ab, Kb, Wb, Kb, Kb, m0, n0, smem);
	s_waitcnt lgkmcnt(2)
	v_mfma_f32_16x16x32_bf16 v[122:125], v[134:137], v[66:69], v[58:61]
	s_waitcnt lgkmcnt(1)
	v_mfma_f32_16x16x32_bf16 v[118:121], v[138:141], v[66:69], v[54:57]
	s_waitcnt lgkmcnt(0)
	v_mfma_f32_16x16x32_bf16 v[114:117], v[142:145], v[66:69], v[46:49]
	v_mfma_f32_16x16x32_bf16 v[110:113], v[78:81], v[70:73], v[42:45]
	v_mfma_f32_16x16x32_bf16 v[106:109], v[134:137], v[70:73], v[38:41]
	v_mfma_f32_16x16x32_bf16 v[102:105], v[138:141], v[70:73], v[34:37]
	v_mfma_f32_16x16x32_bf16 v[98:101], v[142:145], v[70:73], v[30:33]
	v_mfma_f32_16x16x32_bf16 v[94:97], v[78:81], v[74:77], v[26:29]
	v_mfma_f32_16x16x32_bf16 v[90:93], v[134:137], v[74:77], v[22:25]
	v_mfma_f32_16x16x32_bf16 v[86:89], v[138:141], v[74:77], v[18:21]
	v_mfma_f32_16x16x32_bf16 v[82:85], v[142:145], v[74:77], v[14:17]
	v_mfma_f32_16x16x32_bf16 v[78:81], v[78:81], v[130:133], v[10:13]
	v_mfma_f32_16x16x32_bf16 v[74:77], v[134:137], v[130:133], v[6:9]
	v_mfma_f32_16x16x32_bf16 v[70:73], v[138:141], v[130:133], v[2:5]
	v_mfma_f32_16x16x32_bf16 v[66:69], v[142:145], v[130:133], v[50:53]
	s_cmp_eq_u32 s11, 1
	s_movk_i32 s6, 0x200
	v_mov_b32_e32 v8, v163
	s_cselect_b32 s18, s6, 0x100
	s_mov_b32 s6, 0x1caa1000
	s_mov_b32 s7, 0xba0000
	s_cselect_b32 s6, s6, 0x18481000
	v_ashrrev_i32_e32 v9, 6, v8
	v_bfe_u32 v0, v8, 2, 4
	s_cselect_b32 s7, s7, 0xca0000
	s_cselect_b32 s15, 9, 8
	s_cmp_eq_u32 s11, 0
	v_and_b32_e32 v2, 3, v8
	v_lshrrev_b32_e32 v3, 4, v8
	v_lshl_or_b32 v6, v9, 5, v0
	s_cselect_b32 s6, 0x1b781000, s6
	v_bitop3_b32 v5, v3, v2, 2 bitop3:0x6c
	v_add_u32_e32 v2, s13, v6
	s_cselect_b32 s16, 0xb20000, s7
	s_add_u32 s6, s62, s6
	v_ashrrev_i32_e32 v3, 31, v2
	s_addc_u32 s7, s63, 0
	v_lshlrev_b64 v[2:3], s15, v[2:3]
	v_and_b32_e32 v4, 63, v8
	v_lshl_add_u64 v[2:3], v[2:3], 1, s[6:7]
	v_lshlrev_b32_e32 v0, 4, v5
	s_mov_b32 s17, s2
	v_lshl_add_u64 v[228:229], v[2:3], 0, v[0:1]
	v_add_u32_e32 v2, s12, v6
	v_lshlrev_b32_e32 v4, 4, v4
	s_add_u32 s16, s44, s16
	v_ashrrev_i32_e32 v3, 31, v2
	v_lshl_or_b32 v250, v9, 11, v4
	s_addc_u32 s17, s45, 0
	v_lshlrev_b64 v[2:3], s15, v[2:3]
	v_readfirstlane_b32 s6, v250
	v_or_b32_e32 v7, 0x400, v250
	v_lshl_add_u64 v[2:3], v[2:3], 1, s[16:17]
	v_add_u32_e32 v6, 0x2000, v250
	s_mov_b32 m0, s6
	s_lshl_b32 s64, s18, 5
	v_readfirstlane_b32 s6, v7
	global_load_lds_dwordx4 v[228:229], off
	v_lshl_add_u64 v[4:5], v[228:229], 0, s[64:65]
	s_mov_b32 m0, s6
	v_lshl_add_u64 v[230:231], v[2:3], 0, v[0:1]
	v_readfirstlane_b32 s6, v6
	v_add_u32_e32 v0, 0x2400, v250
	global_load_lds_dwordx4 v[4:5], off
	s_mov_b32 m0, s6
	v_readfirstlane_b32 s6, v0
	v_add_u32_e32 v0, 0x4000, v250
	global_load_lds_dwordx4 v[230:231], off
	v_lshl_add_u64 v[2:3], v[230:231], 0, s[64:65]
	s_mov_b32 m0, s6
	v_readfirstlane_b32 s6, v0
	v_add_u32_e32 v0, 0x4400, v250
	global_load_lds_dwordx4 v[2:3], off
	v_lshl_add_u64 v[6:7], v[228:229], 0, 64
	s_mov_b32 m0, s6
	v_readfirstlane_b32 s6, v0
	v_add_u32_e32 v0, 0x6000, v250
	global_load_lds_dwordx4 v[6:7], off
	v_lshl_add_u64 v[4:5], v[4:5], 0, 64
	s_mov_b32 m0, s6
	v_readfirstlane_b32 s6, v0
	v_add_u32_e32 v0, 0x6400, v250
	global_load_lds_dwordx4 v[4:5], off
	v_lshl_add_u64 v[4:5], v[230:231], 0, 64
	s_mov_b32 m0, s6
	v_readfirstlane_b32 s6, v0
	global_load_lds_dwordx4 v[4:5], off
	v_lshl_add_u64 v[2:3], v[2:3], 0, 64
	s_mov_b32 m0, s6
	v_lshlrev_b32_e32 v0, 6, v8
	global_load_lds_dwordx4 v[2:3], off
	v_lshlrev_b32_e32 v2, 2, v8
	v_and_b32_e32 v3, 48, v8
	v_bitop3_b32 v2, v2, v3, 32 bitop3:0x6c
	v_and_or_b32 v248, v0, s59, v2
	v_lshlrev_b32_e32 v2, 5, v8
	s_lshl_b32 s6, s18, 4
	v_lshlrev_b32_e32 v0, 12, v9
	v_and_b32_e32 v249, 0xfffff000, v2
	v_mov_b32_e32 v2, 0
	s_mov_b32 s16, 1
	s_mov_b32 s15, 0
	s_lshr_b32 s17, s18, 5
	v_and_b32_e32 v0, 0x1000, v0
	s_mov_b32 s64, 64
	s_lshl_b32 s6, s6, 1
	v_mov_b32_e32 v3, v2
	v_mov_b32_e32 v4, v2
	v_mov_b32_e32 v5, v2
	v_mov_b32_e32 v6, v2
	v_mov_b32_e32 v7, v2
	v_mov_b32_e32 v8, v2
	v_mov_b32_e32 v9, v2
	v_mov_b32_e32 v10, v2
	v_mov_b32_e32 v11, v2
	v_mov_b32_e32 v12, v2
	v_mov_b32_e32 v13, v2
	v_mov_b32_e32 v14, v2
	v_mov_b32_e32 v15, v2
	v_mov_b32_e32 v16, v2
	v_mov_b32_e32 v17, v2
	v_mov_b32_e32 v18, v2
	v_mov_b32_e32 v19, v2
	v_mov_b32_e32 v20, v2
	v_mov_b32_e32 v21, v2
	v_mov_b32_e32 v22, v2
	v_mov_b32_e32 v23, v2
	v_mov_b32_e32 v24, v2
	v_mov_b32_e32 v25, v2
	v_mov_b32_e32 v26, v2
	v_mov_b32_e32 v27, v2
	v_mov_b32_e32 v28, v2
	v_mov_b32_e32 v29, v2
	v_mov_b32_e32 v30, v2
	v_mov_b32_e32 v31, v2
	v_mov_b32_e32 v32, v2
	v_mov_b32_e32 v33, v2
	v_mov_b32_e32 v34, v2
	v_mov_b32_e32 v35, v2
	v_mov_b32_e32 v36, v2
	v_mov_b32_e32 v37, v2
	v_mov_b32_e32 v38, v2
	v_mov_b32_e32 v39, v2
	v_mov_b32_e32 v40, v2
	v_mov_b32_e32 v41, v2
	v_mov_b32_e32 v42, v2
	v_mov_b32_e32 v43, v2
	v_mov_b32_e32 v44, v2
	v_mov_b32_e32 v45, v2
	v_mov_b32_e32 v46, v2
	v_mov_b32_e32 v47, v2
	v_mov_b32_e32 v48, v2
	v_mov_b32_e32 v49, v2
	v_mov_b32_e32 v50, v2
	v_mov_b32_e32 v51, v2
	v_mov_b32_e32 v52, v2
	v_mov_b32_e32 v53, v2
	v_mov_b32_e32 v54, v2
	v_mov_b32_e32 v55, v2
	v_mov_b32_e32 v56, v2
	v_mov_b32_e32 v57, v2
	v_mov_b32_e32 v58, v2
	v_mov_b32_e32 v59, v2
	v_mov_b32_e32 v60, v2
	v_mov_b32_e32 v61, v2
	v_mov_b32_e32 v62, v2
	v_mov_b32_e32 v63, v2
	v_mov_b32_e32 v64, v2
	v_mov_b32_e32 v65, v2
	s_branch .LBB0_483

; DI void phase_norm(const float* xl, const float* xc, const float* tab  , u16* hb, int M) {
;     ...
;   const int wave = tid__ >> 6, lane = tid__ & 63;
;   const int nw = gridDim.x * 4, rpw = (M + nw - 1) / nw;
;   const int rbeg = (blk__ * 4 + wave) * rpw, rend = min(rbeg + rpw, M);
;   int cur_b9 = -1;
;   float4 g[4], sh[4];
; #pragma unroll
;   for (int i = 0; i < 4; ++i) { g[i] = make_float4(0.f, 0.f, 0.f, 0.f); sh[i] = g[i]; }
;   float4 vn[4];
;   if (rbeg < rend) {
;     const float* xp0 = xrow(xl, xc, rbeg);
; #pragma unroll
;     for (int i = 0; i < 4; ++i) vn[i] = *(const float4*)(xp0 + i * 256 + lane * 4);
;   }
;   for (int r = rbeg; r < rend; ++r) {
;     const int b9 = r < NTL ? r >> 12 : 8;
;     float4 v[4];
; #pragma unroll
;     for (int i = 0; i < 4; ++i) v[i] = vn[i];
;     {
;       const float* xpn = xrow(xl, xc, min(r + 1, rend - 1));
; #pragma unroll
;       for (int i = 0; i < 4; ++i) vn[i] = *(const float4*)(xpn + i * 256 + lane * 4);
.LBB0_486:
	s_andn2_b64 vcc, exec, s[4:5]
	s_cbranch_vccnz .LBB0_496
	v_mov_b32_e32 v18, v163
	s_mov_b32 s4, s2
	s_nop 0
	v_ashrrev_i32_e32 v0, 6, v18
	v_lshl_add_u32 v0, s4, 2, v0
	v_readlane_b32 s4, v254, 56
	s_nop 1
	v_mul_lo_u32 v66, v0, s4
	v_add_u32_e32 v0, s4, v66
	v_readlane_b32 s4, v253, 48
	s_nop 1
	v_min_i32_e32 v69, s4, v0
	v_cmp_lt_i32_e32 vcc, v66, v69
	s_and_saveexec_b64 s[4:5], vcc
	s_cbranch_execz .LBB0_492
	v_add_u32_e32 v0, 0xffff8000, v66
	v_cmp_gt_i32_e32 vcc, s58, v66
	v_readlane_b32 s6, v253, 55
	v_ashrrev_i32_e32 v67, 31, v66
	v_cndmask_b32_e32 v2, v0, v66, vcc
	v_mov_b32_e32 v0, s6
	v_readlane_b32 s6, v253, 53
	v_cndmask_b32_e32 v3, 0, v67, vcc
	v_lshlrev_b64 v[2:3], 12, v[2:3]
	s_waitcnt vmcnt(0)
	v_mov_b32_e32 v4, s6
	v_readlane_b32 s6, v253, 56
	v_cndmask_b32_e32 v5, v0, v4, vcc
	v_lshrrev_b32_e32 v20, 1, v66
	v_mov_b32_e32 v21, 0
	v_lshlrev_b64 v[20:21], 12, v[20:21]
	v_and_b32_e32 v90, 1, v66
	v_lshl_or_b32 v20, v90, 6, v20
	v_mov_b32_e32 v0, s6
	v_readlane_b32 s6, v253, 54
	v_mov_b32_e32 v73, -1
	v_add_u32_e32 v72, -1, v69
	v_mov_b32_e32 v4, s6
	v_cndmask_b32_e32 v4, v0, v4, vcc
	v_lshlrev_b32_e32 v0, 2, v18
	v_and_b32_e32 v68, 0xfc, v0
	v_lshl_add_u64 v[2:3], v[4:5], 0, v[2:3]
	v_lshlrev_b32_e32 v0, 2, v68
	v_lshl_add_u64 v[14:15], v[2:3], 0, v[0:1]
	flat_load_dwordx4 v[2:5], v[14:15]
	flat_load_dwordx4 v[6:9], v[14:15] offset:1024
	flat_load_dwordx4 v[10:13], v[14:15] offset:2048
	s_nop 0
	flat_load_dwordx4 v[14:17], v[14:15] offset:3072
	v_bfe_u32 v0, v18, 3, 3
	v_lshl_or_b32 v20, v0, 7, v20
	v_and_b32_e32 v0, 7, v18
	v_lshl_or_b32 v20, v0, 3, v20
	v_mov_b32_e32 v0, v1
	v_lshl_add_u64 v[70:71], s[52:53], 0, v[20:21]
	s_mov_b64 s[6:7], 0
	v_mov_b64_e32 v[44:45], v[0:1]
	s_waitcnt lgkmcnt(0)
	v_mov_b64_e32 v[42:43], v[0:1]
	v_mov_b64_e32 v[32:33], v[0:1]
	v_mov_b64_e32 v[30:31], v[0:1]
	v_mov_b64_e32 v[28:29], v[0:1]
	v_mov_b64_e32 v[26:27], v[0:1]
	v_mov_b64_e32 v[40:41], v[0:1]
	v_mov_b64_e32 v[38:39], v[0:1]
	v_mov_b64_e32 v[18:19], v[0:1]
	v_mov_b64_e32 v[20:21], v[0:1]
	v_mov_b64_e32 v[22:23], v[0:1]
	v_mov_b64_e32 v[24:25], v[0:1]
	v_mov_b64_e32 v[34:35], v[0:1]
	v_mov_b64_e32 v[36:37], v[0:1]
	v_mov_b64_e32 v[46:47], v[0:1]
	v_mov_b64_e32 v[48:49], v[0:1]
	s_branch .LBB0_490
; DI unsigned pack2(float a, float b) { float2_t v = {a, b}; bf16x2_t r = __builtin_convertvector(v, bf16x2_t); return __builtin_bit_cast(unsigned, r); }
; DI void phase_norm(const float* xl, const float* xc, const float* tab  , u16* hb, int M) {
;     ...
;   for (int r = rbeg; r < rend; ++r) {
;     const int b9 = r < NTL ? r >> 12 : 8;
;     float4 v[4];
; #pragma unroll
;     for (int i = 0; i < 4; ++i) v[i] = vn[i];
;     {
;       const float* xpn = xrow(xl, xc, min(r + 1, rend - 1));
; #pragma unroll
;       for (int i = 0; i < 4; ++i) vn[i] = *(const float4*)(xpn + i * 256 + lane * 4);
;     }
;     if (b9 != cur_b9) {
;       cur_b9 = b9;
;       const float* t = tab + b9 * 2048;
; #pragma unroll
;       for (int i = 0; i < 4; ++i) { g[i] = *(const float4*)(t + i * 256 + lane * 4); sh[i] = *(const float4*)(t + 1024 + i * 256 + lane * 4); }
;     }
;     float s = 0.f;
; #pragma unroll
;     for (int i = 0; i < 4; ++i) s += v[i].x * v[i].x + v[i].y * v[i].y + v[i].z * v[i].z + v[i].w * v[i].w;
;     s = wavesum(s);
;     const float rs = rsqrtf(s * (1.f / 1024.f) + 1e-6f);
; #pragma unroll
;     for (int i = 0; i < 4; ++i) {
;       const int k = i * 256 + lane * 4;
;       *(uint2*)(hb + (size_t)r * 1024 + k) = make_uint2(pack2(v[i].x * rs * g[i].x + sh[i].x, v[i].y * rs * g[i].y + sh[i].y), pack2(v[i].z * rs * g[i].z + sh[i].z, v[i].w * rs * g[i].w + sh[i].w));
;     }
.LBB0_489:
	s_or_b64 exec, exec, s[8:9]
	s_waitcnt vmcnt(0) lgkmcnt(0)
	v_pk_mul_f32 v[74:75], v[2:3], v[2:3]
	v_pk_mul_f32 v[78:79], v[6:7], v[6:7]
	v_mov_b32_e32 v82, v14
	v_mov_b32_e32 v83, v10
	v_pk_mul_f32 v[76:77], v[4:5], v[4:5]
	v_pk_mul_f32 v[80:81], v[8:9], v[8:9]
	v_pk_mul_f32 v[82:83], v[82:83], v[82:83]
	v_mov_b32_e32 v84, v15
	v_mov_b32_e32 v85, v11
	v_add_f32_e32 v0, v75, v74
	v_add_f32_e32 v67, v79, v78
	v_pk_fma_f32 v[82:83], v[84:85], v[84:85], v[82:83]
	v_mov_b32_e32 v84, v16
	v_mov_b32_e32 v85, v12
	v_add_f32_e32 v0, v76, v0
	v_add_f32_e32 v67, v80, v67
	v_pk_fma_f32 v[82:83], v[84:85], v[84:85], v[82:83]
	v_mov_b32_e32 v84, v17
	v_mov_b32_e32 v85, v13
	v_add_f32_e32 v0, v77, v0
	v_add_f32_e32 v67, v81, v67
	v_pk_fma_f32 v[82:83], v[84:85], v[84:85], v[82:83]
	v_add_f32_e32 v0, v67, v0
	v_add_f32_e32 v0, v83, v0
	v_add_f32_e32 v0, v82, v0
	s_nop 1
	v_add_f32_dpp v0, v0, v0 row_ror:8 row_mask:0xf bank_mask:0xf bound_ctrl:1
	s_nop 1
	v_add_f32_dpp v0, v0, v0 row_ror:4 row_mask:0xf bank_mask:0xf bound_ctrl:1
	s_nop 1
	v_add_f32_dpp v0, v0, v0 row_ror:2 row_mask:0xf bank_mask:0xf bound_ctrl:1
	s_nop 1
	v_add_f32_dpp v0, v0, v0 row_ror:1 row_mask:0xf bank_mask:0xf bound_ctrl:1
	s_nop 0
	v_readlane_b32 s9, v0, 16
	v_readlane_b32 s8, v0, 0
	s_nop 0
	v_mov_b32_e32 v67, s9
	v_add_f32_e32 v67, s8, v67
	v_readlane_b32 s8, v0, 32
	s_nop 1
	v_add_f32_e32 v67, s8, v67
	v_readlane_b32 s8, v0, 48
	s_nop 1
	v_add_f32_e32 v0, s8, v67
	v_fmamk_f32 v0, v0, 0x3a800000, v162
	v_mul_f32_e32 v67, 0x4b800000, v0
	v_cmp_gt_f32_e32 vcc, s31, v0
	s_mov_b64 s[8:9], 0x800
	s_nop 0
	v_cndmask_b32_e32 v0, v0, v67, vcc
	v_rsq_f32_e32 v0, v0
	s_nop 0
	v_mul_f32_e32 v67, 0x45800000, v0
	v_cndmask_b32_e32 v0, v0, v67, vcc
	v_pk_mul_f32 v[2:3], v[2:3], v[0:1] op_sel_hi:[1,0]
	v_pk_mul_f32 v[4:5], v[4:5], v[0:1] op_sel_hi:[1,0]
	v_pk_fma_f32 v[2:3], v[18:19], v[2:3], v[38:39]
	v_pk_fma_f32 v[4:5], v[20:21], v[4:5], v[40:41]
	v_cvt_pk_bf16_f32 v2, v2, v3
	v_cvt_pk_bf16_f32 v3, v4, v5
	flat_store_dwordx2 v[70:71], v[2:3]
	v_pk_mul_f32 v[2:3], v[6:7], v[0:1] op_sel_hi:[1,0]
	v_pk_mul_f32 v[4:5], v[8:9], v[0:1] op_sel_hi:[1,0]
	v_pk_fma_f32 v[2:3], v[22:23], v[2:3], v[26:27]
	v_pk_fma_f32 v[4:5], v[24:25], v[4:5], v[28:29]
	v_cvt_pk_bf16_f32 v2, v2, v3
	v_cvt_pk_bf16_f32 v3, v4, v5
	flat_store_dwordx2 v[70:71], v[2:3] offset:1024
	v_pk_mul_f32 v[2:3], v[10:11], v[0:1] op_sel_hi:[1,0]
	v_pk_mul_f32 v[4:5], v[12:13], v[0:1] op_sel_hi:[1,0]
	v_pk_fma_f32 v[2:3], v[34:35], v[2:3], v[30:31]
	v_pk_fma_f32 v[4:5], v[36:37], v[4:5], v[32:33]
	v_cvt_pk_bf16_f32 v2, v2, v3
	v_cvt_pk_bf16_f32 v3, v4, v5
	flat_store_dwordx2 v[70:71], v[2:3] offset:2048
	v_pk_mul_f32 v[2:3], v[14:15], v[0:1] op_sel_hi:[1,0]
	v_pk_mul_f32 v[4:5], v[16:17], v[0:1] op_sel_hi:[1,0]
	v_pk_fma_f32 v[2:3], v[46:47], v[2:3], v[42:43]
	v_pk_fma_f32 v[4:5], v[48:49], v[4:5], v[44:45]
	v_cvt_pk_bf16_f32 v2, v2, v3
	v_cvt_pk_bf16_f32 v3, v4, v5
	v_cmp_ge_i32_e32 vcc, v66, v69
	flat_store_dwordx2 v[70:71], v[2:3] offset:3072
	v_and_b32_e32 v90, 1, v66
	v_mul_u32_u24_e32 v90, 0xf80, v90
	v_sub_u32_e32 v90, 0xfc0, v90
	v_mov_b32_e32 v91, 0
	v_lshl_add_u64 v[70:71], v[70:71], 0, v[90:91]
	s_or_b64 s[6:7], vcc, s[6:7]
	v_mov_b64_e32 v[4:5], v[64:65]
	v_mov_b64_e32 v[2:3], v[62:63]
	v_mov_b64_e32 v[8:9], v[60:61]
	v_mov_b64_e32 v[6:7], v[58:59]
	v_mov_b64_e32 v[12:13], v[56:57]
	v_mov_b64_e32 v[10:11], v[54:55]
	v_mov_b64_e32 v[16:17], v[52:53]
	v_mov_b64_e32 v[14:15], v[50:51]
	s_andn2_b64 exec, exec, s[6:7]
	s_cbranch_execz .LBB0_492
.LBB0_490:
	v_min_i32_e32 v67, 0x8000, v66
	v_add_u32_e32 v66, 1, v66
	v_min_i32_e32 v0, v66, v72
	v_add_u32_e32 v50, 0xffff8000, v0
	v_cmp_gt_i32_e32 vcc, s58, v0
	v_readlane_b32 s8, v253, 55
	v_ashrrev_i32_e32 v51, 31, v0
	v_cndmask_b32_e32 v50, v50, v0, vcc
	v_mov_b32_e32 v0, s8
	v_readlane_b32 s8, v253, 53
	v_cndmask_b32_e32 v51, 0, v51, vcc
	v_lshlrev_b64 v[50:51], 12, v[50:51]
	v_mov_b32_e32 v52, s8
	v_readlane_b32 s8, v253, 56
	v_cndmask_b32_e32 v53, v0, v52, vcc
	v_ashrrev_i32_e32 v67, 12, v67
	v_mov_b32_e32 v0, s8
	v_readlane_b32 s8, v253, 54
	s_nop 1
	v_mov_b32_e32 v52, s8
	v_cndmask_b32_e32 v52, v0, v52, vcc
	v_lshl_add_u64 v[50:51], v[52:53], 0, v[50:51]
	v_lshlrev_b32_e32 v0, 2, v68
	v_lshl_add_u64 v[50:51], v[50:51], 0, v[0:1]
	flat_load_dwordx4 v[62:65], v[50:51]
	flat_load_dwordx4 v[58:61], v[50:51] offset:1024
	flat_load_dwordx4 v[54:57], v[50:51] offset:2048
	s_nop 0
	flat_load_dwordx4 v[50:53], v[50:51] offset:3072
	v_cmp_ne_u32_e32 vcc, v67, v73
	s_and_saveexec_b64 s[8:9], vcc
	s_cbranch_execz .LBB0_489
	v_lshlrev_b32_e32 v18, 11, v67
	v_readlane_b32 s10, v253, 60
	v_ashrrev_i32_e32 v19, 31, v18
	v_readlane_b32 s11, v253, 61
	v_mov_b32_e32 v73, v67
	s_nop 0
	v_lshl_add_u64 v[18:19], v[18:19], 2, s[10:11]
	v_lshl_add_u64 v[38:39], v[18:19], 0, v[0:1]
	s_mov_b64 s[10:11], 0x1000
	v_add_co_u32_e32 v40, vcc, 0x1000, v38
	v_lshl_add_u64 v[42:43], v[38:39], 0, s[10:11]
	s_nop 0
	v_addc_co_u32_e32 v41, vcc, 0, v39, vcc
	flat_load_dwordx4 v[18:21], v[38:39]
	flat_load_dwordx4 v[22:25], v[38:39] offset:1024
	flat_load_dwordx4 v[26:29], v[42:43] offset:1024
	flat_load_dwordx4 v[30:33], v[42:43] offset:2048
	flat_load_dwordx4 v[34:37], v[38:39] offset:2048
	flat_load_dwordx4 v[46:49], v[38:39] offset:3072
	s_nop 0
	flat_load_dwordx4 v[38:41], v[40:41]
	s_nop 0
	flat_load_dwordx4 v[42:45], v[42:43] offset:3072
	s_branch .LBB0_489

; DI bool tile_map(int it, int NTM, int NTN, int blk, int nblk, int& tm, int& tn) {
;   const int xcd = blk & 7, local = blk >> 3, LB = nblk >> 3;
;   const int R = NTM >> 3;
;   const int s = it * LB + local;
;   if (s >= R * NTN) return false;
;   const int F = R >> 3, per_full = 8 * NTN;
;   int mg, r, gm;
;   if (s < F * per_full) { mg = s / per_full; r = s - mg * per_full; gm = 8; }
;   else { mg = F; r = s - F * per_full; gm = R - F * 8; }
;   const int ng = r / (gm * 8);
;   const int r2 = r - ng * gm * 8;
;   const int mi = r2 % gm, ni = r2 / gm;
;   tm = xcd * R + mg * 8 + mi; tn = ng * 8 + ni;
;   return true;
; template <int MI, int NI>
; DI void gemm256(f32x4 (&acc)[MI][NI], const u16* __restrict__ A, int lda, const u16* __restrict__ Bt, int ldb, int K, int m0, int n0, char* smem) {
;     ...
;   const int srow = lane >> 2, scol = ((lane & 3) ^ ((lane >> 5) << 1)) * 8;
;   const u16* Ag = A + (size_t)(m0 + wave * NAW * 16 + srow) * lda + scol;
;   const u16* Bg = Bt + (size_t)(n0 + wave * NBW * 16 + srow) * ldb + scol;
;   char* la = smem + (wave * NAW) * 1024 + lane * 16;
;   char* lb = smem + ABYTES + (wave * NBW) * 1024 + lane * 16;
;     ...
;   const int nk = K >> 5;
;   G256_ISSUE(0, 0);
;   if (nk > 1) G256_ISSUE(1, 32);
.LBB0_856:
	s_lshl_b32 s7, s0, 3
	v_cvt_f32_ubyte0_e32 v0, s7
	v_rcp_iflag_f32_e32 v0, v0
	s_sub_i32 s9, 0, s7
	s_add_i32 s4, s5, s4
	s_abs_i32 s5, s4
	v_mul_f32_e32 v0, 0x4f7ffffe, v0
	v_cvt_u32_f32_e32 v0, v0
	s_ashr_i32 s8, s4, 31
	v_mov_b32_e32 v8, v163
	v_readfirstlane_b32 s10, v0
	s_mul_i32 s9, s9, s10
	s_mul_hi_u32 s9, s10, s9
	s_add_i32 s10, s10, s9
	s_mul_hi_u32 s9, s5, s10
	v_cvt_f32_ubyte0_e32 v0, s0
	s_mul_i32 s10, s9, s7
	v_rcp_iflag_f32_e32 v0, v0
	s_sub_i32 s5, s5, s10
	s_add_i32 s11, s9, 1
	s_sub_i32 s10, s5, s7
	s_cmp_ge_u32 s5, s7
	s_cselect_b32 s9, s11, s9
	v_mul_f32_e32 v0, 0x4f7ffffe, v0
	s_cselect_b32 s5, s10, s5
	s_add_i32 s10, s9, 1
	v_cvt_u32_f32_e32 v0, v0
	s_cmp_ge_u32 s5, s7
	s_cselect_b32 s5, s10, s9
	s_xor_b32 s9, s5, s8
	s_sub_i32 s10, s9, s8
	s_sub_i32 s11, 0, s0
	v_readfirstlane_b32 s12, v0
	s_mul_i32 s5, s10, s7
	s_mul_i32 s11, s11, s12
	s_sub_i32 s4, s4, s5
	s_mul_hi_u32 s11, s12, s11
	s_abs_i32 s5, s4
	s_add_i32 s12, s12, s11
	s_mul_hi_u32 s11, s5, s12
	s_mul_i32 s12, s11, s0
	s_sub_i32 s5, s5, s12
	s_ashr_i32 s7, s4, 31
	s_add_i32 s12, s11, 1
	s_sub_i32 s13, s5, s0
	s_cmp_ge_u32 s5, s0
	s_cselect_b32 s11, s12, s11
	s_cselect_b32 s5, s13, s5
	s_add_i32 s12, s11, 1
	s_cmp_ge_u32 s5, s0
	s_cselect_b32 s5, s12, s11
	s_xor_b32 s11, s5, s7
	s_sub_i32 s12, s11, s7
	s_mul_i32 s0, s12, s0
	s_add_i32 s1, s1, s15
	s_sub_i32 s0, s4, s0
	s_add_i32 s1, s1, s0
	s_lshl_b32 s5, s1, 8
	v_and_b32_e32 v0, 3, v8
	v_lshrrev_b32_e32 v2, 4, v8
	v_and_b32_e32 v10, 0xffffffc0, v8
	v_bfe_u32 v9, v8, 2, 4
	v_bitop3_b32 v0, v2, v0, 2 bitop3:0x6c
	v_add_u32_e32 v2, s5, v10
	s_lshl_b32 s0, s10, 10
	s_lshl_b32 s4, s12, 7
	v_and_b32_e32 v6, 63, v8
	v_ashrrev_i32_e32 v7, 6, v8
	v_or_b32_e32 v2, v2, v9
	s_add_i32 s4, s4, s0
	s_mov_b32 s0, s2
	v_ashrrev_i32_e32 v3, 31, v2
	v_lshlrev_b32_e32 v12, 12, v7
	v_lshlrev_b32_e32 v6, 4, v6
	v_lshlrev_b64 v[2:3], 11, v[2:3]
	v_or_b32_e32 v138, v12, v6
	v_lshl_add_u64 v[2:3], s[22:23], 0, v[2:3]
	v_lshlrev_b32_e32 v0, 4, v0
	v_readfirstlane_b32 s0, v138
	v_or_b32_e32 v14, 0x400, v138
	v_lshl_add_u64 v[2:3], v[2:3], 0, v[0:1]
	v_bfe_i32 v199, v163, 2, 1
	v_and_b32_e32 v198, 0xfffff840, v199
	v_lshl_add_u64 v[2:3], v[2:3], 0, v[198:199]
	v_lshlrev_b32_e32 v11, 5, v7
	s_mov_b32 m0, s0
	v_readfirstlane_b32 s0, v14
	v_add_u32_e32 v4, s4, v11
	v_lshl_or_b32 v139, v7, 11, v6
	global_load_lds_dwordx4 v[2:3], off
	v_lshl_add_u64 v[6:7], v[2:3], 0, s[68:69]
	s_mov_b32 m0, s0
	s_mov_b64 s[0:1], 0x10000
	v_or_b32_e32 v14, 0x800, v138
	v_or_b32_e32 v4, v4, v9
	global_load_lds_dwordx4 v[6:7], off
	v_lshl_add_u64 v[6:7], v[2:3], 0, s[0:1]
	v_readfirstlane_b32 s0, v14
	v_ashrrev_i32_e32 v5, 31, v4
	s_mov_b32 m0, s0
	s_mov_b64 s[0:1], 0x18000
	v_or_b32_e32 v14, 0xc00, v138
	v_lshlrev_b64 v[4:5], 11, v[4:5]
	v_add_u32_e32 v13, 0x4000, v139
	global_load_lds_dwordx4 v[6:7], off
	v_lshl_add_u64 v[6:7], v[2:3], 0, s[0:1]
	v_readfirstlane_b32 s0, v14
	v_lshl_add_u64 v[4:5], s[44:45], 0, v[4:5]
	s_mov_b32 m0, s0
	v_readfirstlane_b32 s0, v13
	v_add_u32_e32 v13, 0x4400, v139
	global_load_lds_dwordx4 v[6:7], off
	v_lshl_add_u64 v[4:5], v[4:5], 0, v[0:1]
	v_bfe_i32 v199, v163, 2, 1
	v_and_b32_e32 v198, 0xfffff840, v199
	v_lshl_add_u64 v[4:5], v[4:5], 0, v[198:199]
	s_mov_b32 m0, s0
	v_readfirstlane_b32 s0, v13
	v_add_u32_e32 v13, 0x6000, v138
	global_load_lds_dwordx4 v[4:5], off
	v_lshl_add_u64 v[6:7], v[4:5], 0, s[68:69]
	s_mov_b32 m0, s0
	v_readfirstlane_b32 s0, v13
	v_add_u32_e32 v13, 0x6400, v138
	global_load_lds_dwordx4 v[6:7], off
	s_mov_b64 s[98:99], 0x80
	v_lshl_add_u64 v[6:7], v[2:3], 0, s[98:99]
	s_mov_b32 m0, s0
	v_readfirstlane_b32 s0, v13
	global_load_lds_dwordx4 v[6:7], off
	s_mov_b64 s[98:99], 0x8080
	v_lshl_add_u64 v[6:7], v[2:3], 0, s[98:99]
	s_mov_b32 m0, s0
	s_mov_b64 s[0:1], 0x10080
	v_add_u32_e32 v13, 0x6800, v138
	global_load_lds_dwordx4 v[6:7], off
	v_lshl_add_u64 v[6:7], v[2:3], 0, s[0:1]
	v_readfirstlane_b32 s0, v13
	s_mov_b32 m0, s0
	s_mov_b64 s[0:1], 0x18080
	global_load_lds_dwordx4 v[6:7], off
	v_add_u32_e32 v6, 0x6c00, v138
	v_lshl_add_u64 v[2:3], v[2:3], 0, s[0:1]
	v_readfirstlane_b32 s0, v6
	v_add_u32_e32 v6, 0xa000, v139
	s_mov_b32 m0, s0
	v_readfirstlane_b32 s0, v6
	global_load_lds_dwordx4 v[2:3], off
	s_mov_b64 s[98:99], 0x80
	v_lshl_add_u64 v[2:3], v[4:5], 0, s[98:99]
	s_mov_b32 m0, s0
	s_lshl_b32 s1, s11, 7
	global_load_lds_dwordx4 v[2:3], off
	s_mov_b64 s[98:99], 0x8080
	v_lshl_add_u64 v[2:3], v[4:5], 0, s[98:99]
	v_add_u32_e32 v4, 0xa400, v139
	s_mov_b32 s6, 0
	v_readfirstlane_b32 s0, v4
	s_mov_b32 m0, s0
	v_and_b32_e32 v4, 48, v8
	global_load_lds_dwordx4 v[2:3], off
	v_lshlrev_b32_e32 v3, 2, v8
	s_lshl_b32 s0, s9, 10
	v_lshlrev_b32_e32 v2, 6, v8
	v_bitop3_b32 v3, v3, v4, 32 bitop3:0x6c
	s_add_i32 s1, s1, s0
	v_and_or_b32 v140, v2, s59, v3
	v_and_b32_e32 v142, 0xffffe000, v2
	v_or_b32_e32 v2, s1, v9
	v_add_u32_e32 v2, v2, v11
	s_lshl_b32 s0, s7, 7
	v_subrev_u32_e32 v2, s0, v2
	s_lshl_b32 s0, s8, 10
	v_subrev_u32_e32 v2, s0, v2
	v_ashrrev_i32_e32 v3, 31, v2
	v_lshlrev_b64 v[2:3], 11, v[2:3]
	v_readlane_b32 s0, v254, 52
	v_or_b32_e32 v2, v2, v0
	v_readlane_b32 s1, v254, 53
	v_and_b32_e32 v141, 0x1000, v12
	s_nop 0
	v_lshl_add_u64 v[130:131], s[0:1], 0, v[2:3]
	v_or_b32_e32 v2, s5, v9
	v_add_u32_e32 v2, v2, v10
	v_ashrrev_i32_e32 v3, 31, v2
	v_lshlrev_b64 v[2:3], 11, v[2:3]
	v_or_b32_e32 v2, v2, v0
	v_lshl_add_u64 v[132:133], s[62:63], 0, v[2:3]
	v_mov_b32_e32 v2, 0
	s_mov_b64 s[0:1], 0
	v_mov_b32_e32 v3, v2
	v_mov_b32_e32 v4, v2
	v_mov_b32_e32 v5, v2
	v_mov_b32_e32 v6, v2
	v_mov_b32_e32 v7, v2
	v_mov_b32_e32 v8, v2
	v_mov_b32_e32 v9, v2
	v_mov_b32_e32 v10, v2
	v_mov_b32_e32 v11, v2
	v_mov_b32_e32 v12, v2
	v_mov_b32_e32 v13, v2
	v_mov_b32_e32 v14, v2
	v_mov_b32_e32 v15, v2
	v_mov_b32_e32 v16, v2
	v_mov_b32_e32 v17, v2
	v_mov_b32_e32 v18, v2
	v_mov_b32_e32 v19, v2
	v_mov_b32_e32 v20, v2
	v_mov_b32_e32 v21, v2
	v_mov_b32_e32 v22, v2
	v_mov_b32_e32 v23, v2
	v_mov_b32_e32 v24, v2
	v_mov_b32_e32 v25, v2
	s_waitcnt lgkmcnt(0)
; template <int MI, int NI>
; DI void gemm256(f32x4 (&acc)[MI][NI], const u16* __restrict__ A, int lda, const u16* __restrict__ Bt, int ldb, int K, int m0, int n0, char* smem) {
;     ...
;   G256_ISSUE(0, 0);
;   if (nk > 1) G256_ISSUE(1, 32);
;   const int foff = lr * 64 + ((lq ^ ((lr >> 3) << 1)) * 16);
;   int st = 0;
;   for (int kt = 0; kt < nk; ++kt) {
;     if (kt + 1 < nk) asm volatile("s_waitcnt vmcnt(%0) lgkmcnt(0)" :: "n"(LPS) : "memory");
;     else asm volatile("s_waitcnt vmcnt(0) lgkmcnt(0)" ::: "memory");
;     __builtin_amdgcn_s_barrier();
;     __builtin_amdgcn_s_setprio(1);
;     const char* sb = smem + st * STAGE + foff;
;     bf16x8 af[MI], bfr[NI];
; #pragma unroll
;     for (int mi = 0; mi < MI; ++mi) af[mi] = *(const bf16x8*)(sb + (wr * MI + mi) * 1024);
; #pragma unroll
;     for (int ni = 0; ni < NI; ++ni) bfr[ni] = *(const bf16x8*)(sb + ABYTES + (wc * NI + ni) * 1024);
;     __builtin_amdgcn_sched_barrier(0x0);
;     if (kt + 2 < nk) { const int s2 = st >= 1 ? st - 1 : 2; G256_ISSUE(s2, (kt + 2) * 32); }
;     __builtin_amdgcn_s_setprio(0);
; #pragma unroll
;     for (int mi = 0; mi < MI; ++mi)
; #pragma unroll
;       for (int ni = 0; ni < NI; ++ni)
;         acc[mi][ni] = __builtin_amdgcn_mfma_f32_16x16x32_bf16(bfr[ni], af[mi], acc[mi][ni], 0, 0, 0);
;     st = st == 2 ? 0 : st + 1;
;   }
	v_mov_b32_e32 v26, v2
	v_mov_b32_e32 v27, v2
	v_mov_b32_e32 v28, v2
	v_mov_b32_e32 v29, v2
	v_mov_b32_e32 v30, v2
	v_mov_b32_e32 v31, v2
	v_mov_b32_e32 v32, v2
	v_mov_b32_e32 v33, v2
	v_mov_b32_e32 v34, v2
	v_mov_b32_e32 v35, v2
	v_mov_b32_e32 v36, v2
	v_mov_b32_e32 v37, v2
	v_mov_b32_e32 v38, v2
	v_mov_b32_e32 v39, v2
	v_mov_b32_e32 v40, v2
	v_mov_b32_e32 v41, v2
	v_mov_b32_e32 v42, v2
	v_mov_b32_e32 v43, v2
	v_mov_b32_e32 v44, v2
	v_mov_b32_e32 v45, v2
	v_mov_b32_e32 v46, v2
	v_mov_b32_e32 v47, v2
	v_mov_b32_e32 v48, v2
	v_mov_b32_e32 v49, v2
	v_mov_b32_e32 v50, v2
	v_mov_b32_e32 v51, v2
	v_mov_b32_e32 v52, v2
	v_mov_b32_e32 v53, v2
	v_mov_b32_e32 v54, v2
	v_mov_b32_e32 v55, v2
	v_mov_b32_e32 v56, v2
	v_mov_b32_e32 v57, v2
	v_mov_b32_e32 v58, v2
	v_mov_b32_e32 v59, v2
	v_mov_b32_e32 v60, v2
	v_mov_b32_e32 v61, v2
	v_mov_b32_e32 v62, v2
	v_mov_b32_e32 v63, v2
	v_mov_b32_e32 v64, v2
	v_mov_b32_e32 v65, v2
	v_mov_b32_e32 v66, v2
	v_mov_b32_e32 v67, v2
	v_mov_b32_e32 v68, v2
	v_mov_b32_e32 v69, v2
	v_mov_b32_e32 v70, v2
	v_mov_b32_e32 v71, v2
	v_mov_b32_e32 v72, v2
	v_mov_b32_e32 v73, v2
	v_mov_b32_e32 v74, v2
	v_mov_b32_e32 v75, v2
	v_mov_b32_e32 v76, v2
	v_mov_b32_e32 v77, v2
	v_mov_b32_e32 v78, v2
	v_mov_b32_e32 v79, v2
	v_mov_b32_e32 v80, v2
	v_mov_b32_e32 v81, v2
	v_mov_b32_e32 v82, v2
	v_mov_b32_e32 v83, v2
	v_mov_b32_e32 v84, v2
	v_mov_b32_e32 v85, v2
	v_mov_b32_e32 v86, v2
	v_mov_b32_e32 v87, v2
	v_mov_b32_e32 v88, v2
	v_mov_b32_e32 v89, v2
	v_mov_b32_e32 v90, v2
	v_mov_b32_e32 v91, v2
	v_mov_b32_e32 v92, v2
	v_mov_b32_e32 v93, v2
	v_mov_b32_e32 v94, v2
	v_mov_b32_e32 v95, v2
	v_mov_b32_e32 v96, v2
	v_mov_b32_e32 v97, v2
	v_mov_b32_e32 v98, v2
	v_mov_b32_e32 v99, v2
	v_mov_b32_e32 v100, v2
	v_mov_b32_e32 v101, v2
	v_mov_b32_e32 v102, v2
	v_mov_b32_e32 v103, v2
	v_mov_b32_e32 v104, v2
	v_mov_b32_e32 v105, v2
	v_mov_b32_e32 v106, v2
	v_mov_b32_e32 v107, v2
	v_mov_b32_e32 v108, v2
	v_mov_b32_e32 v109, v2
	v_mov_b32_e32 v110, v2
	v_mov_b32_e32 v111, v2
	v_mov_b32_e32 v112, v2
	v_mov_b32_e32 v113, v2
	v_mov_b32_e32 v114, v2
	v_mov_b32_e32 v115, v2
	v_mov_b32_e32 v116, v2
	v_mov_b32_e32 v117, v2
	v_mov_b32_e32 v118, v2
	v_mov_b32_e32 v119, v2
	v_mov_b32_e32 v120, v2
	v_mov_b32_e32 v121, v2
	v_mov_b32_e32 v122, v2
	v_mov_b32_e32 v123, v2
	v_mov_b32_e32 v124, v2
	v_mov_b32_e32 v125, v2
	v_mov_b32_e32 v126, v2
	v_mov_b32_e32 v127, v2
	v_mov_b32_e32 v128, v2
	v_mov_b32_e32 v129, v2
	s_mov_b64 s[8:9], 0x10d81100
	v_lshl_add_u64 v[198:199], v[132:133], 0, s[8:9]
	s_mov_b64 s[8:9], 0x10d89100
	v_lshl_add_u64 v[200:201], v[132:133], 0, s[8:9]
	s_mov_b64 s[8:9], 0x10d91100
	v_lshl_add_u64 v[202:203], v[132:133], 0, s[8:9]
	s_mov_b64 s[8:9], 0x10d99100
	v_lshl_add_u64 v[204:205], v[132:133], 0, s[8:9]
	s_mov_b64 s[8:9], 0x941100
	v_lshl_add_u64 v[206:207], v[130:131], 0, s[8:9]
	s_mov_b64 s[8:9], 0x949100
	v_lshl_add_u64 v[208:209], v[130:131], 0, s[8:9]
	v_bfe_i32 v197, v163, 2, 1
	v_and_b32_e32 v196, 0xfffff840, v197
	v_lshl_add_u64 v[198:199], v[198:199], 0, v[196:197]
	v_lshl_add_u64 v[200:201], v[200:201], 0, v[196:197]
	v_lshl_add_u64 v[202:203], v[202:203], 0, v[196:197]
	v_lshl_add_u64 v[204:205], v[204:205], 0, v[196:197]
	v_and_b32_e32 v196, 0xfffff840, v197
	v_lshl_add_u64 v[206:207], v[206:207], 0, v[196:197]
	v_lshl_add_u64 v[208:209], v[208:209], 0, v[196:197]
	s_mov_b64 s[98:99], 0x80
	v_add_u32_e32 v143, v140, v142
	v_add_u32_e32 v0, v140, v141
	v_readfirstlane_b32 s7, v138
	v_readfirstlane_b32 s0, v139
	s_mov_b32 s6, 0
	s_movk_i32 s1, 29
	s_add_i32 s0, s0, 0x4000
	s_waitcnt vmcnt(6) lgkmcnt(0)
	s_barrier
	ds_read_b128 v[144:147], v143
	ds_read_b128 v[148:151], v143 offset:1024
	ds_read_b128 v[152:155], v143 offset:2048
	ds_read_b128 v[156:159], v143 offset:3072
	ds_read_b128 v[180:183], v0 offset:16384
	ds_read_b128 v[184:187], v0 offset:17408
	ds_read_b128 v[188:191], v0 offset:18432
	ds_read_b128 v[192:195], v0 offset:19456
.Lpipe_zgemm:
	v_add_u32_e32 v160, s6, v143
	ds_read_b128 v[164:167], v160 offset:4096
	ds_read_b128 v[168:171], v160 offset:5120
	ds_read_b128 v[172:175], v160 offset:6144
	ds_read_b128 v[176:179], v160 offset:7168
	s_add_i32 s8, s6, 0xffffa000
	s_cmp_eq_u32 s6, 0
	s_cselect_b32 s8, 0xc000, s8
	s_add_i32 s9, s8, s7
	s_add_i32 s8, s8, s0
	s_mov_b32 m0, s9
	s_waitcnt lgkmcnt(7)
	v_mfma_f32_16x16x32_bf16 v[126:129], v[180:183], v[144:147], v[126:129]
	global_load_lds_dwordx4 v[198:199], off
	v_mfma_f32_16x16x32_bf16 v[110:113], v[180:183], v[148:151], v[110:113]
	v_lshl_add_u64 v[198:199], v[198:199], 0, s[98:99]
	s_add_i32 m0, s9, 0x400
	v_mfma_f32_16x16x32_bf16 v[94:97], v[180:183], v[152:155], v[94:97]
	global_load_lds_dwordx4 v[200:201], off
	v_mfma_f32_16x16x32_bf16 v[78:81], v[180:183], v[156:159], v[78:81]
	v_lshl_add_u64 v[200:201], v[200:201], 0, s[98:99]
	s_add_i32 m0, s9, 0x800
	s_waitcnt lgkmcnt(6)
	v_mfma_f32_16x16x32_bf16 v[122:125], v[184:187], v[144:147], v[122:125]
	global_load_lds_dwordx4 v[202:203], off
	v_mfma_f32_16x16x32_bf16 v[106:109], v[184:187], v[148:151], v[106:109]
	v_lshl_add_u64 v[202:203], v[202:203], 0, s[98:99]
	s_add_i32 m0, s9, 0xc00
	v_mfma_f32_16x16x32_bf16 v[90:93], v[184:187], v[152:155], v[90:93]
	global_load_lds_dwordx4 v[204:205], off
	v_mfma_f32_16x16x32_bf16 v[74:77], v[184:187], v[156:159], v[74:77]
	v_lshl_add_u64 v[204:205], v[204:205], 0, s[98:99]
	s_mov_b32 m0, s8
	s_waitcnt lgkmcnt(5)
	v_mfma_f32_16x16x32_bf16 v[118:121], v[188:191], v[144:147], v[118:121]
	global_load_lds_dwordx4 v[206:207], off
	v_mfma_f32_16x16x32_bf16 v[102:105], v[188:191], v[148:151], v[102:105]
	v_lshl_add_u64 v[206:207], v[206:207], 0, s[98:99]
	s_add_i32 m0, s8, 0x400
	v_mfma_f32_16x16x32_bf16 v[86:89], v[188:191], v[152:155], v[86:89]
	global_load_lds_dwordx4 v[208:209], off
	v_mfma_f32_16x16x32_bf16 v[70:73], v[188:191], v[156:159], v[70:73]
	v_lshl_add_u64 v[208:209], v[208:209], 0, s[98:99]
	s_waitcnt lgkmcnt(4)
	v_mfma_f32_16x16x32_bf16 v[114:117], v[192:195], v[144:147], v[114:117]
	v_mfma_f32_16x16x32_bf16 v[98:101], v[192:195], v[148:151], v[98:101]
	v_mfma_f32_16x16x32_bf16 v[82:85], v[192:195], v[152:155], v[82:85]
	v_mfma_f32_16x16x32_bf16 v[66:69], v[192:195], v[156:159], v[66:69]
	s_waitcnt vmcnt(6) lgkmcnt(0)
	s_barrier
; template <int MI, int NI>
; DI void gemm256(f32x4 (&acc)[MI][NI], const u16* __restrict__ A, int lda, const u16* __restrict__ Bt, int ldb, int K, int m0, int n0, char* smem) {
;     ...
;   for (int kt = 0; kt < nk; ++kt) {
;     if (kt + 1 < nk) asm volatile("s_waitcnt vmcnt(%0) lgkmcnt(0)" :: "n"(LPS) : "memory");
;     else asm volatile("s_waitcnt vmcnt(0) lgkmcnt(0)" ::: "memory");
;     __builtin_amdgcn_s_barrier();
;     __builtin_amdgcn_s_setprio(1);
;     const char* sb = smem + st * STAGE + foff;
;     bf16x8 af[MI], bfr[NI];
; #pragma unroll
;     for (int mi = 0; mi < MI; ++mi) af[mi] = *(const bf16x8*)(sb + (wr * MI + mi) * 1024);
; #pragma unroll
;     for (int ni = 0; ni < NI; ++ni) bfr[ni] = *(const bf16x8*)(sb + ABYTES + (wc * NI + ni) * 1024);
;     __builtin_amdgcn_sched_barrier(0x0);
;     if (kt + 2 < nk) { const int s2 = st >= 1 ? st - 1 : 2; G256_ISSUE(s2, (kt + 2) * 32); }
;     __builtin_amdgcn_s_setprio(0);
; #pragma unroll
;     for (int mi = 0; mi < MI; ++mi)
; #pragma unroll
;       for (int ni = 0; ni < NI; ++ni)
;         acc[mi][ni] = __builtin_amdgcn_mfma_f32_16x16x32_bf16(bfr[ni], af[mi], acc[mi][ni], 0, 0, 0);
;     st = st == 2 ? 0 : st + 1;
;   }
;   asm volatile("s_waitcnt lgkmcnt(0)" ::: "memory");
;   __builtin_amdgcn_s_barrier();
	s_add_i32 s9, s6, 0x6000
	s_cmp_eq_u32 s6, 0xc000
	s_cselect_b32 s6, 0, s9
	v_add_u32_e32 v196, s6, v143
	v_add_u32_e32 v197, s6, v0
	v_mfma_f32_16x16x32_bf16 v[62:65], v[180:183], v[164:167], v[62:65]
	ds_read_b128 v[144:147], v196
	v_mfma_f32_16x16x32_bf16 v[46:49], v[180:183], v[168:171], v[46:49]
	ds_read_b128 v[148:151], v196 offset:1024
	v_mfma_f32_16x16x32_bf16 v[30:33], v[180:183], v[172:175], v[30:33]
	ds_read_b128 v[152:155], v196 offset:2048
	v_mfma_f32_16x16x32_bf16 v[14:17], v[180:183], v[176:179], v[14:17]
	ds_read_b128 v[156:159], v196 offset:3072
	ds_read_b128 v[180:183], v197 offset:16384
	v_mfma_f32_16x16x32_bf16 v[58:61], v[184:187], v[164:167], v[58:61]
	v_mfma_f32_16x16x32_bf16 v[42:45], v[184:187], v[168:171], v[42:45]
	v_mfma_f32_16x16x32_bf16 v[26:29], v[184:187], v[172:175], v[26:29]
	v_mfma_f32_16x16x32_bf16 v[10:13], v[184:187], v[176:179], v[10:13]
	ds_read_b128 v[184:187], v197 offset:17408
	v_mfma_f32_16x16x32_bf16 v[54:57], v[188:191], v[164:167], v[54:57]
	v_mfma_f32_16x16x32_bf16 v[38:41], v[188:191], v[168:171], v[38:41]
	v_mfma_f32_16x16x32_bf16 v[22:25], v[188:191], v[172:175], v[22:25]
	v_mfma_f32_16x16x32_bf16 v[6:9], v[188:191], v[176:179], v[6:9]
	ds_read_b128 v[188:191], v197 offset:18432
	v_mfma_f32_16x16x32_bf16 v[50:53], v[192:195], v[164:167], v[50:53]
	v_mfma_f32_16x16x32_bf16 v[34:37], v[192:195], v[168:171], v[34:37]
	v_mfma_f32_16x16x32_bf16 v[18:21], v[192:195], v[172:175], v[18:21]
	v_mfma_f32_16x16x32_bf16 v[2:5], v[192:195], v[176:179], v[2:5]
	ds_read_b128 v[192:195], v197 offset:19456
	s_sub_i32 s1, s1, 1
	s_cmp_lg_u32 s1, 0
	s_cbranch_scc1 .Lpipe_zgemm
	v_add_u32_e32 v160, s6, v143
	ds_read_b128 v[164:167], v160 offset:4096
	ds_read_b128 v[168:171], v160 offset:5120
	ds_read_b128 v[172:175], v160 offset:6144
	ds_read_b128 v[176:179], v160 offset:7168
	s_add_i32 s8, s6, 0xffffa000
	s_cmp_eq_u32 s6, 0
	s_cselect_b32 s8, 0xc000, s8
	s_add_i32 s9, s8, s7
	s_add_i32 s8, s8, s0
	s_mov_b32 m0, s9
	s_waitcnt lgkmcnt(7)
	v_mfma_f32_16x16x32_bf16 v[126:129], v[180:183], v[144:147], v[126:129]
	global_load_lds_dwordx4 v[198:199], off
	v_mfma_f32_16x16x32_bf16 v[110:113], v[180:183], v[148:151], v[110:113]
	v_lshl_add_u64 v[198:199], v[198:199], 0, s[98:99]
	s_add_i32 m0, s9, 0x400
	v_mfma_f32_16x16x32_bf16 v[94:97], v[180:183], v[152:155], v[94:97]
	global_load_lds_dwordx4 v[200:201], off
	v_mfma_f32_16x16x32_bf16 v[78:81], v[180:183], v[156:159], v[78:81]
	v_lshl_add_u64 v[200:201], v[200:201], 0, s[98:99]
	s_add_i32 m0, s9, 0x800
	s_waitcnt lgkmcnt(6)
	v_mfma_f32_16x16x32_bf16 v[122:125], v[184:187], v[144:147], v[122:125]
	global_load_lds_dwordx4 v[202:203], off
	v_mfma_f32_16x16x32_bf16 v[106:109], v[184:187], v[148:151], v[106:109]
	v_lshl_add_u64 v[202:203], v[202:203], 0, s[98:99]
	s_add_i32 m0, s9, 0xc00
	v_mfma_f32_16x16x32_bf16 v[90:93], v[184:187], v[152:155], v[90:93]
	global_load_lds_dwordx4 v[204:205], off
	v_mfma_f32_16x16x32_bf16 v[74:77], v[184:187], v[156:159], v[74:77]
	v_lshl_add_u64 v[204:205], v[204:205], 0, s[98:99]
	s_mov_b32 m0, s8
	s_waitcnt lgkmcnt(5)
	v_mfma_f32_16x16x32_bf16 v[118:121], v[188:191], v[144:147], v[118:121]
	global_load_lds_dwordx4 v[206:207], off
	v_mfma_f32_16x16x32_bf16 v[102:105], v[188:191], v[148:151], v[102:105]
	v_lshl_add_u64 v[206:207], v[206:207], 0, s[98:99]
	s_add_i32 m0, s8, 0x400
	v_mfma_f32_16x16x32_bf16 v[86:89], v[188:191], v[152:155], v[86:89]
	global_load_lds_dwordx4 v[208:209], off
	v_mfma_f32_16x16x32_bf16 v[70:73], v[188:191], v[156:159], v[70:73]
	v_lshl_add_u64 v[208:209], v[208:209], 0, s[98:99]
	s_waitcnt lgkmcnt(4)
	v_mfma_f32_16x16x32_bf16 v[114:117], v[192:195], v[144:147], v[114:117]
	v_mfma_f32_16x16x32_bf16 v[98:101], v[192:195], v[148:151], v[98:101]
	v_mfma_f32_16x16x32_bf16 v[82:85], v[192:195], v[152:155], v[82:85]
	v_mfma_f32_16x16x32_bf16 v[66:69], v[192:195], v[156:159], v[66:69]
	s_waitcnt lgkmcnt(0)
	v_mfma_f32_16x16x32_bf16 v[62:65], v[180:183], v[164:167], v[62:65]
	v_mfma_f32_16x16x32_bf16 v[46:49], v[180:183], v[168:171], v[46:49]
	v_mfma_f32_16x16x32_bf16 v[30:33], v[180:183], v[172:175], v[30:33]
	v_mfma_f32_16x16x32_bf16 v[14:17], v[180:183], v[176:179], v[14:17]
	v_mfma_f32_16x16x32_bf16 v[58:61], v[184:187], v[164:167], v[58:61]
	v_mfma_f32_16x16x32_bf16 v[42:45], v[184:187], v[168:171], v[42:45]
	v_mfma_f32_16x16x32_bf16 v[26:29], v[184:187], v[172:175], v[26:29]
	v_mfma_f32_16x16x32_bf16 v[10:13], v[184:187], v[176:179], v[10:13]
	v_mfma_f32_16x16x32_bf16 v[54:57], v[188:191], v[164:167], v[54:57]
	v_mfma_f32_16x16x32_bf16 v[38:41], v[188:191], v[168:171], v[38:41]
	v_mfma_f32_16x16x32_bf16 v[22:25], v[188:191], v[172:175], v[22:25]
	v_mfma_f32_16x16x32_bf16 v[6:9], v[188:191], v[176:179], v[6:9]
	v_mfma_f32_16x16x32_bf16 v[50:53], v[192:195], v[164:167], v[50:53]
	v_mfma_f32_16x16x32_bf16 v[34:37], v[192:195], v[168:171], v[34:37]
	v_mfma_f32_16x16x32_bf16 v[18:21], v[192:195], v[172:175], v[18:21]
	v_mfma_f32_16x16x32_bf16 v[2:5], v[192:195], v[176:179], v[2:5]
	s_waitcnt vmcnt(6) lgkmcnt(0)
	s_barrier
	s_setprio 1
	v_add_u32_e32 v0, v140, v142
	s_waitcnt vmcnt(0)
	ds_read_b128 v[130:133], v0
	ds_read_b128 v[142:145], v0 offset:1024
	ds_read_b128 v[146:149], v0 offset:2048
	ds_read_b128 v[150:153], v0 offset:3072
	ds_read_b128 v[154:157], v0 offset:4096
	ds_read_b128 v[158:161], v0 offset:5120
	ds_read_b128 v[164:167], v0 offset:6144
	ds_read_b128 v[168:171], v0 offset:7168
	v_add_u32_e32 v220, v140, v141
	ds_read_b128 v[138:141], v220 offset:16384
	ds_read_b128 v[172:175], v220 offset:17408
	ds_read_b128 v[176:179], v220 offset:18432
	ds_read_b128 v[180:183], v220 offset:19456
	s_setprio 0
	s_waitcnt lgkmcnt(3)
	v_mfma_f32_16x16x32_bf16 v[126:129], v[138:141], v[130:133], v[126:129]
	s_waitcnt vmcnt(0) lgkmcnt(0)
	s_barrier
; DI unsigned pack2(float a, float b) { float2_t v = {a, b}; bf16x2_t r = __builtin_convertvector(v, bf16x2_t); return __builtin_bit_cast(unsigned, r); }
; #define EPI_BEGIN const int lr1_ = launder_v(lr), lq1_ = launder_v(lq), wr1_ = launder_v(wr), wc1_ = launder_v(wc); { const int lr = lr1_, lq = lq1_, wr = wr1_, wc = wc1_; (void)lr; (void)lq; (void)wr; (void)wc;
; template <int MI, int NI>
; DI void gemm256(f32x4 (&acc)[MI][NI], const u16* __restrict__ A, int lda, const u16* __restrict__ Bt, int ldb, int K, int m0, int n0, char* smem) {
;     ...
; #pragma unroll
;     for (int mi = 0; mi < MI; ++mi)
; #pragma unroll
;       for (int ni = 0; ni < NI; ++ni)
;         acc[mi][ni] = __builtin_amdgcn_mfma_f32_16x16x32_bf16(bfr[ni], af[mi], acc[mi][ni], 0, 0, 0);
;     st = st == 2 ? 0 : st + 1;
;   }
; DI void phase_zgemm(const Params& p, int l, char* smem) {
;     ...
;     EPI_BEGIN
; #pragma unroll
;     for (int mi = 0; mi < 8; mi += 2) {
;       const int m = m0 + wr * 128 + (mi + (lq & 1)) * 16 + lr;
; #pragma unroll
;       for (int ni = 0; ni < 4; ++ni) {
;         const int n = n0 + wc * 64 + ni * 16 + (lq >> 1) * 8;
;         const uint4 v = widen16(make_uint2(pack2(acc[mi][ni][0], acc[mi][ni][1]), pack2(acc[mi][ni][2], acc[mi][ni][3])),
;                                 make_uint2(pack2(acc[mi + 1][ni][0], acc[mi + 1][ni][1]), pack2(acc[mi + 1][ni][2], acc[mi + 1][ni][3])));
;         if (n < ZA) *(uint4*)(za + (size_t)m * ZA + n) = v;
;         else if (n < ZA + ZR) *(uint4*)(zr + (size_t)m * ZR + (n - ZA)) = v;
;       }
;     }
	s_waitcnt lgkmcnt(2)
	v_mfma_f32_16x16x32_bf16 v[122:125], v[172:175], v[130:133], v[122:125]
	s_waitcnt lgkmcnt(1)
	v_mfma_f32_16x16x32_bf16 v[118:121], v[176:179], v[130:133], v[118:121]
	s_waitcnt lgkmcnt(0)
	v_mfma_f32_16x16x32_bf16 v[130:133], v[180:183], v[130:133], v[114:117]
	v_mfma_f32_16x16x32_bf16 v[110:113], v[138:141], v[142:145], v[110:113]
	v_mfma_f32_16x16x32_bf16 v[102:105], v[176:179], v[142:145], v[102:105]
	v_mfma_f32_16x16x32_bf16 v[94:97], v[138:141], v[146:149], v[94:97]
	v_mfma_f32_16x16x32_bf16 v[86:89], v[176:179], v[146:149], v[86:89]
	v_mfma_f32_16x16x32_bf16 v[78:81], v[138:141], v[150:153], v[78:81]
	v_mfma_f32_16x16x32_bf16 v[70:73], v[176:179], v[150:153], v[70:73]
	v_mfma_f32_16x16x32_bf16 v[62:65], v[138:141], v[154:157], v[62:65]
	v_mfma_f32_16x16x32_bf16 v[54:57], v[176:179], v[154:157], v[54:57]
	v_mfma_f32_16x16x32_bf16 v[46:49], v[138:141], v[158:161], v[46:49]
	v_mfma_f32_16x16x32_bf16 v[38:41], v[176:179], v[158:161], v[38:41]
	v_mfma_f32_16x16x32_bf16 v[30:33], v[138:141], v[164:167], v[30:33]
	v_mfma_f32_16x16x32_bf16 v[22:25], v[176:179], v[164:167], v[22:25]
	v_mfma_f32_16x16x32_bf16 v[14:17], v[138:141], v[168:171], v[14:17]
	v_mfma_f32_16x16x32_bf16 v[6:9], v[176:179], v[168:171], v[6:9]
	v_mfma_f32_16x16x32_bf16 v[184:187], v[172:175], v[142:145], v[106:109]
	v_mfma_f32_16x16x32_bf16 v[142:145], v[180:183], v[142:145], v[98:101]
	v_mfma_f32_16x16x32_bf16 v[188:191], v[172:175], v[146:149], v[90:93]
	v_mfma_f32_16x16x32_bf16 v[146:149], v[180:183], v[146:149], v[82:85]
	v_mfma_f32_16x16x32_bf16 v[192:195], v[172:175], v[150:153], v[74:77]
	v_mfma_f32_16x16x32_bf16 v[150:153], v[180:183], v[150:153], v[66:69]
	v_mfma_f32_16x16x32_bf16 v[196:199], v[172:175], v[154:157], v[58:61]
	v_mfma_f32_16x16x32_bf16 v[154:157], v[180:183], v[154:157], v[50:53]
	v_mfma_f32_16x16x32_bf16 v[200:203], v[172:175], v[158:161], v[42:45]
	v_mfma_f32_16x16x32_bf16 v[158:161], v[180:183], v[158:161], v[34:37]
	v_mfma_f32_16x16x32_bf16 v[204:207], v[172:175], v[164:167], v[26:29]
	v_mfma_f32_16x16x32_bf16 v[164:167], v[180:183], v[164:167], v[18:21]
	v_mfma_f32_16x16x32_bf16 v[138:141], v[172:175], v[168:171], v[10:13]
	v_mfma_f32_16x16x32_bf16 v[168:171], v[180:183], v[168:171], v[2:5]
	s_setprio 1
	s_nop 1
	ds_read_b128 v[2:5], v0 offset:24576
	ds_read_b128 v[10:13], v0 offset:25600
	ds_read_b128 v[18:21], v0 offset:26624
	ds_read_b128 v[26:29], v0 offset:27648
	ds_read_b128 v[34:37], v0 offset:28672
	ds_read_b128 v[172:175], v0 offset:29696
	ds_read_b128 v[176:179], v0 offset:30720
	ds_read_b128 v[180:183], v0 offset:31744
	ds_read_b128 v[208:211], v220 offset:40960
	ds_read_b128 v[212:215], v220 offset:41984
	ds_read_b128 v[216:219], v220 offset:43008
	ds_read_b128 v[220:223], v220 offset:44032
	s_setprio 0
	s_waitcnt lgkmcnt(3)
	v_mfma_f32_16x16x32_bf16 v[224:227], v[208:211], v[2:5], v[126:129]
	v_mov_b32_e32 v0, v136
	s_waitcnt lgkmcnt(0)
	s_barrier
	s_waitcnt lgkmcnt(2)
	v_mfma_f32_16x16x32_bf16 v[114:117], v[212:215], v[2:5], v[122:125]
	s_movk_i32 s0, 0x900
	s_waitcnt lgkmcnt(1)
	v_mfma_f32_16x16x32_bf16 v[106:109], v[216:219], v[2:5], v[118:121]
	s_nop 0
	v_cvt_pk_bf16_f32 v122, v224, v225
	v_cvt_pk_bf16_f32 v123, v226, v227
	s_waitcnt lgkmcnt(0)
	v_mfma_f32_16x16x32_bf16 v[98:101], v[220:223], v[2:5], v[130:133]
	v_mov_b32_e32 v2, v137
	v_mov_b32_e32 v3, v134
	v_mov_b32_e32 v4, v135
	v_lshlrev_b32_e32 v3, 7, v3
	v_add3_u32 v132, v0, s5, v3
	v_lshlrev_b32_e32 v3, 2, v2
	v_and_b32_e32 v3, -8, v3
	v_lshlrev_b32_e32 v0, 6, v4
	v_add3_u32 v126, v3, s4, v0
	v_lshlrev_b32_e32 v0, 4, v2
	v_mfma_f32_16x16x32_bf16 v[228:231], v[208:211], v[10:13], v[110:113]
	v_and_b32_e32 v133, 16, v0
	v_add_u32_e32 v0, v132, v133
	v_mfma_f32_16x16x32_bf16 v[118:121], v[212:215], v[10:13], v[184:187]
	v_mfma_f32_16x16x32_bf16 v[110:113], v[216:219], v[10:13], v[102:105]
	s_nop 3
	v_cvt_pk_bf16_f32 v124, v228, v229
	v_cvt_pk_bf16_f32 v125, v230, v231
	s_nop 0
	v_permlane16_swap_b32_e32 v122, v124
	v_mfma_f32_16x16x32_bf16 v[102:105], v[220:223], v[10:13], v[142:145]
	v_permlane16_swap_b32_e32 v123, v125
	v_mfma_f32_16x16x32_bf16 v[10:13], v[216:219], v[176:179], v[22:25]
	s_nop 2
	v_mov_b64_e32 v[22:23], s[62:63]
	v_mfma_f32_16x16x32_bf16 v[90:93], v[208:211], v[18:21], v[94:97]
	v_mad_i64_i32 v[128:129], s[0:1], v0, s0, v[22:23]
	s_movk_i32 s0, 0x39f
	v_mfma_f32_16x16x32_bf16 v[82:85], v[212:215], v[18:21], v[188:191]
	v_cmp_lt_i32_e64 s[0:1], s0, v126
	v_mfma_f32_16x16x32_bf16 v[74:77], v[216:219], v[18:21], v[86:89]
	v_mfma_f32_16x16x32_bf16 v[66:69], v[220:223], v[18:21], v[146:149]
	v_mfma_f32_16x16x32_bf16 v[94:97], v[208:211], v[26:29], v[78:81]
	v_mfma_f32_16x16x32_bf16 v[86:89], v[212:215], v[26:29], v[192:195]
	v_mfma_f32_16x16x32_bf16 v[78:81], v[216:219], v[26:29], v[70:73]
	v_mfma_f32_16x16x32_bf16 v[70:73], v[220:223], v[26:29], v[150:153]
	v_mfma_f32_16x16x32_bf16 v[58:61], v[208:211], v[34:37], v[62:65]
	v_mfma_f32_16x16x32_bf16 v[50:53], v[212:215], v[34:37], v[196:199]
	v_mfma_f32_16x16x32_bf16 v[42:45], v[216:219], v[34:37], v[54:57]
	v_mfma_f32_16x16x32_bf16 v[34:37], v[220:223], v[34:37], v[154:157]
	v_mfma_f32_16x16x32_bf16 v[62:65], v[208:211], v[172:175], v[46:49]
	v_mfma_f32_16x16x32_bf16 v[54:57], v[212:215], v[172:175], v[200:203]
	v_mfma_f32_16x16x32_bf16 v[46:49], v[216:219], v[172:175], v[38:41]
	v_mfma_f32_16x16x32_bf16 v[38:41], v[220:223], v[172:175], v[158:161]
	v_mfma_f32_16x16x32_bf16 v[26:29], v[208:211], v[176:179], v[30:33]
	v_mfma_f32_16x16x32_bf16 v[18:21], v[212:215], v[176:179], v[204:207]
	v_mfma_f32_16x16x32_bf16 v[2:5], v[220:223], v[176:179], v[164:167]
	v_mfma_f32_16x16x32_bf16 v[30:33], v[208:211], v[180:183], v[14:17]
	v_mfma_f32_16x16x32_bf16 v[22:25], v[212:215], v[180:183], v[138:141]
	v_mfma_f32_16x16x32_bf16 v[14:17], v[216:219], v[180:183], v[6:9]
	v_mfma_f32_16x16x32_bf16 v[6:9], v[220:223], v[180:183], v[168:171]
	s_and_saveexec_b64 s[4:5], s[0:1]
	s_xor_b64 s[4:5], exec, s[4:5]
	s_cbranch_execz .LBB0_862
	s_movk_i32 s6, 0x820
	v_cmp_gt_u32_e32 vcc, s6, v126
	s_and_saveexec_b64 s[6:7], vcc
	s_cbranch_execz .LBB0_861
	v_mov_b32_e32 v127, v1
	v_lshl_add_u64 v[130:131], v[126:127], 1, v[128:129]
	v_add_co_u32_e32 v130, vcc, 0x47e0000, v130
	s_nop 1
	v_addc_co_u32_e32 v131, vcc, 0, v131, vcc
	flat_store_dwordx4 v[130:131], v[122:125] offset:2240

; template <int MI, int NI>
; DI void gemm256(f32x4 (&acc)[MI][NI], const u16* __restrict__ A, int lda, const u16* __restrict__ Bt, int ldb, int K, int m0, int n0, char* smem) {
;     ...
;   const int srow = lane >> 2, scol = ((lane & 3) ^ ((lane >> 5) << 1)) * 8;
;   const u16* Ag = A + (size_t)(m0 + wave * NAW * 16 + srow) * lda + scol;
;   const u16* Bg = Bt + (size_t)(n0 + wave * NBW * 16 + srow) * ldb + scol;
;   char* la = smem + (wave * NAW) * 1024 + lane * 16;
;   char* lb = smem + ABYTES + (wave * NBW) * 1024 + lane * 16;
;     ...
;   const int nk = K >> 5;
;   G256_ISSUE(0, 0);
;   if (nk > 1) G256_ISSUE(1, 32);
; DI void phase_resid(const Params& p, const u16* A, int K, const u16* Bt, const float* gate  ,
;                     const float* xl_in, const float* xc_in, float* xl_out, float* xc_out, int Mout, char* smem) {
;     ...
;   for (int it = 0;; ++it) {
;     int tm, tn;
;     if (!tile_map(it, NTL / 256, 8, blk__, gridDim.x, tm, tn)) break;
;     resid_tile<8, 4>(A, K, Bt, gate, xl_in, xc_in, xl_out, xc_out, tm * 256, tn * 128, smem);
.LBB0_961:
	s_ashr_i32 s1, s0, 31
	s_lshr_b32 s1, s1, 26
	s_add_i32 s1, s0, s1
	s_and_b32 s8, s1, 0xffffffc0
	s_sub_i32 s0, s0, s8
	s_ashr_i32 s8, s0, 31
	s_lshr_b32 s8, s8, 26
	s_add_i32 s9, s0, s8
	s_and_b32 s8, s9, 0xffffffc0
	s_sub_i32 s0, s0, s8
	s_ashr_i32 s8, s0, 31
	s_lshr_b32 s8, s8, 29
	s_lshr_b32 s1, s1, 3
	s_add_i32 s10, s0, s8
	s_and_b32 s1, s1, 0x1ffffff8
	s_and_b32 s8, s10, 0xfffff8
	s_sub_i32 s0, s0, s8
	s_add_i32 s1, s1, s6
	s_add_i32 s1, s1, s0
	s_lshl_b32 s8, s1, 8
	s_lshl_b32 s0, s9, 4
	s_lshl_b32 s1, s10, 4
	s_and_b32 s0, s0, 0xfffffc00
	s_and_b32 s9, s1, 0xffffff80
	s_add_i32 s9, s9, s0
	v_mov_b32_e32 v134, v163
	s_mov_b32 s0, s2
	s_waitcnt vmcnt(0)
	v_mov_b32_e32 v10, v163
	s_mov_b32 s0, s2
	v_ashrrev_i32_e32 v9, 6, v10
	v_and_b32_e32 v0, 3, v10
	v_lshrrev_b32_e32 v2, 4, v10
	v_bitop3_b32 v0, v2, v0, 2 bitop3:0x6c
	v_and_b32_e32 v2, 0xffffffc0, v10
	v_lshlrev_b32_e32 v12, 5, v9
	v_bfe_u32 v11, v10, 2, 4
	v_add_u32_e32 v2, s8, v2
	v_add_u32_e32 v6, s9, v12
	v_and_b32_e32 v8, 63, v10
	v_or_b32_e32 v2, v2, v11
	v_or_b32_e32 v6, v6, v11
	v_ashrrev_i32_e32 v3, 31, v2
	v_ashrrev_i32_e32 v7, 31, v6
	v_readlane_b32 s0, v254, 54
	v_lshlrev_b32_e32 v13, 12, v9
	v_lshlrev_b32_e32 v8, 4, v8
	v_lshlrev_b64 v[2:3], 13, v[2:3]
	v_lshlrev_b64 v[6:7], 13, v[6:7]
	v_readlane_b32 s1, v254, 55
	v_or_b32_e32 v136, v13, v8
	v_lshl_add_u64 v[4:5], s[60:61], 0, v[2:3]
	v_lshlrev_b32_e32 v0, 4, v0
	v_lshl_add_u64 v[6:7], s[0:1], 0, v[6:7]
	v_readfirstlane_b32 s0, v136
	v_or_b32_e32 v15, 0x400, v136
	v_lshl_add_u64 v[4:5], v[4:5], 0, v[0:1]
	v_bfe_i32 v199, v163, 2, 1
	v_and_b32_e32 v198, 0xffffe040, v199
	v_lshl_add_u64 v[4:5], v[4:5], 0, v[198:199]
	s_mov_b32 m0, s0
	s_mov_b64 s[10:11], 0x20000
	v_readfirstlane_b32 s0, v15
	v_lshl_or_b32 v137, v9, 11, v8
	global_load_lds_dwordx4 v[4:5], off
	v_lshl_add_u64 v[8:9], v[4:5], 0, s[10:11]
	s_mov_b32 m0, s0
	s_mov_b64 s[0:1], 0x40000
	v_or_b32_e32 v15, 0x800, v136
	global_load_lds_dwordx4 v[8:9], off
	v_lshl_add_u64 v[8:9], v[4:5], 0, s[0:1]
	v_readfirstlane_b32 s0, v15
	s_mov_b32 m0, s0
	s_mov_b64 s[0:1], 0x60000
	v_or_b32_e32 v15, 0xc00, v136
	v_add_u32_e32 v14, 0x4000, v137
	global_load_lds_dwordx4 v[8:9], off
	v_lshl_add_u64 v[8:9], v[4:5], 0, s[0:1]
	v_readfirstlane_b32 s0, v15
	s_mov_b32 m0, s0
	v_readfirstlane_b32 s0, v14
	v_add_u32_e32 v14, 0x4400, v137
	global_load_lds_dwordx4 v[8:9], off
	v_lshl_add_u64 v[6:7], v[6:7], 0, v[0:1]
	v_bfe_i32 v199, v163, 2, 1
	v_and_b32_e32 v198, 0xffffe040, v199
	v_lshl_add_u64 v[6:7], v[6:7], 0, v[198:199]
	s_mov_b32 m0, s0
	v_readfirstlane_b32 s0, v14
	v_add_u32_e32 v14, 0x6000, v136
	global_load_lds_dwordx4 v[6:7], off
	v_lshl_add_u64 v[8:9], v[6:7], 0, s[10:11]
	s_mov_b32 m0, s0
	v_readfirstlane_b32 s0, v14
	v_add_u32_e32 v14, 0x6400, v136
	global_load_lds_dwordx4 v[8:9], off
	s_mov_b64 s[98:99], 0x80
	v_lshl_add_u64 v[8:9], v[4:5], 0, s[98:99]
	s_mov_b32 m0, s0
	s_mov_b64 s[10:11], 0x20040
	v_readfirstlane_b32 s0, v14
	global_load_lds_dwordx4 v[8:9], off
	s_mov_b64 s[98:99], 0x20080
	v_lshl_add_u64 v[8:9], v[4:5], 0, s[98:99]
	s_mov_b32 m0, s0
	s_mov_b64 s[0:1], 0x40080
	v_add_u32_e32 v14, 0x6800, v136
	global_load_lds_dwordx4 v[8:9], off
	v_lshl_add_u64 v[8:9], v[4:5], 0, s[0:1]
	v_readfirstlane_b32 s0, v14
	s_mov_b32 m0, s0
	s_mov_b64 s[0:1], 0x60080
	global_load_lds_dwordx4 v[8:9], off
	v_add_u32_e32 v8, 0x6c00, v136
	v_lshl_add_u64 v[4:5], v[4:5], 0, s[0:1]
	v_readfirstlane_b32 s0, v8
	v_add_u32_e32 v8, 0xa000, v137
	s_mov_b32 m0, s0
	v_readfirstlane_b32 s0, v8
	global_load_lds_dwordx4 v[4:5], off
	s_mov_b64 s[98:99], 0x80
	v_lshl_add_u64 v[4:5], v[6:7], 0, s[98:99]
	s_mov_b32 m0, s0
	v_or_b32_e32 v2, v2, v0
	global_load_lds_dwordx4 v[4:5], off
	s_mov_b64 s[98:99], 0x20080
	v_lshl_add_u64 v[4:5], v[6:7], 0, s[98:99]
	v_add_u32_e32 v6, 0xa400, v137
	v_lshl_add_u64 v[132:133], s[62:63], 0, v[2:3]
	v_readfirstlane_b32 s0, v6
	s_mov_b32 m0, s0
	v_and_b32_e32 v6, 48, v10
	global_load_lds_dwordx4 v[4:5], off
	v_lshlrev_b32_e32 v5, 2, v10
	v_lshlrev_b32_e32 v4, 6, v10
	v_bitop3_b32 v5, v5, v6, 32 bitop3:0x6c
	v_and_or_b32 v138, v4, s59, v5
	v_and_b32_e32 v139, 0xffffe000, v4
	v_or_b32_e32 v4, s9, v11
	v_add_u32_e32 v4, v4, v12
	v_ashrrev_i32_e32 v5, 31, v4
	v_lshlrev_b64 v[4:5], 13, v[4:5]
	v_readlane_b32 s0, v254, 52
	v_or_b32_e32 v4, v4, v0
	v_readlane_b32 s1, v254, 53
	v_mov_b32_e32 v2, 0
	v_and_b32_e32 v135, 0x1000, v13
	v_lshl_add_u64 v[130:131], s[0:1], 0, v[4:5]
	s_mov_b64 s[0:1], 0
	s_mov_b32 s10, 0
	v_mov_b32_e32 v3, v2
	v_mov_b32_e32 v4, v2
	v_mov_b32_e32 v5, v2
	v_mov_b32_e32 v6, v2
	v_mov_b32_e32 v7, v2
	v_mov_b32_e32 v8, v2
	v_mov_b32_e32 v9, v2
	v_mov_b32_e32 v10, v2
	v_mov_b32_e32 v11, v2
	v_mov_b32_e32 v12, v2
	v_mov_b32_e32 v13, v2
	v_mov_b32_e32 v14, v2
	v_mov_b32_e32 v15, v2
	v_mov_b32_e32 v16, v2
	v_mov_b32_e32 v17, v2
	v_mov_b32_e32 v18, v2
	v_mov_b32_e32 v19, v2
	v_mov_b32_e32 v20, v2
	v_mov_b32_e32 v21, v2
	v_mov_b32_e32 v22, v2
	v_mov_b32_e32 v23, v2
	v_mov_b32_e32 v24, v2
	v_mov_b32_e32 v25, v2
	s_waitcnt lgkmcnt(0)
; template <int MI, int NI>
; DI void gemm256(f32x4 (&acc)[MI][NI], const u16* __restrict__ A, int lda, const u16* __restrict__ Bt, int ldb, int K, int m0, int n0, char* smem) {
;     ...
;   G256_ISSUE(0, 0);
;   if (nk > 1) G256_ISSUE(1, 32);
;   const int foff = lr * 64 + ((lq ^ ((lr >> 3) << 1)) * 16);
;   int st = 0;
;   for (int kt = 0; kt < nk; ++kt) {
;     if (kt + 1 < nk) asm volatile("s_waitcnt vmcnt(%0) lgkmcnt(0)" :: "n"(LPS) : "memory");
;     else asm volatile("s_waitcnt vmcnt(0) lgkmcnt(0)" ::: "memory");
;     __builtin_amdgcn_s_barrier();
;     __builtin_amdgcn_s_setprio(1);
;     const char* sb = smem + st * STAGE + foff;
;     bf16x8 af[MI], bfr[NI];
; #pragma unroll
;     for (int mi = 0; mi < MI; ++mi) af[mi] = *(const bf16x8*)(sb + (wr * MI + mi) * 1024);
; #pragma unroll
;     for (int ni = 0; ni < NI; ++ni) bfr[ni] = *(const bf16x8*)(sb + ABYTES + (wc * NI + ni) * 1024);
;     __builtin_amdgcn_sched_barrier(0x0);
;     if (kt + 2 < nk) { const int s2 = st >= 1 ? st - 1 : 2; G256_ISSUE(s2, (kt + 2) * 32); }
;     __builtin_amdgcn_s_setprio(0);
; #pragma unroll
;     for (int mi = 0; mi < MI; ++mi)
; #pragma unroll
;       for (int ni = 0; ni < NI; ++ni)
;         acc[mi][ni] = __builtin_amdgcn_mfma_f32_16x16x32_bf16(bfr[ni], af[mi], acc[mi][ni], 0, 0, 0);
;     st = st == 2 ? 0 : st + 1;
;   }
	v_mov_b32_e32 v26, v2
	v_mov_b32_e32 v27, v2
	v_mov_b32_e32 v28, v2
	v_mov_b32_e32 v29, v2
	v_mov_b32_e32 v30, v2
	v_mov_b32_e32 v31, v2
	v_mov_b32_e32 v32, v2
	v_mov_b32_e32 v33, v2
	v_mov_b32_e32 v34, v2
	v_mov_b32_e32 v35, v2
	v_mov_b32_e32 v36, v2
	v_mov_b32_e32 v37, v2
	v_mov_b32_e32 v38, v2
	v_mov_b32_e32 v39, v2
	v_mov_b32_e32 v40, v2
	v_mov_b32_e32 v41, v2
	v_mov_b32_e32 v42, v2
	v_mov_b32_e32 v43, v2
	v_mov_b32_e32 v44, v2
	v_mov_b32_e32 v45, v2
	v_mov_b32_e32 v46, v2
	v_mov_b32_e32 v47, v2
	v_mov_b32_e32 v48, v2
	v_mov_b32_e32 v49, v2
	v_mov_b32_e32 v50, v2
	v_mov_b32_e32 v51, v2
	v_mov_b32_e32 v52, v2
	v_mov_b32_e32 v53, v2
	v_mov_b32_e32 v54, v2
	v_mov_b32_e32 v55, v2
	v_mov_b32_e32 v56, v2
	v_mov_b32_e32 v57, v2
	v_mov_b32_e32 v58, v2
	v_mov_b32_e32 v59, v2
	v_mov_b32_e32 v60, v2
	v_mov_b32_e32 v61, v2
	v_mov_b32_e32 v62, v2
	v_mov_b32_e32 v63, v2
	v_mov_b32_e32 v64, v2
	v_mov_b32_e32 v65, v2
	v_mov_b32_e32 v66, v2
	v_mov_b32_e32 v67, v2
	v_mov_b32_e32 v68, v2
	v_mov_b32_e32 v69, v2
	v_mov_b32_e32 v70, v2
	v_mov_b32_e32 v71, v2
	v_mov_b32_e32 v72, v2
	v_mov_b32_e32 v73, v2
	v_mov_b32_e32 v74, v2
	v_mov_b32_e32 v75, v2
	v_mov_b32_e32 v76, v2
	v_mov_b32_e32 v77, v2
	v_mov_b32_e32 v78, v2
	v_mov_b32_e32 v79, v2
	v_mov_b32_e32 v80, v2
	v_mov_b32_e32 v81, v2
	v_mov_b32_e32 v82, v2
	v_mov_b32_e32 v83, v2
	v_mov_b32_e32 v84, v2
	v_mov_b32_e32 v85, v2
	v_mov_b32_e32 v86, v2
	v_mov_b32_e32 v87, v2
	v_mov_b32_e32 v88, v2
	v_mov_b32_e32 v89, v2
	v_mov_b32_e32 v90, v2
	v_mov_b32_e32 v91, v2
	v_mov_b32_e32 v92, v2
	v_mov_b32_e32 v93, v2
	v_mov_b32_e32 v94, v2
	v_mov_b32_e32 v95, v2
	v_mov_b32_e32 v96, v2
	v_mov_b32_e32 v97, v2
	v_mov_b32_e32 v98, v2
	v_mov_b32_e32 v99, v2
	v_mov_b32_e32 v100, v2
	v_mov_b32_e32 v101, v2
	v_mov_b32_e32 v102, v2
	v_mov_b32_e32 v103, v2
	v_mov_b32_e32 v104, v2
	v_mov_b32_e32 v105, v2
	v_mov_b32_e32 v106, v2
	v_mov_b32_e32 v107, v2
	v_mov_b32_e32 v108, v2
	v_mov_b32_e32 v109, v2
	v_mov_b32_e32 v110, v2
	v_mov_b32_e32 v111, v2
	v_mov_b32_e32 v112, v2
	v_mov_b32_e32 v113, v2
	v_mov_b32_e32 v114, v2
	v_mov_b32_e32 v115, v2
	v_mov_b32_e32 v116, v2
	v_mov_b32_e32 v117, v2
	v_mov_b32_e32 v118, v2
	v_mov_b32_e32 v119, v2
	v_mov_b32_e32 v120, v2
	v_mov_b32_e32 v121, v2
	v_mov_b32_e32 v122, v2
	v_mov_b32_e32 v123, v2
	v_mov_b32_e32 v124, v2
	v_mov_b32_e32 v125, v2
	v_mov_b32_e32 v126, v2
	v_mov_b32_e32 v127, v2
	v_mov_b32_e32 v128, v2
	v_mov_b32_e32 v129, v2
	s_mov_b64 s[12:13], 0x47e1100
	v_lshl_add_u64 v[196:197], v[132:133], 0, s[12:13]
	s_mov_b64 s[12:13], 0x4801100
	v_lshl_add_u64 v[198:199], v[132:133], 0, s[12:13]
	s_mov_b64 s[12:13], 0x4821100
	v_lshl_add_u64 v[200:201], v[132:133], 0, s[12:13]
	s_mov_b64 s[12:13], 0x4841100
	v_lshl_add_u64 v[202:203], v[132:133], 0, s[12:13]
	s_mov_b64 s[12:13], 0x2061100
	v_lshl_add_u64 v[204:205], v[130:131], 0, s[12:13]
	s_mov_b64 s[12:13], 0x2081100
	v_lshl_add_u64 v[206:207], v[130:131], 0, s[12:13]
	v_bfe_i32 v193, v163, 2, 1
	v_and_b32_e32 v192, 0xffffe040, v193
	v_lshl_add_u64 v[196:197], v[196:197], 0, v[192:193]
	v_lshl_add_u64 v[198:199], v[198:199], 0, v[192:193]
	v_lshl_add_u64 v[200:201], v[200:201], 0, v[192:193]
	v_lshl_add_u64 v[202:203], v[202:203], 0, v[192:193]
	v_and_b32_e32 v192, 0xffffe040, v193
	v_lshl_add_u64 v[204:205], v[204:205], 0, v[192:193]
	v_lshl_add_u64 v[206:207], v[206:207], 0, v[192:193]
	s_mov_b64 s[98:99], 0x80
	v_add_u32_e32 v160, v138, v139
	v_add_u32_e32 v0, v138, v135
	v_readfirstlane_b32 s0, v136
	v_readfirstlane_b32 s1, v137
	s_mov_b32 s11, 0
	s_movk_i32 s100, 125
	s_add_i32 s1, s1, 0x4000
	s_waitcnt vmcnt(6) lgkmcnt(0)
	s_barrier
	ds_read_b128 v[140:143], v160
	ds_read_b128 v[144:147], v160 offset:1024
	ds_read_b128 v[148:151], v160 offset:2048
	ds_read_b128 v[152:155], v160 offset:3072
	ds_read_b128 v[176:179], v0 offset:16384
	ds_read_b128 v[180:183], v0 offset:17408
	ds_read_b128 v[184:187], v0 offset:18432
	ds_read_b128 v[188:191], v0 offset:19456
.Lpipe_mlp2:
	v_add_u32_e32 v161, s11, v160
	ds_read_b128 v[156:159], v161 offset:4096
	ds_read_b128 v[164:167], v161 offset:5120
	ds_read_b128 v[168:171], v161 offset:6144
	ds_read_b128 v[172:175], v161 offset:7168
	s_add_i32 s12, s11, 0xffffa000
	s_cmp_eq_u32 s11, 0
	s_cselect_b32 s12, 0xc000, s12
	s_add_i32 s13, s12, s0
	s_add_i32 s12, s12, s1
	s_mov_b32 m0, s13
	s_waitcnt lgkmcnt(7)
	v_mfma_f32_16x16x32_bf16 v[126:129], v[176:179], v[140:143], v[126:129]
	global_load_lds_dwordx4 v[196:197], off
	v_mfma_f32_16x16x32_bf16 v[110:113], v[176:179], v[144:147], v[110:113]
	v_lshl_add_u64 v[196:197], v[196:197], 0, s[98:99]
	s_add_i32 m0, s13, 0x400
	v_mfma_f32_16x16x32_bf16 v[94:97], v[176:179], v[148:151], v[94:97]
	global_load_lds_dwordx4 v[198:199], off
	v_mfma_f32_16x16x32_bf16 v[78:81], v[176:179], v[152:155], v[78:81]
	v_lshl_add_u64 v[198:199], v[198:199], 0, s[98:99]
	s_add_i32 m0, s13, 0x800
	s_waitcnt lgkmcnt(6)
	v_mfma_f32_16x16x32_bf16 v[122:125], v[180:183], v[140:143], v[122:125]
	global_load_lds_dwordx4 v[200:201], off
	v_mfma_f32_16x16x32_bf16 v[106:109], v[180:183], v[144:147], v[106:109]
	v_lshl_add_u64 v[200:201], v[200:201], 0, s[98:99]
	s_add_i32 m0, s13, 0xc00
	v_mfma_f32_16x16x32_bf16 v[90:93], v[180:183], v[148:151], v[90:93]
	global_load_lds_dwordx4 v[202:203], off
	v_mfma_f32_16x16x32_bf16 v[74:77], v[180:183], v[152:155], v[74:77]
	v_lshl_add_u64 v[202:203], v[202:203], 0, s[98:99]
	s_mov_b32 m0, s12
	s_waitcnt lgkmcnt(5)
	v_mfma_f32_16x16x32_bf16 v[118:121], v[184:187], v[140:143], v[118:121]
	global_load_lds_dwordx4 v[204:205], off
	v_mfma_f32_16x16x32_bf16 v[102:105], v[184:187], v[144:147], v[102:105]
	v_lshl_add_u64 v[204:205], v[204:205], 0, s[98:99]
	s_add_i32 m0, s12, 0x400
	v_mfma_f32_16x16x32_bf16 v[86:89], v[184:187], v[148:151], v[86:89]
	global_load_lds_dwordx4 v[206:207], off
	v_mfma_f32_16x16x32_bf16 v[70:73], v[184:187], v[152:155], v[70:73]
	v_lshl_add_u64 v[206:207], v[206:207], 0, s[98:99]
	s_waitcnt lgkmcnt(4)
	v_mfma_f32_16x16x32_bf16 v[114:117], v[188:191], v[140:143], v[114:117]
	v_mfma_f32_16x16x32_bf16 v[98:101], v[188:191], v[144:147], v[98:101]
	v_mfma_f32_16x16x32_bf16 v[82:85], v[188:191], v[148:151], v[82:85]
	v_mfma_f32_16x16x32_bf16 v[66:69], v[188:191], v[152:155], v[66:69]
	s_waitcnt vmcnt(6) lgkmcnt(0)
	s_barrier
; template <int MI, int NI>
; DI void gemm256(f32x4 (&acc)[MI][NI], const u16* __restrict__ A, int lda, const u16* __restrict__ Bt, int ldb, int K, int m0, int n0, char* smem) {
;     ...
;   for (int kt = 0; kt < nk; ++kt) {
;     if (kt + 1 < nk) asm volatile("s_waitcnt vmcnt(%0) lgkmcnt(0)" :: "n"(LPS) : "memory");
;     else asm volatile("s_waitcnt vmcnt(0) lgkmcnt(0)" ::: "memory");
;     __builtin_amdgcn_s_barrier();
;     __builtin_amdgcn_s_setprio(1);
;     const char* sb = smem + st * STAGE + foff;
;     bf16x8 af[MI], bfr[NI];
; #pragma unroll
;     for (int mi = 0; mi < MI; ++mi) af[mi] = *(const bf16x8*)(sb + (wr * MI + mi) * 1024);
; #pragma unroll
;     for (int ni = 0; ni < NI; ++ni) bfr[ni] = *(const bf16x8*)(sb + ABYTES + (wc * NI + ni) * 1024);
;     __builtin_amdgcn_sched_barrier(0x0);
;     if (kt + 2 < nk) { const int s2 = st >= 1 ? st - 1 : 2; G256_ISSUE(s2, (kt + 2) * 32); }
;     __builtin_amdgcn_s_setprio(0);
; #pragma unroll
;     for (int mi = 0; mi < MI; ++mi)
; #pragma unroll
;       for (int ni = 0; ni < NI; ++ni)
;         acc[mi][ni] = __builtin_amdgcn_mfma_f32_16x16x32_bf16(bfr[ni], af[mi], acc[mi][ni], 0, 0, 0);
;     st = st == 2 ? 0 : st + 1;
;   }
;   asm volatile("s_waitcnt lgkmcnt(0)" ::: "memory");
;   __builtin_amdgcn_s_barrier();
	s_add_i32 s13, s11, 0x6000
	s_cmp_eq_u32 s11, 0xc000
	s_cselect_b32 s11, 0, s13
	v_add_u32_e32 v192, s11, v160
	v_add_u32_e32 v193, s11, v0
	v_mfma_f32_16x16x32_bf16 v[62:65], v[176:179], v[156:159], v[62:65]
	ds_read_b128 v[140:143], v192
	v_mfma_f32_16x16x32_bf16 v[46:49], v[176:179], v[164:167], v[46:49]
	ds_read_b128 v[144:147], v192 offset:1024
	v_mfma_f32_16x16x32_bf16 v[30:33], v[176:179], v[168:171], v[30:33]
	ds_read_b128 v[148:151], v192 offset:2048
	v_mfma_f32_16x16x32_bf16 v[14:17], v[176:179], v[172:175], v[14:17]
	ds_read_b128 v[152:155], v192 offset:3072
	ds_read_b128 v[176:179], v193 offset:16384
	v_mfma_f32_16x16x32_bf16 v[58:61], v[180:183], v[156:159], v[58:61]
	v_mfma_f32_16x16x32_bf16 v[42:45], v[180:183], v[164:167], v[42:45]
	v_mfma_f32_16x16x32_bf16 v[26:29], v[180:183], v[168:171], v[26:29]
	v_mfma_f32_16x16x32_bf16 v[10:13], v[180:183], v[172:175], v[10:13]
	ds_read_b128 v[180:183], v193 offset:17408
	v_mfma_f32_16x16x32_bf16 v[54:57], v[184:187], v[156:159], v[54:57]
	v_mfma_f32_16x16x32_bf16 v[38:41], v[184:187], v[164:167], v[38:41]
	v_mfma_f32_16x16x32_bf16 v[22:25], v[184:187], v[168:171], v[22:25]
	v_mfma_f32_16x16x32_bf16 v[6:9], v[184:187], v[172:175], v[6:9]
	ds_read_b128 v[184:187], v193 offset:18432
	v_mfma_f32_16x16x32_bf16 v[50:53], v[188:191], v[156:159], v[50:53]
	v_mfma_f32_16x16x32_bf16 v[34:37], v[188:191], v[164:167], v[34:37]
	v_mfma_f32_16x16x32_bf16 v[18:21], v[188:191], v[168:171], v[18:21]
	v_mfma_f32_16x16x32_bf16 v[2:5], v[188:191], v[172:175], v[2:5]
	ds_read_b128 v[188:191], v193 offset:19456
	s_sub_i32 s100, s100, 1
	s_cmp_lg_u32 s100, 0
	s_cbranch_scc1 .Lpipe_mlp2
	v_add_u32_e32 v161, s11, v160
	ds_read_b128 v[156:159], v161 offset:4096
	ds_read_b128 v[164:167], v161 offset:5120
	ds_read_b128 v[168:171], v161 offset:6144
	ds_read_b128 v[172:175], v161 offset:7168
	s_add_i32 s12, s11, 0xffffa000
	s_cmp_eq_u32 s11, 0
	s_cselect_b32 s12, 0xc000, s12
	s_add_i32 s13, s12, s0
	s_add_i32 s12, s12, s1
	s_mov_b32 m0, s13
	s_waitcnt lgkmcnt(7)
	v_mfma_f32_16x16x32_bf16 v[126:129], v[176:179], v[140:143], v[126:129]
	global_load_lds_dwordx4 v[196:197], off
	v_mfma_f32_16x16x32_bf16 v[110:113], v[176:179], v[144:147], v[110:113]
	v_lshl_add_u64 v[196:197], v[196:197], 0, s[98:99]
	s_add_i32 m0, s13, 0x400
	v_mfma_f32_16x16x32_bf16 v[94:97], v[176:179], v[148:151], v[94:97]
	global_load_lds_dwordx4 v[198:199], off
	v_mfma_f32_16x16x32_bf16 v[78:81], v[176:179], v[152:155], v[78:81]
	v_lshl_add_u64 v[198:199], v[198:199], 0, s[98:99]
	s_add_i32 m0, s13, 0x800
	s_waitcnt lgkmcnt(6)
	v_mfma_f32_16x16x32_bf16 v[122:125], v[180:183], v[140:143], v[122:125]
	global_load_lds_dwordx4 v[200:201], off
	v_mfma_f32_16x16x32_bf16 v[106:109], v[180:183], v[144:147], v[106:109]
	v_lshl_add_u64 v[200:201], v[200:201], 0, s[98:99]
	s_add_i32 m0, s13, 0xc00
	v_mfma_f32_16x16x32_bf16 v[90:93], v[180:183], v[148:151], v[90:93]
	global_load_lds_dwordx4 v[202:203], off
	v_mfma_f32_16x16x32_bf16 v[74:77], v[180:183], v[152:155], v[74:77]
	v_lshl_add_u64 v[202:203], v[202:203], 0, s[98:99]
	s_mov_b32 m0, s12
	s_waitcnt lgkmcnt(5)
	v_mfma_f32_16x16x32_bf16 v[118:121], v[184:187], v[140:143], v[118:121]
	global_load_lds_dwordx4 v[204:205], off
	v_mfma_f32_16x16x32_bf16 v[102:105], v[184:187], v[144:147], v[102:105]
	v_lshl_add_u64 v[204:205], v[204:205], 0, s[98:99]
	s_add_i32 m0, s12, 0x400
	v_mfma_f32_16x16x32_bf16 v[86:89], v[184:187], v[148:151], v[86:89]
	global_load_lds_dwordx4 v[206:207], off
	v_mfma_f32_16x16x32_bf16 v[70:73], v[184:187], v[152:155], v[70:73]
	v_lshl_add_u64 v[206:207], v[206:207], 0, s[98:99]
	s_waitcnt lgkmcnt(4)
	v_mfma_f32_16x16x32_bf16 v[114:117], v[188:191], v[140:143], v[114:117]
	v_mfma_f32_16x16x32_bf16 v[98:101], v[188:191], v[144:147], v[98:101]
	v_mfma_f32_16x16x32_bf16 v[82:85], v[188:191], v[148:151], v[82:85]
	v_mfma_f32_16x16x32_bf16 v[66:69], v[188:191], v[152:155], v[66:69]
	s_waitcnt lgkmcnt(0)
	v_mfma_f32_16x16x32_bf16 v[62:65], v[176:179], v[156:159], v[62:65]
	v_mfma_f32_16x16x32_bf16 v[46:49], v[176:179], v[164:167], v[46:49]
	v_mfma_f32_16x16x32_bf16 v[30:33], v[176:179], v[168:171], v[30:33]
	v_mfma_f32_16x16x32_bf16 v[14:17], v[176:179], v[172:175], v[14:17]
	v_mfma_f32_16x16x32_bf16 v[58:61], v[180:183], v[156:159], v[58:61]
	v_mfma_f32_16x16x32_bf16 v[42:45], v[180:183], v[164:167], v[42:45]
	v_mfma_f32_16x16x32_bf16 v[26:29], v[180:183], v[168:171], v[26:29]
	v_mfma_f32_16x16x32_bf16 v[10:13], v[180:183], v[172:175], v[10:13]
	v_mfma_f32_16x16x32_bf16 v[54:57], v[184:187], v[156:159], v[54:57]
	v_mfma_f32_16x16x32_bf16 v[38:41], v[184:187], v[164:167], v[38:41]
	v_mfma_f32_16x16x32_bf16 v[22:25], v[184:187], v[168:171], v[22:25]
	v_mfma_f32_16x16x32_bf16 v[6:9], v[184:187], v[172:175], v[6:9]
	v_mfma_f32_16x16x32_bf16 v[50:53], v[188:191], v[156:159], v[50:53]
	v_mfma_f32_16x16x32_bf16 v[34:37], v[188:191], v[164:167], v[34:37]
	v_mfma_f32_16x16x32_bf16 v[18:21], v[188:191], v[168:171], v[18:21]
	v_mfma_f32_16x16x32_bf16 v[2:5], v[188:191], v[172:175], v[2:5]
	s_mov_b32 s10, 0
	s_waitcnt vmcnt(6) lgkmcnt(0)
	s_barrier
	s_setprio 1
	s_mul_i32 s0, s10, 0x6000
	v_or_b32_e32 v0, s0, v138
	v_add_u32_e32 v136, v0, v139
	s_waitcnt vmcnt(0)
	ds_read_b128 v[130:133], v136
	ds_read_b128 v[140:143], v136 offset:1024
	ds_read_b128 v[144:147], v136 offset:2048
	ds_read_b128 v[148:151], v136 offset:3072
	ds_read_b128 v[152:155], v136 offset:4096
	ds_read_b128 v[156:159], v136 offset:5120
	ds_read_b128 v[164:167], v136 offset:6144
	ds_read_b128 v[168:171], v136 offset:7168
	v_add_u32_e32 v0, v0, v135
	ds_read_b128 v[172:175], v0 offset:16384
	ds_read_b128 v[176:179], v0 offset:17408
	ds_read_b128 v[180:183], v0 offset:18432
	ds_read_b128 v[184:187], v0 offset:19456
	v_bfe_u32 v0, v134, 6, 1
	s_setprio 0
	s_waitcnt vmcnt(0) lgkmcnt(0)
	s_waitcnt lgkmcnt(3)
	v_mfma_f32_16x16x32_bf16 v[126:129], v[172:175], v[130:133], v[126:129]
	v_ashrrev_i32_e32 v160, 7, v134
	v_and_b32_e32 v161, 15, v134
	v_bfe_u32 v134, v134, 4, 2
	s_waitcnt lgkmcnt(2)
	v_mfma_f32_16x16x32_bf16 v[122:125], v[176:179], v[130:133], v[122:125]
	s_barrier
; #define EPI_BEGIN const int lr1_ = launder_v(lr), lq1_ = launder_v(lq), wr1_ = launder_v(wr), wc1_ = launder_v(wc); { const int lr = lr1_, lq = lq1_, wr = wr1_, wc = wc1_; (void)lr; (void)lq; (void)wr; (void)wc;
; template <int MI, int NI>
; DI void gemm256(f32x4 (&acc)[MI][NI], const u16* __restrict__ A, int lda, const u16* __restrict__ Bt, int ldb, int K, int m0, int n0, char* smem) {
;     ...
; #pragma unroll
;     for (int mi = 0; mi < MI; ++mi)
; #pragma unroll
;       for (int ni = 0; ni < NI; ++ni)
;         acc[mi][ni] = __builtin_amdgcn_mfma_f32_16x16x32_bf16(bfr[ni], af[mi], acc[mi][ni], 0, 0, 0);
;     st = st == 2 ? 0 : st + 1;
;   }
; template <int MI, int NI>
; DI void resid_tile(const u16* A, int K, const u16* Bt, const float* gate, const float* xl_in, const float* xc_in, float* xl_out, float* xc_out,
;                    int m0, int n0, char* smem) {
;     ...
;   EPI_BEGIN
; #pragma unroll
;   for (int mi = 0; mi < MI; ++mi) {
;     const int m = m0 + wr * 16 * MI + mi * 16 + lr;
;     const int b9 = m < NTL ? m >> 12 : 8;
;     const float* xi = xrow(xl_in, xc_in, m);
;     float* xo = m < NTL ? xl_out + (size_t)m * D : xc_out + (size_t)(m - NTL) * D;
; #pragma unroll
;     for (int ni = 0; ni < NI; ++ni) {
;       const int n = n0 + wc * 16 * NI + ni * 16 + lq * 4;
;       const float4 g = *(const float4*)(gate + (size_t)b9 * 6144 + n);
;       const float4 xv = *(const float4*)(xi + n);
;       float4 ov;
;       ov.x = xv.x + g.x * acc[mi][ni][0]; ov.y = xv.y + g.y * acc[mi][ni][1]; ov.z = xv.z + g.z * acc[mi][ni][2]; ov.w = xv.w + g.w * acc[mi][ni][3];
;       *(float4*)(xo + n) = ov;
;     }
;     __builtin_amdgcn_sched_barrier(0);
	s_waitcnt lgkmcnt(1)
	v_mfma_f32_16x16x32_bf16 v[118:121], v[180:183], v[130:133], v[118:121]
	s_waitcnt lgkmcnt(0)
	v_mfma_f32_16x16x32_bf16 v[114:117], v[184:187], v[130:133], v[114:117]
	v_mfma_f32_16x16x32_bf16 v[110:113], v[172:175], v[140:143], v[110:113]
	v_mfma_f32_16x16x32_bf16 v[106:109], v[176:179], v[140:143], v[106:109]
	v_mfma_f32_16x16x32_bf16 v[102:105], v[180:183], v[140:143], v[102:105]
	v_mfma_f32_16x16x32_bf16 v[98:101], v[184:187], v[140:143], v[98:101]
	v_mfma_f32_16x16x32_bf16 v[94:97], v[172:175], v[144:147], v[94:97]
	v_mfma_f32_16x16x32_bf16 v[90:93], v[176:179], v[144:147], v[90:93]
	v_mfma_f32_16x16x32_bf16 v[86:89], v[180:183], v[144:147], v[86:89]
	v_mfma_f32_16x16x32_bf16 v[82:85], v[184:187], v[144:147], v[82:85]
	v_mfma_f32_16x16x32_bf16 v[78:81], v[172:175], v[148:151], v[78:81]
	v_mfma_f32_16x16x32_bf16 v[130:133], v[176:179], v[148:151], v[74:77]
	v_mfma_f32_16x16x32_bf16 v[70:73], v[180:183], v[148:151], v[70:73]
	v_mfma_f32_16x16x32_bf16 v[66:69], v[184:187], v[148:151], v[66:69]
	v_mfma_f32_16x16x32_bf16 v[62:65], v[172:175], v[152:155], v[62:65]
	v_mfma_f32_16x16x32_bf16 v[58:61], v[176:179], v[152:155], v[58:61]
	v_mfma_f32_16x16x32_bf16 v[54:57], v[180:183], v[152:155], v[54:57]
	v_mfma_f32_16x16x32_bf16 v[50:53], v[184:187], v[152:155], v[50:53]
	v_mfma_f32_16x16x32_bf16 v[46:49], v[172:175], v[156:159], v[46:49]
	v_mfma_f32_16x16x32_bf16 v[42:45], v[176:179], v[156:159], v[42:45]
	v_mfma_f32_16x16x32_bf16 v[38:41], v[180:183], v[156:159], v[38:41]
	v_mfma_f32_16x16x32_bf16 v[34:37], v[184:187], v[156:159], v[34:37]
	v_mfma_f32_16x16x32_bf16 v[30:33], v[172:175], v[164:167], v[30:33]
	v_mfma_f32_16x16x32_bf16 v[26:29], v[176:179], v[164:167], v[26:29]
	v_mfma_f32_16x16x32_bf16 v[22:25], v[180:183], v[164:167], v[22:25]
	v_mfma_f32_16x16x32_bf16 v[18:21], v[184:187], v[164:167], v[18:21]
	v_mfma_f32_16x16x32_bf16 v[14:17], v[172:175], v[168:171], v[14:17]
	v_mfma_f32_16x16x32_bf16 v[10:13], v[176:179], v[168:171], v[10:13]
	v_mfma_f32_16x16x32_bf16 v[6:9], v[180:183], v[168:171], v[6:9]
	v_mfma_f32_16x16x32_bf16 v[140:143], v[184:187], v[168:171], v[2:5]
	s_setprio 1
	s_addk_i32 s0, 0x6000
	s_cmp_lg_u32 s10, 2
	s_cselect_b32 s0, s0, 0
	v_or_b32_e32 v168, s0, v138
	v_add_u32_e32 v164, v168, v139
	ds_read_b128 v[2:5], v164
	ds_read_b128 v[74:77], v164 offset:1024
	ds_read_b128 v[136:139], v164 offset:2048
	ds_read_b128 v[144:147], v164 offset:3072
	ds_read_b128 v[148:151], v164 offset:4096
	ds_read_b128 v[152:155], v164 offset:5120
	ds_read_b128 v[156:159], v164 offset:6144
	ds_read_b128 v[164:167], v164 offset:7168
	v_add_u32_e32 v135, v168, v135
	ds_read_b128 v[168:171], v135 offset:16384
	ds_read_b128 v[172:175], v135 offset:17408
	ds_read_b128 v[176:179], v135 offset:18432
	ds_read_b128 v[180:183], v135 offset:19456
	s_setprio 0
	s_waitcnt lgkmcnt(3)
	v_mfma_f32_16x16x32_bf16 v[126:129], v[168:171], v[2:5], v[126:129]
	s_waitcnt lgkmcnt(0)
	s_barrier
	s_waitcnt lgkmcnt(2)
	v_mfma_f32_16x16x32_bf16 v[122:125], v[172:175], v[2:5], v[122:125]
	s_waitcnt lgkmcnt(1)
	v_mfma_f32_16x16x32_bf16 v[184:187], v[176:179], v[2:5], v[118:121]
	v_lshlrev_b32_e32 v0, 6, v0
	s_waitcnt lgkmcnt(0)
	v_mfma_f32_16x16x32_bf16 v[188:191], v[180:183], v[2:5], v[114:117]
	v_lshlrev_b32_e32 v2, 7, v160
	v_mov_b32_e32 v118, s95
	v_mov_b32_e32 v119, s49
	v_add3_u32 v116, v161, s8, v2
	v_lshlrev_b32_e32 v2, 2, v134
	v_add3_u32 v2, v2, s9, v0
	v_min_i32_e32 v0, 0x8000, v116
	v_mfma_f32_16x16x32_bf16 v[110:113], v[168:171], v[74:77], v[110:113]
	v_ashrrev_i32_e32 v117, 31, v116
	v_cmp_gt_i32_e32 vcc, s58, v116
	v_mov_b32_e32 v120, s94
	v_mfma_f32_16x16x32_bf16 v[106:109], v[172:175], v[74:77], v[106:109]
	v_cndmask_b32_e32 v5, 0, v117, vcc
	v_mov_b32_e32 v121, s48
	v_cndmask_b32_e32 v115, v118, v119, vcc
	v_mfma_f32_16x16x32_bf16 v[102:105], v[176:179], v[74:77], v[102:105]
	v_cndmask_b32_e32 v114, v120, v121, vcc
	v_ashrrev_i32_e32 v3, 31, v2
	v_mfma_f32_16x16x32_bf16 v[98:101], v[180:183], v[74:77], v[98:101]
	v_mfma_f32_16x16x32_bf16 v[74:77], v[168:171], v[144:147], v[78:81]
	v_mfma_f32_16x16x32_bf16 v[78:81], v[172:175], v[144:147], v[130:133]
	s_nop 2
	v_ashrrev_i32_e32 v130, 12, v0
	v_add_u32_e32 v0, 0xffff8000, v116
	v_cndmask_b32_e32 v4, v0, v116, vcc
	v_lshlrev_b64 v[4:5], 12, v[4:5]
	v_lshl_add_u64 v[4:5], v[114:115], 0, v[4:5]
	v_mul_hi_i32_i24_e32 v115, 0x6000, v130
	v_mul_i32_i24_e32 v114, 0x6000, v130
	v_lshl_add_u64 v[130:131], s[82:83], 0, v[114:115]
	v_lshlrev_b64 v[114:115], 2, v[2:3]
	v_mfma_f32_16x16x32_bf16 v[94:97], v[168:171], v[136:139], v[94:97]
	v_lshl_add_u64 v[134:135], v[130:131], 0, v[114:115]
	v_mfma_f32_16x16x32_bf16 v[90:93], v[172:175], v[136:139], v[90:93]
	v_mfma_f32_16x16x32_bf16 v[86:89], v[176:179], v[136:139], v[86:89]
	v_mfma_f32_16x16x32_bf16 v[82:85], v[180:183], v[136:139], v[82:85]
	v_lshl_add_u64 v[136:137], v[4:5], 0, v[114:115]
	flat_load_dwordx4 v[2:5], v[134:135]
	flat_load_dwordx4 v[130:133], v[136:137]
	v_mfma_f32_16x16x32_bf16 v[70:73], v[176:179], v[144:147], v[70:73]
	v_lshlrev_b64 v[138:139], 12, v[116:117]
	v_lshl_add_u64 v[138:139], s[48:49], 0, v[138:139]
	s_waitcnt vmcnt(0) lgkmcnt(0)
	v_pk_fma_f32 v[2:3], v[126:127], v[2:3], v[130:131]
	v_mfma_f32_16x16x32_bf16 v[66:69], v[180:183], v[144:147], v[66:69]
	v_lshlrev_b64 v[144:145], 12, v[0:1]
	v_lshl_add_u64 v[144:145], s[94:95], 0, v[144:145]
	v_cndmask_b32_e32 v139, v145, v139, vcc
	v_cndmask_b32_e32 v138, v144, v138, vcc
	v_lshl_add_u64 v[138:139], v[138:139], 0, v[114:115]
	v_pk_fma_f32 v[4:5], v[128:129], v[4:5], v[132:133]
	flat_store_dwordx4 v[138:139], v[2:5]
	flat_load_dwordx4 v[126:129], v[134:135] offset:64
	flat_load_dwordx4 v[130:133], v[136:137] offset:64
	v_mfma_f32_16x16x32_bf16 v[2:5], v[172:175], v[164:167], v[10:13]
	v_mfma_f32_16x16x32_bf16 v[62:65], v[168:171], v[148:151], v[62:65]
	s_waitcnt vmcnt(0) lgkmcnt(0)
; template <int MI, int NI>
; DI void resid_tile(const u16* A, int K, const u16* Bt, const float* gate, const float* xl_in, const float* xc_in, float* xl_out, float* xc_out,
;                    int m0, int n0, char* smem) {
;     ...
; #pragma unroll
;   for (int mi = 0; mi < MI; ++mi) {
;     const int m = m0 + wr * 16 * MI + mi * 16 + lr;
;     const int b9 = m < NTL ? m >> 12 : 8;
;     const float* xi = xrow(xl_in, xc_in, m);
;     float* xo = m < NTL ? xl_out + (size_t)m * D : xc_out + (size_t)(m - NTL) * D;
; #pragma unroll
;     for (int ni = 0; ni < NI; ++ni) {
;       const int n = n0 + wc * 16 * NI + ni * 16 + lq * 4;
;       const float4 g = *(const float4*)(gate + (size_t)b9 * 6144 + n);
;       const float4 xv = *(const float4*)(xi + n);
;       float4 ov;
;       ov.x = xv.x + g.x * acc[mi][ni][0]; ov.y = xv.y + g.y * acc[mi][ni][1]; ov.z = xv.z + g.z * acc[mi][ni][2]; ov.w = xv.w + g.w * acc[mi][ni][3];
;       *(float4*)(xo + n) = ov;
;     }
;     __builtin_amdgcn_sched_barrier(0);
;   }
	s_nop 0
	v_pk_fma_f32 v[10:11], v[122:123], v[126:127], v[130:131]
	v_pk_fma_f32 v[12:13], v[124:125], v[128:129], v[132:133]
	flat_store_dwordx4 v[138:139], v[10:13] offset:64
	flat_load_dwordx4 v[10:13], v[134:135] offset:128
	s_nop 0
	flat_load_dwordx4 v[122:125], v[136:137] offset:128
	v_mfma_f32_16x16x32_bf16 v[58:61], v[172:175], v[148:151], v[58:61]
	s_waitcnt vmcnt(0) lgkmcnt(0)
	v_pk_fma_f32 v[10:11], v[184:185], v[10:11], v[122:123]
	v_pk_fma_f32 v[12:13], v[186:187], v[12:13], v[124:125]
	flat_store_dwordx4 v[138:139], v[10:13] offset:128
	flat_load_dwordx4 v[122:125], v[134:135] offset:192
	flat_load_dwordx4 v[126:129], v[136:137] offset:192
	v_mfma_f32_16x16x32_bf16 v[54:57], v[176:179], v[148:151], v[54:57]
	s_waitcnt vmcnt(0) lgkmcnt(0)
	v_pk_fma_f32 v[122:123], v[188:189], v[122:123], v[126:127]
	v_pk_fma_f32 v[124:125], v[190:191], v[124:125], v[128:129]
	v_mfma_f32_16x16x32_bf16 v[50:53], v[180:183], v[148:151], v[50:53]
	flat_store_dwordx4 v[138:139], v[122:125] offset:192
	v_mfma_f32_16x16x32_bf16 v[46:49], v[168:171], v[152:155], v[46:49]
	v_mfma_f32_16x16x32_bf16 v[42:45], v[172:175], v[152:155], v[42:45]
	v_mfma_f32_16x16x32_bf16 v[38:41], v[176:179], v[152:155], v[38:41]
	v_mfma_f32_16x16x32_bf16 v[34:37], v[180:183], v[152:155], v[34:37]
	v_mfma_f32_16x16x32_bf16 v[30:33], v[168:171], v[156:159], v[30:33]
	v_mfma_f32_16x16x32_bf16 v[26:29], v[172:175], v[156:159], v[26:29]
	v_mfma_f32_16x16x32_bf16 v[22:25], v[176:179], v[156:159], v[22:25]
	v_mfma_f32_16x16x32_bf16 v[18:21], v[180:183], v[156:159], v[18:21]
	v_mfma_f32_16x16x32_bf16 v[14:17], v[168:171], v[164:167], v[14:17]
	v_mfma_f32_16x16x32_bf16 v[6:9], v[176:179], v[164:167], v[6:9]
	v_mfma_f32_16x16x32_bf16 v[10:13], v[180:183], v[164:167], v[140:143]
	v_add_u32_e32 v122, 16, v116
	v_min_i32_e32 v0, 0x8000, v122
	v_cmp_gt_i32_e32 vcc, s58, v122
	v_ashrrev_i32_e32 v117, 12, v0
	v_add_u32_e32 v0, 0xffff8010, v116
	v_ashrrev_i32_e32 v123, 31, v122
	v_cndmask_b32_e32 v125, 0, v123, vcc
	v_cndmask_b32_e32 v124, v0, v122, vcc
	v_cndmask_b32_e32 v127, v118, v119, vcc
	v_cndmask_b32_e32 v126, v120, v121, vcc
	v_lshlrev_b64 v[124:125], 12, v[124:125]
	v_lshl_add_u64 v[124:125], v[126:127], 0, v[124:125]
	v_lshlrev_b64 v[122:123], 12, v[122:123]
	v_lshlrev_b64 v[126:127], 12, v[0:1]
	v_lshl_add_u64 v[122:123], s[48:49], 0, v[122:123]
	v_lshl_add_u64 v[126:127], s[94:95], 0, v[126:127]
	v_cndmask_b32_e32 v123, v127, v123, vcc
	v_cndmask_b32_e32 v122, v126, v122, vcc
	v_mul_hi_i32_i24_e32 v127, 0x6000, v117
	v_mul_i32_i24_e32 v126, 0x6000, v117
	v_lshl_add_u64 v[126:127], s[82:83], 0, v[126:127]
	v_lshl_add_u64 v[130:131], v[126:127], 0, v[114:115]
	v_lshl_add_u64 v[132:133], v[124:125], 0, v[114:115]
	v_lshl_add_u64 v[134:135], v[122:123], 0, v[114:115]
	flat_load_dwordx4 v[122:125], v[130:131]
	flat_load_dwordx4 v[126:129], v[132:133]
	s_waitcnt vmcnt(0) lgkmcnt(0)
	v_pk_fma_f32 v[110:111], v[110:111], v[122:123], v[126:127]
	v_pk_fma_f32 v[112:113], v[112:113], v[124:125], v[128:129]
	flat_store_dwordx4 v[134:135], v[110:113]
	flat_load_dwordx4 v[110:113], v[130:131] offset:64
	s_nop 0
	flat_load_dwordx4 v[122:125], v[132:133] offset:64
	s_waitcnt vmcnt(0) lgkmcnt(0)
	v_pk_fma_f32 v[106:107], v[106:107], v[110:111], v[122:123]
	v_pk_fma_f32 v[108:109], v[108:109], v[112:113], v[124:125]
	flat_store_dwordx4 v[134:135], v[106:109] offset:64
	flat_load_dwordx4 v[106:109], v[130:131] offset:128
	s_nop 0
	flat_load_dwordx4 v[110:113], v[132:133] offset:128
	s_waitcnt vmcnt(0) lgkmcnt(0)
	v_pk_fma_f32 v[102:103], v[102:103], v[106:107], v[110:111]
	v_pk_fma_f32 v[104:105], v[104:105], v[108:109], v[112:113]
	flat_store_dwordx4 v[134:135], v[102:105] offset:128
	flat_load_dwordx4 v[102:105], v[130:131] offset:192
	s_nop 0
	flat_load_dwordx4 v[106:109], v[132:133] offset:192
	s_waitcnt vmcnt(0) lgkmcnt(0)
	v_pk_fma_f32 v[98:99], v[98:99], v[102:103], v[106:107]
	v_pk_fma_f32 v[100:101], v[100:101], v[104:105], v[108:109]
	flat_store_dwordx4 v[134:135], v[98:101] offset:192
	s_nop 1
	v_add_u32_e32 v98, 32, v116
	v_min_i32_e32 v0, 0x8000, v98
	v_cmp_gt_i32_e32 vcc, s58, v98
	v_ashrrev_i32_e32 v104, 12, v0
	v_add_u32_e32 v0, 0xffff8020, v116
	v_ashrrev_i32_e32 v99, 31, v98
	v_cndmask_b32_e32 v101, 0, v99, vcc
	v_cndmask_b32_e32 v100, v0, v98, vcc
	v_cndmask_b32_e32 v103, v118, v119, vcc
	v_cndmask_b32_e32 v102, v120, v121, vcc
	v_lshlrev_b64 v[100:101], 12, v[100:101]
	v_lshl_add_u64 v[100:101], v[102:103], 0, v[100:101]
	v_lshlrev_b64 v[98:99], 12, v[98:99]
	v_lshlrev_b64 v[102:103], 12, v[0:1]
	v_lshl_add_u64 v[98:99], s[48:49], 0, v[98:99]
	v_lshl_add_u64 v[102:103], s[94:95], 0, v[102:103]
	v_cndmask_b32_e32 v99, v103, v99, vcc
	v_cndmask_b32_e32 v98, v102, v98, vcc
	v_mul_hi_i32_i24_e32 v103, 0x6000, v104
	v_mul_i32_i24_e32 v102, 0x6000, v104
	v_lshl_add_u64 v[102:103], s[82:83], 0, v[102:103]
	v_lshl_add_u64 v[106:107], v[102:103], 0, v[114:115]
	v_lshl_add_u64 v[108:109], v[100:101], 0, v[114:115]
	v_lshl_add_u64 v[110:111], v[98:99], 0, v[114:115]
	flat_load_dwordx4 v[98:101], v[106:107]
	flat_load_dwordx4 v[102:105], v[108:109]
	s_waitcnt vmcnt(0) lgkmcnt(0)
	v_pk_fma_f32 v[94:95], v[94:95], v[98:99], v[102:103]
	v_pk_fma_f32 v[96:97], v[96:97], v[100:101], v[104:105]
	flat_store_dwordx4 v[110:111], v[94:97]
	flat_load_dwordx4 v[94:97], v[106:107] offset:64
	s_nop 0
	flat_load_dwordx4 v[98:101], v[108:109] offset:64
	s_waitcnt vmcnt(0) lgkmcnt(0)
	v_pk_fma_f32 v[90:91], v[90:91], v[94:95], v[98:99]
	v_pk_fma_f32 v[92:93], v[92:93], v[96:97], v[100:101]
	flat_store_dwordx4 v[110:111], v[90:93] offset:64
	flat_load_dwordx4 v[90:93], v[106:107] offset:128
	s_nop 0
	flat_load_dwordx4 v[94:97], v[108:109] offset:128
	s_waitcnt vmcnt(0) lgkmcnt(0)
; template <int MI, int NI>
; DI void resid_tile(const u16* A, int K, const u16* Bt, const float* gate, const float* xl_in, const float* xc_in, float* xl_out, float* xc_out,
;                    int m0, int n0, char* smem) {
;     ...
; #pragma unroll
;   for (int mi = 0; mi < MI; ++mi) {
;     const int m = m0 + wr * 16 * MI + mi * 16 + lr;
;     const int b9 = m < NTL ? m >> 12 : 8;
;     const float* xi = xrow(xl_in, xc_in, m);
;     float* xo = m < NTL ? xl_out + (size_t)m * D : xc_out + (size_t)(m - NTL) * D;
; #pragma unroll
;     for (int ni = 0; ni < NI; ++ni) {
;       const int n = n0 + wc * 16 * NI + ni * 16 + lq * 4;
;       const float4 g = *(const float4*)(gate + (size_t)b9 * 6144 + n);
;       const float4 xv = *(const float4*)(xi + n);
;       float4 ov;
;       ov.x = xv.x + g.x * acc[mi][ni][0]; ov.y = xv.y + g.y * acc[mi][ni][1]; ov.z = xv.z + g.z * acc[mi][ni][2]; ov.w = xv.w + g.w * acc[mi][ni][3];
;       *(float4*)(xo + n) = ov;
;     }
;     __builtin_amdgcn_sched_barrier(0);
;   }
	v_pk_fma_f32 v[86:87], v[86:87], v[90:91], v[94:95]
	v_pk_fma_f32 v[88:89], v[88:89], v[92:93], v[96:97]
	flat_store_dwordx4 v[110:111], v[86:89] offset:128
	flat_load_dwordx4 v[86:89], v[106:107] offset:192
	s_nop 0
	flat_load_dwordx4 v[90:93], v[108:109] offset:192
	s_waitcnt vmcnt(0) lgkmcnt(0)
	v_pk_fma_f32 v[82:83], v[82:83], v[86:87], v[90:91]
	v_pk_fma_f32 v[84:85], v[84:85], v[88:89], v[92:93]
	flat_store_dwordx4 v[110:111], v[82:85] offset:192
	s_nop 1
	v_add_u32_e32 v82, 48, v116
	v_min_i32_e32 v0, 0x8000, v82
	v_cmp_gt_i32_e32 vcc, s58, v82
	v_ashrrev_i32_e32 v88, 12, v0
	v_add_u32_e32 v0, 0xffff8030, v116
	v_ashrrev_i32_e32 v83, 31, v82
	v_cndmask_b32_e32 v85, 0, v83, vcc
	v_cndmask_b32_e32 v84, v0, v82, vcc
	v_cndmask_b32_e32 v87, v118, v119, vcc
	v_cndmask_b32_e32 v86, v120, v121, vcc
	v_lshlrev_b64 v[84:85], 12, v[84:85]
	v_lshl_add_u64 v[84:85], v[86:87], 0, v[84:85]
	v_lshlrev_b64 v[82:83], 12, v[82:83]
	v_lshlrev_b64 v[86:87], 12, v[0:1]
	v_lshl_add_u64 v[82:83], s[48:49], 0, v[82:83]
	v_lshl_add_u64 v[86:87], s[94:95], 0, v[86:87]
	v_cndmask_b32_e32 v83, v87, v83, vcc
	v_cndmask_b32_e32 v82, v86, v82, vcc
	v_mul_hi_i32_i24_e32 v87, 0x6000, v88
	v_mul_i32_i24_e32 v86, 0x6000, v88
	v_lshl_add_u64 v[86:87], s[82:83], 0, v[86:87]
	v_lshl_add_u64 v[90:91], v[86:87], 0, v[114:115]
	v_lshl_add_u64 v[92:93], v[84:85], 0, v[114:115]
	v_lshl_add_u64 v[94:95], v[82:83], 0, v[114:115]
	flat_load_dwordx4 v[82:85], v[90:91]
	flat_load_dwordx4 v[86:89], v[92:93]
	s_waitcnt vmcnt(0) lgkmcnt(0)
	v_pk_fma_f32 v[74:75], v[74:75], v[82:83], v[86:87]
	v_pk_fma_f32 v[76:77], v[76:77], v[84:85], v[88:89]
	flat_store_dwordx4 v[94:95], v[74:77]
	flat_load_dwordx4 v[74:77], v[90:91] offset:64
	s_nop 0
	flat_load_dwordx4 v[82:85], v[92:93] offset:64
	s_waitcnt vmcnt(0) lgkmcnt(0)
	v_pk_fma_f32 v[74:75], v[78:79], v[74:75], v[82:83]
	v_pk_fma_f32 v[76:77], v[80:81], v[76:77], v[84:85]
	flat_store_dwordx4 v[94:95], v[74:77] offset:64
	flat_load_dwordx4 v[74:77], v[90:91] offset:128
	s_nop 0
	flat_load_dwordx4 v[78:81], v[92:93] offset:128
	s_waitcnt vmcnt(0) lgkmcnt(0)
	v_pk_fma_f32 v[70:71], v[70:71], v[74:75], v[78:79]
	v_pk_fma_f32 v[72:73], v[72:73], v[76:77], v[80:81]
	flat_store_dwordx4 v[94:95], v[70:73] offset:128
	flat_load_dwordx4 v[70:73], v[90:91] offset:192
	s_nop 0
	flat_load_dwordx4 v[74:77], v[92:93] offset:192
	s_waitcnt vmcnt(0) lgkmcnt(0)
	v_pk_fma_f32 v[66:67], v[66:67], v[70:71], v[74:75]
	v_pk_fma_f32 v[68:69], v[68:69], v[72:73], v[76:77]
	flat_store_dwordx4 v[94:95], v[66:69] offset:192
	s_nop 1
	v_add_u32_e32 v66, 64, v116
	v_min_i32_e32 v0, 0x8000, v66
	v_cmp_gt_i32_e32 vcc, s58, v66
	v_ashrrev_i32_e32 v72, 12, v0
	v_add_u32_e32 v0, 0xffff8040, v116
	v_ashrrev_i32_e32 v67, 31, v66
	v_cndmask_b32_e32 v69, 0, v67, vcc
	v_cndmask_b32_e32 v68, v0, v66, vcc
	v_cndmask_b32_e32 v71, v118, v119, vcc
	v_cndmask_b32_e32 v70, v120, v121, vcc
	v_lshlrev_b64 v[68:69], 12, v[68:69]
	v_lshl_add_u64 v[68:69], v[70:71], 0, v[68:69]
	v_lshlrev_b64 v[66:67], 12, v[66:67]
	v_lshlrev_b64 v[70:71], 12, v[0:1]
	v_lshl_add_u64 v[66:67], s[48:49], 0, v[66:67]
	v_lshl_add_u64 v[70:71], s[94:95], 0, v[70:71]
	v_cndmask_b32_e32 v67, v71, v67, vcc
	v_cndmask_b32_e32 v66, v70, v66, vcc
	v_mul_hi_i32_i24_e32 v71, 0x6000, v72
	v_mul_i32_i24_e32 v70, 0x6000, v72
	v_lshl_add_u64 v[70:71], s[82:83], 0, v[70:71]
	v_lshl_add_u64 v[74:75], v[70:71], 0, v[114:115]
	v_lshl_add_u64 v[76:77], v[68:69], 0, v[114:115]
	v_lshl_add_u64 v[78:79], v[66:67], 0, v[114:115]
	flat_load_dwordx4 v[66:69], v[74:75]
	flat_load_dwordx4 v[70:73], v[76:77]
	s_waitcnt vmcnt(0) lgkmcnt(0)
	v_pk_fma_f32 v[62:63], v[62:63], v[66:67], v[70:71]
	v_pk_fma_f32 v[64:65], v[64:65], v[68:69], v[72:73]
	flat_store_dwordx4 v[78:79], v[62:65]
	flat_load_dwordx4 v[62:65], v[74:75] offset:64
	s_nop 0
	flat_load_dwordx4 v[66:69], v[76:77] offset:64
	s_waitcnt vmcnt(0) lgkmcnt(0)
	v_pk_fma_f32 v[58:59], v[58:59], v[62:63], v[66:67]
	v_pk_fma_f32 v[60:61], v[60:61], v[64:65], v[68:69]
	flat_store_dwordx4 v[78:79], v[58:61] offset:64
	flat_load_dwordx4 v[58:61], v[74:75] offset:128
	s_nop 0
	flat_load_dwordx4 v[62:65], v[76:77] offset:128
	s_waitcnt vmcnt(0) lgkmcnt(0)
	v_pk_fma_f32 v[54:55], v[54:55], v[58:59], v[62:63]
	v_pk_fma_f32 v[56:57], v[56:57], v[60:61], v[64:65]
	flat_store_dwordx4 v[78:79], v[54:57] offset:128
	flat_load_dwordx4 v[54:57], v[74:75] offset:192
	s_nop 0
	flat_load_dwordx4 v[58:61], v[76:77] offset:192
	s_waitcnt vmcnt(0) lgkmcnt(0)
	v_pk_fma_f32 v[50:51], v[50:51], v[54:55], v[58:59]
	v_pk_fma_f32 v[52:53], v[52:53], v[56:57], v[60:61]
	flat_store_dwordx4 v[78:79], v[50:53] offset:192
	s_nop 1
	v_add_u32_e32 v50, 0x50, v116
	v_min_i32_e32 v0, 0x8000, v50
	v_cmp_gt_i32_e32 vcc, s58, v50
	v_ashrrev_i32_e32 v56, 12, v0
	v_add_u32_e32 v0, 0xffff8050, v116
	v_ashrrev_i32_e32 v51, 31, v50
	v_cndmask_b32_e32 v53, 0, v51, vcc
	v_cndmask_b32_e32 v52, v0, v50, vcc
	v_cndmask_b32_e32 v55, v118, v119, vcc
	v_cndmask_b32_e32 v54, v120, v121, vcc
	v_lshlrev_b64 v[52:53], 12, v[52:53]
	v_lshl_add_u64 v[52:53], v[54:55], 0, v[52:53]
	v_lshlrev_b64 v[50:51], 12, v[50:51]
	v_lshlrev_b64 v[54:55], 12, v[0:1]
	v_lshl_add_u64 v[50:51], s[48:49], 0, v[50:51]
	v_lshl_add_u64 v[54:55], s[94:95], 0, v[54:55]
	v_cndmask_b32_e32 v51, v55, v51, vcc
	v_cndmask_b32_e32 v50, v54, v50, vcc
	v_mul_hi_i32_i24_e32 v55, 0x6000, v56
	v_mul_i32_i24_e32 v54, 0x6000, v56
	v_lshl_add_u64 v[54:55], s[82:83], 0, v[54:55]
	v_lshl_add_u64 v[58:59], v[54:55], 0, v[114:115]
	v_lshl_add_u64 v[60:61], v[52:53], 0, v[114:115]
	v_lshl_add_u64 v[62:63], v[50:51], 0, v[114:115]
	flat_load_dwordx4 v[50:53], v[58:59]
	flat_load_dwordx4 v[54:57], v[60:61]
	s_waitcnt vmcnt(0) lgkmcnt(0)
; #define LAUNDER_IDS const int tid__ = launder_v((int)threadIdx.x); const int blk__ = launder_s((int)blockIdx.x); (void)tid__; (void)blk__;
; template <int MI, int NI>
; DI void resid_tile(const u16* A, int K, const u16* Bt, const float* gate, const float* xl_in, const float* xc_in, float* xl_out, float* xc_out,
;                    int m0, int n0, char* smem) {
;     ...
; #pragma unroll
;   for (int mi = 0; mi < MI; ++mi) {
;     const int m = m0 + wr * 16 * MI + mi * 16 + lr;
;     const int b9 = m < NTL ? m >> 12 : 8;
;     const float* xi = xrow(xl_in, xc_in, m);
;     float* xo = m < NTL ? xl_out + (size_t)m * D : xc_out + (size_t)(m - NTL) * D;
; #pragma unroll
;     for (int ni = 0; ni < NI; ++ni) {
;       const int n = n0 + wc * 16 * NI + ni * 16 + lq * 4;
;       const float4 g = *(const float4*)(gate + (size_t)b9 * 6144 + n);
;       const float4 xv = *(const float4*)(xi + n);
;       float4 ov;
;       ov.x = xv.x + g.x * acc[mi][ni][0]; ov.y = xv.y + g.y * acc[mi][ni][1]; ov.z = xv.z + g.z * acc[mi][ni][2]; ov.w = xv.w + g.w * acc[mi][ni][3];
;       *(float4*)(xo + n) = ov;
;     }
;     __builtin_amdgcn_sched_barrier(0);
;   }
;   EPI_END
; }
; DI void phase_resid(const Params& p, const u16* A, int K, const u16* Bt, const float* gate  ,
;                     const float* xl_in, const float* xc_in, float* xl_out, float* xc_out, int Mout, char* smem) {
;   LAUNDER_IDS
;   for (int it = 0;; ++it) {
;     int tm, tn;
;     if (!tile_map(it, NTL / 256, 8, blk__, gridDim.x, tm, tn)) break;
;     resid_tile<8, 4>(A, K, Bt, gate, xl_in, xc_in, xl_out, xc_out, tm * 256, tn * 128, smem);
	v_pk_fma_f32 v[46:47], v[46:47], v[50:51], v[54:55]
	v_pk_fma_f32 v[48:49], v[48:49], v[52:53], v[56:57]
	flat_store_dwordx4 v[62:63], v[46:49]
	flat_load_dwordx4 v[46:49], v[58:59] offset:64
	s_nop 0
	flat_load_dwordx4 v[50:53], v[60:61] offset:64
	s_waitcnt vmcnt(0) lgkmcnt(0)
	v_pk_fma_f32 v[42:43], v[42:43], v[46:47], v[50:51]
	v_pk_fma_f32 v[44:45], v[44:45], v[48:49], v[52:53]
	flat_store_dwordx4 v[62:63], v[42:45] offset:64
	flat_load_dwordx4 v[42:45], v[58:59] offset:128
	s_nop 0
	flat_load_dwordx4 v[46:49], v[60:61] offset:128
	s_waitcnt vmcnt(0) lgkmcnt(0)
	v_pk_fma_f32 v[38:39], v[38:39], v[42:43], v[46:47]
	v_pk_fma_f32 v[40:41], v[40:41], v[44:45], v[48:49]
	flat_store_dwordx4 v[62:63], v[38:41] offset:128
	flat_load_dwordx4 v[38:41], v[58:59] offset:192
	s_nop 0
	flat_load_dwordx4 v[42:45], v[60:61] offset:192
	s_waitcnt vmcnt(0) lgkmcnt(0)
	v_pk_fma_f32 v[34:35], v[34:35], v[38:39], v[42:43]
	v_pk_fma_f32 v[36:37], v[36:37], v[40:41], v[44:45]
	flat_store_dwordx4 v[62:63], v[34:37] offset:192
	s_nop 1
	v_add_u32_e32 v34, 0x60, v116
	v_min_i32_e32 v0, 0x8000, v34
	v_cmp_gt_i32_e32 vcc, s58, v34
	v_ashrrev_i32_e32 v40, 12, v0
	v_add_u32_e32 v0, 0xffff8060, v116
	v_ashrrev_i32_e32 v35, 31, v34
	v_cndmask_b32_e32 v37, 0, v35, vcc
	v_cndmask_b32_e32 v36, v0, v34, vcc
	v_cndmask_b32_e32 v39, v118, v119, vcc
	v_cndmask_b32_e32 v38, v120, v121, vcc
	v_lshlrev_b64 v[36:37], 12, v[36:37]
	v_lshl_add_u64 v[36:37], v[38:39], 0, v[36:37]
	v_lshlrev_b64 v[34:35], 12, v[34:35]
	v_lshlrev_b64 v[38:39], 12, v[0:1]
	v_lshl_add_u64 v[34:35], s[48:49], 0, v[34:35]
	v_lshl_add_u64 v[38:39], s[94:95], 0, v[38:39]
	v_cndmask_b32_e32 v35, v39, v35, vcc
	v_cndmask_b32_e32 v34, v38, v34, vcc
	v_mul_hi_i32_i24_e32 v39, 0x6000, v40
	v_mul_i32_i24_e32 v38, 0x6000, v40
	v_lshl_add_u64 v[38:39], s[82:83], 0, v[38:39]
	v_lshl_add_u64 v[42:43], v[38:39], 0, v[114:115]
	v_lshl_add_u64 v[44:45], v[36:37], 0, v[114:115]
	v_lshl_add_u64 v[46:47], v[34:35], 0, v[114:115]
	flat_load_dwordx4 v[34:37], v[42:43]
	flat_load_dwordx4 v[38:41], v[44:45]
	s_waitcnt vmcnt(0) lgkmcnt(0)
	v_pk_fma_f32 v[30:31], v[30:31], v[34:35], v[38:39]
	v_pk_fma_f32 v[32:33], v[32:33], v[36:37], v[40:41]
	flat_store_dwordx4 v[46:47], v[30:33]
	flat_load_dwordx4 v[30:33], v[42:43] offset:64
	s_nop 0
	flat_load_dwordx4 v[34:37], v[44:45] offset:64
	s_waitcnt vmcnt(0) lgkmcnt(0)
	v_pk_fma_f32 v[26:27], v[26:27], v[30:31], v[34:35]
	v_pk_fma_f32 v[28:29], v[28:29], v[32:33], v[36:37]
	flat_store_dwordx4 v[46:47], v[26:29] offset:64
	flat_load_dwordx4 v[26:29], v[42:43] offset:128
	s_nop 0
	flat_load_dwordx4 v[30:33], v[44:45] offset:128
	s_waitcnt vmcnt(0) lgkmcnt(0)
	v_pk_fma_f32 v[22:23], v[22:23], v[26:27], v[30:31]
	v_pk_fma_f32 v[24:25], v[24:25], v[28:29], v[32:33]
	flat_store_dwordx4 v[46:47], v[22:25] offset:128
	flat_load_dwordx4 v[22:25], v[42:43] offset:192
	s_nop 0
	flat_load_dwordx4 v[26:29], v[44:45] offset:192
	s_waitcnt vmcnt(0) lgkmcnt(0)
	v_pk_fma_f32 v[18:19], v[18:19], v[22:23], v[26:27]
	v_pk_fma_f32 v[20:21], v[20:21], v[24:25], v[28:29]
	flat_store_dwordx4 v[46:47], v[18:21] offset:192
	s_nop 1
	v_add_u32_e32 v18, 0x70, v116
	v_min_i32_e32 v0, 0x8000, v18
	v_cmp_gt_i32_e32 vcc, s58, v18
	v_ashrrev_i32_e32 v24, 12, v0
	v_add_u32_e32 v0, 0xffff8070, v116
	v_ashrrev_i32_e32 v19, 31, v18
	v_cndmask_b32_e32 v21, 0, v19, vcc
	v_cndmask_b32_e32 v20, v0, v18, vcc
	v_cndmask_b32_e32 v23, v118, v119, vcc
	v_cndmask_b32_e32 v22, v120, v121, vcc
	v_lshlrev_b64 v[20:21], 12, v[20:21]
	v_lshl_add_u64 v[20:21], v[22:23], 0, v[20:21]
	v_lshlrev_b64 v[18:19], 12, v[18:19]
	v_lshlrev_b64 v[22:23], 12, v[0:1]
	v_lshl_add_u64 v[18:19], s[48:49], 0, v[18:19]
	v_lshl_add_u64 v[22:23], s[94:95], 0, v[22:23]
	v_cndmask_b32_e32 v19, v23, v19, vcc
	v_cndmask_b32_e32 v18, v22, v18, vcc
	v_mul_hi_i32_i24_e32 v23, 0x6000, v24
	v_mul_i32_i24_e32 v22, 0x6000, v24
	v_lshl_add_u64 v[22:23], s[82:83], 0, v[22:23]
	v_lshl_add_u64 v[26:27], v[22:23], 0, v[114:115]
	v_lshl_add_u64 v[28:29], v[20:21], 0, v[114:115]
	v_lshl_add_u64 v[30:31], v[18:19], 0, v[114:115]
	flat_load_dwordx4 v[18:21], v[26:27]
	flat_load_dwordx4 v[22:25], v[28:29]
	s_waitcnt vmcnt(0) lgkmcnt(0)
	v_pk_fma_f32 v[14:15], v[14:15], v[18:19], v[22:23]
	v_pk_fma_f32 v[16:17], v[16:17], v[20:21], v[24:25]
	flat_store_dwordx4 v[30:31], v[14:17]
	flat_load_dwordx4 v[14:17], v[26:27] offset:64
	s_nop 0
	flat_load_dwordx4 v[18:21], v[28:29] offset:64
	s_waitcnt vmcnt(0) lgkmcnt(0)
	v_pk_fma_f32 v[2:3], v[2:3], v[14:15], v[18:19]
	v_pk_fma_f32 v[4:5], v[4:5], v[16:17], v[20:21]
	flat_store_dwordx4 v[30:31], v[2:5] offset:64
	flat_load_dwordx4 v[2:5], v[26:27] offset:128
	s_nop 0
	flat_load_dwordx4 v[14:17], v[28:29] offset:128
	s_waitcnt vmcnt(0) lgkmcnt(0)
	v_pk_fma_f32 v[2:3], v[6:7], v[2:3], v[14:15]
	v_pk_fma_f32 v[4:5], v[8:9], v[4:5], v[16:17]
	flat_store_dwordx4 v[30:31], v[2:5] offset:128
	flat_load_dwordx4 v[2:5], v[26:27] offset:192
	s_nop 0
	flat_load_dwordx4 v[6:9], v[28:29] offset:192
	s_waitcnt vmcnt(0) lgkmcnt(0)
	v_pk_fma_f32 v[2:3], v[10:11], v[2:3], v[6:7]
	v_pk_fma_f32 v[4:5], v[12:13], v[4:5], v[8:9]
	flat_store_dwordx4 v[30:31], v[2:5] offset:192
	s_add_i32 s7, s7, 1
	s_mul_i32 s0, s7, s39
	s_add_i32 s0, s0, s5
	s_cmpk_gt_i32 s0, 0x7f
	s_cbranch_scc0 .LBB0_961

; template <int MI, int NI>
; DI void gemm256(f32x4 (&acc)[MI][NI], const u16* __restrict__ A, int lda, const u16* __restrict__ Bt, int ldb, int K, int m0, int n0, char* smem) {
;     ...
;   const int srow = lane >> 2, scol = ((lane & 3) ^ ((lane >> 5) << 1)) * 8;
;   const u16* Ag = A + (size_t)(m0 + wave * NAW * 16 + srow) * lda + scol;
;   const u16* Bg = Bt + (size_t)(n0 + wave * NBW * 16 + srow) * ldb + scol;
;   char* la = smem + (wave * NAW) * 1024 + lane * 16;
;   char* lb = smem + ABYTES + (wave * NBW) * 1024 + lane * 16;
;     ...
;   const int nk = K >> 5;
;   G256_ISSUE(0, 0);
;   if (nk > 1) G256_ISSUE(1, 32);
;   const int foff = lr * 64 + ((lq ^ ((lr >> 3) << 1)) * 16);
;   int st = 0;
;   for (int kt = 0; kt < nk; ++kt) {
;     if (kt + 1 < nk) asm volatile("s_waitcnt vmcnt(%0) lgkmcnt(0)" :: "n"(LPS) : "memory");
;     else asm volatile("s_waitcnt vmcnt(0) lgkmcnt(0)" ::: "memory");
;     __builtin_amdgcn_s_barrier();
;     __builtin_amdgcn_s_setprio(1);
;     const char* sb = smem + st * STAGE + foff;
;     bf16x8 af[MI], bfr[NI];
; #pragma unroll
;     for (int mi = 0; mi < MI; ++mi) af[mi] = *(const bf16x8*)(sb + (wr * MI + mi) * 1024);
; #pragma unroll
;     for (int ni = 0; ni < NI; ++ni) bfr[ni] = *(const bf16x8*)(sb + ABYTES + (wc * NI + ni) * 1024);
;     __builtin_amdgcn_sched_barrier(0x0);
;     if (kt + 2 < nk) { const int s2 = st >= 1 ? st - 1 : 2; G256_ISSUE(s2, (kt + 2) * 32); }
;     __builtin_amdgcn_s_setprio(0);
; #pragma unroll
;     for (int mi = 0; mi < MI; ++mi)
; #pragma unroll
;       for (int ni = 0; ni < NI; ++ni)
;         acc[mi][ni] = __builtin_amdgcn_mfma_f32_16x16x32_bf16(bfr[ni], af[mi], acc[mi][ni], 0, 0, 0);
;     st = st == 2 ? 0 : st + 1;
;   }
; DI void phase_resid(const Params& p, const u16* A, int K, const u16* Bt, const float* gate  ,
;                     const float* xl_in, const float* xc_in, float* xl_out, float* xc_out, int Mout, char* smem) {
;     ...
;     for (int t = blk__; t < (NTC / 64) * 16; t += gridDim.x) {
;       const int tm = t >> 4, tn = t & 15;
;       resid_tile<2, 2>(A, K, Bt, gate, xl_in, xc_in, xl_out, xc_out, NTL + tm * 64, tn * 64, smem);
.LBB0_966:
	s_lshl_b32 s0, s4, 2
	s_and_b32 s8, s0, 0xffffffc0
	s_lshl_b32 s0, s4, 6
	s_and_b32 s7, s0, 0x3c0
	v_mov_b32_e32 v22, v163
	s_mov_b32 s0, s2
	s_waitcnt vmcnt(0)
	v_mov_b32_e32 v6, v163
	s_add_i32 s8, s8, 0x8000
	v_ashrrev_i32_e32 v8, 6, v6
	v_bfe_u32 v9, v6, 2, 4
	v_lshlrev_b32_e32 v10, 4, v8
	s_mov_b32 s0, s2
	v_and_b32_e32 v0, 3, v6
	v_lshrrev_b32_e32 v2, 4, v6
	v_or_b32_e32 v4, v9, v10
	v_bitop3_b32 v0, v2, v0, 2 bitop3:0x6c
	v_add_u32_e32 v2, s8, v4
	v_add_u32_e32 v4, s7, v4
	v_and_b32_e32 v7, 63, v6
	v_ashrrev_i32_e32 v3, 31, v2
	v_ashrrev_i32_e32 v5, 31, v4
	v_readlane_b32 s0, v254, 54
	v_lshlrev_b32_e32 v11, 10, v8
	v_lshlrev_b64 v[2:3], 13, v[2:3]
	v_lshlrev_b64 v[4:5], 13, v[4:5]
	v_readlane_b32 s1, v254, 55
	v_lshl_or_b32 v27, v7, 4, v11
	v_lshl_add_u64 v[2:3], s[60:61], 0, v[2:3]
	v_lshlrev_b32_e32 v0, 4, v0
	v_lshl_add_u64 v[4:5], s[0:1], 0, v[4:5]
	v_add_u32_e32 v7, 0x1000, v27
	v_readfirstlane_b32 s0, v27
	v_lshl_add_u64 v[2:3], v[2:3], 0, v[0:1]
	v_bfe_i32 v199, v163, 2, 1
	v_and_b32_e32 v198, 0xffffe040, v199
	v_lshl_add_u64 v[2:3], v[2:3], 0, v[198:199]
	s_mov_b32 m0, s0
	v_readfirstlane_b32 s0, v7
	v_add_u32_e32 v7, 0x2000, v27
	v_lshl_add_u64 v[4:5], v[4:5], 0, v[0:1]
	v_bfe_i32 v199, v163, 2, 1
	v_and_b32_e32 v198, 0xffffe040, v199
	v_lshl_add_u64 v[4:5], v[4:5], 0, v[198:199]
	global_load_lds_dwordx4 v[2:3], off
	s_mov_b32 m0, s0
	v_readfirstlane_b32 s0, v7
	global_load_lds_dwordx4 v[4:5], off
	s_mov_b64 s[98:99], 0x80
	v_lshl_add_u64 v[2:3], v[2:3], 0, s[98:99]
	s_mov_b32 m0, s0
	s_and_b32 s1, s6, 0x3c0
	global_load_lds_dwordx4 v[2:3], off
	s_mov_b64 s[98:99], 0x80
	v_lshl_add_u64 v[2:3], v[4:5], 0, s[98:99]
	v_add_u32_e32 v4, 0x3000, v27
	s_waitcnt lgkmcnt(0)
	v_and_b32_e32 v26, 0xfffff800, v11
	v_readfirstlane_b32 s0, v4
	s_mov_b32 m0, s0
	v_and_b32_e32 v4, 48, v6
	global_load_lds_dwordx4 v[2:3], off
	v_lshlrev_b32_e32 v3, 2, v6
	v_lshlrev_b32_e32 v2, 6, v6
	v_bitop3_b32 v3, v3, v4, 32 bitop3:0x6c
	s_and_b32 s0, s5, 0xffffffc0
	v_and_or_b32 v24, v2, s59, v3
	v_lshlrev_b32_e32 v2, 11, v8
	v_and_b32_e32 v23, 0x800, v2
	v_or_b32_e32 v2, s0, v9
	v_add3_u32 v2, v2, v10, s58
	v_ashrrev_i32_e32 v3, 31, v2
	v_lshlrev_b64 v[2:3], 13, v[2:3]
	v_or_b32_e32 v2, v2, v0
	v_lshl_add_u64 v[18:19], s[62:63], 0, v[2:3]
	v_bfe_i32 v199, v163, 2, 1
	v_and_b32_e32 v198, 0xffffe040, v199
	v_lshl_add_u64 v[18:19], v[18:19], 0, v[198:199]
	v_or_b32_e32 v2, s1, v9
	v_add_u32_e32 v2, v2, v10
	v_ashrrev_i32_e32 v3, 31, v2
	v_lshlrev_b64 v[2:3], 13, v[2:3]
	v_readlane_b32 s0, v254, 52
	v_or_b32_e32 v2, v2, v0
	v_readlane_b32 s1, v254, 53
	v_mov_b32_e32 v6, 0
	v_or_b32_e32 v25, 0x400, v11
	v_lshl_add_u64 v[20:21], s[0:1], 0, v[2:3]
	v_bfe_i32 v199, v163, 2, 1
	v_and_b32_e32 v198, 0xffffe040, v199
	v_lshl_add_u64 v[20:21], v[20:21], 0, v[198:199]
	s_mov_b32 s9, 0
	s_mov_b64 s[0:1], 0
	v_mov_b32_e32 v7, v6
	v_mov_b32_e32 v8, v6
	v_mov_b32_e32 v9, v6
	v_mov_b32_e32 v2, v6
	v_mov_b32_e32 v3, v6
	v_mov_b32_e32 v4, v6
	v_mov_b32_e32 v5, v6
	v_mov_b32_e32 v10, v6
	v_mov_b32_e32 v11, v6
	v_mov_b32_e32 v12, v6
	v_mov_b32_e32 v13, v6
	v_mov_b32_e32 v14, v6
	v_mov_b32_e32 v15, v6
	v_mov_b32_e32 v16, v6
	v_mov_b32_e32 v17, v6
.LBB0_967:
	s_waitcnt vmcnt(2) lgkmcnt(0)
	s_barrier
	s_setprio 1
	s_lshl_b32 s10, s9, 13
	v_or_b32_e32 v0, s10, v24
	v_add_u32_e32 v28, v0, v26
	v_add_u32_e32 v32, v0, v25
	v_add_u32_e32 v0, v0, v23
	s_waitcnt vmcnt(0)
	ds_read_b128 v[28:31], v28
	ds_read_b128 v[32:35], v32
	ds_read_b128 v[36:39], v0 offset:4096
	ds_read_b128 v[40:43], v0 offset:5120
	s_addk_i32 s10, 0xe000
	s_cmp_gt_i32 s9, 0
	s_cselect_b32 s10, s10, 0x4000
	v_add_u32_e32 v0, s10, v27
	v_add_u32_e32 v52, 0x1000, v0
	v_lshl_add_u64 v[48:49], v[18:19], 0, s[0:1]
	v_lshl_add_u64 v[48:49], v[48:49], 0, s[0:1]
	v_readfirstlane_b32 s10, v0
	v_lshl_add_u64 v[44:45], v[20:21], 0, s[0:1]
	v_lshl_add_u64 v[44:45], v[44:45], 0, s[0:1]
	s_mov_b64 s[98:99], 0x47e1100
	v_lshl_add_u64 v[50:51], v[48:49], 0, s[98:99]
	s_mov_b32 m0, s10
	v_readfirstlane_b32 s10, v52
	s_mov_b64 s[98:99], 0x2061100
	v_lshl_add_u64 v[46:47], v[44:45], 0, s[98:99]
	global_load_lds_dwordx4 v[50:51], off
	s_mov_b32 m0, s10
	s_nop 0
	global_load_lds_dwordx4 v[46:47], off
	s_setprio 0
	s_waitcnt lgkmcnt(0)
	v_mfma_f32_16x16x32_bf16 v[14:17], v[36:39], v[28:31], v[14:17]
	s_add_i32 s10, s9, 1
	s_waitcnt vmcnt(2) lgkmcnt(0)
	s_cmp_lg_u32 s9, 2
	v_mfma_f32_16x16x32_bf16 v[10:13], v[40:43], v[28:31], v[10:13]
	s_cselect_b32 s9, s10, 0
	s_barrier
	v_mfma_f32_16x16x32_bf16 v[2:5], v[36:39], v[32:35], v[2:5]
	v_mfma_f32_16x16x32_bf16 v[6:9], v[40:43], v[32:35], v[6:9]
	s_setprio 1
	s_lshl_b32 s10, s9, 13
	v_or_b32_e32 v0, s10, v24
	v_add_u32_e32 v28, v0, v26
	v_add_u32_e32 v32, v0, v25
	v_add_u32_e32 v0, v0, v23
	s_waitcnt vmcnt(0)
	ds_read_b128 v[28:31], v28
	ds_read_b128 v[32:35], v32
	ds_read_b128 v[36:39], v0 offset:4096
	ds_read_b128 v[40:43], v0 offset:5120
	s_addk_i32 s10, 0xe000
	s_cmp_gt_i32 s9, 0
	s_cselect_b32 s10, s10, 0x4000
	v_add_u32_e32 v0, s10, v27
	s_mov_b64 s[10:11], 0x20610c0
	v_add_u32_e32 v52, 0x1000, v0
	s_mov_b64 s[98:99], 0x2061180
	v_lshl_add_u64 v[46:47], v[44:45], 0, s[98:99]
	v_readfirstlane_b32 s10, v0
	s_mov_b64 s[98:99], 0x47e1180
	v_lshl_add_u64 v[50:51], v[48:49], 0, s[98:99]
	s_mov_b32 m0, s10
	v_readfirstlane_b32 s10, v52
	global_load_lds_dwordx4 v[50:51], off
	s_mov_b32 m0, s10
	s_nop 0
	global_load_lds_dwordx4 v[46:47], off
	s_setprio 0
	s_waitcnt lgkmcnt(0)
	v_mfma_f32_16x16x32_bf16 v[14:17], v[36:39], v[28:31], v[14:17]
	s_add_i32 s10, s9, 1
	s_waitcnt vmcnt(2) lgkmcnt(0)
	s_cmp_lg_u32 s9, 2
	v_mfma_f32_16x16x32_bf16 v[10:13], v[40:43], v[28:31], v[10:13]
	s_cselect_b32 s9, s10, 0
	s_barrier
; template <int MI, int NI>
; DI void gemm256(f32x4 (&acc)[MI][NI], const u16* __restrict__ A, int lda, const u16* __restrict__ Bt, int ldb, int K, int m0, int n0, char* smem) {
;     ...
;   for (int kt = 0; kt < nk; ++kt) {
;     if (kt + 1 < nk) asm volatile("s_waitcnt vmcnt(%0) lgkmcnt(0)" :: "n"(LPS) : "memory");
;     else asm volatile("s_waitcnt vmcnt(0) lgkmcnt(0)" ::: "memory");
;     __builtin_amdgcn_s_barrier();
;     __builtin_amdgcn_s_setprio(1);
;     const char* sb = smem + st * STAGE + foff;
;     bf16x8 af[MI], bfr[NI];
; #pragma unroll
;     for (int mi = 0; mi < MI; ++mi) af[mi] = *(const bf16x8*)(sb + (wr * MI + mi) * 1024);
; #pragma unroll
;     for (int ni = 0; ni < NI; ++ni) bfr[ni] = *(const bf16x8*)(sb + ABYTES + (wc * NI + ni) * 1024);
;     __builtin_amdgcn_sched_barrier(0x0);
;     if (kt + 2 < nk) { const int s2 = st >= 1 ? st - 1 : 2; G256_ISSUE(s2, (kt + 2) * 32); }
;     __builtin_amdgcn_s_setprio(0);
; #pragma unroll
;     for (int mi = 0; mi < MI; ++mi)
; #pragma unroll
;       for (int ni = 0; ni < NI; ++ni)
;         acc[mi][ni] = __builtin_amdgcn_mfma_f32_16x16x32_bf16(bfr[ni], af[mi], acc[mi][ni], 0, 0, 0);
;     st = st == 2 ? 0 : st + 1;
;   }
;   asm volatile("s_waitcnt lgkmcnt(0)" ::: "memory");
;   __builtin_amdgcn_s_barrier();
; template <int MI, int NI>
; DI void resid_tile(const u16* A, int K, const u16* Bt, const float* gate, const float* xl_in, const float* xc_in, float* xl_out, float* xc_out,
;                    int m0, int n0, char* smem) {
;     ...
;   EPI_BEGIN
; #pragma unroll
;   for (int mi = 0; mi < MI; ++mi) {
;     const int m = m0 + wr * 16 * MI + mi * 16 + lr;
;     const int b9 = m < NTL ? m >> 12 : 8;
;     const float* xi = xrow(xl_in, xc_in, m);
;     float* xo = m < NTL ? xl_out + (size_t)m * D : xc_out + (size_t)(m - NTL) * D;
; #pragma unroll
;     for (int ni = 0; ni < NI; ++ni) {
;       const int n = n0 + wc * 16 * NI + ni * 16 + lq * 4;
;       const float4 g = *(const float4*)(gate + (size_t)b9 * 6144 + n);
;       const float4 xv = *(const float4*)(xi + n);
;       float4 ov;
;       ov.x = xv.x + g.x * acc[mi][ni][0]; ov.y = xv.y + g.y * acc[mi][ni][1]; ov.z = xv.z + g.z * acc[mi][ni][2]; ov.w = xv.w + g.w * acc[mi][ni][3];
;       *(float4*)(xo + n) = ov;
;     }
;     __builtin_amdgcn_sched_barrier(0);
;   }
;   EPI_END
	v_mfma_f32_16x16x32_bf16 v[2:5], v[36:39], v[32:35], v[2:5]
	v_mfma_f32_16x16x32_bf16 v[6:9], v[40:43], v[32:35], v[6:9]
	s_setprio 1
	s_lshl_b32 s10, s9, 13
	v_or_b32_e32 v0, s10, v24
	v_add_u32_e32 v28, v0, v26
	v_add_u32_e32 v32, v0, v25
	v_add_u32_e32 v0, v0, v23
	s_waitcnt vmcnt(0)
	ds_read_b128 v[28:31], v28
	ds_read_b128 v[32:35], v32
	ds_read_b128 v[36:39], v0 offset:4096
	ds_read_b128 v[40:43], v0 offset:5120
	s_addk_i32 s10, 0xe000
	s_cmp_gt_i32 s9, 0
	s_cselect_b32 s10, s10, 0x4000
	v_add_u32_e32 v0, s10, v27
	s_mov_b64 s[10:11], 0x2061100
	v_add_u32_e32 v50, 0x1000, v0
	s_mov_b64 s[98:99], 0x2061200
	v_lshl_add_u64 v[44:45], v[44:45], 0, s[98:99]
	v_readfirstlane_b32 s10, v0
	s_mov_b64 s[98:99], 0x47e1200
	v_lshl_add_u64 v[46:47], v[48:49], 0, s[98:99]
	s_mov_b32 m0, s10
	v_readfirstlane_b32 s10, v50
	global_load_lds_dwordx4 v[46:47], off
	s_mov_b32 m0, s10
	s_nop 0
	global_load_lds_dwordx4 v[44:45], off
	s_setprio 0
	s_add_i32 s10, s9, 1
	s_waitcnt lgkmcnt(0)
	v_mfma_f32_16x16x32_bf16 v[14:17], v[36:39], v[28:31], v[14:17]
	s_cmp_lg_u32 s9, 2
	s_cselect_b32 s9, s10, 0
	s_add_u32 s0, s0, 0xc0
	v_mfma_f32_16x16x32_bf16 v[10:13], v[40:43], v[28:31], v[10:13]
	s_addc_u32 s1, s1, 0
	s_cmpk_eq_i32 s0, 0x1f80
	v_mfma_f32_16x16x32_bf16 v[2:5], v[36:39], v[32:35], v[2:5]
	v_mfma_f32_16x16x32_bf16 v[6:9], v[40:43], v[32:35], v[6:9]
	s_cbranch_scc0 .LBB0_967
	s_waitcnt vmcnt(2) lgkmcnt(0)
	s_barrier
	s_setprio 1
	s_lshl_b32 s0, s9, 13
	v_or_b32_e32 v0, s0, v24
	v_add_u32_e32 v18, v0, v26
	v_add_u32_e32 v27, v0, v25
	v_add_u32_e32 v0, v0, v23
	s_waitcnt vmcnt(0)
	ds_read_b128 v[18:21], v18
	ds_read_b128 v[28:31], v27
	ds_read_b128 v[32:35], v0 offset:4096
	ds_read_b128 v[36:39], v0 offset:5120
	v_bfe_u32 v0, v22, 6, 1
	s_setprio 0
	s_waitcnt vmcnt(0) lgkmcnt(0)
	s_waitcnt lgkmcnt(1)
	v_mfma_f32_16x16x32_bf16 v[14:17], v[32:35], v[18:21], v[14:17]
	v_ashrrev_i32_e32 v40, 7, v22
	v_and_b32_e32 v41, 15, v22
	v_bfe_u32 v22, v22, 4, 2
	s_waitcnt lgkmcnt(0)
	v_mfma_f32_16x16x32_bf16 v[10:13], v[36:39], v[18:21], v[10:13]
	s_barrier
	v_mfma_f32_16x16x32_bf16 v[2:5], v[32:35], v[28:31], v[2:5]
	v_mfma_f32_16x16x32_bf16 v[18:21], v[36:39], v[28:31], v[6:9]
	s_setprio 1
	s_addk_i32 s0, 0x2000
	s_cmp_lg_u32 s9, 2
	s_cselect_b32 s0, s0, 0
	v_or_b32_e32 v28, s0, v24
	v_add_u32_e32 v6, v28, v26
	v_add_u32_e32 v24, v28, v25
	v_add_u32_e32 v23, v28, v23
	ds_read_b128 v[6:9], v6
	ds_read_b128 v[24:27], v24
	ds_read_b128 v[28:31], v23 offset:4096
	ds_read_b128 v[32:35], v23 offset:5120
	s_setprio 0
	s_waitcnt lgkmcnt(1)
	v_mfma_f32_16x16x32_bf16 v[14:17], v[28:31], v[6:9], v[14:17]
	s_waitcnt lgkmcnt(0)
	s_barrier
	s_waitcnt lgkmcnt(0)
	v_mfma_f32_16x16x32_bf16 v[10:13], v[32:35], v[6:9], v[10:13]
	v_mfma_f32_16x16x32_bf16 v[6:9], v[28:31], v[24:27], v[2:5]
	v_lshlrev_b32_e32 v0, 5, v0
	v_mov_b32_e32 v36, s95
	v_mov_b32_e32 v37, s49
	v_mfma_f32_16x16x32_bf16 v[2:5], v[32:35], v[24:27], v[18:21]
	v_mov_b32_e32 v38, s94
	v_mov_b32_e32 v39, s48
	s_nop 0
	v_lshlrev_b32_e32 v18, 5, v40
	v_add3_u32 v26, v41, s8, v18
	v_lshlrev_b32_e32 v18, 2, v22
	v_add3_u32 v18, v18, s7, v0
	v_min_i32_e32 v0, 0x8000, v26
	v_cmp_gt_i32_e32 vcc, s58, v26
	v_ashrrev_i32_e32 v28, 12, v0
	v_add_u32_e32 v0, 0xffff8000, v26
	v_ashrrev_i32_e32 v27, 31, v26
	v_cndmask_b32_e32 v21, 0, v27, vcc
	v_cndmask_b32_e32 v20, v0, v26, vcc
	v_cndmask_b32_e32 v23, v36, v37, vcc
	v_cndmask_b32_e32 v22, v38, v39, vcc
	v_lshlrev_b64 v[20:21], 12, v[20:21]
	v_lshl_add_u64 v[20:21], v[22:23], 0, v[20:21]
	v_lshlrev_b64 v[22:23], 12, v[26:27]
	v_lshlrev_b64 v[24:25], 12, v[0:1]
	v_lshl_add_u64 v[22:23], s[48:49], 0, v[22:23]
	v_lshl_add_u64 v[24:25], s[94:95], 0, v[24:25]
	v_ashrrev_i32_e32 v19, 31, v18
	v_cndmask_b32_e32 v23, v25, v23, vcc
	v_cndmask_b32_e32 v22, v24, v22, vcc
	v_mul_hi_i32_i24_e32 v25, 0x6000, v28
	v_mul_i32_i24_e32 v24, 0x6000, v28
	v_lshl_add_u64 v[24:25], s[82:83], 0, v[24:25]
	v_lshlrev_b64 v[28:29], 2, v[18:19]
	v_lshl_add_u64 v[30:31], v[24:25], 0, v[28:29]
	v_lshl_add_u64 v[32:33], v[20:21], 0, v[28:29]
	v_lshl_add_u64 v[34:35], v[22:23], 0, v[28:29]
	flat_load_dwordx4 v[18:21], v[30:31]
	flat_load_dwordx4 v[22:25], v[32:33]
	s_waitcnt vmcnt(0) lgkmcnt(0)
	v_pk_fma_f32 v[14:15], v[14:15], v[18:19], v[22:23]
	v_pk_fma_f32 v[16:17], v[16:17], v[20:21], v[24:25]
	flat_store_dwordx4 v[34:35], v[14:17]
	flat_load_dwordx4 v[14:17], v[30:31] offset:64
	s_nop 0
	flat_load_dwordx4 v[18:21], v[32:33] offset:64
	s_waitcnt vmcnt(0) lgkmcnt(0)
	v_pk_fma_f32 v[10:11], v[10:11], v[14:15], v[18:19]
	v_pk_fma_f32 v[12:13], v[12:13], v[16:17], v[20:21]
	flat_store_dwordx4 v[34:35], v[10:13] offset:64
	s_nop 1
	v_add_u32_e32 v10, 16, v26
	v_min_i32_e32 v0, 0x8000, v10
	v_cmp_gt_i32_e32 vcc, s58, v10
	v_ashrrev_i32_e32 v16, 12, v0
	v_add_u32_e32 v0, 0xffff8010, v26
	v_ashrrev_i32_e32 v11, 31, v10
	v_cndmask_b32_e32 v13, 0, v11, vcc
	v_cndmask_b32_e32 v12, v0, v10, vcc
	v_cndmask_b32_e32 v15, v36, v37, vcc
	v_cndmask_b32_e32 v14, v38, v39, vcc
	v_lshlrev_b64 v[12:13], 12, v[12:13]
	v_lshl_add_u64 v[12:13], v[14:15], 0, v[12:13]
	v_lshlrev_b64 v[10:11], 12, v[10:11]
	v_lshlrev_b64 v[14:15], 12, v[0:1]
	v_lshl_add_u64 v[10:11], s[48:49], 0, v[10:11]
	v_lshl_add_u64 v[14:15], s[94:95], 0, v[14:15]
	v_cndmask_b32_e32 v11, v15, v11, vcc
	v_cndmask_b32_e32 v10, v14, v10, vcc
	v_mul_hi_i32_i24_e32 v15, 0x6000, v16
	v_mul_i32_i24_e32 v14, 0x6000, v16
	v_lshl_add_u64 v[14:15], s[82:83], 0, v[14:15]
	v_lshl_add_u64 v[18:19], v[14:15], 0, v[28:29]
	v_lshl_add_u64 v[20:21], v[12:13], 0, v[28:29]
	v_lshl_add_u64 v[22:23], v[10:11], 0, v[28:29]
	flat_load_dwordx4 v[10:13], v[18:19]
	flat_load_dwordx4 v[14:17], v[20:21]
	s_waitcnt vmcnt(0) lgkmcnt(0)
	v_pk_fma_f32 v[6:7], v[6:7], v[10:11], v[14:15]
	v_pk_fma_f32 v[8:9], v[8:9], v[12:13], v[16:17]
	flat_store_dwordx4 v[22:23], v[6:9]
	flat_load_dwordx4 v[6:9], v[18:19] offset:64
	s_nop 0
	flat_load_dwordx4 v[10:13], v[20:21] offset:64
	s_waitcnt vmcnt(0) lgkmcnt(0)
	v_pk_fma_f32 v[2:3], v[2:3], v[6:7], v[10:11]
	v_pk_fma_f32 v[4:5], v[4:5], v[8:9], v[12:13]
	flat_store_dwordx4 v[22:23], v[2:5] offset:64
	s_add_i32 s4, s4, s79
	s_add_i32 s5, s5, s40
	s_add_i32 s6, s6, s41
	s_cmpk_gt_i32 s4, 0x1ff
	s_cbranch_scc0 .LBB0_966
